# removed 15 redundant vmcnt(0) between LDS-DMA prefetch issue and ds_read in GEMM k-loops
# speedup vs baseline: 1.0679x; 1.0679x over previous
.LBB0_108:
	s_and_b32 s59, s58, 0x8000
	s_xor_b32 s62, s59, 0x8000
	v_add_u32_e32 v158, s62, v128
	v_lshl_add_u64 v[150:151], v[70:71], 0, s[46:47]
	v_add_u32_e32 v159, 0x4000, v158
	v_readfirstlane_b32 s62, v158
	v_lshl_add_u64 v[152:153], v[150:151], 0, s[28:29]
	v_lshl_add_u64 v[154:155], v[68:69], 0, s[46:47]
	s_mov_b32 m0, s62
	v_readfirstlane_b32 s62, v159
	v_lshl_add_u64 v[156:157], v[154:155], 0, s[28:29]
	global_load_lds_dwordx4 v[152:153], off
	s_mov_b32 m0, s62
	v_lshl_add_u64 v[152:153], v[150:151], 0, s[30:31]
	global_load_lds_dwordx4 v[156:157], off
	v_add_u32_e32 v156, 0x1000, v158
	v_add_u32_e32 v201, s59, v146
	v_readfirstlane_b32 s62, v156
	v_add_u32_e32 v156, 0x5000, v158
	s_mov_b32 m0, s62
	v_readfirstlane_b32 s62, v156
	v_add_u32_e32 v156, 0x2000, v158
	global_load_lds_dwordx4 v[152:153], off
	v_lshl_add_u64 v[152:153], v[154:155], 0, s[30:31]
	s_mov_b32 m0, s62
	v_readfirstlane_b32 s62, v156
	v_add_u32_e32 v156, 0x6000, v158
	global_load_lds_dwordx4 v[152:153], off
	v_lshl_add_u64 v[152:153], v[150:151], 0, s[0:1]
	s_mov_b32 m0, s62
	v_readfirstlane_b32 s62, v156
	global_load_lds_dwordx4 v[152:153], off
	v_lshl_add_u64 v[152:153], v[154:155], 0, s[0:1]
	s_mov_b32 m0, s62
	v_lshl_add_u64 v[150:151], v[150:151], 0, s[22:23]
	global_load_lds_dwordx4 v[152:153], off
	v_add_u32_e32 v152, 0x3000, v158
	v_or_b32_e32 v214, s59, v147
	v_readfirstlane_b32 s62, v152
	v_add_u32_e32 v152, 0x7000, v158
	s_mov_b32 m0, s62
	v_readfirstlane_b32 s62, v152
	global_load_lds_dwordx4 v[150:151], off
	v_lshl_add_u64 v[150:151], v[154:155], 0, s[22:23]
	s_mov_b32 m0, s62
	v_add_u32_e32 v202, v201, v149
	global_load_lds_dwordx4 v[150:151], off
	v_add_u32_e32 v210, v214, v149
	ds_read_b128 v[150:153], v202
	ds_read_b128 v[154:157], v202 offset:2048
	ds_read_b128 v[158:161], v210 offset:16384
	ds_read_b128 v[162:165], v210 offset:18432
	ds_read_b128 v[166:169], v202 offset:4096
	ds_read_b128 v[202:205], v202 offset:6144
	ds_read_b128 v[206:209], v210 offset:20480
	ds_read_b128 v[210:213], v210 offset:22528
	s_setprio 1
	s_waitcnt lgkmcnt(0)
	v_mfma_f32_16x16x32_bf16 v[0:3], v[150:153], v[158:161], v[0:3]
	v_mfma_f32_16x16x32_bf16 v[4:7], v[150:153], v[162:165], v[4:7]
	v_mfma_f32_16x16x32_bf16 v[8:11], v[150:153], v[206:209], v[8:11]
	v_mfma_f32_16x16x32_bf16 v[12:15], v[150:153], v[210:213], v[12:15]
	v_mfma_f32_16x16x32_bf16 v[16:19], v[154:157], v[158:161], v[16:19]
	v_mfma_f32_16x16x32_bf16 v[20:23], v[154:157], v[162:165], v[20:23]
	v_mfma_f32_16x16x32_bf16 v[24:27], v[154:157], v[206:209], v[24:27]
	v_mfma_f32_16x16x32_bf16 v[28:31], v[154:157], v[210:213], v[28:31]
	v_mfma_f32_16x16x32_bf16 v[32:35], v[166:169], v[158:161], v[32:35]
	v_mfma_f32_16x16x32_bf16 v[36:39], v[166:169], v[162:165], v[36:39]
	v_mfma_f32_16x16x32_bf16 v[40:43], v[166:169], v[206:209], v[40:43]
	v_mfma_f32_16x16x32_bf16 v[44:47], v[166:169], v[210:213], v[44:47]
	v_mfma_f32_16x16x32_bf16 v[48:51], v[202:205], v[158:161], v[48:51]
	v_mfma_f32_16x16x32_bf16 v[52:55], v[202:205], v[162:165], v[52:55]
	v_mfma_f32_16x16x32_bf16 v[56:59], v[202:205], v[206:209], v[56:59]
	v_mfma_f32_16x16x32_bf16 v[60:63], v[202:205], v[210:213], v[60:63]
	s_setprio 0
	v_add_u32_e32 v201, v201, v148
	v_add_u32_e32 v210, v214, v148
	ds_read_b128 v[150:153], v201
	ds_read_b128 v[154:157], v201 offset:2048
	ds_read_b128 v[158:161], v210 offset:16384
	ds_read_b128 v[162:165], v210 offset:18432
	ds_read_b128 v[166:169], v201 offset:4096
	ds_read_b128 v[202:205], v201 offset:6144
	ds_read_b128 v[206:209], v210 offset:20480
	ds_read_b128 v[210:213], v210 offset:22528
	s_setprio 1
	s_waitcnt lgkmcnt(5)
	v_mfma_f32_16x16x32_bf16 v[0:3], v[150:153], v[158:161], v[0:3]
	s_waitcnt lgkmcnt(4)
	v_mfma_f32_16x16x32_bf16 v[4:7], v[150:153], v[162:165], v[4:7]
	s_waitcnt lgkmcnt(1)
	v_mfma_f32_16x16x32_bf16 v[8:11], v[150:153], v[206:209], v[8:11]
	s_waitcnt lgkmcnt(0)
	v_mfma_f32_16x16x32_bf16 v[12:15], v[150:153], v[210:213], v[12:15]
	v_mfma_f32_16x16x32_bf16 v[16:19], v[154:157], v[158:161], v[16:19]
	v_mfma_f32_16x16x32_bf16 v[20:23], v[154:157], v[162:165], v[20:23]
	v_mfma_f32_16x16x32_bf16 v[24:27], v[154:157], v[206:209], v[24:27]
	v_mfma_f32_16x16x32_bf16 v[28:31], v[154:157], v[210:213], v[28:31]
	v_mfma_f32_16x16x32_bf16 v[32:35], v[166:169], v[158:161], v[32:35]
	v_mfma_f32_16x16x32_bf16 v[36:39], v[166:169], v[162:165], v[36:39]
	v_mfma_f32_16x16x32_bf16 v[40:43], v[166:169], v[206:209], v[40:43]
	v_mfma_f32_16x16x32_bf16 v[44:47], v[166:169], v[210:213], v[44:47]
	v_mfma_f32_16x16x32_bf16 v[48:51], v[202:205], v[158:161], v[48:51]
	v_mfma_f32_16x16x32_bf16 v[52:55], v[202:205], v[162:165], v[52:55]
	v_mfma_f32_16x16x32_bf16 v[56:59], v[202:205], v[206:209], v[56:59]
	v_mfma_f32_16x16x32_bf16 v[60:63], v[202:205], v[210:213], v[60:63]
	s_setprio 0
	s_waitcnt vmcnt(0)
	s_add_u32 s46, s46, 0x80
	s_addc_u32 s47, s47, 0
	s_add_i32 s58, s58, 0x8000
	s_cmpk_eq_i32 s46, 0x780
	s_barrier
	s_cbranch_scc0 .LBB0_108
	v_add_u32_e32 v128, v146, v149
	v_add_u32_e32 v149, v147, v149
	ds_read_b128 v[68:71], v128 offset:32768
	ds_read_b128 v[150:153], v128 offset:34816
	ds_read_b128 v[154:157], v149 offset:49152
	ds_read_b128 v[158:161], v149 offset:51200
	ds_read_b128 v[162:165], v128 offset:36864
	ds_read_b128 v[166:169], v128 offset:38912
	ds_read_b128 v[202:205], v149 offset:53248
	ds_read_b128 v[206:209], v149 offset:55296
	s_setprio 1
	s_waitcnt lgkmcnt(5)
	v_mfma_f32_16x16x32_bf16 v[0:3], v[68:71], v[154:157], v[0:3]
	s_waitcnt lgkmcnt(4)
	v_mfma_f32_16x16x32_bf16 v[4:7], v[68:71], v[158:161], v[4:7]
	s_waitcnt lgkmcnt(1)
	v_mfma_f32_16x16x32_bf16 v[8:11], v[68:71], v[202:205], v[8:11]
	s_waitcnt lgkmcnt(0)
	v_mfma_f32_16x16x32_bf16 v[12:15], v[68:71], v[206:209], v[12:15]
	v_mfma_f32_16x16x32_bf16 v[16:19], v[150:153], v[154:157], v[16:19]
	v_mfma_f32_16x16x32_bf16 v[20:23], v[150:153], v[158:161], v[20:23]
	v_mfma_f32_16x16x32_bf16 v[24:27], v[150:153], v[202:205], v[24:27]
	v_mfma_f32_16x16x32_bf16 v[28:31], v[150:153], v[206:209], v[28:31]
	v_mfma_f32_16x16x32_bf16 v[32:35], v[162:165], v[154:157], v[32:35]
	v_mfma_f32_16x16x32_bf16 v[36:39], v[162:165], v[158:161], v[36:39]
	v_mfma_f32_16x16x32_bf16 v[40:43], v[162:165], v[202:205], v[40:43]
	v_mfma_f32_16x16x32_bf16 v[44:47], v[162:165], v[206:209], v[44:47]
	v_mfma_f32_16x16x32_bf16 v[48:51], v[166:169], v[154:157], v[48:51]
	v_mfma_f32_16x16x32_bf16 v[52:55], v[166:169], v[158:161], v[52:55]
	v_mfma_f32_16x16x32_bf16 v[56:59], v[166:169], v[202:205], v[56:59]
	v_mfma_f32_16x16x32_bf16 v[60:63], v[166:169], v[206:209], v[60:63]
	s_setprio 0
	v_add_u32_e32 v128, v146, v148
	v_add_u32_e32 v201, v147, v148
	ds_read_b128 v[68:71], v128 offset:32768
	ds_read_b128 v[146:149], v128 offset:34816
	ds_read_b128 v[150:153], v201 offset:49152
	ds_read_b128 v[154:157], v201 offset:51200
	ds_read_b128 v[158:161], v128 offset:36864
	ds_read_b128 v[162:165], v128 offset:38912
	ds_read_b128 v[166:169], v201 offset:53248
	ds_read_b128 v[202:205], v201 offset:55296
	s_setprio 1
	s_waitcnt lgkmcnt(5)
	v_mfma_f32_16x16x32_bf16 v[206:209], v[68:71], v[150:153], v[0:3]
	s_waitcnt lgkmcnt(4)
	v_mfma_f32_16x16x32_bf16 v[210:213], v[68:71], v[154:157], v[4:7]
	s_waitcnt lgkmcnt(1)
	v_mfma_f32_16x16x32_bf16 v[214:217], v[68:71], v[166:169], v[8:11]
	s_waitcnt lgkmcnt(0)
	v_mfma_f32_16x16x32_bf16 v[68:71], v[68:71], v[202:205], v[12:15]
	v_mfma_f32_16x16x32_bf16 v[218:221], v[146:149], v[150:153], v[16:19]
	v_mfma_f32_16x16x32_bf16 v[222:225], v[146:149], v[154:157], v[20:23]
	v_mfma_f32_16x16x32_bf16 v[226:229], v[146:149], v[166:169], v[24:27]
	v_mfma_f32_16x16x32_bf16 v[146:149], v[146:149], v[202:205], v[28:31]
	v_mfma_f32_16x16x32_bf16 v[28:31], v[158:161], v[150:153], v[32:35]
	v_mfma_f32_16x16x32_bf16 v[24:27], v[158:161], v[154:157], v[36:39]
	v_mfma_f32_16x16x32_bf16 v[20:23], v[158:161], v[166:169], v[40:43]
	v_mfma_f32_16x16x32_bf16 v[16:19], v[158:161], v[202:205], v[44:47]
	v_mfma_f32_16x16x32_bf16 v[12:15], v[162:165], v[150:153], v[48:51]
	v_mfma_f32_16x16x32_bf16 v[8:11], v[162:165], v[154:157], v[52:55]
	v_mfma_f32_16x16x32_bf16 v[4:7], v[162:165], v[166:169], v[56:59]
	v_mfma_f32_16x16x32_bf16 v[0:3], v[162:165], v[202:205], v[60:63]
	s_setprio 0
	v_or3_b32 v32, v127, s57, v119
	v_lshlrev_b32_e32 v128, 2, v32
	v_lshl_add_u64 v[32:33], s[44:45], 0, v[128:129]
	v_mul_f32_e32 v36, v79, v206
	v_lshl_add_u64 v[34:35], v[32:33], 0, v[66:67]
	v_fmac_f32_e32 v36, 0x3fd744fd, v138
	s_waitcnt vmcnt(0)
	s_barrier
	global_store_dword v[34:35], v36, off
	v_mul_f32_e32 v36, v76, v210
	v_fmac_f32_e32 v36, 0x3fd744fd, v137
	global_store_dword v[34:35], v36, off offset:64
	v_mul_f32_e32 v36, v75, v214
	v_fmac_f32_e32 v36, 0x3fd744fd, v136
	global_store_dword v[34:35], v36, off offset:128
	v_mul_f32_e32 v36, v78, v68
	v_fmac_f32_e32 v36, 0x3fd744fd, v135
	global_store_dword v[34:35], v36, off offset:192
	v_or_b32_e32 v34, 1, v64
	v_ashrrev_i32_e32 v35, 31, v34
	v_lshlrev_b64 v[34:35], 12, v[34:35]
	v_mul_f32_e32 v36, v79, v207
	v_lshl_add_u64 v[34:35], v[32:33], 0, v[34:35]
	v_fmac_f32_e32 v36, 0x3fd744fd, v145
	global_store_dword v[34:35], v36, off
	v_mul_f32_e32 v36, v76, v211
	v_fmac_f32_e32 v36, 0x3fd744fd, v133
	global_store_dword v[34:35], v36, off offset:64
	v_mul_f32_e32 v36, v75, v215
	v_fmac_f32_e32 v36, 0x3fd744fd, v131
	global_store_dword v[34:35], v36, off offset:128
	v_mul_f32_e32 v36, v78, v69
	v_fmac_f32_e32 v36, 0x3fd744fd, v126
	global_store_dword v[34:35], v36, off offset:192
	v_or_b32_e32 v34, 2, v64
	v_ashrrev_i32_e32 v35, 31, v34
	v_lshlrev_b64 v[34:35], 12, v[34:35]
	v_mul_f32_e32 v36, v79, v208
	v_lshl_add_u64 v[34:35], v[32:33], 0, v[34:35]
	v_fmac_f32_e32 v36, 0x3fd744fd, v144
	global_store_dword v[34:35], v36, off
	v_mul_f32_e32 v36, v76, v212
	v_fmac_f32_e32 v36, 0x3fd744fd, v143
	global_store_dword v[34:35], v36, off offset:64
	v_mul_f32_e32 v36, v75, v216
	v_fmac_f32_e32 v36, 0x3fd744fd, v142
	global_store_dword v[34:35], v36, off offset:128
	v_mul_f32_e32 v36, v78, v70
	v_fmac_f32_e32 v36, 0x3fd744fd, v141
	global_store_dword v[34:35], v36, off offset:192
	v_or_b32_e32 v34, 3, v64
	v_ashrrev_i32_e32 v35, 31, v34
	v_lshlrev_b64 v[34:35], 12, v[34:35]
	v_mul_f32_e32 v36, v79, v209
	v_lshl_add_u64 v[34:35], v[32:33], 0, v[34:35]
	v_fmac_f32_e32 v36, 0x3fd744fd, v117
	global_store_dword v[34:35], v36, off
	v_mul_f32_e32 v36, v76, v213
	v_fmac_f32_e32 v36, 0x3fd744fd, v125
	global_store_dword v[34:35], v36, off offset:64
	v_mul_f32_e32 v36, v75, v217
	v_fmac_f32_e32 v36, 0x3fd744fd, v124
	global_store_dword v[34:35], v36, off offset:128
	v_mul_f32_e32 v36, v78, v71
	v_fmac_f32_e32 v36, 0x3fd744fd, v122
	global_store_dword v[34:35], v36, off offset:192
	v_or_b32_e32 v34, 16, v64
	v_ashrrev_i32_e32 v35, 31, v34
	v_lshlrev_b64 v[34:35], 12, v[34:35]
	v_mul_f32_e32 v36, v79, v218
	v_lshl_add_u64 v[34:35], v[32:33], 0, v[34:35]
	v_fmac_f32_e32 v36, 0x3fd744fd, v140
	global_store_dword v[34:35], v36, off
	v_mul_f32_e32 v36, v76, v222
	v_fmac_f32_e32 v36, 0x3fd744fd, v121
	global_store_dword v[34:35], v36, off offset:64
	v_mul_f32_e32 v36, v75, v226
	v_fmac_f32_e32 v36, 0x3fd744fd, v120
	global_store_dword v[34:35], v36, off offset:128
	v_mul_f32_e32 v36, v78, v146
	v_fmac_f32_e32 v36, 0x3fd744fd, v118
	global_store_dword v[34:35], v36, off offset:192
	v_or_b32_e32 v34, 17, v64
	v_ashrrev_i32_e32 v35, 31, v34
	v_lshlrev_b64 v[34:35], 12, v[34:35]
	v_mul_f32_e32 v36, v79, v219
	v_lshl_add_u64 v[34:35], v[32:33], 0, v[34:35]
	v_fmac_f32_e32 v36, 0x3fd744fd, v139
	global_store_dword v[34:35], v36, off
	v_mul_f32_e32 v36, v76, v223
	v_fmac_f32_e32 v36, 0x3fd744fd, v116
	global_store_dword v[34:35], v36, off offset:64
	v_mul_f32_e32 v36, v75, v227
	v_fmac_f32_e32 v36, 0x3fd744fd, v115
	global_store_dword v[34:35], v36, off offset:128
	v_mul_f32_e32 v36, v78, v147
	v_fmac_f32_e32 v36, 0x3fd744fd, v114
	global_store_dword v[34:35], v36, off offset:192
	v_or_b32_e32 v34, 18, v64
	v_ashrrev_i32_e32 v35, 31, v34
	v_lshlrev_b64 v[34:35], 12, v[34:35]
	v_mul_f32_e32 v36, v79, v220
	v_lshl_add_u64 v[34:35], v[32:33], 0, v[34:35]
	v_fmac_f32_e32 v36, 0x3fd744fd, v110
	global_store_dword v[34:35], v36, off
	v_mul_f32_e32 v36, v76, v224
	v_fmac_f32_e32 v36, 0x3fd744fd, v109
	global_store_dword v[34:35], v36, off offset:64
	v_mul_f32_e32 v36, v75, v228
	v_fmac_f32_e32 v36, 0x3fd744fd, v107
	global_store_dword v[34:35], v36, off offset:128
	v_mul_f32_e32 v36, v78, v148
	v_fmac_f32_e32 v36, 0x3fd744fd, v123
	global_store_dword v[34:35], v36, off offset:192
	v_or_b32_e32 v34, 19, v64
	v_ashrrev_i32_e32 v35, 31, v34
	v_lshlrev_b64 v[34:35], 12, v[34:35]
	v_mul_f32_e32 v36, v79, v221
	v_lshl_add_u64 v[34:35], v[32:33], 0, v[34:35]
	v_fmac_f32_e32 v36, 0x3fd744fd, v106
	global_store_dword v[34:35], v36, off
	v_mul_f32_e32 v36, v76, v225
	v_fmac_f32_e32 v36, 0x3fd744fd, v105
	global_store_dword v[34:35], v36, off offset:64
	v_mul_f32_e32 v36, v75, v229
	v_fmac_f32_e32 v36, 0x3fd744fd, v104
	global_store_dword v[34:35], v36, off offset:128
	v_mul_f32_e32 v36, v78, v149
	v_fmac_f32_e32 v36, 0x3fd744fd, v103
	global_store_dword v[34:35], v36, off offset:192
	v_or_b32_e32 v34, 32, v64
	v_ashrrev_i32_e32 v35, 31, v34
	v_lshlrev_b64 v[34:35], 12, v[34:35]
	v_mul_f32_e32 v28, v79, v28
	v_mul_f32_e32 v24, v76, v24
	v_mul_f32_e32 v20, v75, v20
	v_mul_f32_e32 v16, v78, v16
	v_lshl_add_u64 v[34:35], v[32:33], 0, v[34:35]
	v_fmac_f32_e32 v28, 0x3fd744fd, v108
	v_fmac_f32_e32 v24, 0x3fd744fd, v113
	v_fmac_f32_e32 v20, 0x3fd744fd, v112
	v_fmac_f32_e32 v16, 0x3fd744fd, v111
	global_store_dword v[34:35], v28, off
	global_store_dword v[34:35], v24, off offset:64
	global_store_dword v[34:35], v20, off offset:128
	global_store_dword v[34:35], v16, off offset:192
	v_or_b32_e32 v34, 33, v64
	v_ashrrev_i32_e32 v35, 31, v34
	v_lshlrev_b64 v[34:35], 12, v[34:35]
	v_mul_f32_e32 v16, v79, v29
	v_lshl_add_u64 v[34:35], v[32:33], 0, v[34:35]
	v_fmac_f32_e32 v16, 0x3fd744fd, v101
	global_store_dword v[34:35], v16, off
	v_mul_f32_e32 v16, v76, v25
	v_fmac_f32_e32 v16, 0x3fd744fd, v98
	global_store_dword v[34:35], v16, off offset:64
	v_mul_f32_e32 v16, v75, v21
	v_fmac_f32_e32 v16, 0x3fd744fd, v94
	global_store_dword v[34:35], v16, off offset:128
	v_mul_f32_e32 v16, v78, v17
	v_fmac_f32_e32 v16, 0x3fd744fd, v92
	global_store_dword v[34:35], v16, off offset:192
	v_or_b32_e32 v16, 34, v64
	v_ashrrev_i32_e32 v17, 31, v16
	v_lshlrev_b64 v[16:17], 12, v[16:17]
	v_mul_f32_e32 v20, v79, v30
	v_lshl_add_u64 v[16:17], v[32:33], 0, v[16:17]
	v_fmac_f32_e32 v20, 0x3fd744fd, v91
	global_store_dword v[16:17], v20, off
	v_mul_f32_e32 v20, v76, v26
	v_fmac_f32_e32 v20, 0x3fd744fd, v102
	global_store_dword v[16:17], v20, off offset:64
	v_mul_f32_e32 v20, v75, v22
	v_mul_f32_e32 v18, v78, v18
	v_fmac_f32_e32 v20, 0x3fd744fd, v99
	v_fmac_f32_e32 v18, 0x3fd744fd, v95
	global_store_dword v[16:17], v20, off offset:128
	global_store_dword v[16:17], v18, off offset:192
	v_or_b32_e32 v16, 35, v64
	v_ashrrev_i32_e32 v17, 31, v16
	v_lshlrev_b64 v[16:17], 12, v[16:17]
	v_mul_f32_e32 v18, v79, v31
	v_lshl_add_u64 v[16:17], v[32:33], 0, v[16:17]
	v_fmac_f32_e32 v18, 0x3fd744fd, v89
	global_store_dword v[16:17], v18, off
	v_mul_f32_e32 v18, v76, v27
	v_fmac_f32_e32 v18, 0x3fd744fd, v88
	global_store_dword v[16:17], v18, off offset:64
	v_mul_f32_e32 v18, v75, v23
	v_fmac_f32_e32 v18, 0x3fd744fd, v96
	global_store_dword v[16:17], v18, off offset:128
	v_mul_f32_e32 v18, v78, v19
	v_fmac_f32_e32 v18, 0x3fd744fd, v93
	global_store_dword v[16:17], v18, off offset:192
	v_or_b32_e32 v16, 48, v64
	v_ashrrev_i32_e32 v17, 31, v16
	v_lshlrev_b64 v[16:17], 12, v[16:17]
	v_mul_f32_e32 v12, v79, v12
	v_mul_f32_e32 v8, v76, v8
	v_mul_f32_e32 v4, v75, v4
	v_mul_f32_e32 v0, v78, v0
	v_lshl_add_u64 v[16:17], v[32:33], 0, v[16:17]
	v_fmac_f32_e32 v12, 0x3fd744fd, v90
	v_fmac_f32_e32 v8, 0x3fd744fd, v86
	v_fmac_f32_e32 v4, 0x3fd744fd, v100
	v_fmac_f32_e32 v0, 0x3fd744fd, v97
	global_store_dword v[16:17], v12, off
	global_store_dword v[16:17], v8, off offset:64
	global_store_dword v[16:17], v4, off offset:128
	global_store_dword v[16:17], v0, off offset:192
	v_or_b32_e32 v16, 49, v64
	v_ashrrev_i32_e32 v17, 31, v16
	v_lshlrev_b64 v[16:17], 12, v[16:17]
	v_mul_f32_e32 v0, v79, v13
	v_lshl_add_u64 v[16:17], v[32:33], 0, v[16:17]
	v_fmac_f32_e32 v0, 0x3fd744fd, v87
	global_store_dword v[16:17], v0, off
	v_mul_f32_e32 v0, v76, v9
	v_fmac_f32_e32 v0, 0x3fd744fd, v84
	global_store_dword v[16:17], v0, off offset:64
	v_mul_f32_e32 v0, v75, v5
	v_fmac_f32_e32 v0, 0x3fd744fd, v82
	global_store_dword v[16:17], v0, off offset:128
	v_mul_f32_e32 v0, v78, v1
	v_fmac_f32_e32 v0, 0x3fd744fd, v80
	global_store_dword v[16:17], v0, off offset:192
	v_or_b32_e32 v0, 50, v64
	v_ashrrev_i32_e32 v1, 31, v0
	v_lshlrev_b64 v[0:1], 12, v[0:1]
	v_mul_f32_e32 v4, v79, v14
	v_lshl_add_u64 v[0:1], v[32:33], 0, v[0:1]
	v_fmac_f32_e32 v4, 0x3fd744fd, v77
	global_store_dword v[0:1], v4, off
	v_mul_f32_e32 v4, v76, v10
	v_fmac_f32_e32 v4, 0x3fd744fd, v85
	global_store_dword v[0:1], v4, off offset:64
	v_mul_f32_e32 v4, v75, v6
	v_mul_f32_e32 v2, v78, v2
	v_fmac_f32_e32 v4, 0x3fd744fd, v83
	v_fmac_f32_e32 v2, 0x3fd744fd, v81
	global_store_dword v[0:1], v4, off offset:128
	global_store_dword v[0:1], v2, off offset:192
	v_or_b32_e32 v0, 51, v64
	v_ashrrev_i32_e32 v1, 31, v0
	v_lshlrev_b64 v[0:1], 12, v[0:1]
	v_mul_f32_e32 v2, v79, v15
	v_lshl_add_u64 v[0:1], v[32:33], 0, v[0:1]
	v_fmac_f32_e32 v2, 0x3fd744fd, v74
	global_store_dword v[0:1], v2, off
	v_mul_f32_e32 v2, v76, v11
	v_fmac_f32_e32 v2, 0x3fd744fd, v73
	global_store_dword v[0:1], v2, off offset:64
	v_mul_f32_e32 v2, v75, v7
	v_fmac_f32_e32 v2, 0x3fd744fd, v72
	global_store_dword v[0:1], v2, off offset:128
	v_mul_f32_e32 v2, v78, v3
	s_add_i32 s56, s56, s33
	s_add_i32 s55, s55, s66
	s_add_i32 s54, s54, s69
	v_fmac_f32_e32 v2, 0x3fd744fd, v65
	s_cmp_gt_u32 s56, 63
	global_store_dword v[0:1], v2, off offset:192
	s_cbranch_scc0 .LBB0_107
	v_readlane_b32 s4, v235, 44
	v_readlane_b32 s5, v235, 45
	s_mul_hi_i32 s52, s4, 0x1b000
	s_mul_i32 s53, s4, 0x1b000
	v_readlane_b32 s4, v235, 34
	v_readlane_b32 s5, v235, 35
	s_add_u32 s46, s4, 0x14ae6000
	s_addc_u32 s47, s5, 0
	s_add_u32 s50, s50, s53
	s_addc_u32 s51, s51, s52
	s_add_u32 s50, s50, 0x17000
	s_addc_u32 s51, s51, 0
	s_mov_b32 s54, s67
	v_readlane_b32 s55, v235, 10
	s_mov_b32 s56, s67
	s_movk_i32 s96, 0x1000
	s_branch .LBB0_112

.LBB0_114:
	s_and_b32 s67, s66, 0x8000
	s_xor_b32 s68, s67, 0x8000
	v_add_u32_e32 v86, s68, v72
	v_lshl_add_u64 v[78:79], v[66:67], 0, s[52:53]
	v_add_u32_e32 v87, 0x4000, v86
	v_readfirstlane_b32 s68, v86
	v_lshl_add_u64 v[80:81], v[78:79], 0, s[4:5]
	v_lshl_add_u64 v[82:83], v[64:65], 0, s[52:53]
	s_mov_b32 m0, s68
	v_readfirstlane_b32 s68, v87
	v_lshl_add_u64 v[84:85], v[82:83], 0, s[4:5]
	global_load_lds_dwordx4 v[80:81], off
	s_mov_b32 m0, s68
	v_lshl_add_u64 v[80:81], v[78:79], 0, s[6:7]
	global_load_lds_dwordx4 v[84:85], off
	v_add_u32_e32 v84, 0x1000, v86
	v_add3_u32 v110, s67, v74, v75
	v_readfirstlane_b32 s68, v84
	v_add_u32_e32 v84, 0x5000, v86
	s_mov_b32 m0, s68
	v_readfirstlane_b32 s68, v84
	v_add_u32_e32 v84, 0x2000, v86
	global_load_lds_dwordx4 v[80:81], off
	v_lshl_add_u64 v[80:81], v[82:83], 0, s[6:7]
	s_mov_b32 m0, s68
	v_readfirstlane_b32 s68, v84
	v_add_u32_e32 v84, 0x6000, v86
	global_load_lds_dwordx4 v[80:81], off
	v_lshl_add_u64 v[80:81], v[78:79], 0, s[8:9]
	s_mov_b32 m0, s68
	v_readfirstlane_b32 s68, v84
	global_load_lds_dwordx4 v[80:81], off
	v_lshl_add_u64 v[80:81], v[82:83], 0, s[8:9]
	s_mov_b32 m0, s68
	v_lshl_add_u64 v[78:79], v[78:79], 0, s[10:11]
	global_load_lds_dwordx4 v[80:81], off
	v_add_u32_e32 v80, 0x3000, v86
	v_add_u32_e32 v98, v110, v77
	v_readfirstlane_b32 s68, v80
	v_add_u32_e32 v80, 0x7000, v86
	s_mov_b32 m0, s68
	v_readfirstlane_b32 s68, v80
	global_load_lds_dwordx4 v[78:79], off
	v_lshl_add_u64 v[78:79], v[82:83], 0, s[10:11]
	s_mov_b32 m0, s68
	s_nop 0
	global_load_lds_dwordx4 v[78:79], off
	v_or_b32_e32 v78, s67, v76
	v_add_u32_e32 v111, v78, v75
	v_add_u32_e32 v106, v111, v77
	ds_read_b128 v[78:81], v98
	ds_read_b128 v[82:85], v98 offset:2048
	ds_read_b128 v[86:89], v106 offset:16384
	ds_read_b128 v[90:93], v106 offset:18432
	ds_read_b128 v[94:97], v98 offset:4096
	ds_read_b128 v[98:101], v98 offset:6144
	ds_read_b128 v[102:105], v106 offset:20480
	ds_read_b128 v[106:109], v106 offset:22528
	s_setprio 1
	s_waitcnt lgkmcnt(0)
	v_mfma_f32_16x16x32_bf16 v[56:59], v[78:81], v[86:89], v[56:59]
	v_mfma_f32_16x16x32_bf16 v[44:47], v[78:81], v[90:93], v[44:47]
	v_mfma_f32_16x16x32_bf16 v[36:39], v[78:81], v[102:105], v[36:39]
	v_mfma_f32_16x16x32_bf16 v[32:35], v[78:81], v[106:109], v[32:35]
	v_mfma_f32_16x16x32_bf16 v[28:31], v[82:85], v[86:89], v[28:31]
	v_mfma_f32_16x16x32_bf16 v[24:27], v[82:85], v[90:93], v[24:27]
	v_mfma_f32_16x16x32_bf16 v[20:23], v[82:85], v[102:105], v[20:23]
	v_mfma_f32_16x16x32_bf16 v[16:19], v[82:85], v[106:109], v[16:19]
	v_mfma_f32_16x16x32_bf16 v[12:15], v[94:97], v[86:89], v[12:15]
	v_mfma_f32_16x16x32_bf16 v[8:11], v[94:97], v[90:93], v[8:11]
	v_mfma_f32_16x16x32_bf16 v[4:7], v[94:97], v[102:105], v[4:7]
	v_mfma_f32_16x16x32_bf16 v[0:3], v[94:97], v[106:109], v[0:3]
	v_mfma_f32_16x16x32_bf16 v[40:43], v[98:101], v[86:89], v[40:43]
	v_mfma_f32_16x16x32_bf16 v[48:51], v[98:101], v[90:93], v[48:51]
	v_mfma_f32_16x16x32_bf16 v[52:55], v[98:101], v[102:105], v[52:55]
	v_mfma_f32_16x16x32_bf16 v[60:63], v[98:101], v[106:109], v[60:63]
	s_setprio 0
	v_add_u32_e32 v98, v110, v73
	v_add_u32_e32 v106, v111, v73
	ds_read_b128 v[78:81], v98
	ds_read_b128 v[82:85], v98 offset:2048
	ds_read_b128 v[86:89], v106 offset:16384
	ds_read_b128 v[90:93], v106 offset:18432
	ds_read_b128 v[94:97], v98 offset:4096
	ds_read_b128 v[98:101], v98 offset:6144
	ds_read_b128 v[102:105], v106 offset:20480
	ds_read_b128 v[106:109], v106 offset:22528
	s_setprio 1
	s_waitcnt lgkmcnt(5)
	v_mfma_f32_16x16x32_bf16 v[56:59], v[78:81], v[86:89], v[56:59]
	s_waitcnt lgkmcnt(4)
	v_mfma_f32_16x16x32_bf16 v[44:47], v[78:81], v[90:93], v[44:47]
	s_waitcnt lgkmcnt(1)
	v_mfma_f32_16x16x32_bf16 v[36:39], v[78:81], v[102:105], v[36:39]
	s_waitcnt lgkmcnt(0)
	v_mfma_f32_16x16x32_bf16 v[32:35], v[78:81], v[106:109], v[32:35]
	v_mfma_f32_16x16x32_bf16 v[28:31], v[82:85], v[86:89], v[28:31]
	v_mfma_f32_16x16x32_bf16 v[24:27], v[82:85], v[90:93], v[24:27]
	v_mfma_f32_16x16x32_bf16 v[20:23], v[82:85], v[102:105], v[20:23]
	v_mfma_f32_16x16x32_bf16 v[16:19], v[82:85], v[106:109], v[16:19]
	v_mfma_f32_16x16x32_bf16 v[12:15], v[94:97], v[86:89], v[12:15]
	v_mfma_f32_16x16x32_bf16 v[8:11], v[94:97], v[90:93], v[8:11]
	v_mfma_f32_16x16x32_bf16 v[4:7], v[94:97], v[102:105], v[4:7]
	v_mfma_f32_16x16x32_bf16 v[0:3], v[94:97], v[106:109], v[0:3]
	v_mfma_f32_16x16x32_bf16 v[40:43], v[98:101], v[86:89], v[40:43]
	v_mfma_f32_16x16x32_bf16 v[48:51], v[98:101], v[90:93], v[48:51]
	v_mfma_f32_16x16x32_bf16 v[52:55], v[98:101], v[102:105], v[52:55]
	v_mfma_f32_16x16x32_bf16 v[60:63], v[98:101], v[106:109], v[60:63]
	s_setprio 0
	s_waitcnt vmcnt(0)
	s_add_u32 s52, s52, 0x80
	s_addc_u32 s53, s53, 0
	s_add_i32 s66, s66, 0x8000
	s_cmpk_eq_i32 s52, 0x380
	s_barrier
	s_cbranch_scc0 .LBB0_114
	v_add_u32_e32 v72, v74, v75
	v_add_u32_e32 v102, v76, v75
	v_add_u32_e32 v90, v72, v77
	v_add_u32_e32 v98, v102, v77
	ds_read_b128 v[64:67], v90 offset:32768
	ds_read_b128 v[74:77], v90 offset:34816
	ds_read_b128 v[78:81], v98 offset:49152
	ds_read_b128 v[82:85], v98 offset:51200
	ds_read_b128 v[86:89], v90 offset:36864
	ds_read_b128 v[90:93], v90 offset:38912
	ds_read_b128 v[94:97], v98 offset:53248
	ds_read_b128 v[98:101], v98 offset:55296
	s_setprio 1
	s_waitcnt lgkmcnt(5)
	v_mfma_f32_16x16x32_bf16 v[56:59], v[64:67], v[78:81], v[56:59]
	s_waitcnt lgkmcnt(4)
	v_mfma_f32_16x16x32_bf16 v[44:47], v[64:67], v[82:85], v[44:47]
	s_waitcnt lgkmcnt(1)
	v_mfma_f32_16x16x32_bf16 v[36:39], v[64:67], v[94:97], v[36:39]
	s_waitcnt lgkmcnt(0)
	v_mfma_f32_16x16x32_bf16 v[32:35], v[64:67], v[98:101], v[32:35]
	v_mfma_f32_16x16x32_bf16 v[28:31], v[74:77], v[78:81], v[28:31]
	v_mfma_f32_16x16x32_bf16 v[24:27], v[74:77], v[82:85], v[24:27]
	v_mfma_f32_16x16x32_bf16 v[20:23], v[74:77], v[94:97], v[20:23]
	v_mfma_f32_16x16x32_bf16 v[16:19], v[74:77], v[98:101], v[16:19]
	v_mfma_f32_16x16x32_bf16 v[12:15], v[86:89], v[78:81], v[12:15]
	v_mfma_f32_16x16x32_bf16 v[8:11], v[86:89], v[82:85], v[8:11]
	v_mfma_f32_16x16x32_bf16 v[4:7], v[86:89], v[94:97], v[4:7]
	v_mfma_f32_16x16x32_bf16 v[0:3], v[86:89], v[98:101], v[0:3]
	v_mfma_f32_16x16x32_bf16 v[64:67], v[90:93], v[78:81], v[40:43]
	v_mfma_f32_16x16x32_bf16 v[74:77], v[90:93], v[82:85], v[48:51]
	v_mfma_f32_16x16x32_bf16 v[78:81], v[90:93], v[94:97], v[52:55]
	v_mfma_f32_16x16x32_bf16 v[60:63], v[90:93], v[98:101], v[60:63]
	s_setprio 0
	v_add_u32_e32 v48, v72, v73
	v_add_u32_e32 v49, v102, v73
	ds_read_b128 v[40:43], v48 offset:32768
	ds_read_b128 v[82:85], v48 offset:34816
	ds_read_b128 v[86:89], v49 offset:49152
	ds_read_b128 v[90:93], v49 offset:51200
	ds_read_b128 v[94:97], v48 offset:36864
	ds_read_b128 v[98:101], v48 offset:38912
	ds_read_b128 v[102:105], v49 offset:53248
	ds_read_b128 v[106:109], v49 offset:55296
	s_setprio 1
	s_waitcnt lgkmcnt(5)
	v_mfma_f32_16x16x32_bf16 v[110:113], v[40:43], v[86:89], v[56:59]
	s_waitcnt lgkmcnt(4)
	v_mfma_f32_16x16x32_bf16 v[114:117], v[40:43], v[90:93], v[44:47]
	s_waitcnt lgkmcnt(1)
	v_mfma_f32_16x16x32_bf16 v[52:55], v[40:43], v[102:105], v[36:39]
	s_waitcnt lgkmcnt(0)
	v_mfma_f32_16x16x32_bf16 v[48:51], v[40:43], v[106:109], v[32:35]
	v_mfma_f32_16x16x32_bf16 v[44:47], v[82:85], v[86:89], v[28:31]
	v_mfma_f32_16x16x32_bf16 v[40:43], v[82:85], v[90:93], v[24:27]
	v_mfma_f32_16x16x32_bf16 v[36:39], v[82:85], v[102:105], v[20:23]
	v_mfma_f32_16x16x32_bf16 v[32:35], v[82:85], v[106:109], v[16:19]
	v_mfma_f32_16x16x32_bf16 v[28:31], v[94:97], v[86:89], v[12:15]
	v_mfma_f32_16x16x32_bf16 v[24:27], v[94:97], v[90:93], v[8:11]
	v_mfma_f32_16x16x32_bf16 v[20:23], v[94:97], v[102:105], v[4:7]
	v_mfma_f32_16x16x32_bf16 v[16:19], v[94:97], v[106:109], v[0:3]
	v_mfma_f32_16x16x32_bf16 v[12:15], v[98:101], v[86:89], v[64:67]
	v_mfma_f32_16x16x32_bf16 v[8:11], v[98:101], v[90:93], v[74:77]
	v_mfma_f32_16x16x32_bf16 v[4:7], v[98:101], v[102:105], v[78:81]
	v_mfma_f32_16x16x32_bf16 v[0:3], v[98:101], v[106:109], v[60:63]
	s_setprio 0
	v_lshlrev_b32_e32 v56, 6, v68
	v_or3_b32 v56, v56, s57, v69
	v_lshlrev_b32_e32 v128, 2, v56
	s_waitcnt vmcnt(0)
	s_barrier
	global_load_dword v62, v128, s[50:51]
	global_load_dword v63, v128, s[50:51] offset:64
	global_load_dword v64, v128, s[50:51] offset:128
	global_load_dword v65, v128, s[50:51] offset:192
	v_lshl_add_u32 v56, v70, 6, s63
	v_lshl_or_b32 v58, v71, 2, v56
	v_ashrrev_i32_e32 v59, 31, v58
	v_lshl_add_u64 v[56:57], s[46:47], 0, v[128:129]
	v_lshlrev_b64 v[60:61], 12, v[58:59]
	v_lshl_add_u64 v[60:61], v[56:57], 0, v[60:61]
	s_waitcnt vmcnt(3)
	v_mul_f32_e32 v59, v110, v62
	global_store_dword v[60:61], v59, off
	s_waitcnt vmcnt(3)
	v_mul_f32_e32 v59, v114, v63
	s_waitcnt vmcnt(2)
	v_mul_f32_e32 v52, v52, v64
	s_waitcnt vmcnt(1)
	v_mul_f32_e32 v48, v48, v65
	global_store_dword v[60:61], v59, off offset:64
	global_store_dword v[60:61], v52, off offset:128
	global_store_dword v[60:61], v48, off offset:192
	v_or_b32_e32 v60, 1, v58
	v_ashrrev_i32_e32 v61, 31, v60
	v_lshlrev_b64 v[60:61], 12, v[60:61]
	v_lshl_add_u64 v[60:61], v[56:57], 0, v[60:61]
	v_mul_f32_e32 v48, v111, v62
	global_store_dword v[60:61], v48, off
	v_mul_f32_e32 v48, v115, v63
	global_store_dword v[60:61], v48, off offset:64
	v_mul_f32_e32 v48, v53, v64
	global_store_dword v[60:61], v48, off offset:128
	v_mul_f32_e32 v48, v49, v65
	global_store_dword v[60:61], v48, off offset:192
	v_or_b32_e32 v48, 2, v58
	v_ashrrev_i32_e32 v49, 31, v48
	v_lshlrev_b64 v[48:49], 12, v[48:49]
	v_lshl_add_u64 v[48:49], v[56:57], 0, v[48:49]
	v_mul_f32_e32 v52, v112, v62
	global_store_dword v[48:49], v52, off
	v_mul_f32_e32 v52, v116, v63
	global_store_dword v[48:49], v52, off offset:64
	v_mul_f32_e32 v52, v54, v64
	v_mul_f32_e32 v50, v50, v65
	global_store_dword v[48:49], v52, off offset:128
	global_store_dword v[48:49], v50, off offset:192
	v_or_b32_e32 v48, 3, v58
	v_ashrrev_i32_e32 v49, 31, v48
	v_lshlrev_b64 v[48:49], 12, v[48:49]
	v_lshl_add_u64 v[48:49], v[56:57], 0, v[48:49]
	v_mul_f32_e32 v50, v113, v62
	global_store_dword v[48:49], v50, off
	v_mul_f32_e32 v50, v117, v63
	global_store_dword v[48:49], v50, off offset:64
	v_mul_f32_e32 v50, v55, v64
	global_store_dword v[48:49], v50, off offset:128
	v_mul_f32_e32 v50, v51, v65
	global_store_dword v[48:49], v50, off offset:192
	v_or_b32_e32 v48, 16, v58
	v_ashrrev_i32_e32 v49, 31, v48
	v_lshlrev_b64 v[48:49], 12, v[48:49]
	v_lshl_add_u64 v[48:49], v[56:57], 0, v[48:49]
	v_mul_f32_e32 v44, v44, v62
	v_mul_f32_e32 v40, v40, v63
	v_mul_f32_e32 v36, v36, v64
	v_mul_f32_e32 v32, v32, v65
	global_store_dword v[48:49], v44, off
	global_store_dword v[48:49], v40, off offset:64
	global_store_dword v[48:49], v36, off offset:128
	global_store_dword v[48:49], v32, off offset:192
	v_or_b32_e32 v48, 17, v58
	v_ashrrev_i32_e32 v49, 31, v48
	v_lshlrev_b64 v[48:49], 12, v[48:49]
	v_lshl_add_u64 v[48:49], v[56:57], 0, v[48:49]
	v_mul_f32_e32 v32, v45, v62
	global_store_dword v[48:49], v32, off
	v_mul_f32_e32 v32, v41, v63
	global_store_dword v[48:49], v32, off offset:64
	v_mul_f32_e32 v32, v37, v64
	global_store_dword v[48:49], v32, off offset:128
	v_mul_f32_e32 v32, v33, v65
	global_store_dword v[48:49], v32, off offset:192
	v_or_b32_e32 v32, 18, v58
	v_ashrrev_i32_e32 v33, 31, v32
	v_lshlrev_b64 v[32:33], 12, v[32:33]
	v_lshl_add_u64 v[32:33], v[56:57], 0, v[32:33]
	v_mul_f32_e32 v36, v46, v62
	global_store_dword v[32:33], v36, off
	v_mul_f32_e32 v36, v42, v63
	global_store_dword v[32:33], v36, off offset:64
	v_mul_f32_e32 v36, v38, v64
	v_mul_f32_e32 v34, v34, v65
	global_store_dword v[32:33], v36, off offset:128
	global_store_dword v[32:33], v34, off offset:192
	v_or_b32_e32 v32, 19, v58
	v_ashrrev_i32_e32 v33, 31, v32
	v_lshlrev_b64 v[32:33], 12, v[32:33]
	v_lshl_add_u64 v[32:33], v[56:57], 0, v[32:33]
	v_mul_f32_e32 v34, v47, v62
	global_store_dword v[32:33], v34, off
	v_mul_f32_e32 v34, v43, v63
	global_store_dword v[32:33], v34, off offset:64
	v_mul_f32_e32 v34, v39, v64
	global_store_dword v[32:33], v34, off offset:128
	v_mul_f32_e32 v34, v35, v65
	global_store_dword v[32:33], v34, off offset:192
	v_or_b32_e32 v32, 32, v58
	v_ashrrev_i32_e32 v33, 31, v32
	v_lshlrev_b64 v[32:33], 12, v[32:33]
	v_lshl_add_u64 v[32:33], v[56:57], 0, v[32:33]
	v_mul_f32_e32 v28, v28, v62
	v_mul_f32_e32 v24, v24, v63
	v_mul_f32_e32 v20, v20, v64
	v_mul_f32_e32 v16, v16, v65
	global_store_dword v[32:33], v28, off
	global_store_dword v[32:33], v24, off offset:64
	global_store_dword v[32:33], v20, off offset:128
	global_store_dword v[32:33], v16, off offset:192
	v_or_b32_e32 v32, 33, v58
	v_ashrrev_i32_e32 v33, 31, v32
	v_lshlrev_b64 v[32:33], 12, v[32:33]
	v_lshl_add_u64 v[32:33], v[56:57], 0, v[32:33]
	v_mul_f32_e32 v16, v29, v62
	global_store_dword v[32:33], v16, off
	v_mul_f32_e32 v16, v25, v63
	global_store_dword v[32:33], v16, off offset:64
	v_mul_f32_e32 v16, v21, v64
	global_store_dword v[32:33], v16, off offset:128
	v_mul_f32_e32 v16, v17, v65
	global_store_dword v[32:33], v16, off offset:192
	v_or_b32_e32 v16, 34, v58
	v_ashrrev_i32_e32 v17, 31, v16
	v_lshlrev_b64 v[16:17], 12, v[16:17]
	v_lshl_add_u64 v[16:17], v[56:57], 0, v[16:17]
	v_mul_f32_e32 v20, v30, v62
	global_store_dword v[16:17], v20, off
	v_mul_f32_e32 v20, v26, v63
	global_store_dword v[16:17], v20, off offset:64
	v_mul_f32_e32 v20, v22, v64
	v_mul_f32_e32 v18, v18, v65
	global_store_dword v[16:17], v20, off offset:128
	global_store_dword v[16:17], v18, off offset:192
	v_or_b32_e32 v16, 35, v58
	v_ashrrev_i32_e32 v17, 31, v16
	v_lshlrev_b64 v[16:17], 12, v[16:17]
	v_lshl_add_u64 v[16:17], v[56:57], 0, v[16:17]
	v_mul_f32_e32 v18, v31, v62
	global_store_dword v[16:17], v18, off
	v_mul_f32_e32 v18, v27, v63
	global_store_dword v[16:17], v18, off offset:64
	v_mul_f32_e32 v18, v23, v64
	global_store_dword v[16:17], v18, off offset:128
	v_mul_f32_e32 v18, v19, v65
	global_store_dword v[16:17], v18, off offset:192
	v_or_b32_e32 v16, 48, v58
	v_ashrrev_i32_e32 v17, 31, v16
	v_lshlrev_b64 v[16:17], 12, v[16:17]
	v_lshl_add_u64 v[16:17], v[56:57], 0, v[16:17]
	v_mul_f32_e32 v12, v12, v62
	v_mul_f32_e32 v8, v8, v63
	v_mul_f32_e32 v4, v4, v64
	v_mul_f32_e32 v0, v0, v65
	global_store_dword v[16:17], v12, off
	global_store_dword v[16:17], v8, off offset:64
	global_store_dword v[16:17], v4, off offset:128
	global_store_dword v[16:17], v0, off offset:192
	v_or_b32_e32 v16, 49, v58
	v_ashrrev_i32_e32 v17, 31, v16
	v_lshlrev_b64 v[16:17], 12, v[16:17]
	v_lshl_add_u64 v[16:17], v[56:57], 0, v[16:17]
	v_mul_f32_e32 v0, v13, v62
	global_store_dword v[16:17], v0, off
	v_mul_f32_e32 v0, v9, v63
	global_store_dword v[16:17], v0, off offset:64
	v_mul_f32_e32 v0, v5, v64
	global_store_dword v[16:17], v0, off offset:128
	v_mul_f32_e32 v0, v1, v65
	global_store_dword v[16:17], v0, off offset:192
	v_or_b32_e32 v0, 50, v58
	v_ashrrev_i32_e32 v1, 31, v0
	v_lshlrev_b64 v[0:1], 12, v[0:1]
	v_lshl_add_u64 v[0:1], v[56:57], 0, v[0:1]
	v_mul_f32_e32 v4, v14, v62
	global_store_dword v[0:1], v4, off
	v_mul_f32_e32 v4, v10, v63
	global_store_dword v[0:1], v4, off offset:64
	v_mul_f32_e32 v4, v6, v64
	v_mul_f32_e32 v2, v2, v65
	global_store_dword v[0:1], v4, off offset:128
	global_store_dword v[0:1], v2, off offset:192
	v_or_b32_e32 v0, 51, v58
	v_ashrrev_i32_e32 v1, 31, v0
	v_lshlrev_b64 v[0:1], 12, v[0:1]
	v_lshl_add_u64 v[0:1], v[56:57], 0, v[0:1]
	v_mul_f32_e32 v2, v15, v62
	global_store_dword v[0:1], v2, off
	v_mul_f32_e32 v2, v11, v63
	global_store_dword v[0:1], v2, off offset:64
	v_mul_f32_e32 v2, v7, v64
	global_store_dword v[0:1], v2, off offset:128
	v_mul_f32_e32 v2, v3, v65
	global_store_dword v[0:1], v2, off offset:192
	s_mov_b64 s[52:53], 0
	v_readlane_b32 s67, v235, 23
	v_readlane_b32 s66, v235, 24

.LBB0_118:
	s_and_b32 s58, s62, 0x8000
	s_xor_b32 s59, s58, 0x8000
	v_add_u32_e32 v158, s59, v128
	v_lshl_add_u64 v[150:151], v[70:71], 0, s[52:53]
	v_add_u32_e32 v159, 0x4000, v158
	v_readfirstlane_b32 s59, v158
	v_lshl_add_u64 v[152:153], v[150:151], 0, s[28:29]
	v_lshl_add_u64 v[154:155], v[68:69], 0, s[52:53]
	s_mov_b32 m0, s59
	v_readfirstlane_b32 s59, v159
	v_lshl_add_u64 v[156:157], v[154:155], 0, s[28:29]
	global_load_lds_dwordx4 v[152:153], off
	s_mov_b32 m0, s59
	v_lshl_add_u64 v[152:153], v[150:151], 0, s[30:31]
	global_load_lds_dwordx4 v[156:157], off
	v_add_u32_e32 v156, 0x1000, v158
	v_add_u32_e32 v201, s58, v146
	v_readfirstlane_b32 s59, v156
	v_add_u32_e32 v156, 0x5000, v158
	s_mov_b32 m0, s59
	v_readfirstlane_b32 s59, v156
	v_add_u32_e32 v156, 0x2000, v158
	global_load_lds_dwordx4 v[152:153], off
	v_lshl_add_u64 v[152:153], v[154:155], 0, s[30:31]
	s_mov_b32 m0, s59
	v_readfirstlane_b32 s59, v156
	v_add_u32_e32 v156, 0x6000, v158
	global_load_lds_dwordx4 v[152:153], off
	v_lshl_add_u64 v[152:153], v[150:151], 0, s[0:1]
	s_mov_b32 m0, s59
	v_readfirstlane_b32 s59, v156
	global_load_lds_dwordx4 v[152:153], off
	v_lshl_add_u64 v[152:153], v[154:155], 0, s[0:1]
	s_mov_b32 m0, s59
	v_lshl_add_u64 v[150:151], v[150:151], 0, s[22:23]
	global_load_lds_dwordx4 v[152:153], off
	v_add_u32_e32 v152, 0x3000, v158
	v_or_b32_e32 v214, s58, v147
	v_readfirstlane_b32 s59, v152
	v_add_u32_e32 v152, 0x7000, v158
	s_mov_b32 m0, s59
	v_readfirstlane_b32 s59, v152
	global_load_lds_dwordx4 v[150:151], off
	v_lshl_add_u64 v[150:151], v[154:155], 0, s[22:23]
	s_mov_b32 m0, s59
	v_add_u32_e32 v202, v201, v149
	global_load_lds_dwordx4 v[150:151], off
	v_add_u32_e32 v210, v214, v149
	ds_read_b128 v[150:153], v202
	ds_read_b128 v[154:157], v202 offset:2048
	ds_read_b128 v[158:161], v210 offset:16384
	ds_read_b128 v[162:165], v210 offset:18432
	ds_read_b128 v[166:169], v202 offset:4096
	ds_read_b128 v[202:205], v202 offset:6144
	ds_read_b128 v[206:209], v210 offset:20480
	ds_read_b128 v[210:213], v210 offset:22528
	s_setprio 1
	s_waitcnt lgkmcnt(0)
	v_mfma_f32_16x16x32_bf16 v[0:3], v[150:153], v[158:161], v[0:3]
	v_mfma_f32_16x16x32_bf16 v[4:7], v[150:153], v[162:165], v[4:7]
	v_mfma_f32_16x16x32_bf16 v[8:11], v[150:153], v[206:209], v[8:11]
	v_mfma_f32_16x16x32_bf16 v[12:15], v[150:153], v[210:213], v[12:15]
	v_mfma_f32_16x16x32_bf16 v[16:19], v[154:157], v[158:161], v[16:19]
	v_mfma_f32_16x16x32_bf16 v[20:23], v[154:157], v[162:165], v[20:23]
	v_mfma_f32_16x16x32_bf16 v[24:27], v[154:157], v[206:209], v[24:27]
	v_mfma_f32_16x16x32_bf16 v[28:31], v[154:157], v[210:213], v[28:31]
	v_mfma_f32_16x16x32_bf16 v[32:35], v[166:169], v[158:161], v[32:35]
	v_mfma_f32_16x16x32_bf16 v[36:39], v[166:169], v[162:165], v[36:39]
	v_mfma_f32_16x16x32_bf16 v[40:43], v[166:169], v[206:209], v[40:43]
	v_mfma_f32_16x16x32_bf16 v[44:47], v[166:169], v[210:213], v[44:47]
	v_mfma_f32_16x16x32_bf16 v[48:51], v[202:205], v[158:161], v[48:51]
	v_mfma_f32_16x16x32_bf16 v[52:55], v[202:205], v[162:165], v[52:55]
	v_mfma_f32_16x16x32_bf16 v[56:59], v[202:205], v[206:209], v[56:59]
	v_mfma_f32_16x16x32_bf16 v[60:63], v[202:205], v[210:213], v[60:63]
	s_setprio 0
	v_add_u32_e32 v201, v201, v148
	v_add_u32_e32 v210, v214, v148
	ds_read_b128 v[150:153], v201
	ds_read_b128 v[154:157], v201 offset:2048
	ds_read_b128 v[158:161], v210 offset:16384
	ds_read_b128 v[162:165], v210 offset:18432
	ds_read_b128 v[166:169], v201 offset:4096
	ds_read_b128 v[202:205], v201 offset:6144
	ds_read_b128 v[206:209], v210 offset:20480
	ds_read_b128 v[210:213], v210 offset:22528
	s_setprio 1
	s_waitcnt lgkmcnt(5)
	v_mfma_f32_16x16x32_bf16 v[0:3], v[150:153], v[158:161], v[0:3]
	s_waitcnt lgkmcnt(4)
	v_mfma_f32_16x16x32_bf16 v[4:7], v[150:153], v[162:165], v[4:7]
	s_waitcnt lgkmcnt(1)
	v_mfma_f32_16x16x32_bf16 v[8:11], v[150:153], v[206:209], v[8:11]
	s_waitcnt lgkmcnt(0)
	v_mfma_f32_16x16x32_bf16 v[12:15], v[150:153], v[210:213], v[12:15]
	v_mfma_f32_16x16x32_bf16 v[16:19], v[154:157], v[158:161], v[16:19]
	v_mfma_f32_16x16x32_bf16 v[20:23], v[154:157], v[162:165], v[20:23]
	v_mfma_f32_16x16x32_bf16 v[24:27], v[154:157], v[206:209], v[24:27]
	v_mfma_f32_16x16x32_bf16 v[28:31], v[154:157], v[210:213], v[28:31]
	v_mfma_f32_16x16x32_bf16 v[32:35], v[166:169], v[158:161], v[32:35]
	v_mfma_f32_16x16x32_bf16 v[36:39], v[166:169], v[162:165], v[36:39]
	v_mfma_f32_16x16x32_bf16 v[40:43], v[166:169], v[206:209], v[40:43]
	v_mfma_f32_16x16x32_bf16 v[44:47], v[166:169], v[210:213], v[44:47]
	v_mfma_f32_16x16x32_bf16 v[48:51], v[202:205], v[158:161], v[48:51]
	v_mfma_f32_16x16x32_bf16 v[52:55], v[202:205], v[162:165], v[52:55]
	v_mfma_f32_16x16x32_bf16 v[56:59], v[202:205], v[206:209], v[56:59]
	v_mfma_f32_16x16x32_bf16 v[60:63], v[202:205], v[210:213], v[60:63]
	s_setprio 0
	s_waitcnt vmcnt(0)
	s_add_u32 s52, s52, 0x80
	s_addc_u32 s53, s53, 0
	s_add_i32 s62, s62, 0x8000
	s_cmpk_eq_i32 s52, 0x380
	s_barrier
	s_cbranch_scc0 .LBB0_118
	v_add_u32_e32 v128, v146, v149
	v_add_u32_e32 v149, v147, v149
	ds_read_b128 v[68:71], v128 offset:32768
	ds_read_b128 v[150:153], v128 offset:34816
	ds_read_b128 v[154:157], v149 offset:49152
	ds_read_b128 v[158:161], v149 offset:51200
	ds_read_b128 v[162:165], v128 offset:36864
	ds_read_b128 v[166:169], v128 offset:38912
	ds_read_b128 v[202:205], v149 offset:53248
	ds_read_b128 v[206:209], v149 offset:55296
	s_setprio 1
	s_waitcnt lgkmcnt(5)
	v_mfma_f32_16x16x32_bf16 v[0:3], v[68:71], v[154:157], v[0:3]
	s_waitcnt lgkmcnt(4)
	v_mfma_f32_16x16x32_bf16 v[4:7], v[68:71], v[158:161], v[4:7]
	s_waitcnt lgkmcnt(1)
	v_mfma_f32_16x16x32_bf16 v[8:11], v[68:71], v[202:205], v[8:11]
	s_waitcnt lgkmcnt(0)
	v_mfma_f32_16x16x32_bf16 v[12:15], v[68:71], v[206:209], v[12:15]
	v_mfma_f32_16x16x32_bf16 v[16:19], v[150:153], v[154:157], v[16:19]
	v_mfma_f32_16x16x32_bf16 v[20:23], v[150:153], v[158:161], v[20:23]
	v_mfma_f32_16x16x32_bf16 v[24:27], v[150:153], v[202:205], v[24:27]
	v_mfma_f32_16x16x32_bf16 v[28:31], v[150:153], v[206:209], v[28:31]
	v_mfma_f32_16x16x32_bf16 v[32:35], v[162:165], v[154:157], v[32:35]
	v_mfma_f32_16x16x32_bf16 v[36:39], v[162:165], v[158:161], v[36:39]
	v_mfma_f32_16x16x32_bf16 v[40:43], v[162:165], v[202:205], v[40:43]
	v_mfma_f32_16x16x32_bf16 v[44:47], v[162:165], v[206:209], v[44:47]
	v_mfma_f32_16x16x32_bf16 v[48:51], v[166:169], v[154:157], v[48:51]
	v_mfma_f32_16x16x32_bf16 v[52:55], v[166:169], v[158:161], v[52:55]
	v_mfma_f32_16x16x32_bf16 v[56:59], v[166:169], v[202:205], v[56:59]
	v_mfma_f32_16x16x32_bf16 v[60:63], v[166:169], v[206:209], v[60:63]
	s_setprio 0
	v_add_u32_e32 v128, v146, v148
	v_add_u32_e32 v201, v147, v148
	ds_read_b128 v[68:71], v128 offset:32768
	ds_read_b128 v[146:149], v128 offset:34816
	ds_read_b128 v[150:153], v201 offset:49152
	ds_read_b128 v[154:157], v201 offset:51200
	ds_read_b128 v[158:161], v128 offset:36864
	ds_read_b128 v[162:165], v128 offset:38912
	ds_read_b128 v[166:169], v201 offset:53248
	ds_read_b128 v[202:205], v201 offset:55296
	s_setprio 1
	s_waitcnt lgkmcnt(5)
	v_mfma_f32_16x16x32_bf16 v[206:209], v[68:71], v[150:153], v[0:3]
	s_waitcnt lgkmcnt(4)
	v_mfma_f32_16x16x32_bf16 v[210:213], v[68:71], v[154:157], v[4:7]
	s_waitcnt lgkmcnt(1)
	v_mfma_f32_16x16x32_bf16 v[214:217], v[68:71], v[166:169], v[8:11]
	s_waitcnt lgkmcnt(0)
	v_mfma_f32_16x16x32_bf16 v[68:71], v[68:71], v[202:205], v[12:15]
	v_mfma_f32_16x16x32_bf16 v[218:221], v[146:149], v[150:153], v[16:19]
	v_mfma_f32_16x16x32_bf16 v[222:225], v[146:149], v[154:157], v[20:23]
	v_mfma_f32_16x16x32_bf16 v[226:229], v[146:149], v[166:169], v[24:27]
	v_mfma_f32_16x16x32_bf16 v[146:149], v[146:149], v[202:205], v[28:31]
	v_mfma_f32_16x16x32_bf16 v[28:31], v[158:161], v[150:153], v[32:35]
	v_mfma_f32_16x16x32_bf16 v[24:27], v[158:161], v[154:157], v[36:39]
	v_mfma_f32_16x16x32_bf16 v[20:23], v[158:161], v[166:169], v[40:43]
	v_mfma_f32_16x16x32_bf16 v[16:19], v[158:161], v[202:205], v[44:47]
	v_mfma_f32_16x16x32_bf16 v[12:15], v[162:165], v[150:153], v[48:51]
	v_mfma_f32_16x16x32_bf16 v[8:11], v[162:165], v[154:157], v[52:55]
	v_mfma_f32_16x16x32_bf16 v[4:7], v[162:165], v[166:169], v[56:59]
	v_mfma_f32_16x16x32_bf16 v[0:3], v[162:165], v[202:205], v[60:63]
	s_setprio 0
	v_or3_b32 v32, v126, s57, v119
	v_lshlrev_b32_e32 v128, 2, v32
	v_lshl_add_u64 v[32:33], s[44:45], 0, v[128:129]
	v_mul_f32_e32 v36, v79, v206
	v_lshl_add_u64 v[34:35], v[32:33], 0, v[66:67]
	v_fmac_f32_e32 v36, 0x3fd744fd, v138
	s_waitcnt vmcnt(0)
	s_barrier
	global_store_dword v[34:35], v36, off
	v_mul_f32_e32 v36, v76, v210
	v_fmac_f32_e32 v36, 0x3fd744fd, v137
	global_store_dword v[34:35], v36, off offset:64
	v_mul_f32_e32 v36, v75, v214
	v_fmac_f32_e32 v36, 0x3fd744fd, v136
	global_store_dword v[34:35], v36, off offset:128
	v_mul_f32_e32 v36, v78, v68
	v_fmac_f32_e32 v36, 0x3fd744fd, v135
	global_store_dword v[34:35], v36, off offset:192
	v_or_b32_e32 v34, 1, v64
	v_ashrrev_i32_e32 v35, 31, v34
	v_lshlrev_b64 v[34:35], 12, v[34:35]
	v_mul_f32_e32 v36, v79, v207
	v_lshl_add_u64 v[34:35], v[32:33], 0, v[34:35]
	v_fmac_f32_e32 v36, 0x3fd744fd, v145
	global_store_dword v[34:35], v36, off
	v_mul_f32_e32 v36, v76, v211
	v_fmac_f32_e32 v36, 0x3fd744fd, v133
	global_store_dword v[34:35], v36, off offset:64
	v_mul_f32_e32 v36, v75, v215
	v_fmac_f32_e32 v36, 0x3fd744fd, v131
	global_store_dword v[34:35], v36, off offset:128
	v_mul_f32_e32 v36, v78, v69
	v_fmac_f32_e32 v36, 0x3fd744fd, v127
	global_store_dword v[34:35], v36, off offset:192
	v_or_b32_e32 v34, 2, v64
	v_ashrrev_i32_e32 v35, 31, v34
	v_lshlrev_b64 v[34:35], 12, v[34:35]
	v_mul_f32_e32 v36, v79, v208
	v_lshl_add_u64 v[34:35], v[32:33], 0, v[34:35]
	v_fmac_f32_e32 v36, 0x3fd744fd, v144
	global_store_dword v[34:35], v36, off
	v_mul_f32_e32 v36, v76, v212
	v_fmac_f32_e32 v36, 0x3fd744fd, v143
	global_store_dword v[34:35], v36, off offset:64
	v_mul_f32_e32 v36, v75, v216
	v_fmac_f32_e32 v36, 0x3fd744fd, v142
	global_store_dword v[34:35], v36, off offset:128
	v_mul_f32_e32 v36, v78, v70
	v_fmac_f32_e32 v36, 0x3fd744fd, v141
	global_store_dword v[34:35], v36, off offset:192
	v_or_b32_e32 v34, 3, v64
	v_ashrrev_i32_e32 v35, 31, v34
	v_lshlrev_b64 v[34:35], 12, v[34:35]
	v_mul_f32_e32 v36, v79, v209
	v_lshl_add_u64 v[34:35], v[32:33], 0, v[34:35]
	v_fmac_f32_e32 v36, 0x3fd744fd, v117
	global_store_dword v[34:35], v36, off
	v_mul_f32_e32 v36, v76, v213
	v_fmac_f32_e32 v36, 0x3fd744fd, v125
	global_store_dword v[34:35], v36, off offset:64
	v_mul_f32_e32 v36, v75, v217
	v_fmac_f32_e32 v36, 0x3fd744fd, v124
	global_store_dword v[34:35], v36, off offset:128
	v_mul_f32_e32 v36, v78, v71
	v_fmac_f32_e32 v36, 0x3fd744fd, v122
	global_store_dword v[34:35], v36, off offset:192
	v_or_b32_e32 v34, 16, v64
	v_ashrrev_i32_e32 v35, 31, v34
	v_lshlrev_b64 v[34:35], 12, v[34:35]
	v_mul_f32_e32 v36, v79, v218
	v_lshl_add_u64 v[34:35], v[32:33], 0, v[34:35]
	v_fmac_f32_e32 v36, 0x3fd744fd, v140
	global_store_dword v[34:35], v36, off
	v_mul_f32_e32 v36, v76, v222
	v_fmac_f32_e32 v36, 0x3fd744fd, v121
	global_store_dword v[34:35], v36, off offset:64
	v_mul_f32_e32 v36, v75, v226
	v_fmac_f32_e32 v36, 0x3fd744fd, v120
	global_store_dword v[34:35], v36, off offset:128
	v_mul_f32_e32 v36, v78, v146
	v_fmac_f32_e32 v36, 0x3fd744fd, v118
	global_store_dword v[34:35], v36, off offset:192
	v_or_b32_e32 v34, 17, v64
	v_ashrrev_i32_e32 v35, 31, v34
	v_lshlrev_b64 v[34:35], 12, v[34:35]
	v_mul_f32_e32 v36, v79, v219
	v_lshl_add_u64 v[34:35], v[32:33], 0, v[34:35]
	v_fmac_f32_e32 v36, 0x3fd744fd, v139
	global_store_dword v[34:35], v36, off
	v_mul_f32_e32 v36, v76, v223
	v_fmac_f32_e32 v36, 0x3fd744fd, v116
	global_store_dword v[34:35], v36, off offset:64
	v_mul_f32_e32 v36, v75, v227
	v_fmac_f32_e32 v36, 0x3fd744fd, v115
	global_store_dword v[34:35], v36, off offset:128
	v_mul_f32_e32 v36, v78, v147
	v_fmac_f32_e32 v36, 0x3fd744fd, v114
	global_store_dword v[34:35], v36, off offset:192
	v_or_b32_e32 v34, 18, v64
	v_ashrrev_i32_e32 v35, 31, v34
	v_lshlrev_b64 v[34:35], 12, v[34:35]
	v_mul_f32_e32 v36, v79, v220
	v_lshl_add_u64 v[34:35], v[32:33], 0, v[34:35]
	v_fmac_f32_e32 v36, 0x3fd744fd, v110
	global_store_dword v[34:35], v36, off
	v_mul_f32_e32 v36, v76, v224
	v_fmac_f32_e32 v36, 0x3fd744fd, v109
	global_store_dword v[34:35], v36, off offset:64
	v_mul_f32_e32 v36, v75, v228
	v_fmac_f32_e32 v36, 0x3fd744fd, v107
	global_store_dword v[34:35], v36, off offset:128
	v_mul_f32_e32 v36, v78, v148
	v_fmac_f32_e32 v36, 0x3fd744fd, v123
	global_store_dword v[34:35], v36, off offset:192
	v_or_b32_e32 v34, 19, v64
	v_ashrrev_i32_e32 v35, 31, v34
	v_lshlrev_b64 v[34:35], 12, v[34:35]
	v_mul_f32_e32 v36, v79, v221
	v_lshl_add_u64 v[34:35], v[32:33], 0, v[34:35]
	v_fmac_f32_e32 v36, 0x3fd744fd, v106
	global_store_dword v[34:35], v36, off
	v_mul_f32_e32 v36, v76, v225
	v_fmac_f32_e32 v36, 0x3fd744fd, v105
	global_store_dword v[34:35], v36, off offset:64
	v_mul_f32_e32 v36, v75, v229
	v_fmac_f32_e32 v36, 0x3fd744fd, v104
	global_store_dword v[34:35], v36, off offset:128
	v_mul_f32_e32 v36, v78, v149
	v_fmac_f32_e32 v36, 0x3fd744fd, v103
	global_store_dword v[34:35], v36, off offset:192
	v_or_b32_e32 v34, 32, v64
	v_ashrrev_i32_e32 v35, 31, v34
	v_lshlrev_b64 v[34:35], 12, v[34:35]
	v_mul_f32_e32 v28, v79, v28
	v_mul_f32_e32 v24, v76, v24
	v_mul_f32_e32 v20, v75, v20
	v_mul_f32_e32 v16, v78, v16
	v_lshl_add_u64 v[34:35], v[32:33], 0, v[34:35]
	v_fmac_f32_e32 v28, 0x3fd744fd, v108
	v_fmac_f32_e32 v24, 0x3fd744fd, v113
	v_fmac_f32_e32 v20, 0x3fd744fd, v112
	v_fmac_f32_e32 v16, 0x3fd744fd, v111
	global_store_dword v[34:35], v28, off
	global_store_dword v[34:35], v24, off offset:64
	global_store_dword v[34:35], v20, off offset:128
	global_store_dword v[34:35], v16, off offset:192
	v_or_b32_e32 v34, 33, v64
	v_ashrrev_i32_e32 v35, 31, v34
	v_lshlrev_b64 v[34:35], 12, v[34:35]
	v_mul_f32_e32 v16, v79, v29
	v_lshl_add_u64 v[34:35], v[32:33], 0, v[34:35]
	v_fmac_f32_e32 v16, 0x3fd744fd, v101
	global_store_dword v[34:35], v16, off
	v_mul_f32_e32 v16, v76, v25
	v_fmac_f32_e32 v16, 0x3fd744fd, v98
	global_store_dword v[34:35], v16, off offset:64
	v_mul_f32_e32 v16, v75, v21
	v_fmac_f32_e32 v16, 0x3fd744fd, v94
	global_store_dword v[34:35], v16, off offset:128
	v_mul_f32_e32 v16, v78, v17
	v_fmac_f32_e32 v16, 0x3fd744fd, v92
	global_store_dword v[34:35], v16, off offset:192
	v_or_b32_e32 v16, 34, v64
	v_ashrrev_i32_e32 v17, 31, v16
	v_lshlrev_b64 v[16:17], 12, v[16:17]
	v_mul_f32_e32 v20, v79, v30
	v_lshl_add_u64 v[16:17], v[32:33], 0, v[16:17]
	v_fmac_f32_e32 v20, 0x3fd744fd, v91
	global_store_dword v[16:17], v20, off
	v_mul_f32_e32 v20, v76, v26
	v_fmac_f32_e32 v20, 0x3fd744fd, v102
	global_store_dword v[16:17], v20, off offset:64
	v_mul_f32_e32 v20, v75, v22
	v_mul_f32_e32 v18, v78, v18
	v_fmac_f32_e32 v20, 0x3fd744fd, v99
	v_fmac_f32_e32 v18, 0x3fd744fd, v95
	global_store_dword v[16:17], v20, off offset:128
	global_store_dword v[16:17], v18, off offset:192
	v_or_b32_e32 v16, 35, v64
	v_ashrrev_i32_e32 v17, 31, v16
	v_lshlrev_b64 v[16:17], 12, v[16:17]
	v_mul_f32_e32 v18, v79, v31
	v_lshl_add_u64 v[16:17], v[32:33], 0, v[16:17]
	v_fmac_f32_e32 v18, 0x3fd744fd, v89
	global_store_dword v[16:17], v18, off
	v_mul_f32_e32 v18, v76, v27
	v_fmac_f32_e32 v18, 0x3fd744fd, v88
	global_store_dword v[16:17], v18, off offset:64
	v_mul_f32_e32 v18, v75, v23
	v_fmac_f32_e32 v18, 0x3fd744fd, v96
	global_store_dword v[16:17], v18, off offset:128
	v_mul_f32_e32 v18, v78, v19
	v_fmac_f32_e32 v18, 0x3fd744fd, v93
	global_store_dword v[16:17], v18, off offset:192
	v_or_b32_e32 v16, 48, v64
	v_ashrrev_i32_e32 v17, 31, v16
	v_lshlrev_b64 v[16:17], 12, v[16:17]
	v_mul_f32_e32 v12, v79, v12
	v_mul_f32_e32 v8, v76, v8
	v_mul_f32_e32 v4, v75, v4
	v_mul_f32_e32 v0, v78, v0
	v_lshl_add_u64 v[16:17], v[32:33], 0, v[16:17]
	v_fmac_f32_e32 v12, 0x3fd744fd, v90
	v_fmac_f32_e32 v8, 0x3fd744fd, v86
	v_fmac_f32_e32 v4, 0x3fd744fd, v100
	v_fmac_f32_e32 v0, 0x3fd744fd, v97
	global_store_dword v[16:17], v12, off
	global_store_dword v[16:17], v8, off offset:64
	global_store_dword v[16:17], v4, off offset:128
	global_store_dword v[16:17], v0, off offset:192
	v_or_b32_e32 v16, 49, v64
	v_ashrrev_i32_e32 v17, 31, v16
	v_lshlrev_b64 v[16:17], 12, v[16:17]
	v_mul_f32_e32 v0, v79, v13
	v_lshl_add_u64 v[16:17], v[32:33], 0, v[16:17]
	v_fmac_f32_e32 v0, 0x3fd744fd, v87
	global_store_dword v[16:17], v0, off
	v_mul_f32_e32 v0, v76, v9
	v_fmac_f32_e32 v0, 0x3fd744fd, v84
	global_store_dword v[16:17], v0, off offset:64
	v_mul_f32_e32 v0, v75, v5
	v_fmac_f32_e32 v0, 0x3fd744fd, v82
	global_store_dword v[16:17], v0, off offset:128
	v_mul_f32_e32 v0, v78, v1
	v_fmac_f32_e32 v0, 0x3fd744fd, v80
	global_store_dword v[16:17], v0, off offset:192
	v_or_b32_e32 v0, 50, v64
	v_ashrrev_i32_e32 v1, 31, v0
	v_lshlrev_b64 v[0:1], 12, v[0:1]
	v_mul_f32_e32 v4, v79, v14
	v_lshl_add_u64 v[0:1], v[32:33], 0, v[0:1]
	v_fmac_f32_e32 v4, 0x3fd744fd, v77
	global_store_dword v[0:1], v4, off
	v_mul_f32_e32 v4, v76, v10
	v_fmac_f32_e32 v4, 0x3fd744fd, v85
	global_store_dword v[0:1], v4, off offset:64
	v_mul_f32_e32 v4, v75, v6
	v_mul_f32_e32 v2, v78, v2
	v_fmac_f32_e32 v4, 0x3fd744fd, v83
	v_fmac_f32_e32 v2, 0x3fd744fd, v81
	global_store_dword v[0:1], v4, off offset:128
	global_store_dword v[0:1], v2, off offset:192
	v_or_b32_e32 v0, 51, v64
	v_ashrrev_i32_e32 v1, 31, v0
	v_lshlrev_b64 v[0:1], 12, v[0:1]
	v_mul_f32_e32 v2, v79, v15
	v_lshl_add_u64 v[0:1], v[32:33], 0, v[0:1]
	v_fmac_f32_e32 v2, 0x3fd744fd, v74
	global_store_dword v[0:1], v2, off
	v_mul_f32_e32 v2, v76, v11
	v_fmac_f32_e32 v2, 0x3fd744fd, v73
	global_store_dword v[0:1], v2, off offset:64
	v_mul_f32_e32 v2, v75, v7
	v_fmac_f32_e32 v2, 0x3fd744fd, v72
	global_store_dword v[0:1], v2, off offset:128
	v_mul_f32_e32 v2, v78, v3
	v_fmac_f32_e32 v2, 0x3fd744fd, v65
	s_movk_i32 s96, 0x1000
	global_store_dword v[0:1], v2, off offset:192
	s_branch .LBB0_111

.LBB0_468:
	v_mov_b32_e32 v6, v170
	s_nop 0
	v_lshrrev_b32_e32 v7, 4, v6
	v_ashrrev_i32_e32 v2, 3, v6
	v_xor_b32_e32 v3, v7, v6
	v_add_u32_e32 v0, v2, v70
	v_ashrrev_i32_e32 v4, 6, v6
	v_ashrrev_i32_e32 v1, 31, v0
	v_lshlrev_b32_e32 v3, 4, v3
	v_add_u32_e32 v2, s57, v2
	v_lshlrev_b64 v[0:1], 8, v[0:1]
	v_and_b32_e32 v128, 0x70, v3
	v_ashrrev_i32_e32 v3, 31, v2
	v_lshlrev_b32_e32 v8, 10, v4
	v_and_b32_e32 v68, 1, v4
	v_lshl_add_u64 v[0:1], s[44:45], 0, v[0:1]
	v_lshlrev_b64 v[2:3], 8, v[2:3]
	v_add_u32_e32 v4, 0x4000, v8
	v_readfirstlane_b32 s40, v8
	v_lshl_add_u64 v[0:1], v[0:1], 0, v[128:129]
	v_lshl_add_u64 v[2:3], s[12:13], 0, v[2:3]
	s_mov_b32 m0, s40
	v_readfirstlane_b32 s40, v4
	v_add_u32_e32 v9, 0x1000, v8
	v_lshl_add_u64 v[2:3], v[2:3], 0, v[128:129]
	s_barrier
	global_load_lds_dwordx4 v[0:1], off
	s_mov_b32 m0, s40
	s_mov_b64 s[4:5], 0x2000
	v_readfirstlane_b32 s40, v9
	v_add_u32_e32 v9, 0x5000, v8
	global_load_lds_dwordx4 v[2:3], off
	v_lshl_add_u64 v[4:5], v[0:1], 0, s[4:5]
	s_mov_b32 m0, s40
	v_readfirstlane_b32 s40, v9
	v_add_u32_e32 v9, 0x2000, v8
	global_load_lds_dwordx4 v[4:5], off
	v_lshl_add_u64 v[4:5], v[2:3], 0, s[4:5]
	s_mov_b32 m0, s40
	s_mov_b64 s[4:5], 0x4000
	v_readfirstlane_b32 s40, v9
	v_add_u32_e32 v9, 0x6000, v8
	global_load_lds_dwordx4 v[4:5], off
	v_lshl_add_u64 v[4:5], v[0:1], 0, s[4:5]
	s_mov_b32 m0, s40
	v_readfirstlane_b32 s40, v9
	v_add_u32_e32 v9, 0x3000, v8
	global_load_lds_dwordx4 v[4:5], off
	v_lshl_add_u64 v[4:5], v[2:3], 0, s[4:5]
	s_mov_b32 m0, s40
	s_mov_b64 s[4:5], 0x6000
	v_readfirstlane_b32 s40, v9
	v_add_u32_e32 v9, 0x7000, v8
	global_load_lds_dwordx4 v[4:5], off
	v_lshl_add_u64 v[4:5], v[0:1], 0, s[4:5]
	s_mov_b32 m0, s40
	v_readfirstlane_b32 s40, v9
	v_add_u32_e32 v9, 0x8000, v8
	global_load_lds_dwordx4 v[4:5], off
	v_lshl_add_u64 v[4:5], v[2:3], 0, s[4:5]
	s_mov_b32 m0, s40
	v_add_u32_e32 v10, 0xc000, v8
	v_readfirstlane_b32 s40, v9
	global_load_lds_dwordx4 v[4:5], off
	v_lshl_add_u64 v[4:5], v[0:1], 0, s[28:29]
	s_mov_b32 m0, s40
	v_readfirstlane_b32 s40, v10
	v_add_u32_e32 v9, 0x9000, v8
	s_waitcnt vmcnt(0)
	s_waitcnt vmcnt(0) lgkmcnt(0)
	s_barrier
	global_load_lds_dwordx4 v[4:5], off
	v_lshl_add_u64 v[4:5], v[2:3], 0, s[28:29]
	s_mov_b32 m0, s40
	s_mov_b64 s[4:5], 0x2080
	v_readfirstlane_b32 s40, v9
	v_add_u32_e32 v9, 0xd000, v8
	global_load_lds_dwordx4 v[4:5], off
	v_lshl_add_u64 v[4:5], v[0:1], 0, s[4:5]
	s_mov_b32 m0, s40
	v_readfirstlane_b32 s40, v9
	v_add_u32_e32 v9, 0xa000, v8
	global_load_lds_dwordx4 v[4:5], off
	v_lshl_add_u64 v[4:5], v[2:3], 0, s[4:5]
	s_mov_b32 m0, s40
	s_mov_b64 s[4:5], 0x4080
	v_readfirstlane_b32 s40, v9
	v_add_u32_e32 v9, 0xe000, v8
	global_load_lds_dwordx4 v[4:5], off
	v_lshl_add_u64 v[4:5], v[0:1], 0, s[4:5]
	s_mov_b32 m0, s40
	v_readfirstlane_b32 s40, v9
	global_load_lds_dwordx4 v[4:5], off
	v_lshl_add_u64 v[4:5], v[2:3], 0, s[4:5]
	s_mov_b32 m0, s40
	s_mov_b64 s[4:5], 0x6080
	global_load_lds_dwordx4 v[4:5], off
	v_add_u32_e32 v4, 0xb000, v8
	v_lshl_add_u64 v[0:1], v[0:1], 0, s[4:5]
	v_readfirstlane_b32 s40, v4
	s_mov_b32 m0, s40
	v_and_b32_e32 v69, 15, v6
	global_load_lds_dwordx4 v[0:1], off
	v_lshl_add_u64 v[0:1], v[2:3], 0, s[4:5]
	v_add_u32_e32 v2, 0xf000, v8
	v_bfe_u32 v72, v6, 1, 3
	v_readfirstlane_b32 s40, v2
	s_mov_b32 m0, s40
	v_ashrrev_i32_e32 v71, 7, v6
	global_load_lds_dwordx4 v[0:1], off
	v_bfe_u32 v124, v6, 4, 2
	v_lshlrev_b32_e32 v6, 7, v69
	v_bitop3_b32 v0, v7, v72, 3 bitop3:0x6c
	v_lshl_or_b32 v73, v71, 13, v6
	v_lshlrev_b32_e32 v0, 4, v0
	v_lshl_or_b32 v74, v68, 13, v6
	v_or_b32_e32 v100, v73, v0
	v_or_b32_e32 v101, v74, v0
	ds_read_b128 v[0:3], v100
	ds_read_b128 v[4:7], v101 offset:16384
	ds_read_b128 v[8:11], v100 offset:2048
	ds_read_b128 v[12:15], v101 offset:18432
	ds_read_b128 v[16:19], v100 offset:4096
	ds_read_b128 v[20:23], v101 offset:20480
	ds_read_b128 v[24:27], v100 offset:6144
	ds_read_b128 v[28:31], v101 offset:22528
	s_setprio 1
	s_waitcnt lgkmcnt(0)
	v_mfma_f32_16x16x32_bf16 v[32:35], v[0:3], v[4:7], 0
	v_mfma_f32_16x16x32_bf16 v[36:39], v[0:3], v[12:15], 0
	v_mfma_f32_16x16x32_bf16 v[40:43], v[0:3], v[20:23], 0
	v_mfma_f32_16x16x32_bf16 v[0:3], v[0:3], v[28:31], 0
	v_mfma_f32_16x16x32_bf16 v[44:47], v[8:11], v[4:7], 0
	v_mfma_f32_16x16x32_bf16 v[48:51], v[8:11], v[12:15], 0
	v_mfma_f32_16x16x32_bf16 v[52:55], v[8:11], v[20:23], 0
	v_mfma_f32_16x16x32_bf16 v[8:11], v[8:11], v[28:31], 0
	v_mfma_f32_16x16x32_bf16 v[56:59], v[16:19], v[4:7], 0
	v_mfma_f32_16x16x32_bf16 v[60:63], v[16:19], v[12:15], 0
	v_mfma_f32_16x16x32_bf16 v[64:67], v[16:19], v[20:23], 0
	v_mfma_f32_16x16x32_bf16 v[16:19], v[16:19], v[28:31], 0
	v_mfma_f32_16x16x32_bf16 v[4:7], v[24:27], v[4:7], 0
	v_mfma_f32_16x16x32_bf16 v[12:15], v[24:27], v[12:15], 0
	v_mfma_f32_16x16x32_bf16 v[20:23], v[24:27], v[20:23], 0
	v_mfma_f32_16x16x32_bf16 v[24:27], v[24:27], v[28:31], 0
	s_setprio 0
	v_bitop3_b32 v28, v124, v72, 4 bitop3:0x36
	v_lshlrev_b32_e32 v28, 4, v28
	v_or_b32_e32 v112, v73, v28
	v_or_b32_e32 v120, v74, v28
	ds_read_b128 v[28:31], v112
	ds_read_b128 v[72:75], v112 offset:2048
	ds_read_b128 v[76:79], v120 offset:16384
	ds_read_b128 v[80:83], v120 offset:18432
	ds_read_b128 v[84:87], v112 offset:4096
	ds_read_b128 v[88:91], v112 offset:6144
	ds_read_b128 v[92:95], v120 offset:20480
	ds_read_b128 v[96:99], v120 offset:22528
	s_setprio 1
	s_waitcnt lgkmcnt(5)
	v_mfma_f32_16x16x32_bf16 v[32:35], v[28:31], v[76:79], v[32:35]
	s_waitcnt lgkmcnt(4)
	v_mfma_f32_16x16x32_bf16 v[36:39], v[28:31], v[80:83], v[36:39]
	s_waitcnt lgkmcnt(1)
	v_mfma_f32_16x16x32_bf16 v[40:43], v[28:31], v[92:95], v[40:43]
	s_waitcnt lgkmcnt(0)
	v_mfma_f32_16x16x32_bf16 v[0:3], v[28:31], v[96:99], v[0:3]
	v_mfma_f32_16x16x32_bf16 v[28:31], v[72:75], v[76:79], v[44:47]
	v_mfma_f32_16x16x32_bf16 v[44:47], v[72:75], v[80:83], v[48:51]
	v_mfma_f32_16x16x32_bf16 v[48:51], v[72:75], v[92:95], v[52:55]
	v_mfma_f32_16x16x32_bf16 v[8:11], v[72:75], v[96:99], v[8:11]
	v_mfma_f32_16x16x32_bf16 v[52:55], v[84:87], v[76:79], v[56:59]
	v_mfma_f32_16x16x32_bf16 v[56:59], v[84:87], v[80:83], v[60:63]
	v_mfma_f32_16x16x32_bf16 v[60:63], v[84:87], v[92:95], v[64:67]
	v_mfma_f32_16x16x32_bf16 v[16:19], v[84:87], v[96:99], v[16:19]
	v_mfma_f32_16x16x32_bf16 v[4:7], v[88:91], v[76:79], v[4:7]
	v_mfma_f32_16x16x32_bf16 v[12:15], v[88:91], v[80:83], v[12:15]
	v_mfma_f32_16x16x32_bf16 v[20:23], v[88:91], v[92:95], v[20:23]
	v_mfma_f32_16x16x32_bf16 v[24:27], v[88:91], v[96:99], v[24:27]
	s_setprio 0
	s_waitcnt vmcnt(0)
	s_barrier
	ds_read_b128 v[64:67], v101 offset:55296
	ds_read_b128 v[72:75], v101 offset:53248
	ds_read_b128 v[76:79], v100 offset:38912
	ds_read_b128 v[80:83], v100 offset:36864
	ds_read_b128 v[84:87], v101 offset:51200
	ds_read_b128 v[88:91], v101 offset:49152
	ds_read_b128 v[92:95], v100 offset:34816
	ds_read_b128 v[96:99], v100 offset:32768
	s_setprio 1
	s_waitcnt lgkmcnt(0)
	v_mfma_f32_16x16x32_bf16 v[32:35], v[96:99], v[88:91], v[32:35]
	v_mfma_f32_16x16x32_bf16 v[36:39], v[96:99], v[84:87], v[36:39]
	v_mfma_f32_16x16x32_bf16 v[40:43], v[96:99], v[72:75], v[40:43]
	v_mfma_f32_16x16x32_bf16 v[0:3], v[96:99], v[64:67], v[0:3]
	v_mfma_f32_16x16x32_bf16 v[48:51], v[92:95], v[72:75], v[48:51]
	v_mfma_f32_16x16x32_bf16 v[8:11], v[92:95], v[64:67], v[8:11]
	v_mfma_f32_16x16x32_bf16 v[52:55], v[80:83], v[88:91], v[52:55]
	v_mfma_f32_16x16x32_bf16 v[16:19], v[80:83], v[64:67], v[16:19]
	v_mfma_f32_16x16x32_bf16 v[64:67], v[76:79], v[64:67], v[24:27]
	v_mfma_f32_16x16x32_bf16 v[96:99], v[92:95], v[88:91], v[28:31]
	v_mfma_f32_16x16x32_bf16 v[100:103], v[92:95], v[84:87], v[44:47]
	v_mfma_f32_16x16x32_bf16 v[92:95], v[80:83], v[84:87], v[56:59]
	v_mfma_f32_16x16x32_bf16 v[104:107], v[80:83], v[72:75], v[60:63]
	v_mfma_f32_16x16x32_bf16 v[80:83], v[76:79], v[88:91], v[4:7]
	v_mfma_f32_16x16x32_bf16 v[84:87], v[76:79], v[84:87], v[12:15]
	v_mfma_f32_16x16x32_bf16 v[72:75], v[76:79], v[72:75], v[20:23]
	s_setprio 0
	ds_read_b128 v[4:7], v112 offset:32768
	s_nop 0
	ds_read_b128 v[20:23], v112 offset:34816
	ds_read_b128 v[76:79], v120 offset:49152
	ds_read_b128 v[88:91], v120 offset:51200
	ds_read_b128 v[108:111], v112 offset:36864
	ds_read_b128 v[112:115], v112 offset:38912
	ds_read_b128 v[116:119], v120 offset:53248
	ds_read_b128 v[120:123], v120 offset:55296
	s_setprio 1
	s_waitcnt lgkmcnt(5)
	v_mfma_f32_16x16x32_bf16 v[60:63], v[4:7], v[76:79], v[32:35]
	s_waitcnt lgkmcnt(4)
	v_mfma_f32_16x16x32_bf16 v[44:47], v[4:7], v[88:91], v[36:39]
	s_waitcnt lgkmcnt(1)
	v_mfma_f32_16x16x32_bf16 v[28:31], v[4:7], v[116:119], v[40:43]
	s_waitcnt lgkmcnt(0)
	v_mfma_f32_16x16x32_bf16 v[12:15], v[4:7], v[120:123], v[0:3]
	v_mfma_f32_16x16x32_bf16 v[56:59], v[20:23], v[76:79], v[96:99]
	v_mfma_f32_16x16x32_bf16 v[40:43], v[20:23], v[88:91], v[100:103]
	v_mfma_f32_16x16x32_bf16 v[24:27], v[20:23], v[116:119], v[48:51]
	v_mfma_f32_16x16x32_bf16 v[8:11], v[20:23], v[120:123], v[8:11]
	v_mfma_f32_16x16x32_bf16 v[52:55], v[108:111], v[76:79], v[52:55]
	v_mfma_f32_16x16x32_bf16 v[36:39], v[108:111], v[88:91], v[92:95]
	v_mfma_f32_16x16x32_bf16 v[20:23], v[108:111], v[116:119], v[104:107]
	v_mfma_f32_16x16x32_bf16 v[4:7], v[108:111], v[120:123], v[16:19]
	v_mfma_f32_16x16x32_bf16 v[48:51], v[112:115], v[76:79], v[80:83]
	v_mfma_f32_16x16x32_bf16 v[32:35], v[112:115], v[88:91], v[84:87]
	v_mfma_f32_16x16x32_bf16 v[16:19], v[112:115], v[116:119], v[72:75]
	v_mfma_f32_16x16x32_bf16 v[0:3], v[112:115], v[120:123], v[64:67]
	s_setprio 0
	s_nop 1
	v_lshl_add_u32 v64, v71, 6, v70
	v_lshl_or_b32 v71, v68, 6, v69
	v_add_u32_e32 v65, s56, v71
	s_movk_i32 s4, 0x6800
	s_waitcnt vmcnt(0)
	v_mul_lo_u32 v66, v65, s4
	v_lshl_or_b32 v64, v124, 2, v64
	v_ashrrev_i32_e32 v67, 31, v66
	v_cmp_eq_u32_e32 vcc, 1, v68
	v_lshl_add_u64 v[68:69], s[66:67], 0, v[66:67]
	v_ashrrev_i32_e32 v65, 31, v64
	s_barrier
	s_and_saveexec_b64 s[52:53], vcc
	s_xor_b64 s[52:53], exec, s[52:53]
	s_cbranch_execz .LBB0_470
	v_cvt_pk_bf16_f32 v60, v60, v61
	v_cvt_pk_bf16_f32 v61, v62, v63
	v_lshl_add_u64 v[62:63], v[64:65], 1, v[68:69]
	global_store_dwordx2 v[62:63], v[60:61], off

.LBB0_541:
	v_mov_b32_e32 v83, v170
	v_readlane_b32 s4, v235, 38
	v_ashrrev_i32_e32 v2, 3, v83
	s_waitcnt vmcnt(4)
	v_lshrrev_b32_e32 v9, 4, v83
	v_add_u32_e32 v0, v2, v82
	v_xor_b32_e32 v3, v9, v83
	v_ashrrev_i32_e32 v1, 31, v0
	v_ashrrev_i32_e32 v8, 6, v83
	v_lshlrev_b64 v[0:1], 9, v[0:1]
	v_readlane_b32 s5, v235, 39
	v_lshlrev_b32_e32 v3, 4, v3
	v_add_u32_e32 v2, s88, v2
	v_lshl_add_u64 v[0:1], s[4:5], 0, v[0:1]
	v_and_b32_e32 v128, 0x70, v3
	v_ashrrev_i32_e32 v3, 31, v2
	v_readlane_b32 s4, v235, 40
	v_lshlrev_b32_e32 v10, 10, v8
	v_lshlrev_b64 v[2:3], 9, v[2:3]
	v_readlane_b32 s5, v235, 41
	v_add_u32_e32 v4, 0x4000, v10
	v_readfirstlane_b32 s58, v10
	v_lshl_add_u64 v[0:1], v[0:1], 0, v[128:129]
	v_lshl_add_u64 v[2:3], s[4:5], 0, v[2:3]
	s_mov_b32 m0, s58
	v_readfirstlane_b32 s59, v4
	v_add_u32_e32 v6, 0x1000, v10
	v_lshl_add_u64 v[2:3], v[2:3], 0, v[128:129]
	s_barrier
	global_load_lds_dwordx4 v[0:1], off
	s_mov_b32 m0, s59
	s_mov_b64 s[4:5], 0x4000
	v_readfirstlane_b32 s89, v6
	v_add_u32_e32 v6, 0x5000, v10
	global_load_lds_dwordx4 v[2:3], off
	v_lshl_add_u64 v[4:5], v[0:1], 0, s[4:5]
	s_mov_b32 m0, s89
	v_readfirstlane_b32 s96, v6
	v_add_u32_e32 v6, 0x2000, v10
	global_load_lds_dwordx4 v[4:5], off
	v_lshl_add_u64 v[4:5], v[2:3], 0, s[4:5]
	s_mov_b32 m0, s96
	s_mov_b64 s[4:5], 0x8000
	v_readfirstlane_b32 s40, v6
	v_add_u32_e32 v6, 0x6000, v10
	global_load_lds_dwordx4 v[4:5], off
	v_lshl_add_u64 v[4:5], v[0:1], 0, s[4:5]
	s_mov_b32 m0, s40
	v_readfirstlane_b32 s41, v6
	v_add_u32_e32 v6, 0x3000, v10
	global_load_lds_dwordx4 v[4:5], off
	v_lshl_add_u64 v[4:5], v[2:3], 0, s[4:5]
	s_mov_b32 m0, s41
	s_mov_b64 s[4:5], 0xc000
	v_readfirstlane_b32 s70, v6
	v_add_u32_e32 v6, 0x7000, v10
	global_load_lds_dwordx4 v[4:5], off
	v_lshl_add_u64 v[4:5], v[0:1], 0, s[4:5]
	s_mov_b32 m0, s70
	v_readfirstlane_b32 s71, v6
	v_add_u32_e32 v11, 0x8000, v10
	global_load_lds_dwordx4 v[4:5], off
	v_lshl_add_u64 v[4:5], v[2:3], 0, s[4:5]
	s_mov_b32 m0, s71
	v_add_u32_e32 v12, 0xc000, v10
	v_readfirstlane_b32 s56, v11
	global_load_lds_dwordx4 v[4:5], off
	v_lshl_add_u64 v[4:5], v[0:1], 0, s[28:29]
	s_mov_b32 m0, s56
	v_readfirstlane_b32 s34, v12
	s_waitcnt vmcnt(0)
	s_waitcnt vmcnt(0) lgkmcnt(0)
	s_barrier
	v_lshl_add_u64 v[6:7], v[2:3], 0, s[28:29]
	global_load_lds_dwordx4 v[4:5], off
	s_mov_b32 m0, s34
	s_mov_b64 s[4:5], 0x4080
	global_load_lds_dwordx4 v[6:7], off
	v_add_u32_e32 v6, 0x9000, v10
	v_lshl_add_u64 v[4:5], v[0:1], 0, s[4:5]
	v_readfirstlane_b32 s35, v6
	v_add_u32_e32 v6, 0xd000, v10
	s_mov_b32 m0, s35
	v_readfirstlane_b32 s36, v6
	v_add_u32_e32 v6, 0xa000, v10
	global_load_lds_dwordx4 v[4:5], off
	v_lshl_add_u64 v[4:5], v[2:3], 0, s[4:5]
	s_mov_b32 m0, s36
	s_mov_b64 s[4:5], 0x8080
	v_readfirstlane_b32 s37, v6
	v_add_u32_e32 v6, 0xe000, v10
	global_load_lds_dwordx4 v[4:5], off
	v_lshl_add_u64 v[4:5], v[0:1], 0, s[4:5]
	s_mov_b32 m0, s37
	v_readfirstlane_b32 s57, v6
	v_add_u32_e32 v6, 0xb000, v10
	global_load_lds_dwordx4 v[4:5], off
	v_lshl_add_u64 v[4:5], v[2:3], 0, s[4:5]
	s_mov_b32 m0, s57
	s_mov_b64 s[4:5], 0xc080
	v_readfirstlane_b32 s62, v6
	v_add_u32_e32 v6, 0xf000, v10
	global_load_lds_dwordx4 v[4:5], off
	v_lshl_add_u64 v[4:5], v[0:1], 0, s[4:5]
	s_mov_b32 m0, s62
	v_readfirstlane_b32 s63, v6
	global_load_lds_dwordx4 v[4:5], off
	v_lshl_add_u64 v[4:5], v[2:3], 0, s[4:5]
	s_mov_b32 m0, s63
	v_and_b32_e32 v64, 15, v83
	global_load_lds_dwordx4 v[4:5], off
	v_and_b32_e32 v65, 1, v8
	v_ashrrev_i32_e32 v120, 7, v83
	v_bfe_u32 v74, v83, 1, 3
	v_lshlrev_b32_e32 v4, 7, v64
	v_lshl_or_b32 v75, v120, 13, v4
	v_lshl_or_b32 v76, v65, 13, v4
	v_bitop3_b32 v4, v9, v74, 3 bitop3:0x6c
	v_lshlrev_b32_e32 v4, 4, v4
	v_or_b32_e32 v104, v75, v4
	v_or_b32_e32 v105, v76, v4
	ds_read_b128 v[4:7], v104
	ds_read_b128 v[8:11], v104 offset:2048
	ds_read_b128 v[12:15], v105 offset:16384
	ds_read_b128 v[16:19], v105 offset:18432
	ds_read_b128 v[20:23], v104 offset:4096
	ds_read_b128 v[24:27], v104 offset:6144
	ds_read_b128 v[28:31], v105 offset:20480
	ds_read_b128 v[32:35], v105 offset:22528
	v_bfe_u32 v121, v83, 4, 2
	s_setprio 1
	s_waitcnt lgkmcnt(0)
	v_mfma_f32_16x16x32_bf16 v[36:39], v[4:7], v[12:15], 0
	v_mfma_f32_16x16x32_bf16 v[40:43], v[4:7], v[16:19], 0
	v_mfma_f32_16x16x32_bf16 v[44:47], v[4:7], v[28:31], 0
	v_mfma_f32_16x16x32_bf16 v[4:7], v[4:7], v[32:35], 0
	v_mfma_f32_16x16x32_bf16 v[48:51], v[8:11], v[12:15], 0
	v_mfma_f32_16x16x32_bf16 v[52:55], v[8:11], v[16:19], 0
	v_mfma_f32_16x16x32_bf16 v[56:59], v[8:11], v[28:31], 0
	v_mfma_f32_16x16x32_bf16 v[8:11], v[8:11], v[32:35], 0
	v_mfma_f32_16x16x32_bf16 v[60:63], v[20:23], v[12:15], 0
	v_mfma_f32_16x16x32_bf16 v[66:69], v[20:23], v[16:19], 0
	v_mfma_f32_16x16x32_bf16 v[70:73], v[20:23], v[28:31], 0
	v_mfma_f32_16x16x32_bf16 v[20:23], v[20:23], v[32:35], 0
	v_mfma_f32_16x16x32_bf16 v[12:15], v[24:27], v[12:15], 0
	v_mfma_f32_16x16x32_bf16 v[16:19], v[24:27], v[16:19], 0
	v_mfma_f32_16x16x32_bf16 v[28:31], v[24:27], v[28:31], 0
	v_mfma_f32_16x16x32_bf16 v[24:27], v[24:27], v[32:35], 0
	s_setprio 0
	v_bitop3_b32 v32, v121, v74, 4 bitop3:0x36
	v_lshlrev_b32_e32 v32, 4, v32
	v_or_b32_e32 v108, v75, v32
	v_or_b32_e32 v116, v76, v32
	ds_read_b128 v[32:35], v108
	ds_read_b128 v[74:77], v108 offset:2048
	ds_read_b128 v[78:81], v116 offset:16384
	ds_read_b128 v[84:87], v116 offset:18432
	ds_read_b128 v[88:91], v108 offset:4096
	ds_read_b128 v[92:95], v108 offset:6144
	ds_read_b128 v[96:99], v116 offset:20480
	ds_read_b128 v[100:103], v116 offset:22528
	s_setprio 1
	s_waitcnt lgkmcnt(5)
	v_mfma_f32_16x16x32_bf16 v[36:39], v[32:35], v[78:81], v[36:39]
	s_waitcnt lgkmcnt(4)
	v_mfma_f32_16x16x32_bf16 v[40:43], v[32:35], v[84:87], v[40:43]
	s_waitcnt lgkmcnt(1)
	v_mfma_f32_16x16x32_bf16 v[44:47], v[32:35], v[96:99], v[44:47]
	s_waitcnt lgkmcnt(0)
	v_mfma_f32_16x16x32_bf16 v[4:7], v[32:35], v[100:103], v[4:7]
	v_mfma_f32_16x16x32_bf16 v[32:35], v[74:77], v[78:81], v[48:51]
	v_mfma_f32_16x16x32_bf16 v[48:51], v[74:77], v[84:87], v[52:55]
	v_mfma_f32_16x16x32_bf16 v[52:55], v[74:77], v[96:99], v[56:59]
	v_mfma_f32_16x16x32_bf16 v[8:11], v[74:77], v[100:103], v[8:11]
	v_mfma_f32_16x16x32_bf16 v[56:59], v[88:91], v[78:81], v[60:63]
	v_mfma_f32_16x16x32_bf16 v[60:63], v[88:91], v[84:87], v[66:69]
	v_mfma_f32_16x16x32_bf16 v[20:23], v[88:91], v[100:103], v[20:23]
	v_mfma_f32_16x16x32_bf16 v[12:15], v[92:95], v[78:81], v[12:15]
	v_mfma_f32_16x16x32_bf16 v[16:19], v[92:95], v[84:87], v[16:19]
	v_mfma_f32_16x16x32_bf16 v[28:31], v[92:95], v[96:99], v[28:31]
	v_mfma_f32_16x16x32_bf16 v[24:27], v[92:95], v[100:103], v[24:27]
	v_mfma_f32_16x16x32_bf16 v[66:69], v[88:91], v[96:99], v[70:73]
	s_setprio 0
	s_mov_b64 s[4:5], 0x100
	s_mov_b32 m0, s58
	v_lshl_add_u64 v[70:71], v[0:1], 0, s[4:5]
	s_waitcnt vmcnt(0)
	s_barrier
	v_lshl_add_u64 v[72:73], v[2:3], 0, s[4:5]
	global_load_lds_dwordx4 v[70:71], off
	s_mov_b32 m0, s59
	s_mov_b64 s[4:5], 0x4100
	global_load_lds_dwordx4 v[72:73], off
	v_lshl_add_u64 v[70:71], v[0:1], 0, s[4:5]
	s_mov_b32 m0, s89
	s_nop 0
	global_load_lds_dwordx4 v[70:71], off
	v_lshl_add_u64 v[70:71], v[2:3], 0, s[4:5]
	s_mov_b32 m0, s96
	s_mov_b64 s[4:5], 0x8100
	global_load_lds_dwordx4 v[70:71], off
	v_lshl_add_u64 v[70:71], v[0:1], 0, s[4:5]
	s_mov_b32 m0, s40
	s_nop 0
	global_load_lds_dwordx4 v[70:71], off
	v_lshl_add_u64 v[70:71], v[2:3], 0, s[4:5]
	s_mov_b32 m0, s41
	s_mov_b64 s[4:5], 0xc100
	global_load_lds_dwordx4 v[70:71], off
	v_lshl_add_u64 v[70:71], v[0:1], 0, s[4:5]
	s_mov_b32 m0, s70
	s_nop 0
	global_load_lds_dwordx4 v[70:71], off
	v_lshl_add_u64 v[70:71], v[2:3], 0, s[4:5]
	s_mov_b32 m0, s71
	s_nop 0
	global_load_lds_dwordx4 v[70:71], off
	ds_read_b128 v[70:73], v104 offset:32768
	ds_read_b128 v[74:77], v104 offset:34816
	ds_read_b128 v[78:81], v105 offset:49152
	ds_read_b128 v[84:87], v105 offset:51200
	ds_read_b128 v[88:91], v104 offset:36864
	ds_read_b128 v[92:95], v104 offset:38912
	ds_read_b128 v[96:99], v105 offset:53248
	ds_read_b128 v[100:103], v105 offset:55296
	s_setprio 1
	s_waitcnt lgkmcnt(0)
	v_mfma_f32_16x16x32_bf16 v[36:39], v[70:73], v[78:81], v[36:39]
	v_mfma_f32_16x16x32_bf16 v[40:43], v[70:73], v[84:87], v[40:43]
	v_mfma_f32_16x16x32_bf16 v[44:47], v[70:73], v[96:99], v[44:47]
	v_mfma_f32_16x16x32_bf16 v[4:7], v[70:73], v[100:103], v[4:7]
	v_mfma_f32_16x16x32_bf16 v[32:35], v[74:77], v[78:81], v[32:35]
	v_mfma_f32_16x16x32_bf16 v[48:51], v[74:77], v[84:87], v[48:51]
	v_mfma_f32_16x16x32_bf16 v[52:55], v[74:77], v[96:99], v[52:55]
	v_mfma_f32_16x16x32_bf16 v[8:11], v[74:77], v[100:103], v[8:11]
	v_mfma_f32_16x16x32_bf16 v[56:59], v[88:91], v[78:81], v[56:59]
	v_mfma_f32_16x16x32_bf16 v[60:63], v[88:91], v[84:87], v[60:63]
	v_mfma_f32_16x16x32_bf16 v[20:23], v[88:91], v[100:103], v[20:23]
	v_mfma_f32_16x16x32_bf16 v[12:15], v[92:95], v[78:81], v[12:15]
	v_mfma_f32_16x16x32_bf16 v[16:19], v[92:95], v[84:87], v[16:19]
	v_mfma_f32_16x16x32_bf16 v[28:31], v[92:95], v[96:99], v[28:31]
	v_mfma_f32_16x16x32_bf16 v[24:27], v[92:95], v[100:103], v[24:27]
	v_mfma_f32_16x16x32_bf16 v[66:69], v[88:91], v[96:99], v[66:69]
	s_setprio 0
	ds_read_b128 v[70:73], v108 offset:32768
	ds_read_b128 v[74:77], v108 offset:34816
	ds_read_b128 v[78:81], v116 offset:49152
	ds_read_b128 v[84:87], v116 offset:51200
	ds_read_b128 v[88:91], v108 offset:36864
	ds_read_b128 v[92:95], v108 offset:38912
	ds_read_b128 v[96:99], v116 offset:53248
	ds_read_b128 v[100:103], v116 offset:55296
	s_setprio 1
	s_waitcnt lgkmcnt(5)
	v_mfma_f32_16x16x32_bf16 v[36:39], v[70:73], v[78:81], v[36:39]
	s_waitcnt lgkmcnt(4)
	v_mfma_f32_16x16x32_bf16 v[40:43], v[70:73], v[84:87], v[40:43]
	s_waitcnt lgkmcnt(1)
	v_mfma_f32_16x16x32_bf16 v[44:47], v[70:73], v[96:99], v[44:47]
	s_waitcnt lgkmcnt(0)
	v_mfma_f32_16x16x32_bf16 v[4:7], v[70:73], v[100:103], v[4:7]
	v_mfma_f32_16x16x32_bf16 v[32:35], v[74:77], v[78:81], v[32:35]
	v_mfma_f32_16x16x32_bf16 v[48:51], v[74:77], v[84:87], v[48:51]
	v_mfma_f32_16x16x32_bf16 v[52:55], v[74:77], v[96:99], v[52:55]
	v_mfma_f32_16x16x32_bf16 v[8:11], v[74:77], v[100:103], v[8:11]
	v_mfma_f32_16x16x32_bf16 v[56:59], v[88:91], v[78:81], v[56:59]
	v_mfma_f32_16x16x32_bf16 v[60:63], v[88:91], v[84:87], v[60:63]
	v_mfma_f32_16x16x32_bf16 v[20:23], v[88:91], v[100:103], v[20:23]
	v_mfma_f32_16x16x32_bf16 v[12:15], v[92:95], v[78:81], v[12:15]
	v_mfma_f32_16x16x32_bf16 v[16:19], v[92:95], v[84:87], v[16:19]
	v_mfma_f32_16x16x32_bf16 v[28:31], v[92:95], v[96:99], v[28:31]
	v_mfma_f32_16x16x32_bf16 v[24:27], v[92:95], v[100:103], v[24:27]
	v_mfma_f32_16x16x32_bf16 v[66:69], v[88:91], v[96:99], v[66:69]
	s_setprio 0
	s_mov_b64 s[4:5], 0x180
	s_mov_b32 m0, s56
	v_lshl_add_u64 v[70:71], v[0:1], 0, s[4:5]
	s_waitcnt vmcnt(0)
	s_barrier
	v_lshl_add_u64 v[72:73], v[2:3], 0, s[4:5]
	global_load_lds_dwordx4 v[70:71], off
	s_mov_b32 m0, s34
	s_mov_b64 s[4:5], 0x4180
	global_load_lds_dwordx4 v[72:73], off
	v_lshl_add_u64 v[70:71], v[0:1], 0, s[4:5]
	s_mov_b32 m0, s35
	s_nop 0
	global_load_lds_dwordx4 v[70:71], off
	v_lshl_add_u64 v[70:71], v[2:3], 0, s[4:5]
	s_mov_b32 m0, s36
	s_mov_b64 s[4:5], 0x8180
	global_load_lds_dwordx4 v[70:71], off
	v_lshl_add_u64 v[70:71], v[0:1], 0, s[4:5]
	s_mov_b32 m0, s37
	s_nop 0
	global_load_lds_dwordx4 v[70:71], off
	v_lshl_add_u64 v[70:71], v[2:3], 0, s[4:5]
	s_mov_b32 m0, s57
	s_mov_b64 s[4:5], 0xc180
	global_load_lds_dwordx4 v[70:71], off
	v_lshl_add_u64 v[0:1], v[0:1], 0, s[4:5]
	s_mov_b32 m0, s62
	s_nop 0
	global_load_lds_dwordx4 v[0:1], off
	v_lshl_add_u64 v[0:1], v[2:3], 0, s[4:5]
	s_mov_b32 m0, s63
	s_nop 0
	global_load_lds_dwordx4 v[0:1], off
	ds_read_b128 v[0:3], v104
	ds_read_b128 v[70:73], v104 offset:2048
	ds_read_b128 v[74:77], v105 offset:16384
	ds_read_b128 v[78:81], v105 offset:18432
	ds_read_b128 v[84:87], v104 offset:4096
	ds_read_b128 v[88:91], v104 offset:6144
	ds_read_b128 v[92:95], v105 offset:20480
	ds_read_b128 v[96:99], v105 offset:22528
	s_setprio 1
	s_waitcnt lgkmcnt(0)
	v_mfma_f32_16x16x32_bf16 v[36:39], v[0:3], v[74:77], v[36:39]
	v_mfma_f32_16x16x32_bf16 v[40:43], v[0:3], v[78:81], v[40:43]
	v_mfma_f32_16x16x32_bf16 v[44:47], v[0:3], v[92:95], v[44:47]
	v_mfma_f32_16x16x32_bf16 v[0:3], v[0:3], v[96:99], v[4:7]
	v_mfma_f32_16x16x32_bf16 v[4:7], v[70:73], v[74:77], v[32:35]
	v_mfma_f32_16x16x32_bf16 v[32:35], v[70:73], v[78:81], v[48:51]
	v_mfma_f32_16x16x32_bf16 v[48:51], v[70:73], v[92:95], v[52:55]
	v_mfma_f32_16x16x32_bf16 v[8:11], v[70:73], v[96:99], v[8:11]
	v_mfma_f32_16x16x32_bf16 v[52:55], v[84:87], v[74:77], v[56:59]
	v_mfma_f32_16x16x32_bf16 v[56:59], v[84:87], v[78:81], v[60:63]
	v_mfma_f32_16x16x32_bf16 v[60:63], v[84:87], v[92:95], v[66:69]
	v_mfma_f32_16x16x32_bf16 v[20:23], v[84:87], v[96:99], v[20:23]
	v_mfma_f32_16x16x32_bf16 v[12:15], v[88:91], v[74:77], v[12:15]
	v_mfma_f32_16x16x32_bf16 v[16:19], v[88:91], v[78:81], v[16:19]
	v_mfma_f32_16x16x32_bf16 v[28:31], v[88:91], v[92:95], v[28:31]
	v_mfma_f32_16x16x32_bf16 v[24:27], v[88:91], v[96:99], v[24:27]
	s_setprio 0
	ds_read_b128 v[66:69], v108
	ds_read_b128 v[70:73], v108 offset:2048
	ds_read_b128 v[74:77], v116 offset:16384
	ds_read_b128 v[78:81], v116 offset:18432
	ds_read_b128 v[84:87], v108 offset:4096
	ds_read_b128 v[88:91], v108 offset:6144
	ds_read_b128 v[92:95], v116 offset:20480
	ds_read_b128 v[96:99], v116 offset:22528
	s_setprio 1
	s_waitcnt lgkmcnt(5)
	v_mfma_f32_16x16x32_bf16 v[36:39], v[66:69], v[74:77], v[36:39]
	s_waitcnt lgkmcnt(4)
	v_mfma_f32_16x16x32_bf16 v[40:43], v[66:69], v[78:81], v[40:43]
	s_waitcnt lgkmcnt(1)
	v_mfma_f32_16x16x32_bf16 v[44:47], v[66:69], v[92:95], v[44:47]
	s_waitcnt lgkmcnt(0)
	v_mfma_f32_16x16x32_bf16 v[0:3], v[66:69], v[96:99], v[0:3]
	v_mfma_f32_16x16x32_bf16 v[4:7], v[70:73], v[74:77], v[4:7]
	v_mfma_f32_16x16x32_bf16 v[32:35], v[70:73], v[78:81], v[32:35]
	v_mfma_f32_16x16x32_bf16 v[48:51], v[70:73], v[92:95], v[48:51]
	v_mfma_f32_16x16x32_bf16 v[8:11], v[70:73], v[96:99], v[8:11]
	v_mfma_f32_16x16x32_bf16 v[52:55], v[84:87], v[74:77], v[52:55]
	v_mfma_f32_16x16x32_bf16 v[56:59], v[84:87], v[78:81], v[56:59]
	v_mfma_f32_16x16x32_bf16 v[60:63], v[84:87], v[92:95], v[60:63]
	v_mfma_f32_16x16x32_bf16 v[20:23], v[84:87], v[96:99], v[20:23]
	v_mfma_f32_16x16x32_bf16 v[12:15], v[88:91], v[74:77], v[12:15]
	v_mfma_f32_16x16x32_bf16 v[16:19], v[88:91], v[78:81], v[16:19]
	v_mfma_f32_16x16x32_bf16 v[28:31], v[88:91], v[92:95], v[28:31]
	v_mfma_f32_16x16x32_bf16 v[24:27], v[88:91], v[96:99], v[24:27]
	s_setprio 0
	s_waitcnt vmcnt(0)
	s_barrier
	ds_read_b128 v[66:69], v105 offset:55296
	ds_read_b128 v[70:73], v105 offset:53248
	ds_read_b128 v[74:77], v104 offset:38912
	ds_read_b128 v[78:81], v104 offset:36864
	ds_read_b128 v[84:87], v105 offset:51200
	ds_read_b128 v[88:91], v105 offset:49152
	ds_read_b128 v[92:95], v104 offset:34816
	ds_read_b128 v[96:99], v104 offset:32768
	s_setprio 1
	s_waitcnt lgkmcnt(0)
	v_mfma_f32_16x16x32_bf16 v[36:39], v[96:99], v[88:91], v[36:39]
	v_mfma_f32_16x16x32_bf16 v[40:43], v[96:99], v[84:87], v[40:43]
	v_mfma_f32_16x16x32_bf16 v[100:103], v[96:99], v[70:73], v[44:47]
	v_mfma_f32_16x16x32_bf16 v[0:3], v[96:99], v[66:69], v[0:3]
	v_mfma_f32_16x16x32_bf16 v[4:7], v[92:95], v[88:91], v[4:7]
	v_mfma_f32_16x16x32_bf16 v[32:35], v[92:95], v[84:87], v[32:35]
	v_mfma_f32_16x16x32_bf16 v[48:51], v[92:95], v[70:73], v[48:51]
	v_mfma_f32_16x16x32_bf16 v[8:11], v[92:95], v[66:69], v[8:11]
	v_mfma_f32_16x16x32_bf16 v[52:55], v[78:81], v[88:91], v[52:55]
	v_mfma_f32_16x16x32_bf16 v[16:19], v[74:77], v[84:87], v[16:19]
	v_mfma_f32_16x16x32_bf16 v[92:95], v[78:81], v[84:87], v[56:59]
	v_mfma_f32_16x16x32_bf16 v[96:99], v[78:81], v[70:73], v[60:63]
	v_mfma_f32_16x16x32_bf16 v[78:81], v[78:81], v[66:69], v[20:23]
	v_mfma_f32_16x16x32_bf16 v[88:91], v[74:77], v[88:91], v[12:15]
	v_mfma_f32_16x16x32_bf16 v[70:73], v[74:77], v[70:73], v[28:31]
	v_mfma_f32_16x16x32_bf16 v[66:69], v[74:77], v[66:69], v[24:27]
	s_setprio 0
	ds_read_b128 v[12:15], v108 offset:32768
	ds_read_b128 v[20:23], v108 offset:34816
	ds_read_b128 v[74:77], v116 offset:49152
	ds_read_b128 v[84:87], v116 offset:51200
	ds_read_b128 v[104:107], v108 offset:36864
	ds_read_b128 v[108:111], v108 offset:38912
	ds_read_b128 v[112:115], v116 offset:53248
	ds_read_b128 v[116:119], v116 offset:55296
	s_setprio 1
	s_waitcnt lgkmcnt(5)
	v_mfma_f32_16x16x32_bf16 v[60:63], v[12:15], v[74:77], v[36:39]
	s_waitcnt lgkmcnt(4)
	v_mfma_f32_16x16x32_bf16 v[44:47], v[12:15], v[84:87], v[40:43]
	s_waitcnt lgkmcnt(1)
	v_mfma_f32_16x16x32_bf16 v[28:31], v[12:15], v[112:115], v[100:103]
	s_waitcnt lgkmcnt(0)
	v_mfma_f32_16x16x32_bf16 v[12:15], v[12:15], v[116:119], v[0:3]
	v_mfma_f32_16x16x32_bf16 v[56:59], v[20:23], v[74:77], v[4:7]
	v_mfma_f32_16x16x32_bf16 v[40:43], v[20:23], v[84:87], v[32:35]
	v_mfma_f32_16x16x32_bf16 v[24:27], v[20:23], v[112:115], v[48:51]
	v_mfma_f32_16x16x32_bf16 v[8:11], v[20:23], v[116:119], v[8:11]
	v_mfma_f32_16x16x32_bf16 v[52:55], v[104:107], v[74:77], v[52:55]
	v_mfma_f32_16x16x32_bf16 v[36:39], v[104:107], v[84:87], v[92:95]
	v_mfma_f32_16x16x32_bf16 v[20:23], v[104:107], v[112:115], v[96:99]
	v_mfma_f32_16x16x32_bf16 v[4:7], v[104:107], v[116:119], v[78:81]
	v_mfma_f32_16x16x32_bf16 v[48:51], v[108:111], v[74:77], v[88:91]
	v_mfma_f32_16x16x32_bf16 v[32:35], v[108:111], v[84:87], v[16:19]
	v_mfma_f32_16x16x32_bf16 v[16:19], v[108:111], v[112:115], v[70:73]
	v_mfma_f32_16x16x32_bf16 v[0:3], v[108:111], v[116:119], v[66:69]
	s_setprio 0
	s_nop 1
	v_lshl_add_u32 v66, v120, 6, v82
	v_lshlrev_b32_e32 v65, 6, v65
	v_lshl_or_b32 v100, v121, 2, v66
	v_add_u32_e32 v66, s88, v65
	v_lshrrev_b32_e32 v86, 4, v66
	v_mul_lo_u16_e32 v66, 0xab, v86
	v_lshrrev_b16_e32 v66, 10, v66
	v_mul_lo_u16_e32 v66, 6, v66
	v_sub_u16_e32 v66, v86, v66
	v_cmp_gt_u16_sdwa s[36:37], v66, v187 src0_sel:BYTE_0 src1_sel:DWORD
	v_lshlrev_b16_e32 v66, 4, v66
	s_waitcnt vmcnt(0)
	v_or_b32_e32 v84, 0xffffffc0, v64
	v_and_b32_e32 v66, 0xf0, v66
	v_and_b32_e32 v67, 8, v83
	v_add_u32_e32 v101, v84, v66
	v_lshlrev_b32_e32 v66, 5, v100
	v_cmp_eq_u32_e64 s[34:35], 0, v67
	s_and_b64 s[58:59], vcc, s[36:37]
	v_and_b32_e32 v83, 0x1f980, v66
	s_barrier
	s_and_saveexec_b64 s[56:57], s[58:59]
	s_cbranch_execz .LBB0_543
	v_add_lshl_u32 v66, v101, v83, 1
	v_ashrrev_i32_e32 v67, 31, v66
	v_lshl_add_u64 v[66:67], v[66:67], 2, s[50:51]
	global_load_dwordx2 v[66:67], v[66:67], off
	v_and_b32_e32 v69, 64, v188
	v_xor_b32_e32 v68, 8, v188
	v_add_u32_e32 v69, 64, v69
	v_cmp_lt_i32_e64 s[36:37], v68, v69
	s_nop 1
	v_cndmask_b32_e64 v68, v188, v68, s[36:37]
	v_lshlrev_b32_e32 v68, 2, v68
	ds_bpermute_b32 v68, v68, v60
	s_waitcnt vmcnt(0) lgkmcnt(0)
	v_mul_f32_e32 v67, v67, v68
	v_cndmask_b32_e64 v67, v67, -v67, s[34:35]
	v_fmac_f32_e32 v67, v60, v66
	v_mov_b32_e32 v60, v67

.LBB0_716:
	s_andn2_saveexec_b64 s[34:35], s[12:13]
	s_cbranch_execz .LBB0_718
	v_mov_b32_e32 v6, v170
	v_lshl_add_u32 v0, v48, 6, v192
	v_readlane_b32 s4, v235, 42
	v_lshrrev_b32_e32 v8, 4, v6
	v_and_b32_e32 v96, 0x7fffff80, v0
	v_lshlrev_b32_e32 v0, 7, v48
	v_ashrrev_i32_e32 v4, 3, v6
	v_xor_b32_e32 v2, v8, v6
	v_readlane_b32 s5, v235, 43
	v_and_b32_e32 v97, 0x80, v0
	v_add_u32_e32 v3, v4, v96
	v_mov_b64_e32 v[0:1], s[4:5]
	v_lshlrev_b32_e32 v2, 4, v2
	v_ashrrev_i32_e32 v7, 6, v6
	v_mad_i64_i32 v[0:1], s[36:37], v3, s64, v[0:1]
	v_and_b32_e32 v128, 0x70, v2
	v_and_b32_e32 v98, 1, v7
	v_lshl_add_u64 v[0:1], v[0:1], 0, v[128:129]
	s_mov_b64 s[4:5], 0x200
	v_add_u32_e32 v4, v4, v97
	v_lshlrev_b32_e32 v7, 10, v7
	v_lshl_add_u64 v[2:3], v[0:1], 0, s[4:5]
	v_ashrrev_i32_e32 v5, 31, v4
	v_readlane_b32 s4, v234, 7
	v_add_u32_e32 v9, 0x4000, v7
	v_readfirstlane_b32 s36, v7
	v_lshlrev_b64 v[4:5], 8, v[4:5]
	v_readlane_b32 s5, v234, 8
	s_mov_b32 m0, s36
	v_readfirstlane_b32 s36, v9
	v_lshl_add_u64 v[4:5], s[4:5], 0, v[4:5]
	s_waitcnt lgkmcnt(0)
	s_barrier
	global_load_lds_dwordx4 v[2:3], off
	s_mov_b32 m0, s36
	s_mov_b64 s[36:37], 0x6200
	v_add_u32_e32 v9, 0x1000, v7
	v_lshl_add_u64 v[4:5], v[4:5], 0, v[128:129]
	v_lshl_add_u64 v[2:3], v[0:1], 0, s[36:37]
	v_readfirstlane_b32 s36, v9
	v_add_u32_e32 v9, 0x5000, v7
	global_load_lds_dwordx4 v[4:5], off
	s_mov_b32 m0, s36
	s_mov_b64 s[4:5], 0x2000
	v_readfirstlane_b32 s36, v9
	global_load_lds_dwordx4 v[2:3], off
	v_lshl_add_u64 v[2:3], v[4:5], 0, s[4:5]
	s_mov_b32 m0, s36
	s_mov_b64 s[36:37], 0xc200
	v_add_u32_e32 v9, 0x2000, v7
	global_load_lds_dwordx4 v[2:3], off
	v_lshl_add_u64 v[2:3], v[0:1], 0, s[36:37]
	v_readfirstlane_b32 s36, v9
	v_add_u32_e32 v9, 0x6000, v7
	s_mov_b32 m0, s36
	s_mov_b64 s[4:5], 0x4000
	v_readfirstlane_b32 s36, v9
	global_load_lds_dwordx4 v[2:3], off
	v_lshl_add_u64 v[2:3], v[4:5], 0, s[4:5]
	s_mov_b32 m0, s36
	s_mov_b64 s[36:37], 0x12200
	v_add_u32_e32 v9, 0x3000, v7
	global_load_lds_dwordx4 v[2:3], off
	v_lshl_add_u64 v[2:3], v[0:1], 0, s[36:37]
	v_readfirstlane_b32 s36, v9
	v_add_u32_e32 v9, 0x7000, v7
	s_mov_b32 m0, s36
	s_mov_b64 s[4:5], 0x6000
	v_readfirstlane_b32 s36, v9
	global_load_lds_dwordx4 v[2:3], off
	v_lshl_add_u64 v[2:3], v[4:5], 0, s[4:5]
	s_mov_b32 m0, s36
	v_add_u32_e32 v9, 0x8000, v7
	s_mov_b64 s[36:37], 0x280
	global_load_lds_dwordx4 v[2:3], off
	v_add_u32_e32 v10, 0xc000, v7
	v_lshl_add_u64 v[2:3], v[0:1], 0, s[36:37]
	v_readfirstlane_b32 s36, v9
	s_mov_b32 m0, s36
	v_readfirstlane_b32 s36, v10
	s_waitcnt vmcnt(0)
	s_waitcnt vmcnt(0) lgkmcnt(0)
	s_barrier
	global_load_lds_dwordx4 v[2:3], off
	v_lshl_add_u64 v[2:3], v[4:5], 0, s[28:29]
	s_mov_b32 m0, s36
	s_mov_b64 s[36:37], 0x6280
	v_add_u32_e32 v9, 0x9000, v7
	global_load_lds_dwordx4 v[2:3], off
	v_lshl_add_u64 v[2:3], v[0:1], 0, s[36:37]
	v_readfirstlane_b32 s36, v9
	v_add_u32_e32 v9, 0xd000, v7
	s_mov_b32 m0, s36
	s_mov_b64 s[4:5], 0x2080
	v_readfirstlane_b32 s36, v9
	global_load_lds_dwordx4 v[2:3], off
	v_lshl_add_u64 v[2:3], v[4:5], 0, s[4:5]
	s_mov_b32 m0, s36
	s_mov_b64 s[36:37], 0xc280
	v_add_u32_e32 v9, 0xa000, v7
	global_load_lds_dwordx4 v[2:3], off
	v_lshl_add_u64 v[2:3], v[0:1], 0, s[36:37]
	v_readfirstlane_b32 s36, v9
	v_add_u32_e32 v9, 0xe000, v7
	s_mov_b32 m0, s36
	s_mov_b64 s[4:5], 0x4080
	v_readfirstlane_b32 s36, v9
	global_load_lds_dwordx4 v[2:3], off
	v_lshl_add_u64 v[2:3], v[4:5], 0, s[4:5]
	s_mov_b32 m0, s36
	s_mov_b64 s[36:37], 0x12280
	global_load_lds_dwordx4 v[2:3], off
	v_add_u32_e32 v2, 0xb000, v7
	v_lshl_add_u64 v[0:1], v[0:1], 0, s[36:37]
	v_readfirstlane_b32 s36, v2
	v_add_u32_e32 v2, 0xf000, v7
	s_mov_b32 m0, s36
	s_mov_b64 s[4:5], 0x6080
	v_readfirstlane_b32 s36, v2
	global_load_lds_dwordx4 v[0:1], off
	v_lshl_add_u64 v[0:1], v[4:5], 0, s[4:5]
	s_mov_b32 m0, s36
	v_and_b32_e32 v99, 15, v6
	global_load_lds_dwordx4 v[0:1], off
	v_bfe_u32 v68, v6, 1, 3
	v_ashrrev_i32_e32 v100, 7, v6
	v_bfe_u32 v101, v6, 4, 2
	v_lshlrev_b32_e32 v6, 7, v99
	v_bitop3_b32 v0, v8, v68, 3 bitop3:0x6c
	v_lshl_or_b32 v69, v100, 13, v6
	v_lshlrev_b32_e32 v0, 4, v0
	v_lshl_or_b32 v70, v98, 13, v6
	v_or_b32_e32 v102, v69, v0
	v_or_b32_e32 v103, v70, v0
	ds_read_b128 v[0:3], v102
	ds_read_b128 v[4:7], v103 offset:16384
	ds_read_b128 v[8:11], v102 offset:2048
	ds_read_b128 v[12:15], v103 offset:18432
	ds_read_b128 v[16:19], v102 offset:4096
	ds_read_b128 v[20:23], v103 offset:20480
	ds_read_b128 v[24:27], v102 offset:6144
	ds_read_b128 v[28:31], v103 offset:22528
	s_setprio 1
	s_waitcnt lgkmcnt(0)
	v_mfma_f32_16x16x32_bf16 v[32:35], v[0:3], v[4:7], 0
	v_mfma_f32_16x16x32_bf16 v[36:39], v[0:3], v[12:15], 0
	v_mfma_f32_16x16x32_bf16 v[40:43], v[0:3], v[20:23], 0
	v_mfma_f32_16x16x32_bf16 v[0:3], v[0:3], v[28:31], 0
	v_mfma_f32_16x16x32_bf16 v[44:47], v[8:11], v[4:7], 0
	v_mfma_f32_16x16x32_bf16 v[48:51], v[8:11], v[12:15], 0
	v_mfma_f32_16x16x32_bf16 v[52:55], v[8:11], v[20:23], 0
	v_mfma_f32_16x16x32_bf16 v[8:11], v[8:11], v[28:31], 0
	v_mfma_f32_16x16x32_bf16 v[56:59], v[16:19], v[4:7], 0
	v_mfma_f32_16x16x32_bf16 v[60:63], v[16:19], v[12:15], 0
	v_mfma_f32_16x16x32_bf16 v[64:67], v[16:19], v[20:23], 0
	v_mfma_f32_16x16x32_bf16 v[16:19], v[16:19], v[28:31], 0
	v_mfma_f32_16x16x32_bf16 v[4:7], v[24:27], v[4:7], 0
	v_mfma_f32_16x16x32_bf16 v[12:15], v[24:27], v[12:15], 0
	v_mfma_f32_16x16x32_bf16 v[20:23], v[24:27], v[20:23], 0
	v_mfma_f32_16x16x32_bf16 v[24:27], v[24:27], v[28:31], 0
	s_setprio 0
	v_bitop3_b32 v28, v101, v68, 4 bitop3:0x36
	v_lshlrev_b32_e32 v28, 4, v28
	v_or_b32_e32 v104, v69, v28
	v_or_b32_e32 v105, v70, v28
	ds_read_b128 v[28:31], v104
	ds_read_b128 v[68:71], v104 offset:2048
	ds_read_b128 v[72:75], v105 offset:16384
	ds_read_b128 v[76:79], v105 offset:18432
	ds_read_b128 v[80:83], v104 offset:4096
	ds_read_b128 v[84:87], v104 offset:6144
	ds_read_b128 v[88:91], v105 offset:20480
	ds_read_b128 v[92:95], v105 offset:22528
	s_setprio 1
	s_waitcnt lgkmcnt(5)
	v_mfma_f32_16x16x32_bf16 v[32:35], v[28:31], v[72:75], v[32:35]
	s_waitcnt lgkmcnt(4)
	v_mfma_f32_16x16x32_bf16 v[36:39], v[28:31], v[76:79], v[36:39]
	s_waitcnt lgkmcnt(1)
	v_mfma_f32_16x16x32_bf16 v[40:43], v[28:31], v[88:91], v[40:43]
	s_waitcnt lgkmcnt(0)
	v_mfma_f32_16x16x32_bf16 v[0:3], v[28:31], v[92:95], v[0:3]
	v_mfma_f32_16x16x32_bf16 v[28:31], v[68:71], v[72:75], v[44:47]
	v_mfma_f32_16x16x32_bf16 v[44:47], v[68:71], v[76:79], v[48:51]
	v_mfma_f32_16x16x32_bf16 v[48:51], v[68:71], v[88:91], v[52:55]
	v_mfma_f32_16x16x32_bf16 v[8:11], v[68:71], v[92:95], v[8:11]
	v_mfma_f32_16x16x32_bf16 v[52:55], v[80:83], v[72:75], v[56:59]
	v_mfma_f32_16x16x32_bf16 v[56:59], v[80:83], v[76:79], v[60:63]
	v_mfma_f32_16x16x32_bf16 v[60:63], v[80:83], v[88:91], v[64:67]
	v_mfma_f32_16x16x32_bf16 v[16:19], v[80:83], v[92:95], v[16:19]
	v_mfma_f32_16x16x32_bf16 v[4:7], v[84:87], v[72:75], v[4:7]
	v_mfma_f32_16x16x32_bf16 v[12:15], v[84:87], v[76:79], v[12:15]
	v_mfma_f32_16x16x32_bf16 v[20:23], v[84:87], v[88:91], v[20:23]
	v_mfma_f32_16x16x32_bf16 v[24:27], v[84:87], v[92:95], v[24:27]
	s_setprio 0
	s_waitcnt vmcnt(0)
	s_barrier
	ds_read_b128 v[64:67], v103 offset:55296
	ds_read_b128 v[68:71], v103 offset:53248
	ds_read_b128 v[72:75], v102 offset:38912
	ds_read_b128 v[76:79], v102 offset:36864
	ds_read_b128 v[80:83], v103 offset:51200
	ds_read_b128 v[84:87], v103 offset:49152
	ds_read_b128 v[88:91], v102 offset:34816
	ds_read_b128 v[92:95], v102 offset:32768
	s_setprio 1
	s_waitcnt lgkmcnt(0)
	v_mfma_f32_16x16x32_bf16 v[32:35], v[92:95], v[84:87], v[32:35]
	v_mfma_f32_16x16x32_bf16 v[36:39], v[92:95], v[80:83], v[36:39]
	v_mfma_f32_16x16x32_bf16 v[40:43], v[92:95], v[68:71], v[40:43]
	v_mfma_f32_16x16x32_bf16 v[0:3], v[92:95], v[64:67], v[0:3]
	v_mfma_f32_16x16x32_bf16 v[28:31], v[88:91], v[84:87], v[28:31]
	v_mfma_f32_16x16x32_bf16 v[44:47], v[88:91], v[80:83], v[44:47]
	v_mfma_f32_16x16x32_bf16 v[48:51], v[88:91], v[68:71], v[48:51]
	v_mfma_f32_16x16x32_bf16 v[8:11], v[88:91], v[64:67], v[8:11]
	v_mfma_f32_16x16x32_bf16 v[52:55], v[76:79], v[84:87], v[52:55]
	v_mfma_f32_16x16x32_bf16 v[56:59], v[76:79], v[80:83], v[56:59]
	v_mfma_f32_16x16x32_bf16 v[60:63], v[76:79], v[68:71], v[60:63]
	v_mfma_f32_16x16x32_bf16 v[16:19], v[76:79], v[64:67], v[16:19]
	v_mfma_f32_16x16x32_bf16 v[4:7], v[72:75], v[84:87], v[4:7]
	v_mfma_f32_16x16x32_bf16 v[12:15], v[72:75], v[80:83], v[12:15]
	v_mfma_f32_16x16x32_bf16 v[20:23], v[72:75], v[68:71], v[20:23]
	v_mfma_f32_16x16x32_bf16 v[24:27], v[72:75], v[64:67], v[24:27]
	s_setprio 0
	ds_read_b128 v[64:67], v104 offset:32768
	ds_read_b128 v[68:71], v104 offset:34816
	ds_read_b128 v[72:75], v105 offset:49152
	ds_read_b128 v[76:79], v105 offset:51200
	ds_read_b128 v[80:83], v104 offset:36864
	ds_read_b128 v[84:87], v104 offset:38912
	ds_read_b128 v[88:91], v105 offset:53248
	ds_read_b128 v[92:95], v105 offset:55296
	s_setprio 1
	s_waitcnt lgkmcnt(5)
	v_mfma_f32_16x16x32_bf16 v[32:35], v[64:67], v[72:75], v[32:35]
	s_waitcnt lgkmcnt(4)
	v_mfma_f32_16x16x32_bf16 v[36:39], v[64:67], v[76:79], v[36:39]
	s_waitcnt lgkmcnt(1)
	v_mfma_f32_16x16x32_bf16 v[40:43], v[64:67], v[88:91], v[40:43]
	s_waitcnt lgkmcnt(0)
	v_mfma_f32_16x16x32_bf16 v[0:3], v[64:67], v[92:95], v[0:3]
	v_mfma_f32_16x16x32_bf16 v[28:31], v[68:71], v[72:75], v[28:31]
	v_mfma_f32_16x16x32_bf16 v[44:47], v[68:71], v[76:79], v[44:47]
	v_mfma_f32_16x16x32_bf16 v[48:51], v[68:71], v[88:91], v[48:51]
	v_mfma_f32_16x16x32_bf16 v[8:11], v[68:71], v[92:95], v[8:11]
	v_mfma_f32_16x16x32_bf16 v[52:55], v[80:83], v[72:75], v[52:55]
	v_mfma_f32_16x16x32_bf16 v[56:59], v[80:83], v[76:79], v[56:59]
	v_mfma_f32_16x16x32_bf16 v[60:63], v[80:83], v[88:91], v[60:63]
	v_mfma_f32_16x16x32_bf16 v[16:19], v[80:83], v[92:95], v[16:19]
	v_mfma_f32_16x16x32_bf16 v[4:7], v[84:87], v[72:75], v[4:7]
	v_mfma_f32_16x16x32_bf16 v[12:15], v[84:87], v[76:79], v[12:15]
	v_mfma_f32_16x16x32_bf16 v[20:23], v[84:87], v[88:91], v[20:23]
	v_mfma_f32_16x16x32_bf16 v[24:27], v[84:87], v[92:95], v[24:27]
	s_setprio 0
	v_lshl_add_u32 v64, v100, 6, v96
	v_lshlrev_b32_e32 v65, 6, v98
	v_lshl_or_b32 v64, v101, 2, v64
	v_or3_b32 v65, v65, v97, v99
	v_readlane_b32 s4, v234, 9
	v_lshlrev_b32_e32 v128, 2, v65
	v_readlane_b32 s5, v234, 10
	v_ashrrev_i32_e32 v65, 31, v64
	v_lshlrev_b64 v[68:69], 10, v[64:65]
	v_lshl_add_u64 v[66:67], s[4:5], 0, v[128:129]
	v_lshl_add_u64 v[68:69], v[66:67], 0, v[68:69]
	s_waitcnt vmcnt(0)
	s_barrier
	global_store_dword v[68:69], v32, off
	global_store_dword v[68:69], v36, off offset:64
	global_store_dword v[68:69], v40, off offset:128
	global_store_dword v[68:69], v0, off offset:192
	v_or_b32_e32 v68, 1, v64
	v_ashrrev_i32_e32 v69, 31, v68
	v_lshlrev_b64 v[68:69], 10, v[68:69]
	v_lshl_add_u64 v[68:69], v[66:67], 0, v[68:69]
	v_or_b32_e32 v0, 2, v64
	global_store_dword v[68:69], v33, off
	global_store_dword v[68:69], v37, off offset:64
	global_store_dword v[68:69], v41, off offset:128
	global_store_dword v[68:69], v1, off offset:192
	v_ashrrev_i32_e32 v1, 31, v0
	v_lshlrev_b64 v[0:1], 10, v[0:1]
	v_lshl_add_u64 v[0:1], v[66:67], 0, v[0:1]
	global_store_dword v[0:1], v34, off
	global_store_dword v[0:1], v38, off offset:64
	global_store_dword v[0:1], v42, off offset:128
	global_store_dword v[0:1], v2, off offset:192
	v_or_b32_e32 v0, 3, v64
	v_ashrrev_i32_e32 v1, 31, v0
	v_lshlrev_b64 v[0:1], 10, v[0:1]
	v_lshl_add_u64 v[0:1], v[66:67], 0, v[0:1]
	global_store_dword v[0:1], v35, off
	global_store_dword v[0:1], v39, off offset:64
	global_store_dword v[0:1], v43, off offset:128
	global_store_dword v[0:1], v3, off offset:192
	v_or_b32_e32 v0, 16, v64
	v_ashrrev_i32_e32 v1, 31, v0
	v_lshlrev_b64 v[0:1], 10, v[0:1]
	v_lshl_add_u64 v[0:1], v[66:67], 0, v[0:1]
	global_store_dword v[0:1], v28, off
	global_store_dword v[0:1], v44, off offset:64
	global_store_dword v[0:1], v48, off offset:128
	global_store_dword v[0:1], v8, off offset:192
	v_or_b32_e32 v0, 17, v64
	v_ashrrev_i32_e32 v1, 31, v0
	v_lshlrev_b64 v[0:1], 10, v[0:1]
	v_lshl_add_u64 v[0:1], v[66:67], 0, v[0:1]
	global_store_dword v[0:1], v29, off
	global_store_dword v[0:1], v45, off offset:64
	global_store_dword v[0:1], v49, off offset:128
	global_store_dword v[0:1], v9, off offset:192
	v_or_b32_e32 v0, 18, v64
	v_ashrrev_i32_e32 v1, 31, v0
	v_lshlrev_b64 v[0:1], 10, v[0:1]
	v_lshl_add_u64 v[0:1], v[66:67], 0, v[0:1]
	global_store_dword v[0:1], v30, off
	global_store_dword v[0:1], v46, off offset:64
	global_store_dword v[0:1], v50, off offset:128
	global_store_dword v[0:1], v10, off offset:192
	v_or_b32_e32 v0, 19, v64
	v_ashrrev_i32_e32 v1, 31, v0
	v_lshlrev_b64 v[0:1], 10, v[0:1]
	v_lshl_add_u64 v[0:1], v[66:67], 0, v[0:1]
	global_store_dword v[0:1], v31, off
	global_store_dword v[0:1], v47, off offset:64
	global_store_dword v[0:1], v51, off offset:128
	global_store_dword v[0:1], v11, off offset:192
	v_or_b32_e32 v0, 32, v64
	v_ashrrev_i32_e32 v1, 31, v0
	v_lshlrev_b64 v[0:1], 10, v[0:1]
	v_lshl_add_u64 v[0:1], v[66:67], 0, v[0:1]
	global_store_dword v[0:1], v52, off
	global_store_dword v[0:1], v56, off offset:64
	global_store_dword v[0:1], v60, off offset:128
	global_store_dword v[0:1], v16, off offset:192
	v_or_b32_e32 v0, 33, v64
	v_ashrrev_i32_e32 v1, 31, v0
	v_lshlrev_b64 v[0:1], 10, v[0:1]
	v_lshl_add_u64 v[0:1], v[66:67], 0, v[0:1]
	global_store_dword v[0:1], v53, off
	global_store_dword v[0:1], v57, off offset:64
	global_store_dword v[0:1], v61, off offset:128
	global_store_dword v[0:1], v17, off offset:192
	v_or_b32_e32 v0, 34, v64
	v_ashrrev_i32_e32 v1, 31, v0
	v_lshlrev_b64 v[0:1], 10, v[0:1]
	v_lshl_add_u64 v[0:1], v[66:67], 0, v[0:1]
	global_store_dword v[0:1], v54, off
	global_store_dword v[0:1], v58, off offset:64
	global_store_dword v[0:1], v62, off offset:128
	global_store_dword v[0:1], v18, off offset:192
	v_or_b32_e32 v0, 35, v64
	v_ashrrev_i32_e32 v1, 31, v0
	v_lshlrev_b64 v[0:1], 10, v[0:1]
	v_lshl_add_u64 v[0:1], v[66:67], 0, v[0:1]
	global_store_dword v[0:1], v55, off
	global_store_dword v[0:1], v59, off offset:64
	global_store_dword v[0:1], v63, off offset:128
	global_store_dword v[0:1], v19, off offset:192
	v_or_b32_e32 v0, 48, v64
	v_ashrrev_i32_e32 v1, 31, v0
	v_lshlrev_b64 v[0:1], 10, v[0:1]
	v_lshl_add_u64 v[0:1], v[66:67], 0, v[0:1]
	global_store_dword v[0:1], v4, off
	global_store_dword v[0:1], v12, off offset:64
	global_store_dword v[0:1], v20, off offset:128
	global_store_dword v[0:1], v24, off offset:192
	v_or_b32_e32 v0, 49, v64
	v_ashrrev_i32_e32 v1, 31, v0
	v_lshlrev_b64 v[0:1], 10, v[0:1]
	v_lshl_add_u64 v[0:1], v[66:67], 0, v[0:1]
	global_store_dword v[0:1], v5, off
	global_store_dword v[0:1], v13, off offset:64
	global_store_dword v[0:1], v21, off offset:128
	global_store_dword v[0:1], v25, off offset:192
	v_or_b32_e32 v0, 50, v64
	v_ashrrev_i32_e32 v1, 31, v0
	v_lshlrev_b64 v[0:1], 10, v[0:1]
	v_lshl_add_u64 v[0:1], v[66:67], 0, v[0:1]
	global_store_dword v[0:1], v6, off
	global_store_dword v[0:1], v14, off offset:64
	global_store_dword v[0:1], v22, off offset:128
	global_store_dword v[0:1], v26, off offset:192
	v_or_b32_e32 v0, 51, v64
	v_ashrrev_i32_e32 v1, 31, v0
	v_lshlrev_b64 v[0:1], 10, v[0:1]
	v_lshl_add_u64 v[0:1], v[66:67], 0, v[0:1]
	global_store_dword v[0:1], v7, off
	global_store_dword v[0:1], v15, off offset:64
	global_store_dword v[0:1], v23, off offset:128
	global_store_dword v[0:1], v27, off offset:192

.LBB0_719:
	s_andn2_saveexec_b64 s[34:35], s[10:11]
	s_cbranch_execz .LBB0_721
	v_mov_b32_e32 v6, v170
	v_lshl_add_u32 v0, v48, 5, v193
	v_readlane_b32 s4, v235, 42
	v_lshrrev_b32_e32 v8, 4, v6
	v_and_b32_e32 v120, 0x7fffff80, v0
	v_ashrrev_i32_e32 v5, 3, v6
	v_xor_b32_e32 v2, v8, v6
	v_readlane_b32 s5, v235, 43
	v_lshlrev_b32_e32 v121, 7, v48
	v_add_u32_e32 v3, v5, v120
	v_mov_b64_e32 v[0:1], s[4:5]
	v_lshlrev_b32_e32 v2, 4, v2
	v_and_b32_e32 v4, 0x180, v121
	v_ashrrev_i32_e32 v7, 6, v6
	v_mad_i64_i32 v[0:1], s[36:37], v3, s64, v[0:1]
	v_and_b32_e32 v128, 0x70, v2
	v_and_b32_e32 v122, 1, v7
	v_lshl_add_u64 v[0:1], v[0:1], 0, v[128:129]
	s_mov_b64 s[4:5], 0x100
	v_add_u32_e32 v4, v5, v4
	v_lshlrev_b32_e32 v7, 10, v7
	v_lshl_add_u64 v[2:3], v[0:1], 0, s[4:5]
	v_ashrrev_i32_e32 v5, 31, v4
	v_readlane_b32 s4, v234, 3
	v_add_u32_e32 v9, 0x4000, v7
	v_readfirstlane_b32 s36, v7
	v_lshlrev_b64 v[4:5], 8, v[4:5]
	v_readlane_b32 s5, v234, 4
	s_mov_b32 m0, s36
	v_readfirstlane_b32 s36, v9
	v_lshl_add_u64 v[4:5], s[4:5], 0, v[4:5]
	s_waitcnt lgkmcnt(0)
	s_barrier
	global_load_lds_dwordx4 v[2:3], off
	s_mov_b32 m0, s36
	s_mov_b64 s[36:37], 0x6100
	v_add_u32_e32 v9, 0x1000, v7
	v_lshl_add_u64 v[4:5], v[4:5], 0, v[128:129]
	v_lshl_add_u64 v[2:3], v[0:1], 0, s[36:37]
	v_readfirstlane_b32 s36, v9
	v_add_u32_e32 v9, 0x5000, v7
	global_load_lds_dwordx4 v[4:5], off
	s_mov_b32 m0, s36
	s_mov_b64 s[4:5], 0x2000
	v_readfirstlane_b32 s36, v9
	v_add_u32_e32 v9, 0x2000, v7
	global_load_lds_dwordx4 v[2:3], off
	v_lshl_add_u64 v[2:3], v[4:5], 0, s[4:5]
	s_mov_b32 m0, s36
	s_mov_b64 s[4:5], 0xc100
	v_readfirstlane_b32 s36, v9
	v_add_u32_e32 v9, 0x6000, v7
	global_load_lds_dwordx4 v[2:3], off
	v_lshl_add_u64 v[2:3], v[0:1], 0, s[4:5]
	s_mov_b32 m0, s36
	s_mov_b64 s[4:5], 0x4000
	v_readfirstlane_b32 s36, v9
	global_load_lds_dwordx4 v[2:3], off
	v_lshl_add_u64 v[2:3], v[4:5], 0, s[4:5]
	s_mov_b32 m0, s36
	s_mov_b64 s[36:37], 0x12100
	v_add_u32_e32 v9, 0x3000, v7
	global_load_lds_dwordx4 v[2:3], off
	v_lshl_add_u64 v[2:3], v[0:1], 0, s[36:37]
	v_readfirstlane_b32 s36, v9
	v_add_u32_e32 v9, 0x7000, v7
	s_mov_b32 m0, s36
	s_mov_b64 s[4:5], 0x6000
	v_readfirstlane_b32 s36, v9
	v_add_u32_e32 v9, 0x8000, v7
	global_load_lds_dwordx4 v[2:3], off
	v_lshl_add_u64 v[2:3], v[4:5], 0, s[4:5]
	s_mov_b32 m0, s36
	v_add_u32_e32 v10, 0xc000, v7
	s_mov_b64 s[4:5], 0x180
	v_readfirstlane_b32 s36, v9
	global_load_lds_dwordx4 v[2:3], off
	v_lshl_add_u64 v[2:3], v[0:1], 0, s[4:5]
	s_mov_b32 m0, s36
	v_readfirstlane_b32 s36, v10
	s_waitcnt vmcnt(0)
	s_waitcnt vmcnt(0) lgkmcnt(0)
	s_barrier
	global_load_lds_dwordx4 v[2:3], off
	v_lshl_add_u64 v[2:3], v[4:5], 0, s[28:29]
	s_mov_b32 m0, s36
	s_mov_b64 s[36:37], 0x6180
	v_add_u32_e32 v9, 0x9000, v7
	global_load_lds_dwordx4 v[2:3], off
	v_lshl_add_u64 v[2:3], v[0:1], 0, s[36:37]
	v_readfirstlane_b32 s36, v9
	v_add_u32_e32 v9, 0xd000, v7
	s_mov_b32 m0, s36
	s_mov_b64 s[4:5], 0x2080
	v_readfirstlane_b32 s36, v9
	v_add_u32_e32 v9, 0xa000, v7
	global_load_lds_dwordx4 v[2:3], off
	v_lshl_add_u64 v[2:3], v[4:5], 0, s[4:5]
	s_mov_b32 m0, s36
	s_mov_b64 s[4:5], 0xc180
	v_readfirstlane_b32 s36, v9
	v_add_u32_e32 v9, 0xe000, v7
	global_load_lds_dwordx4 v[2:3], off
	v_lshl_add_u64 v[2:3], v[0:1], 0, s[4:5]
	s_mov_b32 m0, s36
	s_mov_b64 s[4:5], 0x4080
	v_readfirstlane_b32 s36, v9
	global_load_lds_dwordx4 v[2:3], off
	v_lshl_add_u64 v[2:3], v[4:5], 0, s[4:5]
	s_mov_b32 m0, s36
	s_mov_b64 s[36:37], 0x12180
	global_load_lds_dwordx4 v[2:3], off
	v_add_u32_e32 v2, 0xb000, v7
	v_lshl_add_u64 v[0:1], v[0:1], 0, s[36:37]
	v_readfirstlane_b32 s36, v2
	v_add_u32_e32 v2, 0xf000, v7
	s_mov_b32 m0, s36
	s_mov_b64 s[4:5], 0x6080
	v_readfirstlane_b32 s36, v2
	global_load_lds_dwordx4 v[0:1], off
	v_lshl_add_u64 v[0:1], v[4:5], 0, s[4:5]
	s_mov_b32 m0, s36
	v_and_b32_e32 v123, 15, v6
	global_load_lds_dwordx4 v[0:1], off
	v_bfe_u32 v68, v6, 1, 3
	v_ashrrev_i32_e32 v124, 7, v6
	v_bfe_u32 v125, v6, 4, 2
	v_lshlrev_b32_e32 v6, 7, v123
	v_bitop3_b32 v0, v8, v68, 3 bitop3:0x6c
	v_lshl_or_b32 v69, v124, 13, v6
	v_lshlrev_b32_e32 v0, 4, v0
	v_lshl_or_b32 v70, v122, 13, v6
	v_or_b32_e32 v96, v69, v0
	v_or_b32_e32 v97, v70, v0
	ds_read_b128 v[0:3], v96
	ds_read_b128 v[4:7], v97 offset:16384
	ds_read_b128 v[8:11], v96 offset:2048
	ds_read_b128 v[12:15], v97 offset:18432
	ds_read_b128 v[16:19], v96 offset:4096
	ds_read_b128 v[20:23], v97 offset:20480
	ds_read_b128 v[24:27], v96 offset:6144
	ds_read_b128 v[28:31], v97 offset:22528
	s_setprio 1
	s_waitcnt lgkmcnt(0)
	v_mfma_f32_16x16x32_bf16 v[32:35], v[0:3], v[4:7], 0
	v_mfma_f32_16x16x32_bf16 v[36:39], v[0:3], v[12:15], 0
	v_mfma_f32_16x16x32_bf16 v[40:43], v[0:3], v[20:23], 0
	v_mfma_f32_16x16x32_bf16 v[0:3], v[0:3], v[28:31], 0
	v_mfma_f32_16x16x32_bf16 v[44:47], v[8:11], v[4:7], 0
	v_mfma_f32_16x16x32_bf16 v[48:51], v[8:11], v[12:15], 0
	v_mfma_f32_16x16x32_bf16 v[52:55], v[8:11], v[20:23], 0
	v_mfma_f32_16x16x32_bf16 v[8:11], v[8:11], v[28:31], 0
	v_mfma_f32_16x16x32_bf16 v[56:59], v[16:19], v[4:7], 0
	v_mfma_f32_16x16x32_bf16 v[60:63], v[16:19], v[12:15], 0
	v_mfma_f32_16x16x32_bf16 v[64:67], v[16:19], v[20:23], 0
	v_mfma_f32_16x16x32_bf16 v[16:19], v[16:19], v[28:31], 0
	v_mfma_f32_16x16x32_bf16 v[4:7], v[24:27], v[4:7], 0
	v_mfma_f32_16x16x32_bf16 v[12:15], v[24:27], v[12:15], 0
	v_mfma_f32_16x16x32_bf16 v[20:23], v[24:27], v[20:23], 0
	v_mfma_f32_16x16x32_bf16 v[24:27], v[24:27], v[28:31], 0
	s_setprio 0
	v_bitop3_b32 v28, v125, v68, 4 bitop3:0x36
	v_lshlrev_b32_e32 v28, 4, v28
	v_or_b32_e32 v108, v69, v28
	v_or_b32_e32 v116, v70, v28
	ds_read_b128 v[28:31], v108
	ds_read_b128 v[68:71], v108 offset:2048
	ds_read_b128 v[72:75], v116 offset:16384
	ds_read_b128 v[76:79], v116 offset:18432
	ds_read_b128 v[80:83], v108 offset:4096
	ds_read_b128 v[84:87], v108 offset:6144
	ds_read_b128 v[88:91], v116 offset:20480
	ds_read_b128 v[92:95], v116 offset:22528
	s_setprio 1
	s_waitcnt lgkmcnt(5)
	v_mfma_f32_16x16x32_bf16 v[32:35], v[28:31], v[72:75], v[32:35]
	s_waitcnt lgkmcnt(4)
	v_mfma_f32_16x16x32_bf16 v[36:39], v[28:31], v[76:79], v[36:39]
	s_waitcnt lgkmcnt(1)
	v_mfma_f32_16x16x32_bf16 v[40:43], v[28:31], v[88:91], v[40:43]
	s_waitcnt lgkmcnt(0)
	v_mfma_f32_16x16x32_bf16 v[0:3], v[28:31], v[92:95], v[0:3]
	v_mfma_f32_16x16x32_bf16 v[28:31], v[68:71], v[72:75], v[44:47]
	v_mfma_f32_16x16x32_bf16 v[44:47], v[68:71], v[76:79], v[48:51]
	v_mfma_f32_16x16x32_bf16 v[48:51], v[68:71], v[88:91], v[52:55]
	v_mfma_f32_16x16x32_bf16 v[8:11], v[68:71], v[92:95], v[8:11]
	v_mfma_f32_16x16x32_bf16 v[52:55], v[80:83], v[72:75], v[56:59]
	v_mfma_f32_16x16x32_bf16 v[56:59], v[80:83], v[76:79], v[60:63]
	v_mfma_f32_16x16x32_bf16 v[60:63], v[80:83], v[88:91], v[64:67]
	v_mfma_f32_16x16x32_bf16 v[16:19], v[80:83], v[92:95], v[16:19]
	v_mfma_f32_16x16x32_bf16 v[4:7], v[84:87], v[72:75], v[4:7]
	v_mfma_f32_16x16x32_bf16 v[12:15], v[84:87], v[76:79], v[12:15]
	v_mfma_f32_16x16x32_bf16 v[20:23], v[84:87], v[88:91], v[20:23]
	v_mfma_f32_16x16x32_bf16 v[24:27], v[84:87], v[92:95], v[24:27]
	s_setprio 0
	s_waitcnt vmcnt(0)
	s_barrier
	ds_read_b128 v[64:67], v97 offset:55296
	ds_read_b128 v[68:71], v97 offset:53248
	ds_read_b128 v[72:75], v96 offset:38912
	ds_read_b128 v[76:79], v96 offset:36864
	ds_read_b128 v[80:83], v97 offset:51200
	ds_read_b128 v[84:87], v97 offset:49152
	ds_read_b128 v[88:91], v96 offset:34816
	ds_read_b128 v[92:95], v96 offset:32768
	s_setprio 1
	s_waitcnt lgkmcnt(0)
	v_mfma_f32_16x16x32_bf16 v[32:35], v[92:95], v[84:87], v[32:35]
	v_mfma_f32_16x16x32_bf16 v[36:39], v[92:95], v[80:83], v[36:39]
	v_mfma_f32_16x16x32_bf16 v[40:43], v[92:95], v[68:71], v[40:43]
	v_mfma_f32_16x16x32_bf16 v[0:3], v[92:95], v[64:67], v[0:3]
	v_mfma_f32_16x16x32_bf16 v[92:95], v[88:91], v[84:87], v[28:31]
	v_mfma_f32_16x16x32_bf16 v[96:99], v[88:91], v[80:83], v[44:47]
	v_mfma_f32_16x16x32_bf16 v[48:51], v[88:91], v[68:71], v[48:51]
	v_mfma_f32_16x16x32_bf16 v[8:11], v[88:91], v[64:67], v[8:11]
	v_mfma_f32_16x16x32_bf16 v[52:55], v[76:79], v[84:87], v[52:55]
	v_mfma_f32_16x16x32_bf16 v[88:91], v[76:79], v[80:83], v[56:59]
	v_mfma_f32_16x16x32_bf16 v[100:103], v[76:79], v[68:71], v[60:63]
	v_mfma_f32_16x16x32_bf16 v[16:19], v[76:79], v[64:67], v[16:19]
	v_mfma_f32_16x16x32_bf16 v[76:79], v[72:75], v[84:87], v[4:7]
	v_mfma_f32_16x16x32_bf16 v[80:83], v[72:75], v[80:83], v[12:15]
	v_mfma_f32_16x16x32_bf16 v[68:71], v[72:75], v[68:71], v[20:23]
	v_mfma_f32_16x16x32_bf16 v[64:67], v[72:75], v[64:67], v[24:27]
	s_setprio 0
	ds_read_b128 v[4:7], v108 offset:32768
	ds_read_b128 v[20:23], v108 offset:34816
	ds_read_b128 v[72:75], v116 offset:49152
	ds_read_b128 v[84:87], v116 offset:51200
	ds_read_b128 v[104:107], v108 offset:36864
	ds_read_b128 v[108:111], v108 offset:38912
	ds_read_b128 v[112:115], v116 offset:53248
	ds_read_b128 v[116:119], v116 offset:55296
	s_setprio 1
	s_waitcnt lgkmcnt(5)
	v_mfma_f32_16x16x32_bf16 v[60:63], v[4:7], v[72:75], v[32:35]
	s_waitcnt lgkmcnt(4)
	v_mfma_f32_16x16x32_bf16 v[44:47], v[4:7], v[84:87], v[36:39]
	s_waitcnt lgkmcnt(1)
	v_mfma_f32_16x16x32_bf16 v[28:31], v[4:7], v[112:115], v[40:43]
	s_waitcnt lgkmcnt(0)
	v_mfma_f32_16x16x32_bf16 v[12:15], v[4:7], v[116:119], v[0:3]
	v_mfma_f32_16x16x32_bf16 v[56:59], v[20:23], v[72:75], v[92:95]
	v_mfma_f32_16x16x32_bf16 v[40:43], v[20:23], v[84:87], v[96:99]
	v_mfma_f32_16x16x32_bf16 v[24:27], v[20:23], v[112:115], v[48:51]
	v_mfma_f32_16x16x32_bf16 v[8:11], v[20:23], v[116:119], v[8:11]
	v_mfma_f32_16x16x32_bf16 v[52:55], v[104:107], v[72:75], v[52:55]
	v_mfma_f32_16x16x32_bf16 v[36:39], v[104:107], v[84:87], v[88:91]
	v_mfma_f32_16x16x32_bf16 v[20:23], v[104:107], v[112:115], v[100:103]
	v_mfma_f32_16x16x32_bf16 v[4:7], v[104:107], v[116:119], v[16:19]
	v_mfma_f32_16x16x32_bf16 v[48:51], v[108:111], v[72:75], v[76:79]
	v_mfma_f32_16x16x32_bf16 v[32:35], v[108:111], v[84:87], v[80:83]
	v_mfma_f32_16x16x32_bf16 v[16:19], v[108:111], v[112:115], v[68:71]
	v_mfma_f32_16x16x32_bf16 v[0:3], v[108:111], v[116:119], v[64:67]
	s_setprio 0
	s_nop 1
	v_lshlrev_b32_e32 v66, 6, v122
	v_and_b32_e32 v68, 0x80, v121
	v_or3_b32 v66, v66, v68, v123
	v_and_b32_e32 v68, 0x100, v121
	v_or_b32_e32 v68, s2, v68
	v_or_b32_e32 v70, v68, v66
	s_mov_b64 s[36:37], s[8:9]
	v_readlane_b32 s4, v237, 35
	v_ashrrev_i32_e32 v71, 31, v70
	v_readlane_b32 s10, v237, 41
	v_readlane_b32 s11, v237, 42
	s_waitcnt vmcnt(0)
	s_barrier
	s_nop 0
	v_lshl_add_u64 v[70:71], v[70:71], 2, s[10:11]
	global_load_dword v69, v[70:71], off
	v_readlane_b32 s8, v237, 39
	v_readlane_b32 s9, v237, 40
	s_mov_b64 s[8:9], s[36:37]
	v_lshl_add_u32 v64, v124, 6, v120
	v_lshl_or_b32 v64, v125, 2, v64
	v_bfe_u32 v67, v121, 8, 1
	v_readlane_b32 s5, v237, 36
	v_ashrrev_i32_e32 v65, 31, v64
	v_mul_u32_u24_e32 v128, 0x3000, v67
	v_readlane_b32 s4, v234, 5
	v_lshl_add_u64 v[64:65], v[64:65], 0, v[128:129]
	v_lshlrev_b32_e32 v128, 2, v66
	v_readlane_b32 s5, v234, 6
	v_lshlrev_b64 v[64:65], 10, v[64:65]
	v_mov_b32_e32 v67, v129
	v_lshl_add_u64 v[70:71], s[4:5], 0, v[128:129]
	v_lshl_add_u64 v[64:65], v[70:71], 0, v[64:65]
	s_movk_i32 s4, 0x4000
	v_readlane_b32 s6, v237, 37
	v_readlane_b32 s7, v237, 38
	v_readlane_b32 s12, v237, 43
	v_readlane_b32 s13, v237, 44
	v_readlane_b32 s14, v237, 45
	v_readlane_b32 s15, v237, 46
	v_readlane_b32 s16, v237, 47
	v_readlane_b32 s17, v237, 48
	v_readlane_b32 s18, v237, 49
	v_readlane_b32 s19, v237, 50
	s_waitcnt vmcnt(0)
	v_add_f32_e32 v60, v60, v69
	v_mul_f32_e32 v60, 0xbfb8aa3b, v60
	v_exp_f32_e32 v60, v60
	v_add_f32_e32 v56, v56, v69
	v_mul_f32_e32 v56, 0xbfb8aa3b, v56
	v_exp_f32_e32 v56, v56
	v_add_f32_e32 v60, 1.0, v60
	v_div_scale_f32 v72, s[36:37], v60, v60, 1.0
	v_rcp_f32_e32 v73, v72
	v_add_f32_e32 v56, 1.0, v56
	v_add_f32_e32 v52, v52, v69
	v_mul_f32_e32 v52, 0xbfb8aa3b, v52
	v_fma_f32 v74, -v72, v73, 1.0
	v_fmac_f32_e32 v73, v74, v73
	v_div_scale_f32 v74, vcc, 1.0, v60, 1.0
	v_mul_f32_e32 v75, v74, v73
	v_fma_f32 v76, -v72, v75, v74
	v_fmac_f32_e32 v75, v76, v73
	v_fma_f32 v72, -v72, v75, v74
	v_div_fmas_f32 v72, v72, v73, v75
	v_div_fixup_f32 v60, v72, v60, 1.0
	global_store_dword v[64:65], v60, off
	v_add_f32_e32 v60, v61, v69
	v_mul_f32_e32 v60, 0xbfb8aa3b, v60
	v_exp_f32_e32 v60, v60
	v_exp_f32_e32 v52, v52
	v_add_f32_e32 v48, v48, v69
	v_mul_f32_e32 v48, 0xbfb8aa3b, v48
	v_add_f32_e32 v60, 1.0, v60
	v_div_scale_f32 v61, s[36:37], v60, v60, 1.0
	v_rcp_f32_e32 v70, v61
	v_add_f32_e32 v52, 1.0, v52
	v_exp_f32_e32 v48, v48
	v_fma_f32 v71, -v61, v70, 1.0
	v_fmac_f32_e32 v70, v71, v70
	v_div_scale_f32 v71, vcc, 1.0, v60, 1.0
	v_mul_f32_e32 v72, v71, v70
	v_fma_f32 v73, -v61, v72, v71
	v_fmac_f32_e32 v72, v73, v70
	v_fma_f32 v61, -v61, v72, v71
	v_div_fmas_f32 v61, v61, v70, v72
	v_div_fixup_f32 v60, v61, v60, 1.0
	global_store_dword v[64:65], v60, off offset:1024
	v_add_f32_e32 v60, v62, v69
	v_mul_f32_e32 v60, 0xbfb8aa3b, v60
	v_exp_f32_e32 v60, v60
	v_add_f32_e32 v48, 1.0, v48
	v_add_f32_e32 v60, 1.0, v60
	v_div_scale_f32 v61, s[36:37], v60, v60, 1.0
	v_rcp_f32_e32 v62, v61
	s_nop 0
	v_fma_f32 v70, -v61, v62, 1.0
	v_fmac_f32_e32 v62, v70, v62
	v_div_scale_f32 v70, vcc, 1.0, v60, 1.0
	v_mul_f32_e32 v71, v70, v62
	v_fma_f32 v72, -v61, v71, v70
	v_fmac_f32_e32 v71, v72, v62
	v_fma_f32 v61, -v61, v71, v70
	v_div_fmas_f32 v61, v61, v62, v71
	v_div_fixup_f32 v60, v61, v60, 1.0
	global_store_dword v[64:65], v60, off offset:2048
	v_add_f32_e32 v60, v63, v69
	v_mul_f32_e32 v60, 0xbfb8aa3b, v60
	v_exp_f32_e32 v60, v60
	s_nop 0
	v_add_f32_e32 v60, 1.0, v60
	v_div_scale_f32 v61, s[36:37], v60, v60, 1.0
	v_rcp_f32_e32 v62, v61
	s_nop 0
	v_fma_f32 v63, -v61, v62, 1.0
	v_fmac_f32_e32 v62, v63, v62
	v_div_scale_f32 v63, vcc, 1.0, v60, 1.0
	v_mul_f32_e32 v70, v63, v62
	v_fma_f32 v71, -v61, v70, v63
	v_fmac_f32_e32 v70, v71, v62
	v_fma_f32 v61, -v61, v70, v63
	v_div_fmas_f32 v61, v61, v62, v70
	v_div_fixup_f32 v60, v61, v60, 1.0
	global_store_dword v[64:65], v60, off offset:3072
	v_div_scale_f32 v60, s[36:37], v56, v56, 1.0
	v_rcp_f32_e32 v61, v60
	s_nop 0
	v_fma_f32 v62, -v60, v61, 1.0
	v_fmac_f32_e32 v61, v62, v61
	v_div_scale_f32 v62, vcc, 1.0, v56, 1.0
	v_mul_f32_e32 v63, v62, v61
	v_fma_f32 v70, -v60, v63, v62
	v_fmac_f32_e32 v63, v70, v61
	v_fma_f32 v60, -v60, v63, v62
	v_div_fmas_f32 v60, v60, v61, v63
	v_div_fixup_f32 v56, v60, v56, 1.0
	v_add_co_u32_e32 v60, vcc, s4, v64
	s_mov_b32 s4, 0x8000
	s_nop 0
	v_addc_co_u32_e32 v61, vcc, 0, v65, vcc
	global_store_dword v[60:61], v56, off
	v_add_f32_e32 v56, v57, v69
	v_mul_f32_e32 v56, 0xbfb8aa3b, v56
	v_exp_f32_e32 v56, v56
	s_nop 0
	v_add_f32_e32 v56, 1.0, v56
	v_div_scale_f32 v57, s[36:37], v56, v56, 1.0
	v_rcp_f32_e32 v62, v57
	s_nop 0
	v_fma_f32 v63, -v57, v62, 1.0
	v_fmac_f32_e32 v62, v63, v62
	v_div_scale_f32 v63, vcc, 1.0, v56, 1.0
	v_mul_f32_e32 v70, v63, v62
	v_fma_f32 v71, -v57, v70, v63
	v_fmac_f32_e32 v70, v71, v62
	v_fma_f32 v57, -v57, v70, v63
	v_div_fmas_f32 v57, v57, v62, v70
	v_div_fixup_f32 v56, v57, v56, 1.0
	global_store_dword v[60:61], v56, off offset:1024
	v_add_f32_e32 v56, v58, v69
	v_mul_f32_e32 v56, 0xbfb8aa3b, v56
	v_exp_f32_e32 v56, v56
	s_nop 0
	v_add_f32_e32 v56, 1.0, v56
	v_div_scale_f32 v57, s[36:37], v56, v56, 1.0
	v_rcp_f32_e32 v58, v57
	s_nop 0
	v_fma_f32 v62, -v57, v58, 1.0
	v_fmac_f32_e32 v58, v62, v58
	v_div_scale_f32 v62, vcc, 1.0, v56, 1.0
	v_mul_f32_e32 v63, v62, v58
	v_fma_f32 v70, -v57, v63, v62
	v_fmac_f32_e32 v63, v70, v58
	v_fma_f32 v57, -v57, v63, v62
	v_div_fmas_f32 v57, v57, v58, v63
	v_div_fixup_f32 v56, v57, v56, 1.0
	global_store_dword v[60:61], v56, off offset:2048
	v_add_f32_e32 v56, v59, v69
	v_mul_f32_e32 v56, 0xbfb8aa3b, v56
	v_exp_f32_e32 v56, v56
	s_nop 0
	v_add_f32_e32 v56, 1.0, v56
	v_div_scale_f32 v57, s[36:37], v56, v56, 1.0
	v_rcp_f32_e32 v58, v57
	s_nop 0
	v_fma_f32 v59, -v57, v58, 1.0
	v_fmac_f32_e32 v58, v59, v58
	v_div_scale_f32 v59, vcc, 1.0, v56, 1.0
	v_mul_f32_e32 v62, v59, v58
	v_fma_f32 v63, -v57, v62, v59
	v_fmac_f32_e32 v62, v63, v58
	v_fma_f32 v57, -v57, v62, v59
	v_div_fmas_f32 v57, v57, v58, v62
	v_div_fixup_f32 v56, v57, v56, 1.0
	global_store_dword v[60:61], v56, off offset:3072
	v_div_scale_f32 v56, s[36:37], v52, v52, 1.0
	v_rcp_f32_e32 v57, v56
	s_nop 0
	v_fma_f32 v58, -v56, v57, 1.0
	v_fmac_f32_e32 v57, v58, v57
	v_div_scale_f32 v58, vcc, 1.0, v52, 1.0
	v_mul_f32_e32 v59, v58, v57
	v_fma_f32 v62, -v56, v59, v58
	v_fmac_f32_e32 v59, v62, v57
	v_fma_f32 v56, -v56, v59, v58
	v_div_fmas_f32 v56, v56, v57, v59
	v_div_fixup_f32 v52, v56, v52, 1.0
	v_add_co_u32_e32 v56, vcc, s4, v64
	s_mov_b32 s4, 0xc000
	s_nop 0
	v_addc_co_u32_e32 v57, vcc, 0, v65, vcc
	global_store_dword v[56:57], v52, off
	v_add_f32_e32 v52, v53, v69
	v_mul_f32_e32 v52, 0xbfb8aa3b, v52
	v_exp_f32_e32 v52, v52
	s_nop 0
	v_add_f32_e32 v52, 1.0, v52
	v_div_scale_f32 v53, s[36:37], v52, v52, 1.0
	v_rcp_f32_e32 v58, v53
	s_nop 0
	v_fma_f32 v59, -v53, v58, 1.0
	v_fmac_f32_e32 v58, v59, v58
	v_div_scale_f32 v59, vcc, 1.0, v52, 1.0
	v_mul_f32_e32 v62, v59, v58
	v_fma_f32 v63, -v53, v62, v59
	v_fmac_f32_e32 v62, v63, v58
	v_fma_f32 v53, -v53, v62, v59
	v_div_fmas_f32 v53, v53, v58, v62
	v_div_fixup_f32 v52, v53, v52, 1.0
	global_store_dword v[56:57], v52, off offset:1024
	v_add_f32_e32 v52, v54, v69
	v_mul_f32_e32 v52, 0xbfb8aa3b, v52
	v_exp_f32_e32 v52, v52
	s_nop 0
	v_add_f32_e32 v52, 1.0, v52
	v_div_scale_f32 v53, s[36:37], v52, v52, 1.0
	v_rcp_f32_e32 v54, v53
	s_nop 0
	v_fma_f32 v58, -v53, v54, 1.0
	v_fmac_f32_e32 v54, v58, v54
	v_div_scale_f32 v58, vcc, 1.0, v52, 1.0
	v_mul_f32_e32 v59, v58, v54
	v_fma_f32 v62, -v53, v59, v58
	v_fmac_f32_e32 v59, v62, v54
	v_fma_f32 v53, -v53, v59, v58
	v_div_fmas_f32 v53, v53, v54, v59
	v_div_fixup_f32 v52, v53, v52, 1.0
	global_store_dword v[56:57], v52, off offset:2048
	v_add_f32_e32 v52, v55, v69
	v_mul_f32_e32 v52, 0xbfb8aa3b, v52
	v_exp_f32_e32 v52, v52
	s_nop 0
	v_add_f32_e32 v52, 1.0, v52
	v_div_scale_f32 v53, s[36:37], v52, v52, 1.0
	v_rcp_f32_e32 v54, v53
	s_nop 0
	v_fma_f32 v55, -v53, v54, 1.0
	v_fmac_f32_e32 v54, v55, v54
	v_div_scale_f32 v55, vcc, 1.0, v52, 1.0
	v_mul_f32_e32 v58, v55, v54
	v_fma_f32 v59, -v53, v58, v55
	v_fmac_f32_e32 v58, v59, v54
	v_fma_f32 v53, -v53, v58, v55
	v_div_fmas_f32 v53, v53, v54, v58
	v_div_fixup_f32 v52, v53, v52, 1.0
	global_store_dword v[56:57], v52, off offset:3072
	v_div_scale_f32 v52, s[36:37], v48, v48, 1.0
	v_rcp_f32_e32 v53, v52
	s_nop 0
	v_fma_f32 v54, -v52, v53, 1.0
	v_fmac_f32_e32 v53, v54, v53
	v_div_scale_f32 v54, vcc, 1.0, v48, 1.0
	v_mul_f32_e32 v55, v54, v53
	v_fma_f32 v58, -v52, v55, v54
	v_fmac_f32_e32 v55, v58, v53
	v_fma_f32 v52, -v52, v55, v54
	v_div_fmas_f32 v52, v52, v53, v55
	v_div_fixup_f32 v48, v52, v48, 1.0
	v_add_co_u32_e32 v52, vcc, s4, v64
	s_nop 1
	v_addc_co_u32_e32 v53, vcc, 0, v65, vcc
	global_store_dword v[52:53], v48, off
	v_add_f32_e32 v48, v49, v69
	v_mul_f32_e32 v48, 0xbfb8aa3b, v48
	v_exp_f32_e32 v48, v48
	s_nop 0
	v_add_f32_e32 v48, 1.0, v48
	v_div_scale_f32 v49, s[36:37], v48, v48, 1.0
	v_rcp_f32_e32 v54, v49
	s_nop 0
	v_fma_f32 v55, -v49, v54, 1.0
	v_fmac_f32_e32 v54, v55, v54
	v_div_scale_f32 v55, vcc, 1.0, v48, 1.0
	v_mul_f32_e32 v58, v55, v54
	v_fma_f32 v59, -v49, v58, v55
	v_fmac_f32_e32 v58, v59, v54
	v_fma_f32 v49, -v49, v58, v55
	v_div_fmas_f32 v49, v49, v54, v58
	v_div_fixup_f32 v48, v49, v48, 1.0
	global_store_dword v[52:53], v48, off offset:1024
	v_add_f32_e32 v48, v50, v69
	v_mul_f32_e32 v48, 0xbfb8aa3b, v48
	v_exp_f32_e32 v48, v48
	s_nop 0
	v_add_f32_e32 v48, 1.0, v48
	v_div_scale_f32 v49, s[36:37], v48, v48, 1.0
	v_rcp_f32_e32 v50, v49
	s_nop 0
	v_fma_f32 v54, -v49, v50, 1.0
	v_fmac_f32_e32 v50, v54, v50
	v_div_scale_f32 v54, vcc, 1.0, v48, 1.0
	v_mul_f32_e32 v55, v54, v50
	v_fma_f32 v58, -v49, v55, v54
	v_fmac_f32_e32 v55, v58, v50
	v_fma_f32 v49, -v49, v55, v54
	v_div_fmas_f32 v49, v49, v50, v55
	v_div_fixup_f32 v48, v49, v48, 1.0
	global_store_dword v[52:53], v48, off offset:2048
	v_add_f32_e32 v48, v51, v69
	v_mul_f32_e32 v48, 0xbfb8aa3b, v48
	v_exp_f32_e32 v48, v48
	v_ashrrev_i32_e32 v69, 31, v68
	v_add_f32_e32 v48, 1.0, v48
	v_div_scale_f32 v49, s[36:37], v48, v48, 1.0
	v_rcp_f32_e32 v50, v49
	s_nop 0
	v_fma_f32 v51, -v49, v50, 1.0
	v_fmac_f32_e32 v50, v51, v50
	v_div_scale_f32 v51, vcc, 1.0, v48, 1.0
	v_mul_f32_e32 v54, v51, v50
	v_fma_f32 v55, -v49, v54, v51
	v_fmac_f32_e32 v54, v55, v50
	v_fma_f32 v49, -v49, v54, v51
	v_div_fmas_f32 v49, v49, v50, v54
	v_div_fixup_f32 v48, v49, v48, 1.0
	global_store_dword v[52:53], v48, off offset:3072
	v_lshl_add_u64 v[48:49], v[68:69], 0, v[66:67]
	v_lshl_add_u64 v[48:49], v[48:49], 2, s[10:11]
	global_load_dword v50, v[48:49], off offset:64
	s_waitcnt vmcnt(0)
	v_add_f32_e32 v44, v44, v50
	v_mul_f32_e32 v44, 0xbfb8aa3b, v44
	v_exp_f32_e32 v44, v44
	v_add_f32_e32 v40, v40, v50
	v_mul_f32_e32 v40, 0xbfb8aa3b, v40
	v_exp_f32_e32 v40, v40
	v_add_f32_e32 v44, 1.0, v44
	v_div_scale_f32 v51, s[36:37], v44, v44, 1.0
	v_rcp_f32_e32 v54, v51
	v_add_f32_e32 v40, 1.0, v40
	v_add_f32_e32 v36, v36, v50
	v_mul_f32_e32 v36, 0xbfb8aa3b, v36
	v_fma_f32 v55, -v51, v54, 1.0
	v_fmac_f32_e32 v54, v55, v54
	v_div_scale_f32 v55, vcc, 1.0, v44, 1.0
	v_mul_f32_e32 v58, v55, v54
	v_fma_f32 v59, -v51, v58, v55
	v_fmac_f32_e32 v58, v59, v54
	v_fma_f32 v51, -v51, v58, v55
	v_div_fmas_f32 v51, v51, v54, v58
	v_div_fixup_f32 v44, v51, v44, 1.0
	global_store_dword v[64:65], v44, off offset:64
	v_add_f32_e32 v44, v45, v50
	v_mul_f32_e32 v44, 0xbfb8aa3b, v44
	v_exp_f32_e32 v44, v44
	v_exp_f32_e32 v36, v36
	v_add_f32_e32 v32, v32, v50
	v_mul_f32_e32 v32, 0xbfb8aa3b, v32
	v_add_f32_e32 v44, 1.0, v44
	v_div_scale_f32 v45, s[36:37], v44, v44, 1.0
	v_rcp_f32_e32 v51, v45
	v_add_f32_e32 v36, 1.0, v36
	v_exp_f32_e32 v32, v32
	v_fma_f32 v54, -v45, v51, 1.0
	v_fmac_f32_e32 v51, v54, v51
	v_div_scale_f32 v54, vcc, 1.0, v44, 1.0
	v_mul_f32_e32 v55, v54, v51
	v_fma_f32 v58, -v45, v55, v54
	v_fmac_f32_e32 v55, v58, v51
	v_fma_f32 v45, -v45, v55, v54
	v_div_fmas_f32 v45, v45, v51, v55
	v_div_fixup_f32 v44, v45, v44, 1.0
	global_store_dword v[64:65], v44, off offset:1088
	v_add_f32_e32 v44, v46, v50
	v_mul_f32_e32 v44, 0xbfb8aa3b, v44
	v_exp_f32_e32 v44, v44
	v_add_f32_e32 v32, 1.0, v32
	v_add_f32_e32 v44, 1.0, v44
	v_div_scale_f32 v45, s[36:37], v44, v44, 1.0
	v_rcp_f32_e32 v46, v45
	s_nop 0
	v_fma_f32 v51, -v45, v46, 1.0
	v_fmac_f32_e32 v46, v51, v46
	v_div_scale_f32 v51, vcc, 1.0, v44, 1.0
	v_mul_f32_e32 v54, v51, v46
	v_fma_f32 v55, -v45, v54, v51
	v_fmac_f32_e32 v54, v55, v46
	v_fma_f32 v45, -v45, v54, v51
	v_div_fmas_f32 v45, v45, v46, v54
	v_div_fixup_f32 v44, v45, v44, 1.0
	global_store_dword v[64:65], v44, off offset:2112
	v_add_f32_e32 v44, v47, v50
	v_mul_f32_e32 v44, 0xbfb8aa3b, v44
	v_exp_f32_e32 v44, v44
	s_nop 0
	v_add_f32_e32 v44, 1.0, v44
	v_div_scale_f32 v45, s[36:37], v44, v44, 1.0
	v_rcp_f32_e32 v46, v45
	s_nop 0
	v_fma_f32 v47, -v45, v46, 1.0
	v_fmac_f32_e32 v46, v47, v46
	v_div_scale_f32 v47, vcc, 1.0, v44, 1.0
	v_mul_f32_e32 v51, v47, v46
	v_fma_f32 v54, -v45, v51, v47
	v_fmac_f32_e32 v51, v54, v46
	v_fma_f32 v45, -v45, v51, v47
	v_div_fmas_f32 v45, v45, v46, v51
	v_div_fixup_f32 v44, v45, v44, 1.0
	global_store_dword v[64:65], v44, off offset:3136
	v_div_scale_f32 v44, s[36:37], v40, v40, 1.0
	v_rcp_f32_e32 v45, v44
	s_nop 0
	v_fma_f32 v46, -v44, v45, 1.0
	v_fmac_f32_e32 v45, v46, v45
	v_div_scale_f32 v46, vcc, 1.0, v40, 1.0
	v_mul_f32_e32 v47, v46, v45
	v_fma_f32 v51, -v44, v47, v46
	v_fmac_f32_e32 v47, v51, v45
	v_fma_f32 v44, -v44, v47, v46
	v_div_fmas_f32 v44, v44, v45, v47
	v_div_fixup_f32 v40, v44, v40, 1.0
	global_store_dword v[60:61], v40, off offset:64
	v_add_f32_e32 v40, v41, v50
	v_mul_f32_e32 v40, 0xbfb8aa3b, v40
	v_exp_f32_e32 v40, v40
	s_nop 0
	v_add_f32_e32 v40, 1.0, v40
	v_div_scale_f32 v41, s[36:37], v40, v40, 1.0
	v_rcp_f32_e32 v44, v41
	s_nop 0
	v_fma_f32 v45, -v41, v44, 1.0
	v_fmac_f32_e32 v44, v45, v44
	v_div_scale_f32 v45, vcc, 1.0, v40, 1.0
	v_mul_f32_e32 v46, v45, v44
	v_fma_f32 v47, -v41, v46, v45
	v_fmac_f32_e32 v46, v47, v44
	v_fma_f32 v41, -v41, v46, v45
	v_div_fmas_f32 v41, v41, v44, v46
	v_div_fixup_f32 v40, v41, v40, 1.0
	global_store_dword v[60:61], v40, off offset:1088
	v_add_f32_e32 v40, v42, v50
	v_mul_f32_e32 v40, 0xbfb8aa3b, v40
	v_exp_f32_e32 v40, v40
	s_nop 0
	v_add_f32_e32 v40, 1.0, v40
	v_div_scale_f32 v41, s[36:37], v40, v40, 1.0
	v_rcp_f32_e32 v42, v41
	s_nop 0
	v_fma_f32 v44, -v41, v42, 1.0
	v_fmac_f32_e32 v42, v44, v42
	v_div_scale_f32 v44, vcc, 1.0, v40, 1.0
	v_mul_f32_e32 v45, v44, v42
	v_fma_f32 v46, -v41, v45, v44
	v_fmac_f32_e32 v45, v46, v42
	v_fma_f32 v41, -v41, v45, v44
	v_div_fmas_f32 v41, v41, v42, v45
	v_div_fixup_f32 v40, v41, v40, 1.0
	global_store_dword v[60:61], v40, off offset:2112
	v_add_f32_e32 v40, v43, v50
	v_mul_f32_e32 v40, 0xbfb8aa3b, v40
	v_exp_f32_e32 v40, v40
	s_nop 0
	v_add_f32_e32 v40, 1.0, v40
	v_div_scale_f32 v41, s[36:37], v40, v40, 1.0
	v_rcp_f32_e32 v42, v41
	s_nop 0
	v_fma_f32 v43, -v41, v42, 1.0
	v_fmac_f32_e32 v42, v43, v42
	v_div_scale_f32 v43, vcc, 1.0, v40, 1.0
	v_mul_f32_e32 v44, v43, v42
	v_fma_f32 v45, -v41, v44, v43
	v_fmac_f32_e32 v44, v45, v42
	v_fma_f32 v41, -v41, v44, v43
	v_div_fmas_f32 v41, v41, v42, v44
	v_div_fixup_f32 v40, v41, v40, 1.0
	global_store_dword v[60:61], v40, off offset:3136
	v_div_scale_f32 v40, s[36:37], v36, v36, 1.0
	v_rcp_f32_e32 v41, v40
	s_nop 0
	v_fma_f32 v42, -v40, v41, 1.0
	v_fmac_f32_e32 v41, v42, v41
	v_div_scale_f32 v42, vcc, 1.0, v36, 1.0
	v_mul_f32_e32 v43, v42, v41
	v_fma_f32 v44, -v40, v43, v42
	v_fmac_f32_e32 v43, v44, v41
	v_fma_f32 v40, -v40, v43, v42
	v_div_fmas_f32 v40, v40, v41, v43
	v_div_fixup_f32 v36, v40, v36, 1.0
	global_store_dword v[56:57], v36, off offset:64
	v_add_f32_e32 v36, v37, v50
	v_mul_f32_e32 v36, 0xbfb8aa3b, v36
	v_exp_f32_e32 v36, v36
	s_nop 0
	v_add_f32_e32 v36, 1.0, v36
	v_div_scale_f32 v37, s[36:37], v36, v36, 1.0
	v_rcp_f32_e32 v40, v37
	s_nop 0
	v_fma_f32 v41, -v37, v40, 1.0
	v_fmac_f32_e32 v40, v41, v40
	v_div_scale_f32 v41, vcc, 1.0, v36, 1.0
	v_mul_f32_e32 v42, v41, v40
	v_fma_f32 v43, -v37, v42, v41
	v_fmac_f32_e32 v42, v43, v40
	v_fma_f32 v37, -v37, v42, v41
	v_div_fmas_f32 v37, v37, v40, v42
	v_div_fixup_f32 v36, v37, v36, 1.0
	global_store_dword v[56:57], v36, off offset:1088
	v_add_f32_e32 v36, v38, v50
	v_mul_f32_e32 v36, 0xbfb8aa3b, v36
	v_exp_f32_e32 v36, v36
	s_nop 0
	v_add_f32_e32 v36, 1.0, v36
	v_div_scale_f32 v37, s[36:37], v36, v36, 1.0
	v_rcp_f32_e32 v38, v37
	s_nop 0
	v_fma_f32 v40, -v37, v38, 1.0
	v_fmac_f32_e32 v38, v40, v38
	v_div_scale_f32 v40, vcc, 1.0, v36, 1.0
	v_mul_f32_e32 v41, v40, v38
	v_fma_f32 v42, -v37, v41, v40
	v_fmac_f32_e32 v41, v42, v38
	v_fma_f32 v37, -v37, v41, v40
	v_div_fmas_f32 v37, v37, v38, v41
	v_div_fixup_f32 v36, v37, v36, 1.0
	global_store_dword v[56:57], v36, off offset:2112
	v_add_f32_e32 v36, v39, v50
	v_mul_f32_e32 v36, 0xbfb8aa3b, v36
	v_exp_f32_e32 v36, v36
	s_nop 0
	v_add_f32_e32 v36, 1.0, v36
	v_div_scale_f32 v37, s[36:37], v36, v36, 1.0
	v_rcp_f32_e32 v38, v37
	s_nop 0
	v_fma_f32 v39, -v37, v38, 1.0
	v_fmac_f32_e32 v38, v39, v38
	v_div_scale_f32 v39, vcc, 1.0, v36, 1.0
	v_mul_f32_e32 v40, v39, v38
	v_fma_f32 v41, -v37, v40, v39
	v_fmac_f32_e32 v40, v41, v38
	v_fma_f32 v37, -v37, v40, v39
	v_div_fmas_f32 v37, v37, v38, v40
	v_div_fixup_f32 v36, v37, v36, 1.0
	global_store_dword v[56:57], v36, off offset:3136
	v_div_scale_f32 v36, s[36:37], v32, v32, 1.0
	v_rcp_f32_e32 v37, v36
	s_nop 0
	v_fma_f32 v38, -v36, v37, 1.0
	v_fmac_f32_e32 v37, v38, v37
	v_div_scale_f32 v38, vcc, 1.0, v32, 1.0
	v_mul_f32_e32 v39, v38, v37
	v_fma_f32 v40, -v36, v39, v38
	v_fmac_f32_e32 v39, v40, v37
	v_fma_f32 v36, -v36, v39, v38
	v_div_fmas_f32 v36, v36, v37, v39
	v_div_fixup_f32 v32, v36, v32, 1.0
	global_store_dword v[52:53], v32, off offset:64
	v_add_f32_e32 v32, v33, v50
	v_mul_f32_e32 v32, 0xbfb8aa3b, v32
	v_exp_f32_e32 v32, v32
	s_nop 0
	v_add_f32_e32 v32, 1.0, v32
	v_div_scale_f32 v33, s[36:37], v32, v32, 1.0
	v_rcp_f32_e32 v36, v33
	s_nop 0
	v_fma_f32 v37, -v33, v36, 1.0
	v_fmac_f32_e32 v36, v37, v36
	v_div_scale_f32 v37, vcc, 1.0, v32, 1.0
	v_mul_f32_e32 v38, v37, v36
	v_fma_f32 v39, -v33, v38, v37
	v_fmac_f32_e32 v38, v39, v36
	v_fma_f32 v33, -v33, v38, v37
	v_div_fmas_f32 v33, v33, v36, v38
	v_div_fixup_f32 v32, v33, v32, 1.0
	global_store_dword v[52:53], v32, off offset:1088
	v_add_f32_e32 v32, v34, v50
	v_mul_f32_e32 v32, 0xbfb8aa3b, v32
	v_exp_f32_e32 v32, v32
	s_nop 0
	v_add_f32_e32 v32, 1.0, v32
	v_div_scale_f32 v33, s[36:37], v32, v32, 1.0
	v_rcp_f32_e32 v34, v33
	s_nop 0
	v_fma_f32 v36, -v33, v34, 1.0
	v_fmac_f32_e32 v34, v36, v34
	v_div_scale_f32 v36, vcc, 1.0, v32, 1.0
	v_mul_f32_e32 v37, v36, v34
	v_fma_f32 v38, -v33, v37, v36
	v_fmac_f32_e32 v37, v38, v34
	v_fma_f32 v33, -v33, v37, v36
	v_div_fmas_f32 v33, v33, v34, v37
	v_div_fixup_f32 v32, v33, v32, 1.0
	global_store_dword v[52:53], v32, off offset:2112
	v_add_f32_e32 v32, v35, v50
	v_mul_f32_e32 v32, 0xbfb8aa3b, v32
	v_exp_f32_e32 v32, v32
	s_nop 0
	v_add_f32_e32 v32, 1.0, v32
	v_div_scale_f32 v33, s[36:37], v32, v32, 1.0
	v_rcp_f32_e32 v34, v33
	s_nop 0
	v_fma_f32 v35, -v33, v34, 1.0
	v_fmac_f32_e32 v34, v35, v34
	v_div_scale_f32 v35, vcc, 1.0, v32, 1.0
	v_mul_f32_e32 v36, v35, v34
	v_fma_f32 v37, -v33, v36, v35
	v_fmac_f32_e32 v36, v37, v34
	v_fma_f32 v33, -v33, v36, v35
	v_div_fmas_f32 v33, v33, v34, v36
	v_div_fixup_f32 v32, v33, v32, 1.0
	global_store_dword v[52:53], v32, off offset:3136
	global_load_dword v32, v[48:49], off offset:128
	s_waitcnt vmcnt(0)
	v_add_f32_e32 v28, v28, v32
	v_mul_f32_e32 v28, 0xbfb8aa3b, v28
	v_exp_f32_e32 v28, v28
	v_add_f32_e32 v24, v24, v32
	v_mul_f32_e32 v24, 0xbfb8aa3b, v24
	v_exp_f32_e32 v24, v24
	v_add_f32_e32 v28, 1.0, v28
	v_div_scale_f32 v33, s[36:37], v28, v28, 1.0
	v_rcp_f32_e32 v34, v33
	v_add_f32_e32 v24, 1.0, v24
	v_add_f32_e32 v20, v20, v32
	v_mul_f32_e32 v20, 0xbfb8aa3b, v20
	v_fma_f32 v35, -v33, v34, 1.0
	v_fmac_f32_e32 v34, v35, v34
	v_div_scale_f32 v35, vcc, 1.0, v28, 1.0
	v_mul_f32_e32 v36, v35, v34
	v_fma_f32 v37, -v33, v36, v35
	v_fmac_f32_e32 v36, v37, v34
	v_fma_f32 v33, -v33, v36, v35
	v_div_fmas_f32 v33, v33, v34, v36
	v_div_fixup_f32 v28, v33, v28, 1.0
	global_store_dword v[64:65], v28, off offset:128
	v_add_f32_e32 v28, v29, v32
	v_mul_f32_e32 v28, 0xbfb8aa3b, v28
	v_exp_f32_e32 v28, v28
	v_exp_f32_e32 v20, v20
	v_add_f32_e32 v16, v16, v32
	v_mul_f32_e32 v16, 0xbfb8aa3b, v16
	v_add_f32_e32 v28, 1.0, v28
	v_div_scale_f32 v29, s[36:37], v28, v28, 1.0
	v_rcp_f32_e32 v33, v29
	v_add_f32_e32 v20, 1.0, v20
	v_exp_f32_e32 v16, v16
	v_fma_f32 v34, -v29, v33, 1.0
	v_fmac_f32_e32 v33, v34, v33
	v_div_scale_f32 v34, vcc, 1.0, v28, 1.0
	v_mul_f32_e32 v35, v34, v33
	v_fma_f32 v36, -v29, v35, v34
	v_fmac_f32_e32 v35, v36, v33
	v_fma_f32 v29, -v29, v35, v34
	v_div_fmas_f32 v29, v29, v33, v35
	v_div_fixup_f32 v28, v29, v28, 1.0
	global_store_dword v[64:65], v28, off offset:1152
	v_add_f32_e32 v28, v30, v32
	v_mul_f32_e32 v28, 0xbfb8aa3b, v28
	v_exp_f32_e32 v28, v28
	v_add_f32_e32 v16, 1.0, v16
	v_add_f32_e32 v28, 1.0, v28
	v_div_scale_f32 v29, s[36:37], v28, v28, 1.0
	v_rcp_f32_e32 v30, v29
	s_nop 0
	v_fma_f32 v33, -v29, v30, 1.0
	v_fmac_f32_e32 v30, v33, v30
	v_div_scale_f32 v33, vcc, 1.0, v28, 1.0
	v_mul_f32_e32 v34, v33, v30
	v_fma_f32 v35, -v29, v34, v33
	v_fmac_f32_e32 v34, v35, v30
	v_fma_f32 v29, -v29, v34, v33
	v_div_fmas_f32 v29, v29, v30, v34
	v_div_fixup_f32 v28, v29, v28, 1.0
	global_store_dword v[64:65], v28, off offset:2176
	v_add_f32_e32 v28, v31, v32
	v_mul_f32_e32 v28, 0xbfb8aa3b, v28
	v_exp_f32_e32 v28, v28
	s_nop 0
	v_add_f32_e32 v28, 1.0, v28
	v_div_scale_f32 v29, s[36:37], v28, v28, 1.0
	v_rcp_f32_e32 v30, v29
	s_nop 0
	v_fma_f32 v31, -v29, v30, 1.0
	v_fmac_f32_e32 v30, v31, v30
	v_div_scale_f32 v31, vcc, 1.0, v28, 1.0
	v_mul_f32_e32 v33, v31, v30
	v_fma_f32 v34, -v29, v33, v31
	v_fmac_f32_e32 v33, v34, v30
	v_fma_f32 v29, -v29, v33, v31
	v_div_fmas_f32 v29, v29, v30, v33
	v_div_fixup_f32 v28, v29, v28, 1.0
	global_store_dword v[64:65], v28, off offset:3200
	v_div_scale_f32 v28, s[36:37], v24, v24, 1.0
	v_rcp_f32_e32 v29, v28
	s_nop 0
	v_fma_f32 v30, -v28, v29, 1.0
	v_fmac_f32_e32 v29, v30, v29
	v_div_scale_f32 v30, vcc, 1.0, v24, 1.0
	v_mul_f32_e32 v31, v30, v29
	v_fma_f32 v33, -v28, v31, v30
	v_fmac_f32_e32 v31, v33, v29
	v_fma_f32 v28, -v28, v31, v30
	v_div_fmas_f32 v28, v28, v29, v31
	v_div_fixup_f32 v24, v28, v24, 1.0
	global_store_dword v[60:61], v24, off offset:128
	v_add_f32_e32 v24, v25, v32
	v_mul_f32_e32 v24, 0xbfb8aa3b, v24
	v_exp_f32_e32 v24, v24
	s_nop 0
	v_add_f32_e32 v24, 1.0, v24
	v_div_scale_f32 v25, s[36:37], v24, v24, 1.0
	v_rcp_f32_e32 v28, v25
	s_nop 0
	v_fma_f32 v29, -v25, v28, 1.0
	v_fmac_f32_e32 v28, v29, v28
	v_div_scale_f32 v29, vcc, 1.0, v24, 1.0
	v_mul_f32_e32 v30, v29, v28
	v_fma_f32 v31, -v25, v30, v29
	v_fmac_f32_e32 v30, v31, v28
	v_fma_f32 v25, -v25, v30, v29
	v_div_fmas_f32 v25, v25, v28, v30
	v_div_fixup_f32 v24, v25, v24, 1.0
	global_store_dword v[60:61], v24, off offset:1152
	v_add_f32_e32 v24, v26, v32
	v_mul_f32_e32 v24, 0xbfb8aa3b, v24
	v_exp_f32_e32 v24, v24
	s_nop 0
	v_add_f32_e32 v24, 1.0, v24
	v_div_scale_f32 v25, s[36:37], v24, v24, 1.0
	v_rcp_f32_e32 v26, v25
	s_nop 0
	v_fma_f32 v28, -v25, v26, 1.0
	v_fmac_f32_e32 v26, v28, v26
	v_div_scale_f32 v28, vcc, 1.0, v24, 1.0
	v_mul_f32_e32 v29, v28, v26
	v_fma_f32 v30, -v25, v29, v28
	v_fmac_f32_e32 v29, v30, v26
	v_fma_f32 v25, -v25, v29, v28
	v_div_fmas_f32 v25, v25, v26, v29
	v_div_fixup_f32 v24, v25, v24, 1.0
	global_store_dword v[60:61], v24, off offset:2176
	v_add_f32_e32 v24, v27, v32
	v_mul_f32_e32 v24, 0xbfb8aa3b, v24
	v_exp_f32_e32 v24, v24
	s_nop 0
	v_add_f32_e32 v24, 1.0, v24
	v_div_scale_f32 v25, s[36:37], v24, v24, 1.0
	v_rcp_f32_e32 v26, v25
	s_nop 0
	v_fma_f32 v27, -v25, v26, 1.0
	v_fmac_f32_e32 v26, v27, v26
	v_div_scale_f32 v27, vcc, 1.0, v24, 1.0
	v_mul_f32_e32 v28, v27, v26
	v_fma_f32 v29, -v25, v28, v27
	v_fmac_f32_e32 v28, v29, v26
	v_fma_f32 v25, -v25, v28, v27
	v_div_fmas_f32 v25, v25, v26, v28
	v_div_fixup_f32 v24, v25, v24, 1.0
	global_store_dword v[60:61], v24, off offset:3200
	v_div_scale_f32 v24, s[36:37], v20, v20, 1.0
	v_rcp_f32_e32 v25, v24
	s_nop 0
	v_fma_f32 v26, -v24, v25, 1.0
	v_fmac_f32_e32 v25, v26, v25
	v_div_scale_f32 v26, vcc, 1.0, v20, 1.0
	v_mul_f32_e32 v27, v26, v25
	v_fma_f32 v28, -v24, v27, v26
	v_fmac_f32_e32 v27, v28, v25
	v_fma_f32 v24, -v24, v27, v26
	v_div_fmas_f32 v24, v24, v25, v27
	v_div_fixup_f32 v20, v24, v20, 1.0
	global_store_dword v[56:57], v20, off offset:128
	v_add_f32_e32 v20, v21, v32
	v_mul_f32_e32 v20, 0xbfb8aa3b, v20
	v_exp_f32_e32 v20, v20
	s_nop 0
	v_add_f32_e32 v20, 1.0, v20
	v_div_scale_f32 v21, s[36:37], v20, v20, 1.0
	v_rcp_f32_e32 v24, v21
	s_nop 0
	v_fma_f32 v25, -v21, v24, 1.0
	v_fmac_f32_e32 v24, v25, v24
	v_div_scale_f32 v25, vcc, 1.0, v20, 1.0
	v_mul_f32_e32 v26, v25, v24
	v_fma_f32 v27, -v21, v26, v25
	v_fmac_f32_e32 v26, v27, v24
	v_fma_f32 v21, -v21, v26, v25
	v_div_fmas_f32 v21, v21, v24, v26
	v_div_fixup_f32 v20, v21, v20, 1.0
	global_store_dword v[56:57], v20, off offset:1152
	v_add_f32_e32 v20, v22, v32
	v_mul_f32_e32 v20, 0xbfb8aa3b, v20
	v_exp_f32_e32 v20, v20
	s_nop 0
	v_add_f32_e32 v20, 1.0, v20
	v_div_scale_f32 v21, s[36:37], v20, v20, 1.0
	v_rcp_f32_e32 v22, v21
	s_nop 0
	v_fma_f32 v24, -v21, v22, 1.0
	v_fmac_f32_e32 v22, v24, v22
	v_div_scale_f32 v24, vcc, 1.0, v20, 1.0
	v_mul_f32_e32 v25, v24, v22
	v_fma_f32 v26, -v21, v25, v24
	v_fmac_f32_e32 v25, v26, v22
	v_fma_f32 v21, -v21, v25, v24
	v_div_fmas_f32 v21, v21, v22, v25
	v_div_fixup_f32 v20, v21, v20, 1.0
	global_store_dword v[56:57], v20, off offset:2176
	v_add_f32_e32 v20, v23, v32
	v_mul_f32_e32 v20, 0xbfb8aa3b, v20
	v_exp_f32_e32 v20, v20
	s_nop 0
	v_add_f32_e32 v20, 1.0, v20
	v_div_scale_f32 v21, s[36:37], v20, v20, 1.0
	v_rcp_f32_e32 v22, v21
	s_nop 0
	v_fma_f32 v23, -v21, v22, 1.0
	v_fmac_f32_e32 v22, v23, v22
	v_div_scale_f32 v23, vcc, 1.0, v20, 1.0
	v_mul_f32_e32 v24, v23, v22
	v_fma_f32 v25, -v21, v24, v23
	v_fmac_f32_e32 v24, v25, v22
	v_fma_f32 v21, -v21, v24, v23
	v_div_fmas_f32 v21, v21, v22, v24
	v_div_fixup_f32 v20, v21, v20, 1.0
	global_store_dword v[56:57], v20, off offset:3200
	v_div_scale_f32 v20, s[36:37], v16, v16, 1.0
	v_rcp_f32_e32 v21, v20
	s_nop 0
	v_fma_f32 v22, -v20, v21, 1.0
	v_fmac_f32_e32 v21, v22, v21
	v_div_scale_f32 v22, vcc, 1.0, v16, 1.0
	v_mul_f32_e32 v23, v22, v21
	v_fma_f32 v24, -v20, v23, v22
	v_fmac_f32_e32 v23, v24, v21
	v_fma_f32 v20, -v20, v23, v22
	v_div_fmas_f32 v20, v20, v21, v23
	v_div_fixup_f32 v16, v20, v16, 1.0
	global_store_dword v[52:53], v16, off offset:128
	v_add_f32_e32 v16, v17, v32
	v_mul_f32_e32 v16, 0xbfb8aa3b, v16
	v_exp_f32_e32 v16, v16
	s_nop 0
	v_add_f32_e32 v16, 1.0, v16
	v_div_scale_f32 v17, s[36:37], v16, v16, 1.0
	v_rcp_f32_e32 v20, v17
	s_nop 0
	v_fma_f32 v21, -v17, v20, 1.0
	v_fmac_f32_e32 v20, v21, v20
	v_div_scale_f32 v21, vcc, 1.0, v16, 1.0
	v_mul_f32_e32 v22, v21, v20
	v_fma_f32 v23, -v17, v22, v21
	v_fmac_f32_e32 v22, v23, v20
	v_fma_f32 v17, -v17, v22, v21
	v_div_fmas_f32 v17, v17, v20, v22
	v_div_fixup_f32 v16, v17, v16, 1.0
	global_store_dword v[52:53], v16, off offset:1152
	v_add_f32_e32 v16, v18, v32
	v_mul_f32_e32 v16, 0xbfb8aa3b, v16
	v_exp_f32_e32 v16, v16
	s_nop 0
	v_add_f32_e32 v16, 1.0, v16
	v_div_scale_f32 v17, s[36:37], v16, v16, 1.0
	v_rcp_f32_e32 v18, v17
	s_nop 0
	v_fma_f32 v20, -v17, v18, 1.0
	v_fmac_f32_e32 v18, v20, v18
	v_div_scale_f32 v20, vcc, 1.0, v16, 1.0
	v_mul_f32_e32 v21, v20, v18
	v_fma_f32 v22, -v17, v21, v20
	v_fmac_f32_e32 v21, v22, v18
	v_fma_f32 v17, -v17, v21, v20
	v_div_fmas_f32 v17, v17, v18, v21
	v_div_fixup_f32 v16, v17, v16, 1.0
	global_store_dword v[52:53], v16, off offset:2176
	v_add_f32_e32 v16, v19, v32
	v_mul_f32_e32 v16, 0xbfb8aa3b, v16
	v_exp_f32_e32 v16, v16
	s_nop 0
	v_add_f32_e32 v16, 1.0, v16
	v_div_scale_f32 v17, s[36:37], v16, v16, 1.0
	v_rcp_f32_e32 v18, v17
	s_nop 0
	v_fma_f32 v19, -v17, v18, 1.0
	v_fmac_f32_e32 v18, v19, v18
	v_div_scale_f32 v19, vcc, 1.0, v16, 1.0
	v_mul_f32_e32 v20, v19, v18
	v_fma_f32 v21, -v17, v20, v19
	v_fmac_f32_e32 v20, v21, v18
	v_fma_f32 v17, -v17, v20, v19
	v_div_fmas_f32 v17, v17, v18, v20
	v_div_fixup_f32 v16, v17, v16, 1.0
	global_store_dword v[52:53], v16, off offset:3200
	global_load_dword v16, v[48:49], off offset:192
	s_waitcnt vmcnt(0)
	v_add_f32_e32 v12, v12, v16
	v_mul_f32_e32 v12, 0xbfb8aa3b, v12
	v_exp_f32_e32 v12, v12
	v_add_f32_e32 v8, v8, v16
	v_mul_f32_e32 v8, 0xbfb8aa3b, v8
	v_exp_f32_e32 v8, v8
	v_add_f32_e32 v12, 1.0, v12
	v_div_scale_f32 v17, s[36:37], v12, v12, 1.0
	v_rcp_f32_e32 v18, v17
	v_add_f32_e32 v8, 1.0, v8
	v_add_f32_e32 v4, v4, v16
	v_mul_f32_e32 v4, 0xbfb8aa3b, v4
	v_fma_f32 v19, -v17, v18, 1.0
	v_fmac_f32_e32 v18, v19, v18
	v_div_scale_f32 v19, vcc, 1.0, v12, 1.0
	v_mul_f32_e32 v20, v19, v18
	v_fma_f32 v21, -v17, v20, v19
	v_fmac_f32_e32 v20, v21, v18
	v_fma_f32 v17, -v17, v20, v19
	v_div_fmas_f32 v17, v17, v18, v20
	v_div_fixup_f32 v12, v17, v12, 1.0
	global_store_dword v[64:65], v12, off offset:192
	v_add_f32_e32 v12, v13, v16
	v_mul_f32_e32 v12, 0xbfb8aa3b, v12
	v_exp_f32_e32 v12, v12
	v_exp_f32_e32 v4, v4
	v_add_f32_e32 v0, v0, v16
	v_mul_f32_e32 v0, 0xbfb8aa3b, v0
	v_add_f32_e32 v12, 1.0, v12
	v_div_scale_f32 v13, s[36:37], v12, v12, 1.0
	v_rcp_f32_e32 v17, v13
	v_add_f32_e32 v4, 1.0, v4
	v_exp_f32_e32 v0, v0
	v_fma_f32 v18, -v13, v17, 1.0
	v_fmac_f32_e32 v17, v18, v17
	v_div_scale_f32 v18, vcc, 1.0, v12, 1.0
	v_mul_f32_e32 v19, v18, v17
	v_fma_f32 v20, -v13, v19, v18
	v_fmac_f32_e32 v19, v20, v17
	v_fma_f32 v13, -v13, v19, v18
	v_div_fmas_f32 v13, v13, v17, v19
	v_div_fixup_f32 v12, v13, v12, 1.0
	global_store_dword v[64:65], v12, off offset:1216
	v_add_f32_e32 v12, v14, v16
	v_mul_f32_e32 v12, 0xbfb8aa3b, v12
	v_exp_f32_e32 v12, v12
	v_add_f32_e32 v0, 1.0, v0
	v_add_f32_e32 v12, 1.0, v12
	v_div_scale_f32 v13, s[36:37], v12, v12, 1.0
	v_rcp_f32_e32 v14, v13
	s_nop 0
	v_fma_f32 v17, -v13, v14, 1.0
	v_fmac_f32_e32 v14, v17, v14
	v_div_scale_f32 v17, vcc, 1.0, v12, 1.0
	v_mul_f32_e32 v18, v17, v14
	v_fma_f32 v19, -v13, v18, v17
	v_fmac_f32_e32 v18, v19, v14
	v_fma_f32 v13, -v13, v18, v17
	v_div_fmas_f32 v13, v13, v14, v18
	v_div_fixup_f32 v12, v13, v12, 1.0
	global_store_dword v[64:65], v12, off offset:2240
	v_add_f32_e32 v12, v15, v16
	v_mul_f32_e32 v12, 0xbfb8aa3b, v12
	v_exp_f32_e32 v12, v12
	s_nop 0
	v_add_f32_e32 v12, 1.0, v12
	v_div_scale_f32 v13, s[36:37], v12, v12, 1.0
	v_rcp_f32_e32 v14, v13
	s_nop 0
	v_fma_f32 v15, -v13, v14, 1.0
	v_fmac_f32_e32 v14, v15, v14
	v_div_scale_f32 v15, vcc, 1.0, v12, 1.0
	v_mul_f32_e32 v17, v15, v14
	v_fma_f32 v18, -v13, v17, v15
	v_fmac_f32_e32 v17, v18, v14
	v_fma_f32 v13, -v13, v17, v15
	v_div_fmas_f32 v13, v13, v14, v17
	v_div_fixup_f32 v12, v13, v12, 1.0
	global_store_dword v[64:65], v12, off offset:3264
	v_div_scale_f32 v12, s[36:37], v8, v8, 1.0
	v_rcp_f32_e32 v13, v12
	s_nop 0
	v_fma_f32 v14, -v12, v13, 1.0
	v_fmac_f32_e32 v13, v14, v13
	v_div_scale_f32 v14, vcc, 1.0, v8, 1.0
	v_mul_f32_e32 v15, v14, v13
	v_fma_f32 v17, -v12, v15, v14
	v_fmac_f32_e32 v15, v17, v13
	v_fma_f32 v12, -v12, v15, v14
	v_div_fmas_f32 v12, v12, v13, v15
	v_div_fixup_f32 v8, v12, v8, 1.0
	global_store_dword v[60:61], v8, off offset:192
	v_add_f32_e32 v8, v9, v16
	v_mul_f32_e32 v8, 0xbfb8aa3b, v8
	v_exp_f32_e32 v8, v8
	s_nop 0
	v_add_f32_e32 v8, 1.0, v8
	v_div_scale_f32 v9, s[36:37], v8, v8, 1.0
	v_rcp_f32_e32 v12, v9
	s_nop 0
	v_fma_f32 v13, -v9, v12, 1.0
	v_fmac_f32_e32 v12, v13, v12
	v_div_scale_f32 v13, vcc, 1.0, v8, 1.0
	v_mul_f32_e32 v14, v13, v12
	v_fma_f32 v15, -v9, v14, v13
	v_fmac_f32_e32 v14, v15, v12
	v_fma_f32 v9, -v9, v14, v13
	v_div_fmas_f32 v9, v9, v12, v14
	v_div_fixup_f32 v8, v9, v8, 1.0
	global_store_dword v[60:61], v8, off offset:1216
	v_add_f32_e32 v8, v10, v16
	v_mul_f32_e32 v8, 0xbfb8aa3b, v8
	v_exp_f32_e32 v8, v8
	s_nop 0
	v_add_f32_e32 v8, 1.0, v8
	v_div_scale_f32 v9, s[36:37], v8, v8, 1.0
	v_rcp_f32_e32 v10, v9
	s_nop 0
	v_fma_f32 v12, -v9, v10, 1.0
	v_fmac_f32_e32 v10, v12, v10
	v_div_scale_f32 v12, vcc, 1.0, v8, 1.0
	v_mul_f32_e32 v13, v12, v10
	v_fma_f32 v14, -v9, v13, v12
	v_fmac_f32_e32 v13, v14, v10
	v_fma_f32 v9, -v9, v13, v12
	v_div_fmas_f32 v9, v9, v10, v13
	v_div_fixup_f32 v8, v9, v8, 1.0
	global_store_dword v[60:61], v8, off offset:2240
	v_add_f32_e32 v8, v11, v16
	v_mul_f32_e32 v8, 0xbfb8aa3b, v8
	v_exp_f32_e32 v8, v8
	s_nop 0
	v_add_f32_e32 v8, 1.0, v8
	v_div_scale_f32 v9, s[36:37], v8, v8, 1.0
	v_rcp_f32_e32 v10, v9
	s_nop 0
	v_fma_f32 v11, -v9, v10, 1.0
	v_fmac_f32_e32 v10, v11, v10
	v_div_scale_f32 v11, vcc, 1.0, v8, 1.0
	v_mul_f32_e32 v12, v11, v10
	v_fma_f32 v13, -v9, v12, v11
	v_fmac_f32_e32 v12, v13, v10
	v_fma_f32 v9, -v9, v12, v11
	v_div_fmas_f32 v9, v9, v10, v12
	v_div_fixup_f32 v8, v9, v8, 1.0
	global_store_dword v[60:61], v8, off offset:3264
	v_div_scale_f32 v8, s[36:37], v4, v4, 1.0
	v_rcp_f32_e32 v9, v8
	s_nop 0
	v_fma_f32 v10, -v8, v9, 1.0
	v_fmac_f32_e32 v9, v10, v9
	v_div_scale_f32 v10, vcc, 1.0, v4, 1.0
	v_mul_f32_e32 v11, v10, v9
	v_fma_f32 v12, -v8, v11, v10
	v_fmac_f32_e32 v11, v12, v9
	v_fma_f32 v8, -v8, v11, v10
	v_div_fmas_f32 v8, v8, v9, v11
	v_div_fixup_f32 v4, v8, v4, 1.0
	global_store_dword v[56:57], v4, off offset:192
	v_add_f32_e32 v4, v5, v16
	v_mul_f32_e32 v4, 0xbfb8aa3b, v4
	v_exp_f32_e32 v4, v4
	s_nop 0
	v_add_f32_e32 v4, 1.0, v4
	v_div_scale_f32 v5, s[36:37], v4, v4, 1.0
	v_rcp_f32_e32 v8, v5
	s_nop 0
	v_fma_f32 v9, -v5, v8, 1.0
	v_fmac_f32_e32 v8, v9, v8
	v_div_scale_f32 v9, vcc, 1.0, v4, 1.0
	v_mul_f32_e32 v10, v9, v8
	v_fma_f32 v11, -v5, v10, v9
	v_fmac_f32_e32 v10, v11, v8
	v_fma_f32 v5, -v5, v10, v9
	v_div_fmas_f32 v5, v5, v8, v10
	v_div_fixup_f32 v4, v5, v4, 1.0
	global_store_dword v[56:57], v4, off offset:1216
	v_add_f32_e32 v4, v6, v16
	v_mul_f32_e32 v4, 0xbfb8aa3b, v4
	v_exp_f32_e32 v4, v4
	s_nop 0
	v_add_f32_e32 v4, 1.0, v4
	v_div_scale_f32 v5, s[36:37], v4, v4, 1.0
	v_rcp_f32_e32 v6, v5
	s_nop 0
	v_fma_f32 v8, -v5, v6, 1.0
	v_fmac_f32_e32 v6, v8, v6
	v_div_scale_f32 v8, vcc, 1.0, v4, 1.0
	v_mul_f32_e32 v9, v8, v6
	v_fma_f32 v10, -v5, v9, v8
	v_fmac_f32_e32 v9, v10, v6
	v_fma_f32 v5, -v5, v9, v8
	v_div_fmas_f32 v5, v5, v6, v9
	v_div_fixup_f32 v4, v5, v4, 1.0
	global_store_dword v[56:57], v4, off offset:2240
	v_add_f32_e32 v4, v7, v16
	v_mul_f32_e32 v4, 0xbfb8aa3b, v4
	v_exp_f32_e32 v4, v4
	s_nop 0
	v_add_f32_e32 v4, 1.0, v4
	v_div_scale_f32 v5, s[36:37], v4, v4, 1.0
	v_rcp_f32_e32 v6, v5
	s_nop 0
	v_fma_f32 v7, -v5, v6, 1.0
	v_fmac_f32_e32 v6, v7, v6
	v_div_scale_f32 v7, vcc, 1.0, v4, 1.0
	v_mul_f32_e32 v8, v7, v6
	v_fma_f32 v9, -v5, v8, v7
	v_fmac_f32_e32 v8, v9, v6
	v_fma_f32 v5, -v5, v8, v7
	v_div_fmas_f32 v5, v5, v6, v8
	v_div_fixup_f32 v4, v5, v4, 1.0
	global_store_dword v[56:57], v4, off offset:3264
	v_div_scale_f32 v4, s[36:37], v0, v0, 1.0
	v_rcp_f32_e32 v5, v4
	s_nop 0
	v_fma_f32 v6, -v4, v5, 1.0
	v_fmac_f32_e32 v5, v6, v5
	v_div_scale_f32 v6, vcc, 1.0, v0, 1.0
	v_mul_f32_e32 v7, v6, v5
	v_fma_f32 v8, -v4, v7, v6
	v_fmac_f32_e32 v7, v8, v5
	v_fma_f32 v4, -v4, v7, v6
	v_div_fmas_f32 v4, v4, v5, v7
	v_div_fixup_f32 v0, v4, v0, 1.0
	global_store_dword v[52:53], v0, off offset:192
	v_add_f32_e32 v0, v1, v16
	v_mul_f32_e32 v0, 0xbfb8aa3b, v0
	v_exp_f32_e32 v0, v0
	s_nop 0
	v_add_f32_e32 v0, 1.0, v0
	v_div_scale_f32 v1, s[36:37], v0, v0, 1.0
	v_rcp_f32_e32 v4, v1
	s_nop 0
	v_fma_f32 v5, -v1, v4, 1.0
	v_fmac_f32_e32 v4, v5, v4
	v_div_scale_f32 v5, vcc, 1.0, v0, 1.0
	v_mul_f32_e32 v6, v5, v4
	v_fma_f32 v7, -v1, v6, v5
	v_fmac_f32_e32 v6, v7, v4
	v_fma_f32 v1, -v1, v6, v5
	v_div_fmas_f32 v1, v1, v4, v6
	v_div_fixup_f32 v0, v1, v0, 1.0
	global_store_dword v[52:53], v0, off offset:1216
	v_add_f32_e32 v0, v2, v16
	v_mul_f32_e32 v0, 0xbfb8aa3b, v0
	v_exp_f32_e32 v0, v0
	s_nop 0
	v_add_f32_e32 v0, 1.0, v0
	v_div_scale_f32 v1, s[36:37], v0, v0, 1.0
	v_rcp_f32_e32 v2, v1
	s_nop 0
	v_fma_f32 v4, -v1, v2, 1.0
	v_fmac_f32_e32 v2, v4, v2
	v_div_scale_f32 v4, vcc, 1.0, v0, 1.0
	v_mul_f32_e32 v5, v4, v2
	v_fma_f32 v6, -v1, v5, v4
	v_fmac_f32_e32 v5, v6, v2
	v_fma_f32 v1, -v1, v5, v4
	v_div_fmas_f32 v1, v1, v2, v5
	v_div_fixup_f32 v0, v1, v0, 1.0
	global_store_dword v[52:53], v0, off offset:2240
	v_add_f32_e32 v0, v3, v16
	v_mul_f32_e32 v0, 0xbfb8aa3b, v0
	v_exp_f32_e32 v0, v0
	s_nop 0
	v_add_f32_e32 v0, 1.0, v0
	v_div_scale_f32 v1, s[36:37], v0, v0, 1.0
	v_rcp_f32_e32 v2, v1
	s_nop 0
	v_fma_f32 v3, -v1, v2, 1.0
	v_fmac_f32_e32 v2, v3, v2
	v_div_scale_f32 v3, vcc, 1.0, v0, 1.0
	v_mul_f32_e32 v4, v3, v2
	v_fma_f32 v5, -v1, v4, v3
	v_fmac_f32_e32 v4, v5, v2
	v_fma_f32 v1, -v1, v4, v3
	v_div_fmas_f32 v1, v1, v2, v4
	v_div_fixup_f32 v0, v1, v0, 1.0
	global_store_dword v[52:53], v0, off offset:3264

.LBB0_722:
	s_andn2_saveexec_b64 s[36:37], s[8:9]
	s_cbranch_execz .LBB0_724
	v_lshl_add_u32 v0, v48, 5, v194
	v_lshlrev_b32_e32 v121, 7, v48
	v_mov_b32_e32 v6, v170
	v_readlane_b32 s4, v235, 42
	v_and_b32_e32 v120, 0x7fffff80, v0
	v_and_b32_e32 v2, 0x180, v121
	v_readlane_b32 s5, v235, 43
	v_lshrrev_b32_e32 v7, 4, v6
	v_ashrrev_i32_e32 v3, 3, v6
	v_ashrrev_i32_e32 v4, 6, v6
	v_xor_b32_e32 v5, v7, v6
	v_add_u32_e32 v8, v3, v120
	v_mov_b64_e32 v[0:1], s[4:5]
	v_add_u32_e32 v2, v3, v2
	v_mad_i64_i32 v[0:1], s[34:35], v8, s64, v[0:1]
	v_lshlrev_b32_e32 v5, 4, v5
	v_ashrrev_i32_e32 v3, 31, v2
	v_readlane_b32 s4, v234, 27
	v_lshlrev_b32_e32 v8, 10, v4
	v_and_b32_e32 v122, 1, v4
	v_and_b32_e32 v128, 0x70, v5
	v_lshlrev_b64 v[2:3], 8, v[2:3]
	v_readlane_b32 s5, v234, 28
	v_add_u32_e32 v4, 0x4000, v8
	v_readfirstlane_b32 s34, v8
	v_lshl_add_u64 v[0:1], v[0:1], 0, v[128:129]
	v_lshl_add_u64 v[2:3], s[4:5], 0, v[2:3]
	s_mov_b32 m0, s34
	v_readfirstlane_b32 s34, v4
	v_add_u32_e32 v9, 0x1000, v8
	v_lshl_add_u64 v[2:3], v[2:3], 0, v[128:129]
	s_waitcnt lgkmcnt(0)
	s_barrier
	global_load_lds_dwordx4 v[0:1], off
	s_mov_b32 m0, s34
	s_mov_b64 s[6:7], 0x6000
	v_readfirstlane_b32 s34, v9
	v_add_u32_e32 v9, 0x5000, v8
	global_load_lds_dwordx4 v[2:3], off
	v_lshl_add_u64 v[4:5], v[0:1], 0, s[6:7]
	s_mov_b32 m0, s34
	s_mov_b64 s[4:5], 0x2000
	v_readfirstlane_b32 s34, v9
	v_add_u32_e32 v9, 0x2000, v8
	global_load_lds_dwordx4 v[4:5], off
	v_lshl_add_u64 v[4:5], v[2:3], 0, s[4:5]
	s_mov_b32 m0, s34
	s_mov_b64 s[4:5], 0xc000
	v_readfirstlane_b32 s34, v9
	v_add_u32_e32 v9, 0x6000, v8
	global_load_lds_dwordx4 v[4:5], off
	v_lshl_add_u64 v[4:5], v[0:1], 0, s[4:5]
	s_mov_b32 m0, s34
	s_mov_b64 s[4:5], 0x4000
	v_readfirstlane_b32 s34, v9
	global_load_lds_dwordx4 v[4:5], off
	v_lshl_add_u64 v[4:5], v[2:3], 0, s[4:5]
	s_mov_b32 m0, s34
	s_mov_b64 s[34:35], 0x12000
	v_add_u32_e32 v9, 0x3000, v8
	global_load_lds_dwordx4 v[4:5], off
	v_lshl_add_u64 v[4:5], v[0:1], 0, s[34:35]
	v_readfirstlane_b32 s34, v9
	v_add_u32_e32 v9, 0x7000, v8
	s_mov_b32 m0, s34
	v_readfirstlane_b32 s34, v9
	v_add_u32_e32 v9, 0x8000, v8
	global_load_lds_dwordx4 v[4:5], off
	v_lshl_add_u64 v[4:5], v[2:3], 0, s[6:7]
	s_mov_b32 m0, s34
	v_add_u32_e32 v10, 0xc000, v8
	v_readfirstlane_b32 s34, v9
	global_load_lds_dwordx4 v[4:5], off
	v_lshl_add_u64 v[4:5], v[0:1], 0, s[28:29]
	s_mov_b32 m0, s34
	v_readfirstlane_b32 s34, v10
	v_add_u32_e32 v9, 0x9000, v8
	s_waitcnt vmcnt(0)
	s_waitcnt vmcnt(0) lgkmcnt(0)
	s_barrier
	global_load_lds_dwordx4 v[4:5], off
	v_lshl_add_u64 v[4:5], v[2:3], 0, s[28:29]
	s_mov_b32 m0, s34
	s_mov_b64 s[6:7], 0x6080
	v_readfirstlane_b32 s34, v9
	v_add_u32_e32 v9, 0xd000, v8
	global_load_lds_dwordx4 v[4:5], off
	v_lshl_add_u64 v[4:5], v[0:1], 0, s[6:7]
	s_mov_b32 m0, s34
	s_mov_b64 s[4:5], 0x2080
	v_readfirstlane_b32 s34, v9
	v_add_u32_e32 v9, 0xa000, v8
	global_load_lds_dwordx4 v[4:5], off
	v_lshl_add_u64 v[4:5], v[2:3], 0, s[4:5]
	s_mov_b32 m0, s34
	s_mov_b64 s[4:5], 0xc080
	v_readfirstlane_b32 s34, v9
	v_add_u32_e32 v9, 0xe000, v8
	global_load_lds_dwordx4 v[4:5], off
	v_lshl_add_u64 v[4:5], v[0:1], 0, s[4:5]
	s_mov_b32 m0, s34
	s_mov_b64 s[4:5], 0x4080
	v_readfirstlane_b32 s34, v9
	global_load_lds_dwordx4 v[4:5], off
	v_lshl_add_u64 v[4:5], v[2:3], 0, s[4:5]
	s_mov_b32 m0, s34
	s_mov_b64 s[34:35], 0x12080
	global_load_lds_dwordx4 v[4:5], off
	v_add_u32_e32 v4, 0xb000, v8
	v_lshl_add_u64 v[0:1], v[0:1], 0, s[34:35]
	v_readfirstlane_b32 s34, v4
	s_mov_b32 m0, s34
	v_and_b32_e32 v123, 15, v6
	global_load_lds_dwordx4 v[0:1], off
	v_lshl_add_u64 v[0:1], v[2:3], 0, s[6:7]
	v_add_u32_e32 v2, 0xf000, v8
	v_bfe_u32 v68, v6, 1, 3
	v_readfirstlane_b32 s34, v2
	s_mov_b32 m0, s34
	v_ashrrev_i32_e32 v124, 7, v6
	global_load_lds_dwordx4 v[0:1], off
	v_bfe_u32 v125, v6, 4, 2
	v_lshlrev_b32_e32 v6, 7, v123
	v_bitop3_b32 v0, v7, v68, 3 bitop3:0x6c
	v_lshl_or_b32 v69, v124, 13, v6
	v_lshlrev_b32_e32 v0, 4, v0
	v_lshl_or_b32 v70, v122, 13, v6
	v_or_b32_e32 v96, v69, v0
	v_or_b32_e32 v97, v70, v0
	ds_read_b128 v[0:3], v96
	ds_read_b128 v[4:7], v97 offset:16384
	ds_read_b128 v[8:11], v96 offset:2048
	ds_read_b128 v[12:15], v97 offset:18432
	ds_read_b128 v[16:19], v96 offset:4096
	ds_read_b128 v[20:23], v97 offset:20480
	ds_read_b128 v[24:27], v96 offset:6144
	ds_read_b128 v[28:31], v97 offset:22528
	s_setprio 1
	s_waitcnt lgkmcnt(0)
	v_mfma_f32_16x16x32_bf16 v[32:35], v[0:3], v[4:7], 0
	v_mfma_f32_16x16x32_bf16 v[36:39], v[0:3], v[12:15], 0
	v_mfma_f32_16x16x32_bf16 v[40:43], v[0:3], v[20:23], 0
	v_mfma_f32_16x16x32_bf16 v[0:3], v[0:3], v[28:31], 0
	v_mfma_f32_16x16x32_bf16 v[44:47], v[8:11], v[4:7], 0
	v_mfma_f32_16x16x32_bf16 v[48:51], v[8:11], v[12:15], 0
	v_mfma_f32_16x16x32_bf16 v[52:55], v[8:11], v[20:23], 0
	v_mfma_f32_16x16x32_bf16 v[8:11], v[8:11], v[28:31], 0
	v_mfma_f32_16x16x32_bf16 v[56:59], v[16:19], v[4:7], 0
	v_mfma_f32_16x16x32_bf16 v[60:63], v[16:19], v[12:15], 0
	v_mfma_f32_16x16x32_bf16 v[64:67], v[16:19], v[20:23], 0
	v_mfma_f32_16x16x32_bf16 v[16:19], v[16:19], v[28:31], 0
	v_mfma_f32_16x16x32_bf16 v[4:7], v[24:27], v[4:7], 0
	v_mfma_f32_16x16x32_bf16 v[12:15], v[24:27], v[12:15], 0
	v_mfma_f32_16x16x32_bf16 v[20:23], v[24:27], v[20:23], 0
	v_mfma_f32_16x16x32_bf16 v[24:27], v[24:27], v[28:31], 0
	s_setprio 0
	v_bitop3_b32 v28, v125, v68, 4 bitop3:0x36
	v_lshlrev_b32_e32 v28, 4, v28
	v_or_b32_e32 v108, v69, v28
	v_or_b32_e32 v116, v70, v28
	ds_read_b128 v[28:31], v108
	ds_read_b128 v[68:71], v108 offset:2048
	ds_read_b128 v[72:75], v116 offset:16384
	ds_read_b128 v[76:79], v116 offset:18432
	ds_read_b128 v[80:83], v108 offset:4096
	ds_read_b128 v[84:87], v108 offset:6144
	ds_read_b128 v[88:91], v116 offset:20480
	ds_read_b128 v[92:95], v116 offset:22528
	s_setprio 1
	s_waitcnt lgkmcnt(5)
	v_mfma_f32_16x16x32_bf16 v[32:35], v[28:31], v[72:75], v[32:35]
	s_waitcnt lgkmcnt(4)
	v_mfma_f32_16x16x32_bf16 v[36:39], v[28:31], v[76:79], v[36:39]
	s_waitcnt lgkmcnt(1)
	v_mfma_f32_16x16x32_bf16 v[40:43], v[28:31], v[88:91], v[40:43]
	s_waitcnt lgkmcnt(0)
	v_mfma_f32_16x16x32_bf16 v[0:3], v[28:31], v[92:95], v[0:3]
	v_mfma_f32_16x16x32_bf16 v[28:31], v[68:71], v[72:75], v[44:47]
	v_mfma_f32_16x16x32_bf16 v[44:47], v[68:71], v[76:79], v[48:51]
	v_mfma_f32_16x16x32_bf16 v[48:51], v[68:71], v[88:91], v[52:55]
	v_mfma_f32_16x16x32_bf16 v[8:11], v[68:71], v[92:95], v[8:11]
	v_mfma_f32_16x16x32_bf16 v[52:55], v[80:83], v[72:75], v[56:59]
	v_mfma_f32_16x16x32_bf16 v[56:59], v[80:83], v[76:79], v[60:63]
	v_mfma_f32_16x16x32_bf16 v[60:63], v[80:83], v[88:91], v[64:67]
	v_mfma_f32_16x16x32_bf16 v[16:19], v[80:83], v[92:95], v[16:19]
	v_mfma_f32_16x16x32_bf16 v[4:7], v[84:87], v[72:75], v[4:7]
	v_mfma_f32_16x16x32_bf16 v[12:15], v[84:87], v[76:79], v[12:15]
	v_mfma_f32_16x16x32_bf16 v[20:23], v[84:87], v[88:91], v[20:23]
	v_mfma_f32_16x16x32_bf16 v[24:27], v[84:87], v[92:95], v[24:27]
	s_setprio 0
	s_waitcnt vmcnt(0)
	s_barrier
	ds_read_b128 v[64:67], v97 offset:55296
	ds_read_b128 v[68:71], v97 offset:53248
	ds_read_b128 v[72:75], v96 offset:38912
	ds_read_b128 v[76:79], v96 offset:36864
	ds_read_b128 v[80:83], v97 offset:51200
	ds_read_b128 v[84:87], v97 offset:49152
	ds_read_b128 v[88:91], v96 offset:34816
	ds_read_b128 v[92:95], v96 offset:32768
	s_setprio 1
	s_waitcnt lgkmcnt(0)
	v_mfma_f32_16x16x32_bf16 v[32:35], v[92:95], v[84:87], v[32:35]
	v_mfma_f32_16x16x32_bf16 v[36:39], v[92:95], v[80:83], v[36:39]
	v_mfma_f32_16x16x32_bf16 v[40:43], v[92:95], v[68:71], v[40:43]
	v_mfma_f32_16x16x32_bf16 v[0:3], v[92:95], v[64:67], v[0:3]
	v_mfma_f32_16x16x32_bf16 v[92:95], v[88:91], v[84:87], v[28:31]
	v_mfma_f32_16x16x32_bf16 v[96:99], v[88:91], v[80:83], v[44:47]
	v_mfma_f32_16x16x32_bf16 v[48:51], v[88:91], v[68:71], v[48:51]
	v_mfma_f32_16x16x32_bf16 v[8:11], v[88:91], v[64:67], v[8:11]
	v_mfma_f32_16x16x32_bf16 v[52:55], v[76:79], v[84:87], v[52:55]
	v_mfma_f32_16x16x32_bf16 v[88:91], v[76:79], v[80:83], v[56:59]
	v_mfma_f32_16x16x32_bf16 v[100:103], v[76:79], v[68:71], v[60:63]
	v_mfma_f32_16x16x32_bf16 v[16:19], v[76:79], v[64:67], v[16:19]
	v_mfma_f32_16x16x32_bf16 v[76:79], v[72:75], v[84:87], v[4:7]
	v_mfma_f32_16x16x32_bf16 v[80:83], v[72:75], v[80:83], v[12:15]
	v_mfma_f32_16x16x32_bf16 v[68:71], v[72:75], v[68:71], v[20:23]
	v_mfma_f32_16x16x32_bf16 v[64:67], v[72:75], v[64:67], v[24:27]
	s_setprio 0
	ds_read_b128 v[4:7], v108 offset:32768
	ds_read_b128 v[20:23], v108 offset:34816
	ds_read_b128 v[72:75], v116 offset:49152
	ds_read_b128 v[84:87], v116 offset:51200
	ds_read_b128 v[104:107], v108 offset:36864
	ds_read_b128 v[108:111], v108 offset:38912
	ds_read_b128 v[112:115], v116 offset:53248
	ds_read_b128 v[116:119], v116 offset:55296
	s_setprio 1
	s_waitcnt lgkmcnt(5)
	v_mfma_f32_16x16x32_bf16 v[60:63], v[4:7], v[72:75], v[32:35]
	s_waitcnt lgkmcnt(4)
	v_mfma_f32_16x16x32_bf16 v[44:47], v[4:7], v[84:87], v[36:39]
	s_waitcnt lgkmcnt(1)
	v_mfma_f32_16x16x32_bf16 v[28:31], v[4:7], v[112:115], v[40:43]
	s_waitcnt lgkmcnt(0)
	v_mfma_f32_16x16x32_bf16 v[12:15], v[4:7], v[116:119], v[0:3]
	v_mfma_f32_16x16x32_bf16 v[56:59], v[20:23], v[72:75], v[92:95]
	v_mfma_f32_16x16x32_bf16 v[40:43], v[20:23], v[84:87], v[96:99]
	v_mfma_f32_16x16x32_bf16 v[24:27], v[20:23], v[112:115], v[48:51]
	v_mfma_f32_16x16x32_bf16 v[8:11], v[20:23], v[116:119], v[8:11]
	v_mfma_f32_16x16x32_bf16 v[52:55], v[104:107], v[72:75], v[52:55]
	v_mfma_f32_16x16x32_bf16 v[36:39], v[104:107], v[84:87], v[88:91]
	v_mfma_f32_16x16x32_bf16 v[20:23], v[104:107], v[112:115], v[100:103]
	v_mfma_f32_16x16x32_bf16 v[4:7], v[104:107], v[116:119], v[16:19]
	v_mfma_f32_16x16x32_bf16 v[48:51], v[108:111], v[72:75], v[76:79]
	v_mfma_f32_16x16x32_bf16 v[32:35], v[108:111], v[84:87], v[80:83]
	v_mfma_f32_16x16x32_bf16 v[16:19], v[108:111], v[112:115], v[68:71]
	v_mfma_f32_16x16x32_bf16 v[0:3], v[108:111], v[116:119], v[64:67]
	s_setprio 0
	s_nop 1
	v_lshlrev_b32_e32 v66, 6, v122
	v_and_b32_e32 v68, 0x80, v121
	v_or3_b32 v66, v66, v68, v123
	v_and_b32_e32 v68, 0x100, v121
	v_or_b32_e32 v68, s2, v68
	v_or_b32_e32 v70, v68, v66
	v_readlane_b32 s4, v237, 35
	v_ashrrev_i32_e32 v71, 31, v70
	v_readlane_b32 s6, v237, 37
	v_readlane_b32 s7, v237, 38
	s_waitcnt vmcnt(0)
	s_barrier
	s_nop 0
	v_lshl_add_u64 v[70:71], v[70:71], 2, s[6:7]
	global_load_dword v69, v[70:71], off
	v_lshl_add_u32 v64, v124, 6, v120
	v_lshl_or_b32 v64, v125, 2, v64
	v_bfe_u32 v67, v121, 8, 1
	v_readlane_b32 s5, v237, 36
	v_ashrrev_i32_e32 v65, 31, v64
	v_mul_u32_u24_e32 v128, 0x3000, v67
	v_readlane_b32 s4, v234, 29
	v_lshl_add_u64 v[64:65], v[64:65], 0, v[128:129]
	v_lshlrev_b32_e32 v128, 2, v66
	v_readlane_b32 s5, v234, 30
	v_readlane_b32 s9, v237, 40
	s_mov_b32 s9, 0x3f317217
	v_lshl_add_u64 v[70:71], s[4:5], 0, v[128:129]
	s_mov_b32 s5, 0xbfb8aa3b
	v_readlane_b32 s8, v237, 39
	s_mov_b32 s8, 0x7f800000
	v_lshlrev_b64 v[64:65], 10, v[64:65]
	v_lshl_add_u64 v[64:65], v[70:71], 0, v[64:65]
	s_movk_i32 s4, 0x4000
	v_mov_b32_e32 v67, v129
	v_readlane_b32 s10, v237, 41
	v_readlane_b32 s11, v237, 42
	v_readlane_b32 s12, v237, 43
	v_readlane_b32 s13, v237, 44
	v_readlane_b32 s14, v237, 45
	v_readlane_b32 s15, v237, 46
	v_readlane_b32 s16, v237, 47
	v_readlane_b32 s17, v237, 48
	v_readlane_b32 s18, v237, 49
	v_readlane_b32 s19, v237, 50
	s_waitcnt vmcnt(0)
	v_add_f32_e32 v60, v60, v69
	v_max_f32_e64 v72, -v60, 0
	v_mul_f32_e64 v60, |v60|, s5
	v_exp_f32_e32 v60, v60
	v_add_f32_e32 v56, v56, v69
	v_add_f32_e32 v52, v52, v69
	v_add_f32_e32 v48, v48, v69
	v_add_f32_e32 v60, 1.0, v60
	v_cmp_gt_f32_e32 vcc, s85, v60
	s_nop 1
	v_cndmask_b32_e64 v73, 0, 32, vcc
	v_ldexp_f32 v60, v60, v73
	v_log_f32_e32 v60, v60
	s_nop 0
	v_mul_f32_e32 v73, 0x3f317217, v60
	v_fma_f32 v73, v60, s9, -v73
	v_fmac_f32_e32 v73, 0x3377d1cf, v60
	v_fmac_f32_e32 v73, 0x3f317217, v60
	v_cmp_lt_f32_e64 s[34:35], |v60|, s8
	s_nop 1
	v_cndmask_b32_e64 v60, v60, v73, s[34:35]
	v_cndmask_b32_e32 v73, 0, v191, vcc
	v_sub_f32_e32 v60, v60, v73
	v_add_f32_e32 v60, v72, v60
	v_sub_f32_e32 v60, -0.5, v60
	v_mul_f32_e32 v60, 0x3fb8aa3b, v60
	v_exp_f32_e32 v60, v60
	s_nop 0
	v_mul_f32_e32 v60, 0xbfb8aa3b, v60
	v_exp_f32_e32 v60, v60
	global_store_dword v[64:65], v60, off
	v_add_f32_e32 v60, v61, v69
	v_max_f32_e64 v61, -v60, 0
	v_mul_f32_e64 v60, |v60|, s5
	v_exp_f32_e32 v60, v60
	s_nop 0
	v_add_f32_e32 v60, 1.0, v60
	v_cmp_gt_f32_e32 vcc, s85, v60
	s_nop 1
	v_cndmask_b32_e64 v70, 0, 32, vcc
	v_ldexp_f32 v60, v60, v70
	v_log_f32_e32 v60, v60
	s_nop 0
	v_mul_f32_e32 v70, 0x3f317217, v60
	v_fma_f32 v70, v60, s9, -v70
	v_fmac_f32_e32 v70, 0x3377d1cf, v60
	v_fmac_f32_e32 v70, 0x3f317217, v60
	v_cmp_lt_f32_e64 s[34:35], |v60|, s8
	s_nop 1
	v_cndmask_b32_e64 v60, v60, v70, s[34:35]
	v_cndmask_b32_e32 v70, 0, v191, vcc
	v_sub_f32_e32 v60, v60, v70
	v_add_f32_e32 v60, v61, v60
	v_sub_f32_e32 v60, -0.5, v60
	v_mul_f32_e32 v60, 0x3fb8aa3b, v60
	v_exp_f32_e32 v60, v60
	s_nop 0
	v_mul_f32_e32 v60, 0xbfb8aa3b, v60
	v_exp_f32_e32 v60, v60
	global_store_dword v[64:65], v60, off offset:1024
	v_add_f32_e32 v60, v62, v69
	v_max_f32_e64 v61, -v60, 0
	v_mul_f32_e64 v60, |v60|, s5
	v_exp_f32_e32 v60, v60
	s_nop 0
	v_add_f32_e32 v60, 1.0, v60
	v_cmp_gt_f32_e32 vcc, s85, v60
	s_nop 1
	v_cndmask_b32_e64 v62, 0, 32, vcc
	v_ldexp_f32 v60, v60, v62
	v_log_f32_e32 v60, v60
	s_nop 0
	v_mul_f32_e32 v62, 0x3f317217, v60
	v_fma_f32 v62, v60, s9, -v62
	v_fmac_f32_e32 v62, 0x3377d1cf, v60
	v_fmac_f32_e32 v62, 0x3f317217, v60
	v_cmp_lt_f32_e64 s[34:35], |v60|, s8
	s_nop 1
	v_cndmask_b32_e64 v60, v60, v62, s[34:35]
	v_cndmask_b32_e32 v62, 0, v191, vcc
	v_sub_f32_e32 v60, v60, v62
	v_add_f32_e32 v60, v61, v60
	v_sub_f32_e32 v60, -0.5, v60
	v_mul_f32_e32 v60, 0x3fb8aa3b, v60
	v_exp_f32_e32 v60, v60
	s_nop 0
	v_mul_f32_e32 v60, 0xbfb8aa3b, v60
	v_exp_f32_e32 v60, v60
	global_store_dword v[64:65], v60, off offset:2048
	v_add_f32_e32 v60, v63, v69
	v_max_f32_e64 v61, -v60, 0
	v_mul_f32_e64 v60, |v60|, s5
	v_exp_f32_e32 v60, v60
	s_nop 0
	v_add_f32_e32 v60, 1.0, v60
	v_cmp_gt_f32_e32 vcc, s85, v60
	s_nop 1
	v_cndmask_b32_e64 v62, 0, 32, vcc
	v_ldexp_f32 v60, v60, v62
	v_log_f32_e32 v60, v60
	s_nop 0
	v_mul_f32_e32 v62, 0x3f317217, v60
	v_fma_f32 v62, v60, s9, -v62
	v_fmac_f32_e32 v62, 0x3377d1cf, v60
	v_fmac_f32_e32 v62, 0x3f317217, v60
	v_cmp_lt_f32_e64 s[34:35], |v60|, s8
	s_nop 1
	v_cndmask_b32_e64 v60, v60, v62, s[34:35]
	v_cndmask_b32_e32 v62, 0, v191, vcc
	v_sub_f32_e32 v60, v60, v62
	v_add_f32_e32 v60, v61, v60
	v_sub_f32_e32 v60, -0.5, v60
	v_mul_f32_e32 v60, 0x3fb8aa3b, v60
	v_exp_f32_e32 v60, v60
	s_nop 0
	v_mul_f32_e32 v60, 0xbfb8aa3b, v60
	v_exp_f32_e32 v60, v60
	global_store_dword v[64:65], v60, off offset:3072
	v_max_f32_e64 v60, -v56, 0
	v_mul_f32_e64 v56, |v56|, s5
	v_exp_f32_e32 v56, v56
	s_nop 0
	v_add_f32_e32 v56, 1.0, v56
	v_cmp_gt_f32_e32 vcc, s85, v56
	s_nop 1
	v_cndmask_b32_e64 v61, 0, 32, vcc
	v_ldexp_f32 v56, v56, v61
	v_log_f32_e32 v56, v56
	s_nop 0
	v_mul_f32_e32 v61, 0x3f317217, v56
	v_fma_f32 v61, v56, s9, -v61
	v_fmac_f32_e32 v61, 0x3377d1cf, v56
	v_fmac_f32_e32 v61, 0x3f317217, v56
	v_cmp_lt_f32_e64 s[34:35], |v56|, s8
	s_nop 1
	v_cndmask_b32_e64 v56, v56, v61, s[34:35]
	v_cndmask_b32_e32 v61, 0, v191, vcc
	v_sub_f32_e32 v56, v56, v61
	v_add_f32_e32 v56, v60, v56
	v_sub_f32_e32 v56, -0.5, v56
	v_mul_f32_e32 v56, 0x3fb8aa3b, v56
	v_exp_f32_e32 v56, v56
	v_add_co_u32_e32 v60, vcc, s4, v64
	s_mov_b32 s4, 0x8000
	v_mul_f32_e32 v56, 0xbfb8aa3b, v56
	v_exp_f32_e32 v56, v56
	v_addc_co_u32_e32 v61, vcc, 0, v65, vcc
	global_store_dword v[60:61], v56, off
	v_add_f32_e32 v56, v57, v69
	v_max_f32_e64 v57, -v56, 0
	v_mul_f32_e64 v56, |v56|, s5
	v_exp_f32_e32 v56, v56
	s_nop 0
	v_add_f32_e32 v56, 1.0, v56
	v_cmp_gt_f32_e32 vcc, s85, v56
	s_nop 1
	v_cndmask_b32_e64 v62, 0, 32, vcc
	v_ldexp_f32 v56, v56, v62
	v_log_f32_e32 v56, v56
	s_nop 0
	v_mul_f32_e32 v62, 0x3f317217, v56
	v_fma_f32 v62, v56, s9, -v62
	v_fmac_f32_e32 v62, 0x3377d1cf, v56
	v_fmac_f32_e32 v62, 0x3f317217, v56
	v_cmp_lt_f32_e64 s[34:35], |v56|, s8
	s_nop 1
	v_cndmask_b32_e64 v56, v56, v62, s[34:35]
	v_cndmask_b32_e32 v62, 0, v191, vcc
	v_sub_f32_e32 v56, v56, v62
	v_add_f32_e32 v56, v57, v56
	v_sub_f32_e32 v56, -0.5, v56
	v_mul_f32_e32 v56, 0x3fb8aa3b, v56
	v_exp_f32_e32 v56, v56
	s_nop 0
	v_mul_f32_e32 v56, 0xbfb8aa3b, v56
	v_exp_f32_e32 v56, v56
	global_store_dword v[60:61], v56, off offset:1024
	v_add_f32_e32 v56, v58, v69
	v_max_f32_e64 v57, -v56, 0
	v_mul_f32_e64 v56, |v56|, s5
	v_exp_f32_e32 v56, v56
	s_nop 0
	v_add_f32_e32 v56, 1.0, v56
	v_cmp_gt_f32_e32 vcc, s85, v56
	s_nop 1
	v_cndmask_b32_e64 v58, 0, 32, vcc
	v_ldexp_f32 v56, v56, v58
	v_log_f32_e32 v56, v56
	s_nop 0
	v_mul_f32_e32 v58, 0x3f317217, v56
	v_fma_f32 v58, v56, s9, -v58
	v_fmac_f32_e32 v58, 0x3377d1cf, v56
	v_fmac_f32_e32 v58, 0x3f317217, v56
	v_cmp_lt_f32_e64 s[34:35], |v56|, s8
	s_nop 1
	v_cndmask_b32_e64 v56, v56, v58, s[34:35]
	v_cndmask_b32_e32 v58, 0, v191, vcc
	v_sub_f32_e32 v56, v56, v58
	v_add_f32_e32 v56, v57, v56
	v_sub_f32_e32 v56, -0.5, v56
	v_mul_f32_e32 v56, 0x3fb8aa3b, v56
	v_exp_f32_e32 v56, v56
	s_nop 0
	v_mul_f32_e32 v56, 0xbfb8aa3b, v56
	v_exp_f32_e32 v56, v56
	global_store_dword v[60:61], v56, off offset:2048
	v_add_f32_e32 v56, v59, v69
	v_max_f32_e64 v57, -v56, 0
	v_mul_f32_e64 v56, |v56|, s5
	v_exp_f32_e32 v56, v56
	s_nop 0
	v_add_f32_e32 v56, 1.0, v56
	v_cmp_gt_f32_e32 vcc, s85, v56
	s_nop 1
	v_cndmask_b32_e64 v58, 0, 32, vcc
	v_ldexp_f32 v56, v56, v58
	v_log_f32_e32 v56, v56
	s_nop 0
	v_mul_f32_e32 v58, 0x3f317217, v56
	v_fma_f32 v58, v56, s9, -v58
	v_fmac_f32_e32 v58, 0x3377d1cf, v56
	v_fmac_f32_e32 v58, 0x3f317217, v56
	v_cmp_lt_f32_e64 s[34:35], |v56|, s8
	s_nop 1
	v_cndmask_b32_e64 v56, v56, v58, s[34:35]
	v_cndmask_b32_e32 v58, 0, v191, vcc
	v_sub_f32_e32 v56, v56, v58
	v_add_f32_e32 v56, v57, v56
	v_sub_f32_e32 v56, -0.5, v56
	v_mul_f32_e32 v56, 0x3fb8aa3b, v56
	v_exp_f32_e32 v56, v56
	s_nop 0
	v_mul_f32_e32 v56, 0xbfb8aa3b, v56
	v_exp_f32_e32 v56, v56
	global_store_dword v[60:61], v56, off offset:3072
	v_max_f32_e64 v56, -v52, 0
	v_mul_f32_e64 v52, |v52|, s5
	v_exp_f32_e32 v52, v52
	s_nop 0
	v_add_f32_e32 v52, 1.0, v52
	v_cmp_gt_f32_e32 vcc, s85, v52
	s_nop 1
	v_cndmask_b32_e64 v57, 0, 32, vcc
	v_ldexp_f32 v52, v52, v57
	v_log_f32_e32 v52, v52
	s_nop 0
	v_mul_f32_e32 v57, 0x3f317217, v52
	v_fma_f32 v57, v52, s9, -v57
	v_fmac_f32_e32 v57, 0x3377d1cf, v52
	v_fmac_f32_e32 v57, 0x3f317217, v52
	v_cmp_lt_f32_e64 s[34:35], |v52|, s8
	s_nop 1
	v_cndmask_b32_e64 v52, v52, v57, s[34:35]
	v_cndmask_b32_e32 v57, 0, v191, vcc
	v_sub_f32_e32 v52, v52, v57
	v_add_f32_e32 v52, v56, v52
	v_sub_f32_e32 v52, -0.5, v52
	v_mul_f32_e32 v52, 0x3fb8aa3b, v52
	v_exp_f32_e32 v52, v52
	v_add_co_u32_e32 v56, vcc, s4, v64
	s_mov_b32 s4, 0xc000
	v_mul_f32_e32 v52, 0xbfb8aa3b, v52
	v_exp_f32_e32 v52, v52
	v_addc_co_u32_e32 v57, vcc, 0, v65, vcc
	global_store_dword v[56:57], v52, off
	v_add_f32_e32 v52, v53, v69
	v_max_f32_e64 v53, -v52, 0
	v_mul_f32_e64 v52, |v52|, s5
	v_exp_f32_e32 v52, v52
	s_nop 0
	v_add_f32_e32 v52, 1.0, v52
	v_cmp_gt_f32_e32 vcc, s85, v52
	s_nop 1
	v_cndmask_b32_e64 v58, 0, 32, vcc
	v_ldexp_f32 v52, v52, v58
	v_log_f32_e32 v52, v52
	s_nop 0
	v_mul_f32_e32 v58, 0x3f317217, v52
	v_fma_f32 v58, v52, s9, -v58
	v_fmac_f32_e32 v58, 0x3377d1cf, v52
	v_fmac_f32_e32 v58, 0x3f317217, v52
	v_cmp_lt_f32_e64 s[34:35], |v52|, s8
	s_nop 1
	v_cndmask_b32_e64 v52, v52, v58, s[34:35]
	v_cndmask_b32_e32 v58, 0, v191, vcc
	v_sub_f32_e32 v52, v52, v58
	v_add_f32_e32 v52, v53, v52
	v_sub_f32_e32 v52, -0.5, v52
	v_mul_f32_e32 v52, 0x3fb8aa3b, v52
	v_exp_f32_e32 v52, v52
	s_nop 0
	v_mul_f32_e32 v52, 0xbfb8aa3b, v52
	v_exp_f32_e32 v52, v52
	global_store_dword v[56:57], v52, off offset:1024
	v_add_f32_e32 v52, v54, v69
	v_max_f32_e64 v53, -v52, 0
	v_mul_f32_e64 v52, |v52|, s5
	v_exp_f32_e32 v52, v52
	s_nop 0
	v_add_f32_e32 v52, 1.0, v52
	v_cmp_gt_f32_e32 vcc, s85, v52
	s_nop 1
	v_cndmask_b32_e64 v54, 0, 32, vcc
	v_ldexp_f32 v52, v52, v54
	v_log_f32_e32 v52, v52
	s_nop 0
	v_mul_f32_e32 v54, 0x3f317217, v52
	v_fma_f32 v54, v52, s9, -v54
	v_fmac_f32_e32 v54, 0x3377d1cf, v52
	v_fmac_f32_e32 v54, 0x3f317217, v52
	v_cmp_lt_f32_e64 s[34:35], |v52|, s8
	s_nop 1
	v_cndmask_b32_e64 v52, v52, v54, s[34:35]
	v_cndmask_b32_e32 v54, 0, v191, vcc
	v_sub_f32_e32 v52, v52, v54
	v_add_f32_e32 v52, v53, v52
	v_sub_f32_e32 v52, -0.5, v52
	v_mul_f32_e32 v52, 0x3fb8aa3b, v52
	v_exp_f32_e32 v52, v52
	s_nop 0
	v_mul_f32_e32 v52, 0xbfb8aa3b, v52
	v_exp_f32_e32 v52, v52
	global_store_dword v[56:57], v52, off offset:2048
	v_add_f32_e32 v52, v55, v69
	v_max_f32_e64 v53, -v52, 0
	v_mul_f32_e64 v52, |v52|, s5
	v_exp_f32_e32 v52, v52
	s_nop 0
	v_add_f32_e32 v52, 1.0, v52
	v_cmp_gt_f32_e32 vcc, s85, v52
	s_nop 1
	v_cndmask_b32_e64 v54, 0, 32, vcc
	v_ldexp_f32 v52, v52, v54
	v_log_f32_e32 v52, v52
	s_nop 0
	v_mul_f32_e32 v54, 0x3f317217, v52
	v_fma_f32 v54, v52, s9, -v54
	v_fmac_f32_e32 v54, 0x3377d1cf, v52
	v_fmac_f32_e32 v54, 0x3f317217, v52
	v_cmp_lt_f32_e64 s[34:35], |v52|, s8
	s_nop 1
	v_cndmask_b32_e64 v52, v52, v54, s[34:35]
	v_cndmask_b32_e32 v54, 0, v191, vcc
	v_sub_f32_e32 v52, v52, v54
	v_add_f32_e32 v52, v53, v52
	v_sub_f32_e32 v52, -0.5, v52
	v_mul_f32_e32 v52, 0x3fb8aa3b, v52
	v_exp_f32_e32 v52, v52
	s_nop 0
	v_mul_f32_e32 v52, 0xbfb8aa3b, v52
	v_exp_f32_e32 v52, v52
	global_store_dword v[56:57], v52, off offset:3072
	v_max_f32_e64 v52, -v48, 0
	v_mul_f32_e64 v48, |v48|, s5
	v_exp_f32_e32 v48, v48
	s_nop 0
	v_add_f32_e32 v48, 1.0, v48
	v_cmp_gt_f32_e32 vcc, s85, v48
	s_nop 1
	v_cndmask_b32_e64 v53, 0, 32, vcc
	v_ldexp_f32 v48, v48, v53
	v_log_f32_e32 v48, v48
	s_nop 0
	v_mul_f32_e32 v53, 0x3f317217, v48
	v_fma_f32 v53, v48, s9, -v53
	v_fmac_f32_e32 v53, 0x3377d1cf, v48
	v_fmac_f32_e32 v53, 0x3f317217, v48
	v_cmp_lt_f32_e64 s[34:35], |v48|, s8
	s_nop 1
	v_cndmask_b32_e64 v48, v48, v53, s[34:35]
	v_cndmask_b32_e32 v53, 0, v191, vcc
	v_sub_f32_e32 v48, v48, v53
	v_add_f32_e32 v48, v52, v48
	v_sub_f32_e32 v48, -0.5, v48
	v_mul_f32_e32 v48, 0x3fb8aa3b, v48
	v_exp_f32_e32 v48, v48
	v_add_co_u32_e32 v52, vcc, s4, v64
	v_mul_f32_e32 v48, 0xbfb8aa3b, v48
	v_exp_f32_e32 v48, v48
	v_addc_co_u32_e32 v53, vcc, 0, v65, vcc
	global_store_dword v[52:53], v48, off
	v_add_f32_e32 v48, v49, v69
	v_max_f32_e64 v49, -v48, 0
	v_mul_f32_e64 v48, |v48|, s5
	v_exp_f32_e32 v48, v48
	s_nop 0
	v_add_f32_e32 v48, 1.0, v48
	v_cmp_gt_f32_e32 vcc, s85, v48
	s_nop 1
	v_cndmask_b32_e64 v54, 0, 32, vcc
	v_ldexp_f32 v48, v48, v54
	v_log_f32_e32 v48, v48
	s_nop 0
	v_mul_f32_e32 v54, 0x3f317217, v48
	v_fma_f32 v54, v48, s9, -v54
	v_fmac_f32_e32 v54, 0x3377d1cf, v48
	v_fmac_f32_e32 v54, 0x3f317217, v48
	v_cmp_lt_f32_e64 s[34:35], |v48|, s8
	s_nop 1
	v_cndmask_b32_e64 v48, v48, v54, s[34:35]
	v_cndmask_b32_e32 v54, 0, v191, vcc
	v_sub_f32_e32 v48, v48, v54
	v_add_f32_e32 v48, v49, v48
	v_sub_f32_e32 v48, -0.5, v48
	v_mul_f32_e32 v48, 0x3fb8aa3b, v48
	v_exp_f32_e32 v48, v48
	s_nop 0
	v_mul_f32_e32 v48, 0xbfb8aa3b, v48
	v_exp_f32_e32 v48, v48
	global_store_dword v[52:53], v48, off offset:1024
	v_add_f32_e32 v48, v50, v69
	v_max_f32_e64 v49, -v48, 0
	v_mul_f32_e64 v48, |v48|, s5
	v_exp_f32_e32 v48, v48
	s_nop 0
	v_add_f32_e32 v48, 1.0, v48
	v_cmp_gt_f32_e32 vcc, s85, v48
	s_nop 1
	v_cndmask_b32_e64 v50, 0, 32, vcc
	v_ldexp_f32 v48, v48, v50
	v_log_f32_e32 v48, v48
	s_nop 0
	v_mul_f32_e32 v50, 0x3f317217, v48
	v_fma_f32 v50, v48, s9, -v50
	v_fmac_f32_e32 v50, 0x3377d1cf, v48
	v_fmac_f32_e32 v50, 0x3f317217, v48
	v_cmp_lt_f32_e64 s[34:35], |v48|, s8
	s_nop 1
	v_cndmask_b32_e64 v48, v48, v50, s[34:35]
	v_cndmask_b32_e32 v50, 0, v191, vcc
	v_sub_f32_e32 v48, v48, v50
	v_add_f32_e32 v48, v49, v48
	v_sub_f32_e32 v48, -0.5, v48
	v_mul_f32_e32 v48, 0x3fb8aa3b, v48
	v_exp_f32_e32 v48, v48
	s_nop 0
	v_mul_f32_e32 v48, 0xbfb8aa3b, v48
	v_exp_f32_e32 v48, v48
	global_store_dword v[52:53], v48, off offset:2048
	v_add_f32_e32 v48, v51, v69
	v_max_f32_e64 v49, -v48, 0
	v_mul_f32_e64 v48, |v48|, s5
	v_exp_f32_e32 v48, v48
	v_ashrrev_i32_e32 v69, 31, v68
	v_add_f32_e32 v48, 1.0, v48
	v_cmp_gt_f32_e32 vcc, s85, v48
	s_nop 1
	v_cndmask_b32_e64 v50, 0, 32, vcc
	v_ldexp_f32 v48, v48, v50
	v_log_f32_e32 v48, v48
	s_nop 0
	v_mul_f32_e32 v50, 0x3f317217, v48
	v_fma_f32 v50, v48, s9, -v50
	v_fmac_f32_e32 v50, 0x3377d1cf, v48
	v_fmac_f32_e32 v50, 0x3f317217, v48
	v_cmp_lt_f32_e64 s[34:35], |v48|, s8
	s_nop 1
	v_cndmask_b32_e64 v48, v48, v50, s[34:35]
	v_cndmask_b32_e32 v50, 0, v191, vcc
	v_sub_f32_e32 v48, v48, v50
	v_add_f32_e32 v48, v49, v48
	v_sub_f32_e32 v48, -0.5, v48
	v_mul_f32_e32 v48, 0x3fb8aa3b, v48
	v_exp_f32_e32 v48, v48
	s_nop 0
	v_mul_f32_e32 v48, 0xbfb8aa3b, v48
	v_exp_f32_e32 v48, v48
	global_store_dword v[52:53], v48, off offset:3072
	v_lshl_add_u64 v[48:49], v[68:69], 0, v[66:67]
	v_lshl_add_u64 v[48:49], v[48:49], 2, s[6:7]
	global_load_dword v50, v[48:49], off offset:64
	s_waitcnt vmcnt(0)
	v_add_f32_e32 v44, v44, v50
	v_max_f32_e64 v51, -v44, 0
	v_mul_f32_e64 v44, |v44|, s5
	v_exp_f32_e32 v44, v44
	v_add_f32_e32 v40, v40, v50
	v_add_f32_e32 v36, v36, v50
	v_add_f32_e32 v32, v32, v50
	v_add_f32_e32 v44, 1.0, v44
	v_cmp_gt_f32_e32 vcc, s85, v44
	s_nop 1
	v_cndmask_b32_e64 v54, 0, 32, vcc
	v_ldexp_f32 v44, v44, v54
	v_log_f32_e32 v44, v44
	s_nop 0
	v_mul_f32_e32 v54, 0x3f317217, v44
	v_fma_f32 v54, v44, s9, -v54
	v_fmac_f32_e32 v54, 0x3377d1cf, v44
	v_fmac_f32_e32 v54, 0x3f317217, v44
	v_cmp_lt_f32_e64 s[34:35], |v44|, s8
	s_nop 1
	v_cndmask_b32_e64 v44, v44, v54, s[34:35]
	v_cndmask_b32_e32 v54, 0, v191, vcc
	v_sub_f32_e32 v44, v44, v54
	v_add_f32_e32 v44, v51, v44
	v_sub_f32_e32 v44, -0.5, v44
	v_mul_f32_e32 v44, 0x3fb8aa3b, v44
	v_exp_f32_e32 v44, v44
	s_nop 0
	v_mul_f32_e32 v44, 0xbfb8aa3b, v44
	v_exp_f32_e32 v44, v44
	global_store_dword v[64:65], v44, off offset:64
	v_add_f32_e32 v44, v45, v50
	v_max_f32_e64 v45, -v44, 0
	v_mul_f32_e64 v44, |v44|, s5
	v_exp_f32_e32 v44, v44
	s_nop 0
	v_add_f32_e32 v44, 1.0, v44
	v_cmp_gt_f32_e32 vcc, s85, v44
	s_nop 1
	v_cndmask_b32_e64 v51, 0, 32, vcc
	v_ldexp_f32 v44, v44, v51
	v_log_f32_e32 v44, v44
	s_nop 0
	v_mul_f32_e32 v51, 0x3f317217, v44
	v_fma_f32 v51, v44, s9, -v51
	v_fmac_f32_e32 v51, 0x3377d1cf, v44
	v_fmac_f32_e32 v51, 0x3f317217, v44
	v_cmp_lt_f32_e64 s[34:35], |v44|, s8
	s_nop 1
	v_cndmask_b32_e64 v44, v44, v51, s[34:35]
	v_cndmask_b32_e32 v51, 0, v191, vcc
	v_sub_f32_e32 v44, v44, v51
	v_add_f32_e32 v44, v45, v44
	v_sub_f32_e32 v44, -0.5, v44
	v_mul_f32_e32 v44, 0x3fb8aa3b, v44
	v_exp_f32_e32 v44, v44
	s_nop 0
	v_mul_f32_e32 v44, 0xbfb8aa3b, v44
	v_exp_f32_e32 v44, v44
	global_store_dword v[64:65], v44, off offset:1088
	v_add_f32_e32 v44, v46, v50
	v_max_f32_e64 v45, -v44, 0
	v_mul_f32_e64 v44, |v44|, s5
	v_exp_f32_e32 v44, v44
	s_nop 0
	v_add_f32_e32 v44, 1.0, v44
	v_cmp_gt_f32_e32 vcc, s85, v44
	s_nop 1
	v_cndmask_b32_e64 v46, 0, 32, vcc
	v_ldexp_f32 v44, v44, v46
	v_log_f32_e32 v44, v44
	s_nop 0
	v_mul_f32_e32 v46, 0x3f317217, v44
	v_fma_f32 v46, v44, s9, -v46
	v_fmac_f32_e32 v46, 0x3377d1cf, v44
	v_fmac_f32_e32 v46, 0x3f317217, v44
	v_cmp_lt_f32_e64 s[34:35], |v44|, s8
	s_nop 1
	v_cndmask_b32_e64 v44, v44, v46, s[34:35]
	v_cndmask_b32_e32 v46, 0, v191, vcc
	v_sub_f32_e32 v44, v44, v46
	v_add_f32_e32 v44, v45, v44
	v_sub_f32_e32 v44, -0.5, v44
	v_mul_f32_e32 v44, 0x3fb8aa3b, v44
	v_exp_f32_e32 v44, v44
	s_nop 0
	v_mul_f32_e32 v44, 0xbfb8aa3b, v44
	v_exp_f32_e32 v44, v44
	global_store_dword v[64:65], v44, off offset:2112
	v_add_f32_e32 v44, v47, v50
	v_max_f32_e64 v45, -v44, 0
	v_mul_f32_e64 v44, |v44|, s5
	v_exp_f32_e32 v44, v44
	s_nop 0
	v_add_f32_e32 v44, 1.0, v44
	v_cmp_gt_f32_e32 vcc, s85, v44
	s_nop 1
	v_cndmask_b32_e64 v46, 0, 32, vcc
	v_ldexp_f32 v44, v44, v46
	v_log_f32_e32 v44, v44
	s_nop 0
	v_mul_f32_e32 v46, 0x3f317217, v44
	v_fma_f32 v46, v44, s9, -v46
	v_fmac_f32_e32 v46, 0x3377d1cf, v44
	v_fmac_f32_e32 v46, 0x3f317217, v44
	v_cmp_lt_f32_e64 s[34:35], |v44|, s8
	s_nop 1
	v_cndmask_b32_e64 v44, v44, v46, s[34:35]
	v_cndmask_b32_e32 v46, 0, v191, vcc
	v_sub_f32_e32 v44, v44, v46
	v_add_f32_e32 v44, v45, v44
	v_sub_f32_e32 v44, -0.5, v44
	v_mul_f32_e32 v44, 0x3fb8aa3b, v44
	v_exp_f32_e32 v44, v44
	s_nop 0
	v_mul_f32_e32 v44, 0xbfb8aa3b, v44
	v_exp_f32_e32 v44, v44
	global_store_dword v[64:65], v44, off offset:3136
	v_max_f32_e64 v44, -v40, 0
	v_mul_f32_e64 v40, |v40|, s5
	v_exp_f32_e32 v40, v40
	s_nop 0
	v_add_f32_e32 v40, 1.0, v40
	v_cmp_gt_f32_e32 vcc, s85, v40
	s_nop 1
	v_cndmask_b32_e64 v45, 0, 32, vcc
	v_ldexp_f32 v40, v40, v45
	v_log_f32_e32 v40, v40
	s_nop 0
	v_mul_f32_e32 v45, 0x3f317217, v40
	v_fma_f32 v45, v40, s9, -v45
	v_fmac_f32_e32 v45, 0x3377d1cf, v40
	v_fmac_f32_e32 v45, 0x3f317217, v40
	v_cmp_lt_f32_e64 s[34:35], |v40|, s8
	s_nop 1
	v_cndmask_b32_e64 v40, v40, v45, s[34:35]
	v_cndmask_b32_e32 v45, 0, v191, vcc
	v_sub_f32_e32 v40, v40, v45
	v_add_f32_e32 v40, v44, v40
	v_sub_f32_e32 v40, -0.5, v40
	v_mul_f32_e32 v40, 0x3fb8aa3b, v40
	v_exp_f32_e32 v40, v40
	s_nop 0
	v_mul_f32_e32 v40, 0xbfb8aa3b, v40
	v_exp_f32_e32 v40, v40
	global_store_dword v[60:61], v40, off offset:64
	v_add_f32_e32 v40, v41, v50
	v_max_f32_e64 v41, -v40, 0
	v_mul_f32_e64 v40, |v40|, s5
	v_exp_f32_e32 v40, v40
	s_nop 0
	v_add_f32_e32 v40, 1.0, v40
	v_cmp_gt_f32_e32 vcc, s85, v40
	s_nop 1
	v_cndmask_b32_e64 v44, 0, 32, vcc
	v_ldexp_f32 v40, v40, v44
	v_log_f32_e32 v40, v40
	s_nop 0
	v_mul_f32_e32 v44, 0x3f317217, v40
	v_fma_f32 v44, v40, s9, -v44
	v_fmac_f32_e32 v44, 0x3377d1cf, v40
	v_fmac_f32_e32 v44, 0x3f317217, v40
	v_cmp_lt_f32_e64 s[34:35], |v40|, s8
	s_nop 1
	v_cndmask_b32_e64 v40, v40, v44, s[34:35]
	v_cndmask_b32_e32 v44, 0, v191, vcc
	v_sub_f32_e32 v40, v40, v44
	v_add_f32_e32 v40, v41, v40
	v_sub_f32_e32 v40, -0.5, v40
	v_mul_f32_e32 v40, 0x3fb8aa3b, v40
	v_exp_f32_e32 v40, v40
	s_nop 0
	v_mul_f32_e32 v40, 0xbfb8aa3b, v40
	v_exp_f32_e32 v40, v40
	global_store_dword v[60:61], v40, off offset:1088
	v_add_f32_e32 v40, v42, v50
	v_max_f32_e64 v41, -v40, 0
	v_mul_f32_e64 v40, |v40|, s5
	v_exp_f32_e32 v40, v40
	s_nop 0
	v_add_f32_e32 v40, 1.0, v40
	v_cmp_gt_f32_e32 vcc, s85, v40
	s_nop 1
	v_cndmask_b32_e64 v42, 0, 32, vcc
	v_ldexp_f32 v40, v40, v42
	v_log_f32_e32 v40, v40
	s_nop 0
	v_mul_f32_e32 v42, 0x3f317217, v40
	v_fma_f32 v42, v40, s9, -v42
	v_fmac_f32_e32 v42, 0x3377d1cf, v40
	v_fmac_f32_e32 v42, 0x3f317217, v40
	v_cmp_lt_f32_e64 s[34:35], |v40|, s8
	s_nop 1
	v_cndmask_b32_e64 v40, v40, v42, s[34:35]
	v_cndmask_b32_e32 v42, 0, v191, vcc
	v_sub_f32_e32 v40, v40, v42
	v_add_f32_e32 v40, v41, v40
	v_sub_f32_e32 v40, -0.5, v40
	v_mul_f32_e32 v40, 0x3fb8aa3b, v40
	v_exp_f32_e32 v40, v40
	s_nop 0
	v_mul_f32_e32 v40, 0xbfb8aa3b, v40
	v_exp_f32_e32 v40, v40
	global_store_dword v[60:61], v40, off offset:2112
	v_add_f32_e32 v40, v43, v50
	v_max_f32_e64 v41, -v40, 0
	v_mul_f32_e64 v40, |v40|, s5
	v_exp_f32_e32 v40, v40
	s_nop 0
	v_add_f32_e32 v40, 1.0, v40
	v_cmp_gt_f32_e32 vcc, s85, v40
	s_nop 1
	v_cndmask_b32_e64 v42, 0, 32, vcc
	v_ldexp_f32 v40, v40, v42
	v_log_f32_e32 v40, v40
	s_nop 0
	v_mul_f32_e32 v42, 0x3f317217, v40
	v_fma_f32 v42, v40, s9, -v42
	v_fmac_f32_e32 v42, 0x3377d1cf, v40
	v_fmac_f32_e32 v42, 0x3f317217, v40
	v_cmp_lt_f32_e64 s[34:35], |v40|, s8
	s_nop 1
	v_cndmask_b32_e64 v40, v40, v42, s[34:35]
	v_cndmask_b32_e32 v42, 0, v191, vcc
	v_sub_f32_e32 v40, v40, v42
	v_add_f32_e32 v40, v41, v40
	v_sub_f32_e32 v40, -0.5, v40
	v_mul_f32_e32 v40, 0x3fb8aa3b, v40
	v_exp_f32_e32 v40, v40
	s_nop 0
	v_mul_f32_e32 v40, 0xbfb8aa3b, v40
	v_exp_f32_e32 v40, v40
	global_store_dword v[60:61], v40, off offset:3136
	v_max_f32_e64 v40, -v36, 0
	v_mul_f32_e64 v36, |v36|, s5
	v_exp_f32_e32 v36, v36
	s_nop 0
	v_add_f32_e32 v36, 1.0, v36
	v_cmp_gt_f32_e32 vcc, s85, v36
	s_nop 1
	v_cndmask_b32_e64 v41, 0, 32, vcc
	v_ldexp_f32 v36, v36, v41
	v_log_f32_e32 v36, v36
	s_nop 0
	v_mul_f32_e32 v41, 0x3f317217, v36
	v_fma_f32 v41, v36, s9, -v41
	v_fmac_f32_e32 v41, 0x3377d1cf, v36
	v_fmac_f32_e32 v41, 0x3f317217, v36
	v_cmp_lt_f32_e64 s[34:35], |v36|, s8
	s_nop 1
	v_cndmask_b32_e64 v36, v36, v41, s[34:35]
	v_cndmask_b32_e32 v41, 0, v191, vcc
	v_sub_f32_e32 v36, v36, v41
	v_add_f32_e32 v36, v40, v36
	v_sub_f32_e32 v36, -0.5, v36
	v_mul_f32_e32 v36, 0x3fb8aa3b, v36
	v_exp_f32_e32 v36, v36
	s_nop 0
	v_mul_f32_e32 v36, 0xbfb8aa3b, v36
	v_exp_f32_e32 v36, v36
	global_store_dword v[56:57], v36, off offset:64
	v_add_f32_e32 v36, v37, v50
	v_max_f32_e64 v37, -v36, 0
	v_mul_f32_e64 v36, |v36|, s5
	v_exp_f32_e32 v36, v36
	s_nop 0
	v_add_f32_e32 v36, 1.0, v36
	v_cmp_gt_f32_e32 vcc, s85, v36
	s_nop 1
	v_cndmask_b32_e64 v40, 0, 32, vcc
	v_ldexp_f32 v36, v36, v40
	v_log_f32_e32 v36, v36
	s_nop 0
	v_mul_f32_e32 v40, 0x3f317217, v36
	v_fma_f32 v40, v36, s9, -v40
	v_fmac_f32_e32 v40, 0x3377d1cf, v36
	v_fmac_f32_e32 v40, 0x3f317217, v36
	v_cmp_lt_f32_e64 s[34:35], |v36|, s8
	s_nop 1
	v_cndmask_b32_e64 v36, v36, v40, s[34:35]
	v_cndmask_b32_e32 v40, 0, v191, vcc
	v_sub_f32_e32 v36, v36, v40
	v_add_f32_e32 v36, v37, v36
	v_sub_f32_e32 v36, -0.5, v36
	v_mul_f32_e32 v36, 0x3fb8aa3b, v36
	v_exp_f32_e32 v36, v36
	s_nop 0
	v_mul_f32_e32 v36, 0xbfb8aa3b, v36
	v_exp_f32_e32 v36, v36
	global_store_dword v[56:57], v36, off offset:1088
	v_add_f32_e32 v36, v38, v50
	v_max_f32_e64 v37, -v36, 0
	v_mul_f32_e64 v36, |v36|, s5
	v_exp_f32_e32 v36, v36
	s_nop 0
	v_add_f32_e32 v36, 1.0, v36
	v_cmp_gt_f32_e32 vcc, s85, v36
	s_nop 1
	v_cndmask_b32_e64 v38, 0, 32, vcc
	v_ldexp_f32 v36, v36, v38
	v_log_f32_e32 v36, v36
	s_nop 0
	v_mul_f32_e32 v38, 0x3f317217, v36
	v_fma_f32 v38, v36, s9, -v38
	v_fmac_f32_e32 v38, 0x3377d1cf, v36
	v_fmac_f32_e32 v38, 0x3f317217, v36
	v_cmp_lt_f32_e64 s[34:35], |v36|, s8
	s_nop 1
	v_cndmask_b32_e64 v36, v36, v38, s[34:35]
	v_cndmask_b32_e32 v38, 0, v191, vcc
	v_sub_f32_e32 v36, v36, v38
	v_add_f32_e32 v36, v37, v36
	v_sub_f32_e32 v36, -0.5, v36
	v_mul_f32_e32 v36, 0x3fb8aa3b, v36
	v_exp_f32_e32 v36, v36
	s_nop 0
	v_mul_f32_e32 v36, 0xbfb8aa3b, v36
	v_exp_f32_e32 v36, v36
	global_store_dword v[56:57], v36, off offset:2112
	v_add_f32_e32 v36, v39, v50
	v_max_f32_e64 v37, -v36, 0
	v_mul_f32_e64 v36, |v36|, s5
	v_exp_f32_e32 v36, v36
	s_nop 0
	v_add_f32_e32 v36, 1.0, v36
	v_cmp_gt_f32_e32 vcc, s85, v36
	s_nop 1
	v_cndmask_b32_e64 v38, 0, 32, vcc
	v_ldexp_f32 v36, v36, v38
	v_log_f32_e32 v36, v36
	s_nop 0
	v_mul_f32_e32 v38, 0x3f317217, v36
	v_fma_f32 v38, v36, s9, -v38
	v_fmac_f32_e32 v38, 0x3377d1cf, v36
	v_fmac_f32_e32 v38, 0x3f317217, v36
	v_cmp_lt_f32_e64 s[34:35], |v36|, s8
	s_nop 1
	v_cndmask_b32_e64 v36, v36, v38, s[34:35]
	v_cndmask_b32_e32 v38, 0, v191, vcc
	v_sub_f32_e32 v36, v36, v38
	v_add_f32_e32 v36, v37, v36
	v_sub_f32_e32 v36, -0.5, v36
	v_mul_f32_e32 v36, 0x3fb8aa3b, v36
	v_exp_f32_e32 v36, v36
	s_nop 0
	v_mul_f32_e32 v36, 0xbfb8aa3b, v36
	v_exp_f32_e32 v36, v36
	global_store_dword v[56:57], v36, off offset:3136
	v_max_f32_e64 v36, -v32, 0
	v_mul_f32_e64 v32, |v32|, s5
	v_exp_f32_e32 v32, v32
	s_nop 0
	v_add_f32_e32 v32, 1.0, v32
	v_cmp_gt_f32_e32 vcc, s85, v32
	s_nop 1
	v_cndmask_b32_e64 v37, 0, 32, vcc
	v_ldexp_f32 v32, v32, v37
	v_log_f32_e32 v32, v32
	s_nop 0
	v_mul_f32_e32 v37, 0x3f317217, v32
	v_fma_f32 v37, v32, s9, -v37
	v_fmac_f32_e32 v37, 0x3377d1cf, v32
	v_fmac_f32_e32 v37, 0x3f317217, v32
	v_cmp_lt_f32_e64 s[34:35], |v32|, s8
	s_nop 1
	v_cndmask_b32_e64 v32, v32, v37, s[34:35]
	v_cndmask_b32_e32 v37, 0, v191, vcc
	v_sub_f32_e32 v32, v32, v37
	v_add_f32_e32 v32, v36, v32
	v_sub_f32_e32 v32, -0.5, v32
	v_mul_f32_e32 v32, 0x3fb8aa3b, v32
	v_exp_f32_e32 v32, v32
	s_nop 0
	v_mul_f32_e32 v32, 0xbfb8aa3b, v32
	v_exp_f32_e32 v32, v32
	global_store_dword v[52:53], v32, off offset:64
	v_add_f32_e32 v32, v33, v50
	v_max_f32_e64 v33, -v32, 0
	v_mul_f32_e64 v32, |v32|, s5
	v_exp_f32_e32 v32, v32
	s_nop 0
	v_add_f32_e32 v32, 1.0, v32
	v_cmp_gt_f32_e32 vcc, s85, v32
	s_nop 1
	v_cndmask_b32_e64 v36, 0, 32, vcc
	v_ldexp_f32 v32, v32, v36
	v_log_f32_e32 v32, v32
	s_nop 0
	v_mul_f32_e32 v36, 0x3f317217, v32
	v_fma_f32 v36, v32, s9, -v36
	v_fmac_f32_e32 v36, 0x3377d1cf, v32
	v_fmac_f32_e32 v36, 0x3f317217, v32
	v_cmp_lt_f32_e64 s[34:35], |v32|, s8
	s_nop 1
	v_cndmask_b32_e64 v32, v32, v36, s[34:35]
	v_cndmask_b32_e32 v36, 0, v191, vcc
	v_sub_f32_e32 v32, v32, v36
	v_add_f32_e32 v32, v33, v32
	v_sub_f32_e32 v32, -0.5, v32
	v_mul_f32_e32 v32, 0x3fb8aa3b, v32
	v_exp_f32_e32 v32, v32
	s_nop 0
	v_mul_f32_e32 v32, 0xbfb8aa3b, v32
	v_exp_f32_e32 v32, v32
	global_store_dword v[52:53], v32, off offset:1088
	v_add_f32_e32 v32, v34, v50
	v_max_f32_e64 v33, -v32, 0
	v_mul_f32_e64 v32, |v32|, s5
	v_exp_f32_e32 v32, v32
	s_nop 0
	v_add_f32_e32 v32, 1.0, v32
	v_cmp_gt_f32_e32 vcc, s85, v32
	s_nop 1
	v_cndmask_b32_e64 v34, 0, 32, vcc
	v_ldexp_f32 v32, v32, v34
	v_log_f32_e32 v32, v32
	s_nop 0
	v_mul_f32_e32 v34, 0x3f317217, v32
	v_fma_f32 v34, v32, s9, -v34
	v_fmac_f32_e32 v34, 0x3377d1cf, v32
	v_fmac_f32_e32 v34, 0x3f317217, v32
	v_cmp_lt_f32_e64 s[34:35], |v32|, s8
	s_nop 1
	v_cndmask_b32_e64 v32, v32, v34, s[34:35]
	v_cndmask_b32_e32 v34, 0, v191, vcc
	v_sub_f32_e32 v32, v32, v34
	v_add_f32_e32 v32, v33, v32
	v_sub_f32_e32 v32, -0.5, v32
	v_mul_f32_e32 v32, 0x3fb8aa3b, v32
	v_exp_f32_e32 v32, v32
	s_nop 0
	v_mul_f32_e32 v32, 0xbfb8aa3b, v32
	v_exp_f32_e32 v32, v32
	global_store_dword v[52:53], v32, off offset:2112
	v_add_f32_e32 v32, v35, v50
	v_max_f32_e64 v33, -v32, 0
	v_mul_f32_e64 v32, |v32|, s5
	v_exp_f32_e32 v32, v32
	s_nop 0
	v_add_f32_e32 v32, 1.0, v32
	v_cmp_gt_f32_e32 vcc, s85, v32
	s_nop 1
	v_cndmask_b32_e64 v34, 0, 32, vcc
	v_ldexp_f32 v32, v32, v34
	v_log_f32_e32 v32, v32
	s_nop 0
	v_mul_f32_e32 v34, 0x3f317217, v32
	v_fma_f32 v34, v32, s9, -v34
	v_fmac_f32_e32 v34, 0x3377d1cf, v32
	v_fmac_f32_e32 v34, 0x3f317217, v32
	v_cmp_lt_f32_e64 s[34:35], |v32|, s8
	s_nop 1
	v_cndmask_b32_e64 v32, v32, v34, s[34:35]
	v_cndmask_b32_e32 v34, 0, v191, vcc
	v_sub_f32_e32 v32, v32, v34
	v_add_f32_e32 v32, v33, v32
	v_sub_f32_e32 v32, -0.5, v32
	v_mul_f32_e32 v32, 0x3fb8aa3b, v32
	v_exp_f32_e32 v32, v32
	s_nop 0
	v_mul_f32_e32 v32, 0xbfb8aa3b, v32
	v_exp_f32_e32 v32, v32
	global_store_dword v[52:53], v32, off offset:3136
	global_load_dword v32, v[48:49], off offset:128
	s_waitcnt vmcnt(0)
	v_add_f32_e32 v28, v28, v32
	v_max_f32_e64 v33, -v28, 0
	v_mul_f32_e64 v28, |v28|, s5
	v_exp_f32_e32 v28, v28
	v_add_f32_e32 v24, v24, v32
	v_add_f32_e32 v20, v20, v32
	v_add_f32_e32 v16, v16, v32
	v_add_f32_e32 v28, 1.0, v28
	v_cmp_gt_f32_e32 vcc, s85, v28
	s_nop 1
	v_cndmask_b32_e64 v34, 0, 32, vcc
	v_ldexp_f32 v28, v28, v34
	v_log_f32_e32 v28, v28
	s_nop 0
	v_mul_f32_e32 v34, 0x3f317217, v28
	v_fma_f32 v34, v28, s9, -v34
	v_fmac_f32_e32 v34, 0x3377d1cf, v28
	v_fmac_f32_e32 v34, 0x3f317217, v28
	v_cmp_lt_f32_e64 s[34:35], |v28|, s8
	s_nop 1
	v_cndmask_b32_e64 v28, v28, v34, s[34:35]
	v_cndmask_b32_e32 v34, 0, v191, vcc
	v_sub_f32_e32 v28, v28, v34
	v_add_f32_e32 v28, v33, v28
	v_sub_f32_e32 v28, -0.5, v28
	v_mul_f32_e32 v28, 0x3fb8aa3b, v28
	v_exp_f32_e32 v28, v28
	s_nop 0
	v_mul_f32_e32 v28, 0xbfb8aa3b, v28
	v_exp_f32_e32 v28, v28
	global_store_dword v[64:65], v28, off offset:128
	v_add_f32_e32 v28, v29, v32
	v_max_f32_e64 v29, -v28, 0
	v_mul_f32_e64 v28, |v28|, s5
	v_exp_f32_e32 v28, v28
	s_nop 0
	v_add_f32_e32 v28, 1.0, v28
	v_cmp_gt_f32_e32 vcc, s85, v28
	s_nop 1
	v_cndmask_b32_e64 v33, 0, 32, vcc
	v_ldexp_f32 v28, v28, v33
	v_log_f32_e32 v28, v28
	s_nop 0
	v_mul_f32_e32 v33, 0x3f317217, v28
	v_fma_f32 v33, v28, s9, -v33
	v_fmac_f32_e32 v33, 0x3377d1cf, v28
	v_fmac_f32_e32 v33, 0x3f317217, v28
	v_cmp_lt_f32_e64 s[34:35], |v28|, s8
	s_nop 1
	v_cndmask_b32_e64 v28, v28, v33, s[34:35]
	v_cndmask_b32_e32 v33, 0, v191, vcc
	v_sub_f32_e32 v28, v28, v33
	v_add_f32_e32 v28, v29, v28
	v_sub_f32_e32 v28, -0.5, v28
	v_mul_f32_e32 v28, 0x3fb8aa3b, v28
	v_exp_f32_e32 v28, v28
	s_nop 0
	v_mul_f32_e32 v28, 0xbfb8aa3b, v28
	v_exp_f32_e32 v28, v28
	global_store_dword v[64:65], v28, off offset:1152
	v_add_f32_e32 v28, v30, v32
	v_max_f32_e64 v29, -v28, 0
	v_mul_f32_e64 v28, |v28|, s5
	v_exp_f32_e32 v28, v28
	s_nop 0
	v_add_f32_e32 v28, 1.0, v28
	v_cmp_gt_f32_e32 vcc, s85, v28
	s_nop 1
	v_cndmask_b32_e64 v30, 0, 32, vcc
	v_ldexp_f32 v28, v28, v30
	v_log_f32_e32 v28, v28
	s_nop 0
	v_mul_f32_e32 v30, 0x3f317217, v28
	v_fma_f32 v30, v28, s9, -v30
	v_fmac_f32_e32 v30, 0x3377d1cf, v28
	v_fmac_f32_e32 v30, 0x3f317217, v28
	v_cmp_lt_f32_e64 s[34:35], |v28|, s8
	s_nop 1
	v_cndmask_b32_e64 v28, v28, v30, s[34:35]
	v_cndmask_b32_e32 v30, 0, v191, vcc
	v_sub_f32_e32 v28, v28, v30
	v_add_f32_e32 v28, v29, v28
	v_sub_f32_e32 v28, -0.5, v28
	v_mul_f32_e32 v28, 0x3fb8aa3b, v28
	v_exp_f32_e32 v28, v28
	s_nop 0
	v_mul_f32_e32 v28, 0xbfb8aa3b, v28
	v_exp_f32_e32 v28, v28
	global_store_dword v[64:65], v28, off offset:2176
	v_add_f32_e32 v28, v31, v32
	v_max_f32_e64 v29, -v28, 0
	v_mul_f32_e64 v28, |v28|, s5
	v_exp_f32_e32 v28, v28
	s_nop 0
	v_add_f32_e32 v28, 1.0, v28
	v_cmp_gt_f32_e32 vcc, s85, v28
	s_nop 1
	v_cndmask_b32_e64 v30, 0, 32, vcc
	v_ldexp_f32 v28, v28, v30
	v_log_f32_e32 v28, v28
	s_nop 0
	v_mul_f32_e32 v30, 0x3f317217, v28
	v_fma_f32 v30, v28, s9, -v30
	v_fmac_f32_e32 v30, 0x3377d1cf, v28
	v_fmac_f32_e32 v30, 0x3f317217, v28
	v_cmp_lt_f32_e64 s[34:35], |v28|, s8
	s_nop 1
	v_cndmask_b32_e64 v28, v28, v30, s[34:35]
	v_cndmask_b32_e32 v30, 0, v191, vcc
	v_sub_f32_e32 v28, v28, v30
	v_add_f32_e32 v28, v29, v28
	v_sub_f32_e32 v28, -0.5, v28
	v_mul_f32_e32 v28, 0x3fb8aa3b, v28
	v_exp_f32_e32 v28, v28
	s_nop 0
	v_mul_f32_e32 v28, 0xbfb8aa3b, v28
	v_exp_f32_e32 v28, v28
	global_store_dword v[64:65], v28, off offset:3200
	v_max_f32_e64 v28, -v24, 0
	v_mul_f32_e64 v24, |v24|, s5
	v_exp_f32_e32 v24, v24
	s_nop 0
	v_add_f32_e32 v24, 1.0, v24
	v_cmp_gt_f32_e32 vcc, s85, v24
	s_nop 1
	v_cndmask_b32_e64 v29, 0, 32, vcc
	v_ldexp_f32 v24, v24, v29
	v_log_f32_e32 v24, v24
	s_nop 0
	v_mul_f32_e32 v29, 0x3f317217, v24
	v_fma_f32 v29, v24, s9, -v29
	v_fmac_f32_e32 v29, 0x3377d1cf, v24
	v_fmac_f32_e32 v29, 0x3f317217, v24
	v_cmp_lt_f32_e64 s[34:35], |v24|, s8
	s_nop 1
	v_cndmask_b32_e64 v24, v24, v29, s[34:35]
	v_cndmask_b32_e32 v29, 0, v191, vcc
	v_sub_f32_e32 v24, v24, v29
	v_add_f32_e32 v24, v28, v24
	v_sub_f32_e32 v24, -0.5, v24
	v_mul_f32_e32 v24, 0x3fb8aa3b, v24
	v_exp_f32_e32 v24, v24
	s_nop 0
	v_mul_f32_e32 v24, 0xbfb8aa3b, v24
	v_exp_f32_e32 v24, v24
	global_store_dword v[60:61], v24, off offset:128
	v_add_f32_e32 v24, v25, v32
	v_max_f32_e64 v25, -v24, 0
	v_mul_f32_e64 v24, |v24|, s5
	v_exp_f32_e32 v24, v24
	s_nop 0
	v_add_f32_e32 v24, 1.0, v24
	v_cmp_gt_f32_e32 vcc, s85, v24
	s_nop 1
	v_cndmask_b32_e64 v28, 0, 32, vcc
	v_ldexp_f32 v24, v24, v28
	v_log_f32_e32 v24, v24
	s_nop 0
	v_mul_f32_e32 v28, 0x3f317217, v24
	v_fma_f32 v28, v24, s9, -v28
	v_fmac_f32_e32 v28, 0x3377d1cf, v24
	v_fmac_f32_e32 v28, 0x3f317217, v24
	v_cmp_lt_f32_e64 s[34:35], |v24|, s8
	s_nop 1
	v_cndmask_b32_e64 v24, v24, v28, s[34:35]
	v_cndmask_b32_e32 v28, 0, v191, vcc
	v_sub_f32_e32 v24, v24, v28
	v_add_f32_e32 v24, v25, v24
	v_sub_f32_e32 v24, -0.5, v24
	v_mul_f32_e32 v24, 0x3fb8aa3b, v24
	v_exp_f32_e32 v24, v24
	s_nop 0
	v_mul_f32_e32 v24, 0xbfb8aa3b, v24
	v_exp_f32_e32 v24, v24
	global_store_dword v[60:61], v24, off offset:1152
	v_add_f32_e32 v24, v26, v32
	v_max_f32_e64 v25, -v24, 0
	v_mul_f32_e64 v24, |v24|, s5
	v_exp_f32_e32 v24, v24
	s_nop 0
	v_add_f32_e32 v24, 1.0, v24
	v_cmp_gt_f32_e32 vcc, s85, v24
	s_nop 1
	v_cndmask_b32_e64 v26, 0, 32, vcc
	v_ldexp_f32 v24, v24, v26
	v_log_f32_e32 v24, v24
	s_nop 0
	v_mul_f32_e32 v26, 0x3f317217, v24
	v_fma_f32 v26, v24, s9, -v26
	v_fmac_f32_e32 v26, 0x3377d1cf, v24
	v_fmac_f32_e32 v26, 0x3f317217, v24
	v_cmp_lt_f32_e64 s[34:35], |v24|, s8
	s_nop 1
	v_cndmask_b32_e64 v24, v24, v26, s[34:35]
	v_cndmask_b32_e32 v26, 0, v191, vcc
	v_sub_f32_e32 v24, v24, v26
	v_add_f32_e32 v24, v25, v24
	v_sub_f32_e32 v24, -0.5, v24
	v_mul_f32_e32 v24, 0x3fb8aa3b, v24
	v_exp_f32_e32 v24, v24
	s_nop 0
	v_mul_f32_e32 v24, 0xbfb8aa3b, v24
	v_exp_f32_e32 v24, v24
	global_store_dword v[60:61], v24, off offset:2176
	v_add_f32_e32 v24, v27, v32
	v_max_f32_e64 v25, -v24, 0
	v_mul_f32_e64 v24, |v24|, s5
	v_exp_f32_e32 v24, v24
	s_nop 0
	v_add_f32_e32 v24, 1.0, v24
	v_cmp_gt_f32_e32 vcc, s85, v24
	s_nop 1
	v_cndmask_b32_e64 v26, 0, 32, vcc
	v_ldexp_f32 v24, v24, v26
	v_log_f32_e32 v24, v24
	s_nop 0
	v_mul_f32_e32 v26, 0x3f317217, v24
	v_fma_f32 v26, v24, s9, -v26
	v_fmac_f32_e32 v26, 0x3377d1cf, v24
	v_fmac_f32_e32 v26, 0x3f317217, v24
	v_cmp_lt_f32_e64 s[34:35], |v24|, s8
	s_nop 1
	v_cndmask_b32_e64 v24, v24, v26, s[34:35]
	v_cndmask_b32_e32 v26, 0, v191, vcc
	v_sub_f32_e32 v24, v24, v26
	v_add_f32_e32 v24, v25, v24
	v_sub_f32_e32 v24, -0.5, v24
	v_mul_f32_e32 v24, 0x3fb8aa3b, v24
	v_exp_f32_e32 v24, v24
	s_nop 0
	v_mul_f32_e32 v24, 0xbfb8aa3b, v24
	v_exp_f32_e32 v24, v24
	global_store_dword v[60:61], v24, off offset:3200
	v_max_f32_e64 v24, -v20, 0
	v_mul_f32_e64 v20, |v20|, s5
	v_exp_f32_e32 v20, v20
	s_nop 0
	v_add_f32_e32 v20, 1.0, v20
	v_cmp_gt_f32_e32 vcc, s85, v20
	s_nop 1
	v_cndmask_b32_e64 v25, 0, 32, vcc
	v_ldexp_f32 v20, v20, v25
	v_log_f32_e32 v20, v20
	s_nop 0
	v_mul_f32_e32 v25, 0x3f317217, v20
	v_fma_f32 v25, v20, s9, -v25
	v_fmac_f32_e32 v25, 0x3377d1cf, v20
	v_fmac_f32_e32 v25, 0x3f317217, v20
	v_cmp_lt_f32_e64 s[34:35], |v20|, s8
	s_nop 1
	v_cndmask_b32_e64 v20, v20, v25, s[34:35]
	v_cndmask_b32_e32 v25, 0, v191, vcc
	v_sub_f32_e32 v20, v20, v25
	v_add_f32_e32 v20, v24, v20
	v_sub_f32_e32 v20, -0.5, v20
	v_mul_f32_e32 v20, 0x3fb8aa3b, v20
	v_exp_f32_e32 v20, v20
	s_nop 0
	v_mul_f32_e32 v20, 0xbfb8aa3b, v20
	v_exp_f32_e32 v20, v20
	global_store_dword v[56:57], v20, off offset:128
	v_add_f32_e32 v20, v21, v32
	v_max_f32_e64 v21, -v20, 0
	v_mul_f32_e64 v20, |v20|, s5
	v_exp_f32_e32 v20, v20
	s_nop 0
	v_add_f32_e32 v20, 1.0, v20
	v_cmp_gt_f32_e32 vcc, s85, v20
	s_nop 1
	v_cndmask_b32_e64 v24, 0, 32, vcc
	v_ldexp_f32 v20, v20, v24
	v_log_f32_e32 v20, v20
	s_nop 0
	v_mul_f32_e32 v24, 0x3f317217, v20
	v_fma_f32 v24, v20, s9, -v24
	v_fmac_f32_e32 v24, 0x3377d1cf, v20
	v_fmac_f32_e32 v24, 0x3f317217, v20
	v_cmp_lt_f32_e64 s[34:35], |v20|, s8
	s_nop 1
	v_cndmask_b32_e64 v20, v20, v24, s[34:35]
	v_cndmask_b32_e32 v24, 0, v191, vcc
	v_sub_f32_e32 v20, v20, v24
	v_add_f32_e32 v20, v21, v20
	v_sub_f32_e32 v20, -0.5, v20
	v_mul_f32_e32 v20, 0x3fb8aa3b, v20
	v_exp_f32_e32 v20, v20
	s_nop 0
	v_mul_f32_e32 v20, 0xbfb8aa3b, v20
	v_exp_f32_e32 v20, v20
	global_store_dword v[56:57], v20, off offset:1152
	v_add_f32_e32 v20, v22, v32
	v_max_f32_e64 v21, -v20, 0
	v_mul_f32_e64 v20, |v20|, s5
	v_exp_f32_e32 v20, v20
	s_nop 0
	v_add_f32_e32 v20, 1.0, v20
	v_cmp_gt_f32_e32 vcc, s85, v20
	s_nop 1
	v_cndmask_b32_e64 v22, 0, 32, vcc
	v_ldexp_f32 v20, v20, v22
	v_log_f32_e32 v20, v20
	s_nop 0
	v_mul_f32_e32 v22, 0x3f317217, v20
	v_fma_f32 v22, v20, s9, -v22
	v_fmac_f32_e32 v22, 0x3377d1cf, v20
	v_fmac_f32_e32 v22, 0x3f317217, v20
	v_cmp_lt_f32_e64 s[34:35], |v20|, s8
	s_nop 1
	v_cndmask_b32_e64 v20, v20, v22, s[34:35]
	v_cndmask_b32_e32 v22, 0, v191, vcc
	v_sub_f32_e32 v20, v20, v22
	v_add_f32_e32 v20, v21, v20
	v_sub_f32_e32 v20, -0.5, v20
	v_mul_f32_e32 v20, 0x3fb8aa3b, v20
	v_exp_f32_e32 v20, v20
	s_nop 0
	v_mul_f32_e32 v20, 0xbfb8aa3b, v20
	v_exp_f32_e32 v20, v20
	global_store_dword v[56:57], v20, off offset:2176
	v_add_f32_e32 v20, v23, v32
	v_max_f32_e64 v21, -v20, 0
	v_mul_f32_e64 v20, |v20|, s5
	v_exp_f32_e32 v20, v20
	s_nop 0
	v_add_f32_e32 v20, 1.0, v20
	v_cmp_gt_f32_e32 vcc, s85, v20
	s_nop 1
	v_cndmask_b32_e64 v22, 0, 32, vcc
	v_ldexp_f32 v20, v20, v22
	v_log_f32_e32 v20, v20
	s_nop 0
	v_mul_f32_e32 v22, 0x3f317217, v20
	v_fma_f32 v22, v20, s9, -v22
	v_fmac_f32_e32 v22, 0x3377d1cf, v20
	v_fmac_f32_e32 v22, 0x3f317217, v20
	v_cmp_lt_f32_e64 s[34:35], |v20|, s8
	s_nop 1
	v_cndmask_b32_e64 v20, v20, v22, s[34:35]
	v_cndmask_b32_e32 v22, 0, v191, vcc
	v_sub_f32_e32 v20, v20, v22
	v_add_f32_e32 v20, v21, v20
	v_sub_f32_e32 v20, -0.5, v20
	v_mul_f32_e32 v20, 0x3fb8aa3b, v20
	v_exp_f32_e32 v20, v20
	s_nop 0
	v_mul_f32_e32 v20, 0xbfb8aa3b, v20
	v_exp_f32_e32 v20, v20
	global_store_dword v[56:57], v20, off offset:3200
	v_max_f32_e64 v20, -v16, 0
	v_mul_f32_e64 v16, |v16|, s5
	v_exp_f32_e32 v16, v16
	s_nop 0
	v_add_f32_e32 v16, 1.0, v16
	v_cmp_gt_f32_e32 vcc, s85, v16
	s_nop 1
	v_cndmask_b32_e64 v21, 0, 32, vcc
	v_ldexp_f32 v16, v16, v21
	v_log_f32_e32 v16, v16
	s_nop 0
	v_mul_f32_e32 v21, 0x3f317217, v16
	v_fma_f32 v21, v16, s9, -v21
	v_fmac_f32_e32 v21, 0x3377d1cf, v16
	v_fmac_f32_e32 v21, 0x3f317217, v16
	v_cmp_lt_f32_e64 s[34:35], |v16|, s8
	s_nop 1
	v_cndmask_b32_e64 v16, v16, v21, s[34:35]
	v_cndmask_b32_e32 v21, 0, v191, vcc
	v_sub_f32_e32 v16, v16, v21
	v_add_f32_e32 v16, v20, v16
	v_sub_f32_e32 v16, -0.5, v16
	v_mul_f32_e32 v16, 0x3fb8aa3b, v16
	v_exp_f32_e32 v16, v16
	s_nop 0
	v_mul_f32_e32 v16, 0xbfb8aa3b, v16
	v_exp_f32_e32 v16, v16
	global_store_dword v[52:53], v16, off offset:128
	v_add_f32_e32 v16, v17, v32
	v_max_f32_e64 v17, -v16, 0
	v_mul_f32_e64 v16, |v16|, s5
	v_exp_f32_e32 v16, v16
	s_nop 0
	v_add_f32_e32 v16, 1.0, v16
	v_cmp_gt_f32_e32 vcc, s85, v16
	s_nop 1
	v_cndmask_b32_e64 v20, 0, 32, vcc
	v_ldexp_f32 v16, v16, v20
	v_log_f32_e32 v16, v16
	s_nop 0
	v_mul_f32_e32 v20, 0x3f317217, v16
	v_fma_f32 v20, v16, s9, -v20
	v_fmac_f32_e32 v20, 0x3377d1cf, v16
	v_fmac_f32_e32 v20, 0x3f317217, v16
	v_cmp_lt_f32_e64 s[34:35], |v16|, s8
	s_nop 1
	v_cndmask_b32_e64 v16, v16, v20, s[34:35]
	v_cndmask_b32_e32 v20, 0, v191, vcc
	v_sub_f32_e32 v16, v16, v20
	v_add_f32_e32 v16, v17, v16
	v_sub_f32_e32 v16, -0.5, v16
	v_mul_f32_e32 v16, 0x3fb8aa3b, v16
	v_exp_f32_e32 v16, v16
	s_nop 0
	v_mul_f32_e32 v16, 0xbfb8aa3b, v16
	v_exp_f32_e32 v16, v16
	global_store_dword v[52:53], v16, off offset:1152
	v_add_f32_e32 v16, v18, v32
	v_max_f32_e64 v17, -v16, 0
	v_mul_f32_e64 v16, |v16|, s5
	v_exp_f32_e32 v16, v16
	s_nop 0
	v_add_f32_e32 v16, 1.0, v16
	v_cmp_gt_f32_e32 vcc, s85, v16
	s_nop 1
	v_cndmask_b32_e64 v18, 0, 32, vcc
	v_ldexp_f32 v16, v16, v18
	v_log_f32_e32 v16, v16
	s_nop 0
	v_mul_f32_e32 v18, 0x3f317217, v16
	v_fma_f32 v18, v16, s9, -v18
	v_fmac_f32_e32 v18, 0x3377d1cf, v16
	v_fmac_f32_e32 v18, 0x3f317217, v16
	v_cmp_lt_f32_e64 s[34:35], |v16|, s8
	s_nop 1
	v_cndmask_b32_e64 v16, v16, v18, s[34:35]
	v_cndmask_b32_e32 v18, 0, v191, vcc
	v_sub_f32_e32 v16, v16, v18
	v_add_f32_e32 v16, v17, v16
	v_sub_f32_e32 v16, -0.5, v16
	v_mul_f32_e32 v16, 0x3fb8aa3b, v16
	v_exp_f32_e32 v16, v16
	s_nop 0
	v_mul_f32_e32 v16, 0xbfb8aa3b, v16
	v_exp_f32_e32 v16, v16
	global_store_dword v[52:53], v16, off offset:2176
	v_add_f32_e32 v16, v19, v32
	v_max_f32_e64 v17, -v16, 0
	v_mul_f32_e64 v16, |v16|, s5
	v_exp_f32_e32 v16, v16
	s_nop 0
	v_add_f32_e32 v16, 1.0, v16
	v_cmp_gt_f32_e32 vcc, s85, v16
	s_nop 1
	v_cndmask_b32_e64 v18, 0, 32, vcc
	v_ldexp_f32 v16, v16, v18
	v_log_f32_e32 v16, v16
	s_nop 0
	v_mul_f32_e32 v18, 0x3f317217, v16
	v_fma_f32 v18, v16, s9, -v18
	v_fmac_f32_e32 v18, 0x3377d1cf, v16
	v_fmac_f32_e32 v18, 0x3f317217, v16
	v_cmp_lt_f32_e64 s[34:35], |v16|, s8
	s_nop 1
	v_cndmask_b32_e64 v16, v16, v18, s[34:35]
	v_cndmask_b32_e32 v18, 0, v191, vcc
	v_sub_f32_e32 v16, v16, v18
	v_add_f32_e32 v16, v17, v16
	v_sub_f32_e32 v16, -0.5, v16
	v_mul_f32_e32 v16, 0x3fb8aa3b, v16
	v_exp_f32_e32 v16, v16
	s_nop 0
	v_mul_f32_e32 v16, 0xbfb8aa3b, v16
	v_exp_f32_e32 v16, v16
	global_store_dword v[52:53], v16, off offset:3200
	global_load_dword v16, v[48:49], off offset:192
	s_waitcnt vmcnt(0)
	v_add_f32_e32 v12, v12, v16
	v_max_f32_e64 v17, -v12, 0
	v_mul_f32_e64 v12, |v12|, s5
	v_exp_f32_e32 v12, v12
	v_add_f32_e32 v8, v8, v16
	v_add_f32_e32 v4, v4, v16
	v_add_f32_e32 v0, v0, v16
	v_add_f32_e32 v12, 1.0, v12
	v_cmp_gt_f32_e32 vcc, s85, v12
	s_nop 1
	v_cndmask_b32_e64 v18, 0, 32, vcc
	v_ldexp_f32 v12, v12, v18
	v_log_f32_e32 v12, v12
	s_nop 0
	v_mul_f32_e32 v18, 0x3f317217, v12
	v_fma_f32 v18, v12, s9, -v18
	v_fmac_f32_e32 v18, 0x3377d1cf, v12
	v_fmac_f32_e32 v18, 0x3f317217, v12
	v_cmp_lt_f32_e64 s[34:35], |v12|, s8
	s_nop 1
	v_cndmask_b32_e64 v12, v12, v18, s[34:35]
	v_cndmask_b32_e32 v18, 0, v191, vcc
	v_sub_f32_e32 v12, v12, v18
	v_add_f32_e32 v12, v17, v12
	v_sub_f32_e32 v12, -0.5, v12
	v_mul_f32_e32 v12, 0x3fb8aa3b, v12
	v_exp_f32_e32 v12, v12
	s_nop 0
	v_mul_f32_e32 v12, 0xbfb8aa3b, v12
	v_exp_f32_e32 v12, v12
	global_store_dword v[64:65], v12, off offset:192
	v_add_f32_e32 v12, v13, v16
	v_max_f32_e64 v13, -v12, 0
	v_mul_f32_e64 v12, |v12|, s5
	v_exp_f32_e32 v12, v12
	s_nop 0
	v_add_f32_e32 v12, 1.0, v12
	v_cmp_gt_f32_e32 vcc, s85, v12
	s_nop 1
	v_cndmask_b32_e64 v17, 0, 32, vcc
	v_ldexp_f32 v12, v12, v17
	v_log_f32_e32 v12, v12
	s_nop 0
	v_mul_f32_e32 v17, 0x3f317217, v12
	v_fma_f32 v17, v12, s9, -v17
	v_fmac_f32_e32 v17, 0x3377d1cf, v12
	v_fmac_f32_e32 v17, 0x3f317217, v12
	v_cmp_lt_f32_e64 s[34:35], |v12|, s8
	s_nop 1
	v_cndmask_b32_e64 v12, v12, v17, s[34:35]
	v_cndmask_b32_e32 v17, 0, v191, vcc
	v_sub_f32_e32 v12, v12, v17
	v_add_f32_e32 v12, v13, v12
	v_sub_f32_e32 v12, -0.5, v12
	v_mul_f32_e32 v12, 0x3fb8aa3b, v12
	v_exp_f32_e32 v12, v12
	s_nop 0
	v_mul_f32_e32 v12, 0xbfb8aa3b, v12
	v_exp_f32_e32 v12, v12
	global_store_dword v[64:65], v12, off offset:1216
	v_add_f32_e32 v12, v14, v16
	v_max_f32_e64 v13, -v12, 0
	v_mul_f32_e64 v12, |v12|, s5
	v_exp_f32_e32 v12, v12
	s_nop 0
	v_add_f32_e32 v12, 1.0, v12
	v_cmp_gt_f32_e32 vcc, s85, v12
	s_nop 1
	v_cndmask_b32_e64 v14, 0, 32, vcc
	v_ldexp_f32 v12, v12, v14
	v_log_f32_e32 v12, v12
	s_nop 0
	v_mul_f32_e32 v14, 0x3f317217, v12
	v_fma_f32 v14, v12, s9, -v14
	v_fmac_f32_e32 v14, 0x3377d1cf, v12
	v_fmac_f32_e32 v14, 0x3f317217, v12
	v_cmp_lt_f32_e64 s[34:35], |v12|, s8
	s_nop 1
	v_cndmask_b32_e64 v12, v12, v14, s[34:35]
	v_cndmask_b32_e32 v14, 0, v191, vcc
	v_sub_f32_e32 v12, v12, v14
	v_add_f32_e32 v12, v13, v12
	v_sub_f32_e32 v12, -0.5, v12
	v_mul_f32_e32 v12, 0x3fb8aa3b, v12
	v_exp_f32_e32 v12, v12
	s_nop 0
	v_mul_f32_e32 v12, 0xbfb8aa3b, v12
	v_exp_f32_e32 v12, v12
	global_store_dword v[64:65], v12, off offset:2240
	v_add_f32_e32 v12, v15, v16
	v_max_f32_e64 v13, -v12, 0
	v_mul_f32_e64 v12, |v12|, s5
	v_exp_f32_e32 v12, v12
	s_nop 0
	v_add_f32_e32 v12, 1.0, v12
	v_cmp_gt_f32_e32 vcc, s85, v12
	s_nop 1
	v_cndmask_b32_e64 v14, 0, 32, vcc
	v_ldexp_f32 v12, v12, v14
	v_log_f32_e32 v12, v12
	s_nop 0
	v_mul_f32_e32 v14, 0x3f317217, v12
	v_fma_f32 v14, v12, s9, -v14
	v_fmac_f32_e32 v14, 0x3377d1cf, v12
	v_fmac_f32_e32 v14, 0x3f317217, v12
	v_cmp_lt_f32_e64 s[34:35], |v12|, s8
	s_nop 1
	v_cndmask_b32_e64 v12, v12, v14, s[34:35]
	v_cndmask_b32_e32 v14, 0, v191, vcc
	v_sub_f32_e32 v12, v12, v14
	v_add_f32_e32 v12, v13, v12
	v_sub_f32_e32 v12, -0.5, v12
	v_mul_f32_e32 v12, 0x3fb8aa3b, v12
	v_exp_f32_e32 v12, v12
	s_nop 0
	v_mul_f32_e32 v12, 0xbfb8aa3b, v12
	v_exp_f32_e32 v12, v12
	global_store_dword v[64:65], v12, off offset:3264
	v_max_f32_e64 v12, -v8, 0
	v_mul_f32_e64 v8, |v8|, s5
	v_exp_f32_e32 v8, v8
	s_nop 0
	v_add_f32_e32 v8, 1.0, v8
	v_cmp_gt_f32_e32 vcc, s85, v8
	s_nop 1
	v_cndmask_b32_e64 v13, 0, 32, vcc
	v_ldexp_f32 v8, v8, v13
	v_log_f32_e32 v8, v8
	s_nop 0
	v_mul_f32_e32 v13, 0x3f317217, v8
	v_fma_f32 v13, v8, s9, -v13
	v_fmac_f32_e32 v13, 0x3377d1cf, v8
	v_fmac_f32_e32 v13, 0x3f317217, v8
	v_cmp_lt_f32_e64 s[34:35], |v8|, s8
	s_nop 1
	v_cndmask_b32_e64 v8, v8, v13, s[34:35]
	v_cndmask_b32_e32 v13, 0, v191, vcc
	v_sub_f32_e32 v8, v8, v13
	v_add_f32_e32 v8, v12, v8
	v_sub_f32_e32 v8, -0.5, v8
	v_mul_f32_e32 v8, 0x3fb8aa3b, v8
	v_exp_f32_e32 v8, v8
	s_nop 0
	v_mul_f32_e32 v8, 0xbfb8aa3b, v8
	v_exp_f32_e32 v8, v8
	global_store_dword v[60:61], v8, off offset:192
	v_add_f32_e32 v8, v9, v16
	v_max_f32_e64 v9, -v8, 0
	v_mul_f32_e64 v8, |v8|, s5
	v_exp_f32_e32 v8, v8
	s_nop 0
	v_add_f32_e32 v8, 1.0, v8
	v_cmp_gt_f32_e32 vcc, s85, v8
	s_nop 1
	v_cndmask_b32_e64 v12, 0, 32, vcc
	v_ldexp_f32 v8, v8, v12
	v_log_f32_e32 v8, v8
	s_nop 0
	v_mul_f32_e32 v12, 0x3f317217, v8
	v_fma_f32 v12, v8, s9, -v12
	v_fmac_f32_e32 v12, 0x3377d1cf, v8
	v_fmac_f32_e32 v12, 0x3f317217, v8
	v_cmp_lt_f32_e64 s[34:35], |v8|, s8
	s_nop 1
	v_cndmask_b32_e64 v8, v8, v12, s[34:35]
	v_cndmask_b32_e32 v12, 0, v191, vcc
	v_sub_f32_e32 v8, v8, v12
	v_add_f32_e32 v8, v9, v8
	v_sub_f32_e32 v8, -0.5, v8
	v_mul_f32_e32 v8, 0x3fb8aa3b, v8
	v_exp_f32_e32 v8, v8
	s_nop 0
	v_mul_f32_e32 v8, 0xbfb8aa3b, v8
	v_exp_f32_e32 v8, v8
	global_store_dword v[60:61], v8, off offset:1216
	v_add_f32_e32 v8, v10, v16
	v_max_f32_e64 v9, -v8, 0
	v_mul_f32_e64 v8, |v8|, s5
	v_exp_f32_e32 v8, v8
	s_nop 0
	v_add_f32_e32 v8, 1.0, v8
	v_cmp_gt_f32_e32 vcc, s85, v8
	s_nop 1
	v_cndmask_b32_e64 v10, 0, 32, vcc
	v_ldexp_f32 v8, v8, v10
	v_log_f32_e32 v8, v8
	s_nop 0
	v_mul_f32_e32 v10, 0x3f317217, v8
	v_fma_f32 v10, v8, s9, -v10
	v_fmac_f32_e32 v10, 0x3377d1cf, v8
	v_fmac_f32_e32 v10, 0x3f317217, v8
	v_cmp_lt_f32_e64 s[34:35], |v8|, s8
	s_nop 1
	v_cndmask_b32_e64 v8, v8, v10, s[34:35]
	v_cndmask_b32_e32 v10, 0, v191, vcc
	v_sub_f32_e32 v8, v8, v10
	v_add_f32_e32 v8, v9, v8
	v_sub_f32_e32 v8, -0.5, v8
	v_mul_f32_e32 v8, 0x3fb8aa3b, v8
	v_exp_f32_e32 v8, v8
	s_nop 0
	v_mul_f32_e32 v8, 0xbfb8aa3b, v8
	v_exp_f32_e32 v8, v8
	global_store_dword v[60:61], v8, off offset:2240
	v_add_f32_e32 v8, v11, v16
	v_max_f32_e64 v9, -v8, 0
	v_mul_f32_e64 v8, |v8|, s5
	v_exp_f32_e32 v8, v8
	s_nop 0
	v_add_f32_e32 v8, 1.0, v8
	v_cmp_gt_f32_e32 vcc, s85, v8
	s_nop 1
	v_cndmask_b32_e64 v10, 0, 32, vcc
	v_ldexp_f32 v8, v8, v10
	v_log_f32_e32 v8, v8
	s_nop 0
	v_mul_f32_e32 v10, 0x3f317217, v8
	v_fma_f32 v10, v8, s9, -v10
	v_fmac_f32_e32 v10, 0x3377d1cf, v8
	v_fmac_f32_e32 v10, 0x3f317217, v8
	v_cmp_lt_f32_e64 s[34:35], |v8|, s8
	s_nop 1
	v_cndmask_b32_e64 v8, v8, v10, s[34:35]
	v_cndmask_b32_e32 v10, 0, v191, vcc
	v_sub_f32_e32 v8, v8, v10
	v_add_f32_e32 v8, v9, v8
	v_sub_f32_e32 v8, -0.5, v8
	v_mul_f32_e32 v8, 0x3fb8aa3b, v8
	v_exp_f32_e32 v8, v8
	s_nop 0
	v_mul_f32_e32 v8, 0xbfb8aa3b, v8
	v_exp_f32_e32 v8, v8
	global_store_dword v[60:61], v8, off offset:3264
	v_max_f32_e64 v8, -v4, 0
	v_mul_f32_e64 v4, |v4|, s5
	v_exp_f32_e32 v4, v4
	s_nop 0
	v_add_f32_e32 v4, 1.0, v4
	v_cmp_gt_f32_e32 vcc, s85, v4
	s_nop 1
	v_cndmask_b32_e64 v9, 0, 32, vcc
	v_ldexp_f32 v4, v4, v9
	v_log_f32_e32 v4, v4
	s_nop 0
	v_mul_f32_e32 v9, 0x3f317217, v4
	v_fma_f32 v9, v4, s9, -v9
	v_fmac_f32_e32 v9, 0x3377d1cf, v4
	v_fmac_f32_e32 v9, 0x3f317217, v4
	v_cmp_lt_f32_e64 s[34:35], |v4|, s8
	s_nop 1
	v_cndmask_b32_e64 v4, v4, v9, s[34:35]
	v_cndmask_b32_e32 v9, 0, v191, vcc
	v_sub_f32_e32 v4, v4, v9
	v_add_f32_e32 v4, v8, v4
	v_sub_f32_e32 v4, -0.5, v4
	v_mul_f32_e32 v4, 0x3fb8aa3b, v4
	v_exp_f32_e32 v4, v4
	s_nop 0
	v_mul_f32_e32 v4, 0xbfb8aa3b, v4
	v_exp_f32_e32 v4, v4
	global_store_dword v[56:57], v4, off offset:192
	v_add_f32_e32 v4, v5, v16
	v_max_f32_e64 v5, -v4, 0
	v_mul_f32_e64 v4, |v4|, s5
	v_exp_f32_e32 v4, v4
	s_nop 0
	v_add_f32_e32 v4, 1.0, v4
	v_cmp_gt_f32_e32 vcc, s85, v4
	s_nop 1
	v_cndmask_b32_e64 v8, 0, 32, vcc
	v_ldexp_f32 v4, v4, v8
	v_log_f32_e32 v4, v4
	s_nop 0
	v_mul_f32_e32 v8, 0x3f317217, v4
	v_fma_f32 v8, v4, s9, -v8
	v_fmac_f32_e32 v8, 0x3377d1cf, v4
	v_fmac_f32_e32 v8, 0x3f317217, v4
	v_cmp_lt_f32_e64 s[34:35], |v4|, s8
	s_nop 1
	v_cndmask_b32_e64 v4, v4, v8, s[34:35]
	v_cndmask_b32_e32 v8, 0, v191, vcc
	v_sub_f32_e32 v4, v4, v8
	v_add_f32_e32 v4, v5, v4
	v_sub_f32_e32 v4, -0.5, v4
	v_mul_f32_e32 v4, 0x3fb8aa3b, v4
	v_exp_f32_e32 v4, v4
	s_nop 0
	v_mul_f32_e32 v4, 0xbfb8aa3b, v4
	v_exp_f32_e32 v4, v4
	global_store_dword v[56:57], v4, off offset:1216
	v_add_f32_e32 v4, v6, v16
	v_max_f32_e64 v5, -v4, 0
	v_mul_f32_e64 v4, |v4|, s5
	v_exp_f32_e32 v4, v4
	s_nop 0
	v_add_f32_e32 v4, 1.0, v4
	v_cmp_gt_f32_e32 vcc, s85, v4
	s_nop 1
	v_cndmask_b32_e64 v6, 0, 32, vcc
	v_ldexp_f32 v4, v4, v6
	v_log_f32_e32 v4, v4
	s_nop 0
	v_mul_f32_e32 v6, 0x3f317217, v4
	v_fma_f32 v6, v4, s9, -v6
	v_fmac_f32_e32 v6, 0x3377d1cf, v4
	v_fmac_f32_e32 v6, 0x3f317217, v4
	v_cmp_lt_f32_e64 s[34:35], |v4|, s8
	s_nop 1
	v_cndmask_b32_e64 v4, v4, v6, s[34:35]
	v_cndmask_b32_e32 v6, 0, v191, vcc
	v_sub_f32_e32 v4, v4, v6
	v_add_f32_e32 v4, v5, v4
	v_sub_f32_e32 v4, -0.5, v4
	v_mul_f32_e32 v4, 0x3fb8aa3b, v4
	v_exp_f32_e32 v4, v4
	s_nop 0
	v_mul_f32_e32 v4, 0xbfb8aa3b, v4
	v_exp_f32_e32 v4, v4
	global_store_dword v[56:57], v4, off offset:2240
	v_add_f32_e32 v4, v7, v16
	v_max_f32_e64 v5, -v4, 0
	v_mul_f32_e64 v4, |v4|, s5
	v_exp_f32_e32 v4, v4
	s_nop 0
	v_add_f32_e32 v4, 1.0, v4
	v_cmp_gt_f32_e32 vcc, s85, v4
	s_nop 1
	v_cndmask_b32_e64 v6, 0, 32, vcc
	v_ldexp_f32 v4, v4, v6
	v_log_f32_e32 v4, v4
	s_nop 0
	v_mul_f32_e32 v6, 0x3f317217, v4
	v_fma_f32 v6, v4, s9, -v6
	v_fmac_f32_e32 v6, 0x3377d1cf, v4
	v_fmac_f32_e32 v6, 0x3f317217, v4
	v_cmp_lt_f32_e64 s[34:35], |v4|, s8
	s_nop 1
	v_cndmask_b32_e64 v4, v4, v6, s[34:35]
	v_cndmask_b32_e32 v6, 0, v191, vcc
	v_sub_f32_e32 v4, v4, v6
	v_add_f32_e32 v4, v5, v4
	v_sub_f32_e32 v4, -0.5, v4
	v_mul_f32_e32 v4, 0x3fb8aa3b, v4
	v_exp_f32_e32 v4, v4
	s_nop 0
	v_mul_f32_e32 v4, 0xbfb8aa3b, v4
	v_exp_f32_e32 v4, v4
	global_store_dword v[56:57], v4, off offset:3264
	v_max_f32_e64 v4, -v0, 0
	v_mul_f32_e64 v0, |v0|, s5
	v_exp_f32_e32 v0, v0
	s_nop 0
	v_add_f32_e32 v0, 1.0, v0
	v_cmp_gt_f32_e32 vcc, s85, v0
	s_nop 1
	v_cndmask_b32_e64 v5, 0, 32, vcc
	v_ldexp_f32 v0, v0, v5
	v_log_f32_e32 v0, v0
	s_nop 0
	v_mul_f32_e32 v5, 0x3f317217, v0
	v_fma_f32 v5, v0, s9, -v5
	v_fmac_f32_e32 v5, 0x3377d1cf, v0
	v_fmac_f32_e32 v5, 0x3f317217, v0
	v_cmp_lt_f32_e64 s[34:35], |v0|, s8
	s_nop 1
	v_cndmask_b32_e64 v0, v0, v5, s[34:35]
	v_cndmask_b32_e32 v5, 0, v191, vcc
	v_sub_f32_e32 v0, v0, v5
	v_add_f32_e32 v0, v4, v0
	v_sub_f32_e32 v0, -0.5, v0
	v_mul_f32_e32 v0, 0x3fb8aa3b, v0
	v_exp_f32_e32 v0, v0
	s_nop 0
	v_mul_f32_e32 v0, 0xbfb8aa3b, v0
	v_exp_f32_e32 v0, v0
	global_store_dword v[52:53], v0, off offset:192
	v_add_f32_e32 v0, v1, v16
	v_max_f32_e64 v1, -v0, 0
	v_mul_f32_e64 v0, |v0|, s5
	v_exp_f32_e32 v0, v0
	s_nop 0
	v_add_f32_e32 v0, 1.0, v0
	v_cmp_gt_f32_e32 vcc, s85, v0
	s_nop 1
	v_cndmask_b32_e64 v4, 0, 32, vcc
	v_ldexp_f32 v0, v0, v4
	v_log_f32_e32 v0, v0
	s_nop 0
	v_mul_f32_e32 v4, 0x3f317217, v0
	v_fma_f32 v4, v0, s9, -v4
	v_fmac_f32_e32 v4, 0x3377d1cf, v0
	v_fmac_f32_e32 v4, 0x3f317217, v0
	v_cmp_lt_f32_e64 s[34:35], |v0|, s8
	s_nop 1
	v_cndmask_b32_e64 v0, v0, v4, s[34:35]
	v_cndmask_b32_e32 v4, 0, v191, vcc
	v_sub_f32_e32 v0, v0, v4
	v_add_f32_e32 v0, v1, v0
	v_sub_f32_e32 v0, -0.5, v0
	v_mul_f32_e32 v0, 0x3fb8aa3b, v0
	v_exp_f32_e32 v0, v0
	s_nop 0
	v_mul_f32_e32 v0, 0xbfb8aa3b, v0
	v_exp_f32_e32 v0, v0
	global_store_dword v[52:53], v0, off offset:1216
	v_add_f32_e32 v0, v2, v16
	v_max_f32_e64 v1, -v0, 0
	v_mul_f32_e64 v0, |v0|, s5
	v_exp_f32_e32 v0, v0
	s_nop 0
	v_add_f32_e32 v0, 1.0, v0
	v_cmp_gt_f32_e32 vcc, s85, v0
	s_nop 1
	v_cndmask_b32_e64 v2, 0, 32, vcc
	v_ldexp_f32 v0, v0, v2
	v_log_f32_e32 v0, v0
	s_nop 0
	v_mul_f32_e32 v2, 0x3f317217, v0
	v_fma_f32 v2, v0, s9, -v2
	v_fmac_f32_e32 v2, 0x3377d1cf, v0
	v_fmac_f32_e32 v2, 0x3f317217, v0
	v_cmp_lt_f32_e64 s[34:35], |v0|, s8
	s_nop 1
	v_cndmask_b32_e64 v0, v0, v2, s[34:35]
	v_cndmask_b32_e32 v2, 0, v191, vcc
	v_sub_f32_e32 v0, v0, v2
	v_add_f32_e32 v0, v1, v0
	v_sub_f32_e32 v0, -0.5, v0
	v_mul_f32_e32 v0, 0x3fb8aa3b, v0
	v_exp_f32_e32 v0, v0
	s_nop 0
	v_mul_f32_e32 v0, 0xbfb8aa3b, v0
	v_exp_f32_e32 v0, v0
	global_store_dword v[52:53], v0, off offset:2240
	v_add_f32_e32 v0, v3, v16
	v_max_f32_e64 v1, -v0, 0
	v_mul_f32_e64 v0, |v0|, s5
	v_exp_f32_e32 v0, v0
	s_nop 0
	v_add_f32_e32 v0, 1.0, v0
	v_cmp_gt_f32_e32 vcc, s85, v0
	s_nop 1
	v_cndmask_b32_e64 v2, 0, 32, vcc
	v_ldexp_f32 v0, v0, v2
	v_log_f32_e32 v0, v0
	s_nop 0
	v_mul_f32_e32 v2, 0x3f317217, v0
	v_fma_f32 v2, v0, s9, -v2
	v_fmac_f32_e32 v2, 0x3377d1cf, v0
	v_fmac_f32_e32 v2, 0x3f317217, v0
	v_cmp_lt_f32_e64 s[34:35], |v0|, s8
	s_nop 1
	v_cndmask_b32_e64 v0, v0, v2, s[34:35]
	v_cndmask_b32_e32 v2, 0, v191, vcc
	v_sub_f32_e32 v0, v0, v2
	v_add_f32_e32 v0, v1, v0
	v_sub_f32_e32 v0, -0.5, v0
	v_mul_f32_e32 v0, 0x3fb8aa3b, v0
	v_exp_f32_e32 v0, v0
	s_nop 0
	v_mul_f32_e32 v0, 0xbfb8aa3b, v0
	v_exp_f32_e32 v0, v0
	global_store_dword v[52:53], v0, off offset:3264

.LBB0_812:
	s_and_b32 s47, s46, 0x8000
	s_xor_b32 s57, s47, 0x8000
	v_add_u32_e32 v86, s57, v72
	v_lshl_add_u64 v[78:79], v[66:67], 0, s[34:35]
	v_add_u32_e32 v87, 0x4000, v86
	v_readfirstlane_b32 s57, v86
	v_lshl_add_u64 v[80:81], v[78:79], 0, s[28:29]
	v_lshl_add_u64 v[82:83], v[64:65], 0, s[34:35]
	s_mov_b32 m0, s57
	v_readfirstlane_b32 s57, v87
	v_lshl_add_u64 v[84:85], v[82:83], 0, s[28:29]
	global_load_lds_dwordx4 v[80:81], off
	s_mov_b32 m0, s57
	v_lshl_add_u64 v[80:81], v[78:79], 0, s[30:31]
	global_load_lds_dwordx4 v[84:85], off
	v_add_u32_e32 v84, 0x1000, v86
	v_add3_u32 v110, s47, v74, v75
	v_readfirstlane_b32 s57, v84
	v_add_u32_e32 v84, 0x5000, v86
	s_mov_b32 m0, s57
	v_readfirstlane_b32 s57, v84
	v_add_u32_e32 v84, 0x2000, v86
	global_load_lds_dwordx4 v[80:81], off
	v_lshl_add_u64 v[80:81], v[82:83], 0, s[30:31]
	s_mov_b32 m0, s57
	v_readfirstlane_b32 s57, v84
	v_add_u32_e32 v84, 0x6000, v86
	global_load_lds_dwordx4 v[80:81], off
	v_lshl_add_u64 v[80:81], v[78:79], 0, s[0:1]
	s_mov_b32 m0, s57
	v_readfirstlane_b32 s57, v84
	global_load_lds_dwordx4 v[80:81], off
	v_lshl_add_u64 v[80:81], v[82:83], 0, s[0:1]
	s_mov_b32 m0, s57
	v_lshl_add_u64 v[78:79], v[78:79], 0, s[22:23]
	global_load_lds_dwordx4 v[80:81], off
	v_add_u32_e32 v80, 0x3000, v86
	v_add_u32_e32 v98, v110, v76
	v_readfirstlane_b32 s57, v80
	v_add_u32_e32 v80, 0x7000, v86
	s_mov_b32 m0, s57
	v_readfirstlane_b32 s57, v80
	global_load_lds_dwordx4 v[78:79], off
	v_lshl_add_u64 v[78:79], v[82:83], 0, s[22:23]
	s_mov_b32 m0, s57
	s_nop 0
	global_load_lds_dwordx4 v[78:79], off
	v_or_b32_e32 v78, s47, v77
	v_add_u32_e32 v111, v78, v75
	v_add_u32_e32 v106, v111, v76
	ds_read_b128 v[78:81], v98
	ds_read_b128 v[82:85], v98 offset:2048
	ds_read_b128 v[86:89], v106 offset:16384
	ds_read_b128 v[90:93], v106 offset:18432
	ds_read_b128 v[94:97], v98 offset:4096
	ds_read_b128 v[98:101], v98 offset:6144
	ds_read_b128 v[102:105], v106 offset:20480
	ds_read_b128 v[106:109], v106 offset:22528
	s_setprio 1
	s_waitcnt lgkmcnt(0)
	v_mfma_f32_16x16x32_bf16 v[60:63], v[78:81], v[86:89], v[60:63]
	v_mfma_f32_16x16x32_bf16 v[56:59], v[78:81], v[90:93], v[56:59]
	v_mfma_f32_16x16x32_bf16 v[52:55], v[78:81], v[102:105], v[52:55]
	v_mfma_f32_16x16x32_bf16 v[48:51], v[78:81], v[106:109], v[48:51]
	v_mfma_f32_16x16x32_bf16 v[44:47], v[82:85], v[86:89], v[44:47]
	v_mfma_f32_16x16x32_bf16 v[40:43], v[82:85], v[90:93], v[40:43]
	v_mfma_f32_16x16x32_bf16 v[36:39], v[82:85], v[102:105], v[36:39]
	v_mfma_f32_16x16x32_bf16 v[32:35], v[82:85], v[106:109], v[32:35]
	v_mfma_f32_16x16x32_bf16 v[28:31], v[94:97], v[86:89], v[28:31]
	v_mfma_f32_16x16x32_bf16 v[24:27], v[94:97], v[90:93], v[24:27]
	v_mfma_f32_16x16x32_bf16 v[20:23], v[94:97], v[102:105], v[20:23]
	v_mfma_f32_16x16x32_bf16 v[16:19], v[94:97], v[106:109], v[16:19]
	v_mfma_f32_16x16x32_bf16 v[12:15], v[98:101], v[86:89], v[12:15]
	v_mfma_f32_16x16x32_bf16 v[8:11], v[98:101], v[90:93], v[8:11]
	v_mfma_f32_16x16x32_bf16 v[4:7], v[98:101], v[102:105], v[4:7]
	v_mfma_f32_16x16x32_bf16 v[0:3], v[98:101], v[106:109], v[0:3]
	s_setprio 0
	v_add_u32_e32 v98, v110, v73
	v_add_u32_e32 v106, v111, v73
	ds_read_b128 v[78:81], v98
	ds_read_b128 v[82:85], v98 offset:2048
	ds_read_b128 v[86:89], v106 offset:16384
	ds_read_b128 v[90:93], v106 offset:18432
	ds_read_b128 v[94:97], v98 offset:4096
	ds_read_b128 v[98:101], v98 offset:6144
	ds_read_b128 v[102:105], v106 offset:20480
	ds_read_b128 v[106:109], v106 offset:22528
	s_setprio 1
	s_waitcnt lgkmcnt(5)
	v_mfma_f32_16x16x32_bf16 v[60:63], v[78:81], v[86:89], v[60:63]
	s_waitcnt lgkmcnt(4)
	v_mfma_f32_16x16x32_bf16 v[56:59], v[78:81], v[90:93], v[56:59]
	s_waitcnt lgkmcnt(1)
	v_mfma_f32_16x16x32_bf16 v[52:55], v[78:81], v[102:105], v[52:55]
	s_waitcnt lgkmcnt(0)
	v_mfma_f32_16x16x32_bf16 v[48:51], v[78:81], v[106:109], v[48:51]
	v_mfma_f32_16x16x32_bf16 v[44:47], v[82:85], v[86:89], v[44:47]
	v_mfma_f32_16x16x32_bf16 v[40:43], v[82:85], v[90:93], v[40:43]
	v_mfma_f32_16x16x32_bf16 v[36:39], v[82:85], v[102:105], v[36:39]
	v_mfma_f32_16x16x32_bf16 v[32:35], v[82:85], v[106:109], v[32:35]
	v_mfma_f32_16x16x32_bf16 v[28:31], v[94:97], v[86:89], v[28:31]
	v_mfma_f32_16x16x32_bf16 v[24:27], v[94:97], v[90:93], v[24:27]
	v_mfma_f32_16x16x32_bf16 v[20:23], v[94:97], v[102:105], v[20:23]
	v_mfma_f32_16x16x32_bf16 v[16:19], v[94:97], v[106:109], v[16:19]
	v_mfma_f32_16x16x32_bf16 v[12:15], v[98:101], v[86:89], v[12:15]
	v_mfma_f32_16x16x32_bf16 v[8:11], v[98:101], v[90:93], v[8:11]
	v_mfma_f32_16x16x32_bf16 v[4:7], v[98:101], v[102:105], v[4:7]
	v_mfma_f32_16x16x32_bf16 v[0:3], v[98:101], v[106:109], v[0:3]
	s_setprio 0
	s_add_i32 s46, s46, 0x8000
	s_waitcnt vmcnt(0)
	s_add_u32 s34, s34, 0x80
	s_addc_u32 s35, s35, 0
	s_cmpk_eq_i32 s34, 0x780
	s_barrier
	s_cbranch_scc0 .LBB0_812
	v_add_u32_e32 v72, v77, v75
	v_add_u32_e32 v102, v74, v75
	v_add_u32_e32 v90, v72, v76
	v_add_u32_e32 v98, v102, v76
	ds_read_b128 v[64:67], v90 offset:55296
	ds_read_b128 v[74:77], v90 offset:53248
	ds_read_b128 v[78:81], v98 offset:38912
	ds_read_b128 v[82:85], v98 offset:36864
	ds_read_b128 v[86:89], v90 offset:51200
	ds_read_b128 v[90:93], v90 offset:49152
	ds_read_b128 v[94:97], v98 offset:34816
	ds_read_b128 v[98:101], v98 offset:32768
	s_setprio 1
	s_waitcnt lgkmcnt(0)
	v_mfma_f32_16x16x32_bf16 v[60:63], v[98:101], v[90:93], v[60:63]
	v_mfma_f32_16x16x32_bf16 v[56:59], v[98:101], v[86:89], v[56:59]
	v_mfma_f32_16x16x32_bf16 v[52:55], v[98:101], v[74:77], v[52:55]
	v_mfma_f32_16x16x32_bf16 v[48:51], v[98:101], v[64:67], v[48:51]
	v_mfma_f32_16x16x32_bf16 v[44:47], v[94:97], v[90:93], v[44:47]
	v_mfma_f32_16x16x32_bf16 v[40:43], v[94:97], v[86:89], v[40:43]
	v_mfma_f32_16x16x32_bf16 v[36:39], v[94:97], v[74:77], v[36:39]
	v_mfma_f32_16x16x32_bf16 v[32:35], v[94:97], v[64:67], v[32:35]
	v_mfma_f32_16x16x32_bf16 v[28:31], v[82:85], v[90:93], v[28:31]
	v_mfma_f32_16x16x32_bf16 v[24:27], v[82:85], v[86:89], v[24:27]
	v_mfma_f32_16x16x32_bf16 v[20:23], v[82:85], v[74:77], v[20:23]
	v_mfma_f32_16x16x32_bf16 v[16:19], v[82:85], v[64:67], v[16:19]
	v_mfma_f32_16x16x32_bf16 v[12:15], v[78:81], v[90:93], v[12:15]
	v_mfma_f32_16x16x32_bf16 v[8:11], v[78:81], v[86:89], v[8:11]
	v_mfma_f32_16x16x32_bf16 v[4:7], v[78:81], v[74:77], v[4:7]
	v_mfma_f32_16x16x32_bf16 v[0:3], v[78:81], v[64:67], v[0:3]
	s_setprio 0
	v_add_u32_e32 v88, v102, v73
	v_add_u32_e32 v96, v72, v73
	ds_read_b128 v[64:67], v88 offset:32768
	ds_read_b128 v[72:75], v88 offset:34816
	ds_read_b128 v[76:79], v96 offset:49152
	ds_read_b128 v[80:83], v96 offset:51200
	ds_read_b128 v[84:87], v88 offset:36864
	ds_read_b128 v[88:91], v88 offset:38912
	ds_read_b128 v[92:95], v96 offset:53248
	ds_read_b128 v[96:99], v96 offset:55296
	s_setprio 1
	s_waitcnt lgkmcnt(5)
	v_mfma_f32_16x16x32_bf16 v[60:63], v[64:67], v[76:79], v[60:63]
	s_waitcnt lgkmcnt(4)
	v_mfma_f32_16x16x32_bf16 v[56:59], v[64:67], v[80:83], v[56:59]
	s_waitcnt lgkmcnt(1)
	v_mfma_f32_16x16x32_bf16 v[52:55], v[64:67], v[92:95], v[52:55]
	s_waitcnt lgkmcnt(0)
	v_mfma_f32_16x16x32_bf16 v[48:51], v[64:67], v[96:99], v[48:51]
	v_mfma_f32_16x16x32_bf16 v[44:47], v[72:75], v[76:79], v[44:47]
	v_mfma_f32_16x16x32_bf16 v[40:43], v[72:75], v[80:83], v[40:43]
	v_mfma_f32_16x16x32_bf16 v[36:39], v[72:75], v[92:95], v[36:39]
	v_mfma_f32_16x16x32_bf16 v[32:35], v[72:75], v[96:99], v[32:35]
	v_mfma_f32_16x16x32_bf16 v[28:31], v[84:87], v[76:79], v[28:31]
	v_mfma_f32_16x16x32_bf16 v[24:27], v[84:87], v[80:83], v[24:27]
	v_mfma_f32_16x16x32_bf16 v[20:23], v[84:87], v[92:95], v[20:23]
	v_mfma_f32_16x16x32_bf16 v[16:19], v[84:87], v[96:99], v[16:19]
	v_mfma_f32_16x16x32_bf16 v[12:15], v[88:91], v[76:79], v[12:15]
	v_mfma_f32_16x16x32_bf16 v[8:11], v[88:91], v[80:83], v[8:11]
	v_mfma_f32_16x16x32_bf16 v[4:7], v[88:91], v[92:95], v[4:7]
	v_mfma_f32_16x16x32_bf16 v[0:3], v[88:91], v[96:99], v[0:3]
	s_setprio 0
	v_lshl_add_u32 v64, v70, 6, s37
	v_lshl_or_b32 v66, v71, 2, v64
	v_lshlrev_b32_e32 v64, 6, v68
	v_or3_b32 v128, v64, s36, v69
	v_lshl_add_u64 v[64:65], v[128:129], 2, s[60:61]
	v_mad_i64_i32 v[68:69], s[34:35], v66, s65, v[64:65]
	v_or_b32_e32 v82, 1, v66
	s_waitcnt vmcnt(0)
	s_barrier
	global_store_dword v[68:69], v60, off
	global_store_dword v[68:69], v56, off offset:64
	global_store_dword v[68:69], v52, off offset:128
	global_store_dword v[68:69], v48, off offset:192
	v_mad_i64_i32 v[68:69], s[34:35], v82, s65, v[64:65]
	v_or_b32_e32 v81, 2, v66
	global_store_dword v[68:69], v61, off
	global_store_dword v[68:69], v57, off offset:64
	global_store_dword v[68:69], v53, off offset:128
	global_store_dword v[68:69], v49, off offset:192
	v_mad_i64_i32 v[68:69], s[34:35], v81, s65, v[64:65]
	v_or_b32_e32 v80, 3, v66
	global_store_dword v[68:69], v62, off
	global_store_dword v[68:69], v58, off offset:64
	global_store_dword v[68:69], v54, off offset:128
	global_store_dword v[68:69], v50, off offset:192
	v_mad_i64_i32 v[68:69], s[34:35], v80, s65, v[64:65]
	global_store_dword v[68:69], v63, off
	global_store_dword v[68:69], v59, off offset:64
	global_store_dword v[68:69], v55, off offset:128
	global_store_dword v[68:69], v51, off offset:192
	v_or_b32_e32 v79, 16, v66
	v_mad_i64_i32 v[68:69], s[34:35], v79, s65, v[64:65]
	v_or_b32_e32 v78, 17, v66
	global_store_dword v[68:69], v44, off
	global_store_dword v[68:69], v40, off offset:64
	global_store_dword v[68:69], v36, off offset:128
	global_store_dword v[68:69], v32, off offset:192
	v_mad_i64_i32 v[68:69], s[34:35], v78, s65, v[64:65]
	v_or_b32_e32 v77, 18, v66
	global_store_dword v[68:69], v45, off
	global_store_dword v[68:69], v41, off offset:64
	global_store_dword v[68:69], v37, off offset:128
	global_store_dword v[68:69], v33, off offset:192
	v_mad_i64_i32 v[68:69], s[34:35], v77, s65, v[64:65]
	v_or_b32_e32 v76, 19, v66
	global_store_dword v[68:69], v46, off
	global_store_dword v[68:69], v42, off offset:64
	global_store_dword v[68:69], v38, off offset:128
	global_store_dword v[68:69], v34, off offset:192
	v_mad_i64_i32 v[68:69], s[34:35], v76, s65, v[64:65]
	global_store_dword v[68:69], v47, off
	global_store_dword v[68:69], v43, off offset:64
	global_store_dword v[68:69], v39, off offset:128
	global_store_dword v[68:69], v35, off offset:192
	v_or_b32_e32 v75, 32, v66
	v_mad_i64_i32 v[68:69], s[34:35], v75, s65, v[64:65]
	v_or_b32_e32 v74, 33, v66
	global_store_dword v[68:69], v28, off
	global_store_dword v[68:69], v24, off offset:64
	global_store_dword v[68:69], v20, off offset:128
	global_store_dword v[68:69], v16, off offset:192
	v_mad_i64_i32 v[68:69], s[34:35], v74, s65, v[64:65]
	v_or_b32_e32 v73, 34, v66
	global_store_dword v[68:69], v29, off
	global_store_dword v[68:69], v25, off offset:64
	global_store_dword v[68:69], v21, off offset:128
	global_store_dword v[68:69], v17, off offset:192
	v_mad_i64_i32 v[68:69], s[34:35], v73, s65, v[64:65]
	v_or_b32_e32 v72, 35, v66
	global_store_dword v[68:69], v30, off
	global_store_dword v[68:69], v26, off offset:64
	global_store_dword v[68:69], v22, off offset:128
	global_store_dword v[68:69], v18, off offset:192
	v_mad_i64_i32 v[68:69], s[34:35], v72, s65, v[64:65]
	global_store_dword v[68:69], v31, off
	global_store_dword v[68:69], v27, off offset:64
	global_store_dword v[68:69], v23, off offset:128
	global_store_dword v[68:69], v19, off offset:192
	v_or_b32_e32 v71, 48, v66
	v_mad_i64_i32 v[68:69], s[34:35], v71, s65, v[64:65]
	v_or_b32_e32 v70, 49, v66
	global_store_dword v[68:69], v12, off
	global_store_dword v[68:69], v8, off offset:64
	global_store_dword v[68:69], v4, off offset:128
	global_store_dword v[68:69], v0, off offset:192
	v_mad_i64_i32 v[68:69], s[34:35], v70, s65, v[64:65]
	global_store_dword v[68:69], v13, off
	global_store_dword v[68:69], v9, off offset:64
	global_store_dword v[68:69], v5, off offset:128
	global_store_dword v[68:69], v1, off offset:192
	v_or_b32_e32 v69, 50, v66
	v_or_b32_e32 v68, 51, v66
	v_mad_i64_i32 v[84:85], s[34:35], v69, s65, v[64:65]
	v_mad_i64_i32 v[64:65], s[34:35], v68, s65, v[64:65]
	global_store_dword v[84:85], v14, off
	global_store_dword v[84:85], v10, off offset:64
	global_store_dword v[84:85], v6, off offset:128
	global_store_dword v[84:85], v2, off offset:192
	global_store_dword v[64:65], v15, off
	global_store_dword v[64:65], v11, off offset:64
	global_store_dword v[64:65], v7, off offset:128
	global_store_dword v[64:65], v3, off offset:192
	s_addk_i32 s36, 0xfd00
	s_cmpk_lt_u32 s36, 0x180
	s_cbranch_scc0 .LBB0_809
	s_cmp_lg_u32 s36, 0
	s_cselect_b64 s[46:47], -1, 0
	s_cmpk_eq_i32 s36, 0x100
	s_cselect_b64 s[34:35], -1, 0
	v_cndmask_b32_e64 v64, 0, 1, s[34:35]
	s_and_b64 vcc, exec, s[46:47]
	v_cmp_ne_u32_e64 s[34:35], 1, v64
	s_cbranch_vccz .LBB0_1133
	s_and_b64 vcc, exec, s[34:35]
	v_mov_b32_e32 v83, v60
	s_cbranch_vccnz .LBB0_817
	v_mul_f32_e32 v64, 0xbfb8aa3b, v60
	v_exp_f32_e32 v64, v64
	s_nop 0
	v_add_f32_e32 v64, 1.0, v64
	v_div_scale_f32 v65, s[36:37], v64, v64, 1.0
	v_rcp_f32_e32 v67, v65
	v_div_scale_f32 v83, vcc, 1.0, v64, 1.0
	v_fma_f32 v84, -v65, v67, 1.0
	v_fmac_f32_e32 v67, v84, v67
	v_mul_f32_e32 v84, v83, v67
	v_fma_f32 v85, -v65, v84, v83
	v_fmac_f32_e32 v84, v85, v67
	v_fma_f32 v65, -v65, v84, v83
	v_div_fmas_f32 v65, v65, v67, v84
	v_div_fixup_f32 v83, v65, v64, 1.0

.LBB0_1217:
	s_and_b32 s58, s57, 0x8000
	s_xor_b32 s59, s58, 0x8000
	v_add_u32_e32 v160, s59, v147
	v_lshl_add_u64 v[152:153], v[72:73], 0, s[44:45]
	v_add_u32_e32 v161, 0x4000, v160
	v_readfirstlane_b32 s59, v160
	v_lshl_add_u64 v[154:155], v[152:153], 0, s[28:29]
	v_lshl_add_u64 v[156:157], v[70:71], 0, s[44:45]
	s_mov_b32 m0, s59
	v_readfirstlane_b32 s59, v161
	v_lshl_add_u64 v[158:159], v[156:157], 0, s[28:29]
	global_load_lds_dwordx4 v[154:155], off
	s_mov_b32 m0, s59
	v_lshl_add_u64 v[154:155], v[152:153], 0, s[42:43]
	global_load_lds_dwordx4 v[158:159], off
	v_add_u32_e32 v158, 0x1000, v160
	v_add_u32_e32 v168, s58, v148
	v_readfirstlane_b32 s59, v158
	v_add_u32_e32 v158, 0x5000, v160
	s_mov_b32 m0, s59
	v_readfirstlane_b32 s59, v158
	v_add_u32_e32 v158, 0x2000, v160
	global_load_lds_dwordx4 v[154:155], off
	v_lshl_add_u64 v[154:155], v[156:157], 0, s[42:43]
	s_mov_b32 m0, s59
	v_readfirstlane_b32 s59, v158
	v_add_u32_e32 v158, 0x6000, v160
	global_load_lds_dwordx4 v[154:155], off
	v_lshl_add_u64 v[154:155], v[152:153], 0, s[82:83]
	s_mov_b32 m0, s59
	v_readfirstlane_b32 s59, v158
	global_load_lds_dwordx4 v[154:155], off
	v_lshl_add_u64 v[154:155], v[156:157], 0, s[82:83]
	s_mov_b32 m0, s59
	v_lshl_add_u64 v[152:153], v[152:153], 0, s[86:87]
	global_load_lds_dwordx4 v[154:155], off
	v_add_u32_e32 v154, 0x3000, v160
	v_or_b32_e32 v169, s58, v149
	v_readfirstlane_b32 s59, v154
	v_add_u32_e32 v154, 0x7000, v160
	s_mov_b32 m0, s59
	v_readfirstlane_b32 s59, v154
	global_load_lds_dwordx4 v[152:153], off
	v_lshl_add_u64 v[152:153], v[156:157], 0, s[86:87]
	s_mov_b32 m0, s59
	v_add_u32_e32 v201, v168, v151
	global_load_lds_dwordx4 v[152:153], off
	v_add_u32_e32 v214, v169, v151
	ds_read_b128 v[152:155], v201
	ds_read_b128 v[156:159], v201 offset:2048
	ds_read_b128 v[160:163], v214 offset:16384
	ds_read_b128 v[164:167], v214 offset:18432
	ds_read_b128 v[202:205], v201 offset:4096
	ds_read_b128 v[206:209], v201 offset:6144
	ds_read_b128 v[210:213], v214 offset:20480
	ds_read_b128 v[214:217], v214 offset:22528
	s_setprio 1
	s_waitcnt lgkmcnt(0)
	v_mfma_f32_16x16x32_bf16 v[0:3], v[152:155], v[160:163], v[0:3]
	v_mfma_f32_16x16x32_bf16 v[4:7], v[152:155], v[164:167], v[4:7]
	v_mfma_f32_16x16x32_bf16 v[8:11], v[152:155], v[210:213], v[8:11]
	v_mfma_f32_16x16x32_bf16 v[12:15], v[152:155], v[214:217], v[12:15]
	v_mfma_f32_16x16x32_bf16 v[16:19], v[156:159], v[160:163], v[16:19]
	v_mfma_f32_16x16x32_bf16 v[20:23], v[156:159], v[164:167], v[20:23]
	v_mfma_f32_16x16x32_bf16 v[24:27], v[156:159], v[210:213], v[24:27]
	v_mfma_f32_16x16x32_bf16 v[28:31], v[156:159], v[214:217], v[28:31]
	v_mfma_f32_16x16x32_bf16 v[32:35], v[202:205], v[160:163], v[32:35]
	v_mfma_f32_16x16x32_bf16 v[36:39], v[202:205], v[164:167], v[36:39]
	v_mfma_f32_16x16x32_bf16 v[40:43], v[202:205], v[210:213], v[40:43]
	v_mfma_f32_16x16x32_bf16 v[44:47], v[202:205], v[214:217], v[44:47]
	v_mfma_f32_16x16x32_bf16 v[48:51], v[206:209], v[160:163], v[48:51]
	v_mfma_f32_16x16x32_bf16 v[52:55], v[206:209], v[164:167], v[52:55]
	v_mfma_f32_16x16x32_bf16 v[56:59], v[206:209], v[210:213], v[56:59]
	v_mfma_f32_16x16x32_bf16 v[60:63], v[206:209], v[214:217], v[60:63]
	s_setprio 0
	v_add_u32_e32 v168, v168, v150
	v_add_u32_e32 v169, v169, v150
	ds_read_b128 v[152:155], v168
	ds_read_b128 v[156:159], v168 offset:2048
	ds_read_b128 v[160:163], v169 offset:16384
	ds_read_b128 v[164:167], v169 offset:18432
	ds_read_b128 v[202:205], v168 offset:4096
	ds_read_b128 v[206:209], v168 offset:6144
	ds_read_b128 v[210:213], v169 offset:20480
	ds_read_b128 v[214:217], v169 offset:22528
	s_setprio 1
	s_waitcnt lgkmcnt(5)
	v_mfma_f32_16x16x32_bf16 v[0:3], v[152:155], v[160:163], v[0:3]
	s_waitcnt lgkmcnt(4)
	v_mfma_f32_16x16x32_bf16 v[4:7], v[152:155], v[164:167], v[4:7]
	s_waitcnt lgkmcnt(1)
	v_mfma_f32_16x16x32_bf16 v[8:11], v[152:155], v[210:213], v[8:11]
	s_waitcnt lgkmcnt(0)
	v_mfma_f32_16x16x32_bf16 v[12:15], v[152:155], v[214:217], v[12:15]
	v_mfma_f32_16x16x32_bf16 v[16:19], v[156:159], v[160:163], v[16:19]
	v_mfma_f32_16x16x32_bf16 v[20:23], v[156:159], v[164:167], v[20:23]
	v_mfma_f32_16x16x32_bf16 v[24:27], v[156:159], v[210:213], v[24:27]
	v_mfma_f32_16x16x32_bf16 v[28:31], v[156:159], v[214:217], v[28:31]
	v_mfma_f32_16x16x32_bf16 v[32:35], v[202:205], v[160:163], v[32:35]
	v_mfma_f32_16x16x32_bf16 v[36:39], v[202:205], v[164:167], v[36:39]
	v_mfma_f32_16x16x32_bf16 v[40:43], v[202:205], v[210:213], v[40:43]
	v_mfma_f32_16x16x32_bf16 v[44:47], v[202:205], v[214:217], v[44:47]
	v_mfma_f32_16x16x32_bf16 v[48:51], v[206:209], v[160:163], v[48:51]
	v_mfma_f32_16x16x32_bf16 v[52:55], v[206:209], v[164:167], v[52:55]
	v_mfma_f32_16x16x32_bf16 v[56:59], v[206:209], v[210:213], v[56:59]
	v_mfma_f32_16x16x32_bf16 v[60:63], v[206:209], v[214:217], v[60:63]
	s_setprio 0
	s_waitcnt vmcnt(0)
	s_add_u32 s44, s44, 0x80
	s_addc_u32 s45, s45, 0
	s_add_i32 s57, s57, 0x8000
	s_cmpk_eq_i32 s44, 0x1580
	s_barrier
	s_cbranch_scc0 .LBB0_1217
	v_add_u32_e32 v147, v148, v151
	v_add_u32_e32 v151, v149, v151
	ds_read_b128 v[70:73], v147 offset:32768
	ds_read_b128 v[152:155], v147 offset:34816
	ds_read_b128 v[156:159], v151 offset:49152
	ds_read_b128 v[160:163], v151 offset:51200
	ds_read_b128 v[164:167], v147 offset:36864
	ds_read_b128 v[202:205], v147 offset:38912
	ds_read_b128 v[206:209], v151 offset:53248
	ds_read_b128 v[210:213], v151 offset:55296
	s_setprio 1
	s_waitcnt lgkmcnt(5)
	v_mfma_f32_16x16x32_bf16 v[0:3], v[70:73], v[156:159], v[0:3]
	s_waitcnt lgkmcnt(4)
	v_mfma_f32_16x16x32_bf16 v[4:7], v[70:73], v[160:163], v[4:7]
	s_waitcnt lgkmcnt(1)
	v_mfma_f32_16x16x32_bf16 v[8:11], v[70:73], v[206:209], v[8:11]
	s_waitcnt lgkmcnt(0)
	v_mfma_f32_16x16x32_bf16 v[12:15], v[70:73], v[210:213], v[12:15]
	v_mfma_f32_16x16x32_bf16 v[16:19], v[152:155], v[156:159], v[16:19]
	v_mfma_f32_16x16x32_bf16 v[20:23], v[152:155], v[160:163], v[20:23]
	v_mfma_f32_16x16x32_bf16 v[24:27], v[152:155], v[206:209], v[24:27]
	v_mfma_f32_16x16x32_bf16 v[28:31], v[152:155], v[210:213], v[28:31]
	v_mfma_f32_16x16x32_bf16 v[32:35], v[164:167], v[156:159], v[32:35]
	v_mfma_f32_16x16x32_bf16 v[36:39], v[164:167], v[160:163], v[36:39]
	v_mfma_f32_16x16x32_bf16 v[40:43], v[164:167], v[206:209], v[40:43]
	v_mfma_f32_16x16x32_bf16 v[44:47], v[164:167], v[210:213], v[44:47]
	v_mfma_f32_16x16x32_bf16 v[48:51], v[202:205], v[156:159], v[48:51]
	v_mfma_f32_16x16x32_bf16 v[52:55], v[202:205], v[160:163], v[52:55]
	v_mfma_f32_16x16x32_bf16 v[56:59], v[202:205], v[206:209], v[56:59]
	v_mfma_f32_16x16x32_bf16 v[60:63], v[202:205], v[210:213], v[60:63]
	s_setprio 0
	v_add_u32_e32 v147, v148, v150
	v_add_u32_e32 v168, v149, v150
	ds_read_b128 v[70:73], v147 offset:32768
	ds_read_b128 v[148:151], v147 offset:34816
	ds_read_b128 v[152:155], v168 offset:49152
	ds_read_b128 v[156:159], v168 offset:51200
	ds_read_b128 v[160:163], v147 offset:36864
	ds_read_b128 v[164:167], v147 offset:38912
	ds_read_b128 v[202:205], v168 offset:53248
	ds_read_b128 v[206:209], v168 offset:55296
	s_setprio 1
	s_waitcnt lgkmcnt(5)
	v_mfma_f32_16x16x32_bf16 v[210:213], v[70:73], v[152:155], v[0:3]
	s_waitcnt lgkmcnt(4)
	v_mfma_f32_16x16x32_bf16 v[214:217], v[70:73], v[156:159], v[4:7]
	s_waitcnt lgkmcnt(1)
	v_mfma_f32_16x16x32_bf16 v[218:221], v[70:73], v[202:205], v[8:11]
	s_waitcnt lgkmcnt(0)
	v_mfma_f32_16x16x32_bf16 v[70:73], v[70:73], v[206:209], v[12:15]
	v_mfma_f32_16x16x32_bf16 v[222:225], v[148:151], v[152:155], v[16:19]
	v_mfma_f32_16x16x32_bf16 v[226:229], v[148:151], v[156:159], v[20:23]
	v_mfma_f32_16x16x32_bf16 v[230:233], v[148:151], v[202:205], v[24:27]
	v_mfma_f32_16x16x32_bf16 v[148:151], v[148:151], v[206:209], v[28:31]
	v_mfma_f32_16x16x32_bf16 v[28:31], v[160:163], v[152:155], v[32:35]
	v_mfma_f32_16x16x32_bf16 v[24:27], v[160:163], v[156:159], v[36:39]
	v_mfma_f32_16x16x32_bf16 v[20:23], v[160:163], v[202:205], v[40:43]
	v_mfma_f32_16x16x32_bf16 v[16:19], v[160:163], v[206:209], v[44:47]
	v_mfma_f32_16x16x32_bf16 v[12:15], v[164:167], v[152:155], v[48:51]
	v_mfma_f32_16x16x32_bf16 v[8:11], v[164:167], v[156:159], v[52:55]
	v_mfma_f32_16x16x32_bf16 v[4:7], v[164:167], v[202:205], v[56:59]
	v_mfma_f32_16x16x32_bf16 v[0:3], v[164:167], v[206:209], v[60:63]
	s_setprio 0
	v_or3_b32 v32, v125, s56, v118
	v_mul_f32_e32 v39, 0.5, v128
	v_lshlrev_b32_e32 v128, 2, v32
	v_lshl_add_u64 v[32:33], s[36:37], 0, v[128:129]
	v_mul_f32_e32 v40, v39, v210
	v_mul_f32_e32 v38, 0.5, v144
	v_lshl_add_u64 v[34:35], v[32:33], 0, v[68:69]
	v_fmac_f32_e32 v40, 0x3fd744fd, v136
	s_waitcnt vmcnt(0)
	s_barrier
	global_store_dword v[34:35], v40, off
	v_mul_f32_e32 v40, v38, v214
	v_mul_f32_e32 v37, 0.5, v145
	v_fmac_f32_e32 v40, 0x3fd744fd, v135
	global_store_dword v[34:35], v40, off offset:64
	v_mul_f32_e32 v40, v37, v218
	v_mul_f32_e32 v36, 0.5, v146
	v_fmac_f32_e32 v40, 0x3fd744fd, v133
	global_store_dword v[34:35], v40, off offset:128
	v_mul_f32_e32 v40, v36, v70
	v_fmac_f32_e32 v40, 0x3fd744fd, v131
	global_store_dword v[34:35], v40, off offset:192
	v_or_b32_e32 v34, 1, v66
	v_ashrrev_i32_e32 v35, 31, v34
	v_lshlrev_b64 v[34:35], 12, v[34:35]
	v_mul_f32_e32 v40, v39, v211
	v_lshl_add_u64 v[34:35], v[32:33], 0, v[34:35]
	v_fmac_f32_e32 v40, 0x3fd744fd, v143
	global_store_dword v[34:35], v40, off
	v_mul_f32_e32 v40, v38, v215
	v_fmac_f32_e32 v40, 0x3fd744fd, v127
	global_store_dword v[34:35], v40, off offset:64
	v_mul_f32_e32 v40, v37, v219
	v_fmac_f32_e32 v40, 0x3fd744fd, v126
	global_store_dword v[34:35], v40, off offset:128
	v_mul_f32_e32 v40, v36, v71
	v_fmac_f32_e32 v40, 0x3fd744fd, v124
	global_store_dword v[34:35], v40, off offset:192
	v_or_b32_e32 v34, 2, v66
	v_ashrrev_i32_e32 v35, 31, v34
	v_lshlrev_b64 v[34:35], 12, v[34:35]
	v_mul_f32_e32 v40, v39, v212
	v_lshl_add_u64 v[34:35], v[32:33], 0, v[34:35]
	v_fmac_f32_e32 v40, 0x3fd744fd, v142
	global_store_dword v[34:35], v40, off
	v_mul_f32_e32 v40, v38, v216
	v_fmac_f32_e32 v40, 0x3fd744fd, v141
	global_store_dword v[34:35], v40, off offset:64
	v_mul_f32_e32 v40, v37, v220
	v_fmac_f32_e32 v40, 0x3fd744fd, v140
	global_store_dword v[34:35], v40, off offset:128
	v_mul_f32_e32 v40, v36, v72
	v_fmac_f32_e32 v40, 0x3fd744fd, v139
	global_store_dword v[34:35], v40, off offset:192
	v_or_b32_e32 v34, 3, v66
	v_ashrrev_i32_e32 v35, 31, v34
	v_lshlrev_b64 v[34:35], 12, v[34:35]
	v_mul_f32_e32 v40, v39, v213
	v_lshl_add_u64 v[34:35], v[32:33], 0, v[34:35]
	v_fmac_f32_e32 v40, 0x3fd744fd, v115
	global_store_dword v[34:35], v40, off
	v_mul_f32_e32 v40, v38, v217
	v_fmac_f32_e32 v40, 0x3fd744fd, v123
	global_store_dword v[34:35], v40, off offset:64
	v_mul_f32_e32 v40, v37, v221
	v_fmac_f32_e32 v40, 0x3fd744fd, v122
	global_store_dword v[34:35], v40, off offset:128
	v_mul_f32_e32 v40, v36, v73
	v_fmac_f32_e32 v40, 0x3fd744fd, v120
	global_store_dword v[34:35], v40, off offset:192
	v_or_b32_e32 v34, 16, v66
	v_ashrrev_i32_e32 v35, 31, v34
	v_lshlrev_b64 v[34:35], 12, v[34:35]
	v_mul_f32_e32 v40, v39, v222
	v_lshl_add_u64 v[34:35], v[32:33], 0, v[34:35]
	v_fmac_f32_e32 v40, 0x3fd744fd, v138
	global_store_dword v[34:35], v40, off
	v_mul_f32_e32 v40, v38, v226
	v_fmac_f32_e32 v40, 0x3fd744fd, v119
	global_store_dword v[34:35], v40, off offset:64
	v_mul_f32_e32 v40, v37, v230
	v_fmac_f32_e32 v40, 0x3fd744fd, v117
	global_store_dword v[34:35], v40, off offset:128
	v_mul_f32_e32 v40, v36, v148
	v_fmac_f32_e32 v40, 0x3fd744fd, v116
	global_store_dword v[34:35], v40, off offset:192
	v_or_b32_e32 v34, 17, v66
	v_ashrrev_i32_e32 v35, 31, v34
	v_lshlrev_b64 v[34:35], 12, v[34:35]
	v_mul_f32_e32 v40, v39, v223
	v_lshl_add_u64 v[34:35], v[32:33], 0, v[34:35]
	v_fmac_f32_e32 v40, 0x3fd744fd, v137
	global_store_dword v[34:35], v40, off
	v_mul_f32_e32 v40, v38, v227
	v_fmac_f32_e32 v40, 0x3fd744fd, v114
	global_store_dword v[34:35], v40, off offset:64
	v_mul_f32_e32 v40, v37, v231
	v_fmac_f32_e32 v40, 0x3fd744fd, v113
	global_store_dword v[34:35], v40, off offset:128
	v_mul_f32_e32 v40, v36, v149
	v_fmac_f32_e32 v40, 0x3fd744fd, v112
	global_store_dword v[34:35], v40, off offset:192
	v_or_b32_e32 v34, 18, v66
	v_ashrrev_i32_e32 v35, 31, v34
	v_lshlrev_b64 v[34:35], 12, v[34:35]
	v_mul_f32_e32 v40, v39, v224
	v_lshl_add_u64 v[34:35], v[32:33], 0, v[34:35]
	v_fmac_f32_e32 v40, 0x3fd744fd, v108
	global_store_dword v[34:35], v40, off
	v_mul_f32_e32 v40, v38, v228
	v_fmac_f32_e32 v40, 0x3fd744fd, v107
	global_store_dword v[34:35], v40, off offset:64
	v_mul_f32_e32 v40, v37, v232
	v_fmac_f32_e32 v40, 0x3fd744fd, v105
	global_store_dword v[34:35], v40, off offset:128
	v_mul_f32_e32 v40, v36, v150
	v_fmac_f32_e32 v40, 0x3fd744fd, v121
	global_store_dword v[34:35], v40, off offset:192
	v_or_b32_e32 v34, 19, v66
	v_ashrrev_i32_e32 v35, 31, v34
	v_lshlrev_b64 v[34:35], 12, v[34:35]
	v_mul_f32_e32 v40, v39, v225
	v_lshl_add_u64 v[34:35], v[32:33], 0, v[34:35]
	v_fmac_f32_e32 v40, 0x3fd744fd, v104
	global_store_dword v[34:35], v40, off
	v_mul_f32_e32 v40, v38, v229
	v_fmac_f32_e32 v40, 0x3fd744fd, v103
	global_store_dword v[34:35], v40, off offset:64
	v_mul_f32_e32 v40, v37, v233
	v_fmac_f32_e32 v40, 0x3fd744fd, v102
	global_store_dword v[34:35], v40, off offset:128
	v_mul_f32_e32 v40, v36, v151
	v_fmac_f32_e32 v40, 0x3fd744fd, v101
	global_store_dword v[34:35], v40, off offset:192
	v_or_b32_e32 v34, 32, v66
	v_ashrrev_i32_e32 v35, 31, v34
	v_lshlrev_b64 v[34:35], 12, v[34:35]
	v_mul_f32_e32 v28, v39, v28
	v_mul_f32_e32 v24, v38, v24
	v_mul_f32_e32 v20, v37, v20
	v_mul_f32_e32 v16, v36, v16
	v_lshl_add_u64 v[34:35], v[32:33], 0, v[34:35]
	v_fmac_f32_e32 v28, 0x3fd744fd, v106
	v_fmac_f32_e32 v24, 0x3fd744fd, v111
	v_fmac_f32_e32 v20, 0x3fd744fd, v110
	v_fmac_f32_e32 v16, 0x3fd744fd, v109
	global_store_dword v[34:35], v28, off
	global_store_dword v[34:35], v24, off offset:64
	global_store_dword v[34:35], v20, off offset:128
	global_store_dword v[34:35], v16, off offset:192
	v_or_b32_e32 v34, 33, v66
	v_ashrrev_i32_e32 v35, 31, v34
	v_lshlrev_b64 v[34:35], 12, v[34:35]
	v_mul_f32_e32 v16, v39, v29
	v_lshl_add_u64 v[34:35], v[32:33], 0, v[34:35]
	v_fmac_f32_e32 v16, 0x3fd744fd, v99
	global_store_dword v[34:35], v16, off
	v_mul_f32_e32 v16, v38, v25
	v_fmac_f32_e32 v16, 0x3fd744fd, v96
	global_store_dword v[34:35], v16, off offset:64
	v_mul_f32_e32 v16, v37, v21
	v_fmac_f32_e32 v16, 0x3fd744fd, v92
	global_store_dword v[34:35], v16, off offset:128
	v_mul_f32_e32 v16, v36, v17
	v_fmac_f32_e32 v16, 0x3fd744fd, v90
	global_store_dword v[34:35], v16, off offset:192
	v_or_b32_e32 v16, 34, v66
	v_ashrrev_i32_e32 v17, 31, v16
	v_lshlrev_b64 v[16:17], 12, v[16:17]
	v_mul_f32_e32 v20, v39, v30
	v_lshl_add_u64 v[16:17], v[32:33], 0, v[16:17]
	v_fmac_f32_e32 v20, 0x3fd744fd, v89
	global_store_dword v[16:17], v20, off
	v_mul_f32_e32 v20, v38, v26
	v_fmac_f32_e32 v20, 0x3fd744fd, v100
	global_store_dword v[16:17], v20, off offset:64
	v_mul_f32_e32 v20, v37, v22
	v_mul_f32_e32 v18, v36, v18
	v_fmac_f32_e32 v20, 0x3fd744fd, v97
	v_fmac_f32_e32 v18, 0x3fd744fd, v93
	global_store_dword v[16:17], v20, off offset:128
	global_store_dword v[16:17], v18, off offset:192
	v_or_b32_e32 v16, 35, v66
	v_ashrrev_i32_e32 v17, 31, v16
	v_lshlrev_b64 v[16:17], 12, v[16:17]
	v_mul_f32_e32 v18, v39, v31
	v_lshl_add_u64 v[16:17], v[32:33], 0, v[16:17]
	v_fmac_f32_e32 v18, 0x3fd744fd, v87
	global_store_dword v[16:17], v18, off
	v_mul_f32_e32 v18, v38, v27
	v_fmac_f32_e32 v18, 0x3fd744fd, v86
	global_store_dword v[16:17], v18, off offset:64
	v_mul_f32_e32 v18, v37, v23
	v_fmac_f32_e32 v18, 0x3fd744fd, v94
	global_store_dword v[16:17], v18, off offset:128
	v_mul_f32_e32 v18, v36, v19
	v_fmac_f32_e32 v18, 0x3fd744fd, v91
	global_store_dword v[16:17], v18, off offset:192
	v_or_b32_e32 v16, 48, v66
	v_ashrrev_i32_e32 v17, 31, v16
	v_lshlrev_b64 v[16:17], 12, v[16:17]
	v_mul_f32_e32 v12, v39, v12
	v_mul_f32_e32 v8, v38, v8
	v_mul_f32_e32 v4, v37, v4
	v_mul_f32_e32 v0, v36, v0
	v_lshl_add_u64 v[16:17], v[32:33], 0, v[16:17]
	v_fmac_f32_e32 v12, 0x3fd744fd, v88
	v_fmac_f32_e32 v8, 0x3fd744fd, v84
	v_fmac_f32_e32 v4, 0x3fd744fd, v98
	v_fmac_f32_e32 v0, 0x3fd744fd, v95
	global_store_dword v[16:17], v12, off
	global_store_dword v[16:17], v8, off offset:64
	global_store_dword v[16:17], v4, off offset:128
	global_store_dword v[16:17], v0, off offset:192
	v_or_b32_e32 v16, 49, v66
	v_ashrrev_i32_e32 v17, 31, v16
	v_lshlrev_b64 v[16:17], 12, v[16:17]
	v_mul_f32_e32 v0, v39, v13
	v_lshl_add_u64 v[16:17], v[32:33], 0, v[16:17]
	v_fmac_f32_e32 v0, 0x3fd744fd, v85
	global_store_dword v[16:17], v0, off
	v_mul_f32_e32 v0, v38, v9
	v_fmac_f32_e32 v0, 0x3fd744fd, v82
	global_store_dword v[16:17], v0, off offset:64
	v_mul_f32_e32 v0, v37, v5
	v_fmac_f32_e32 v0, 0x3fd744fd, v80
	global_store_dword v[16:17], v0, off offset:128
	v_mul_f32_e32 v0, v36, v1
	v_fmac_f32_e32 v0, 0x3fd744fd, v78
	global_store_dword v[16:17], v0, off offset:192
	v_or_b32_e32 v0, 50, v66
	v_ashrrev_i32_e32 v1, 31, v0
	v_lshlrev_b64 v[0:1], 12, v[0:1]
	v_mul_f32_e32 v4, v39, v14
	v_lshl_add_u64 v[0:1], v[32:33], 0, v[0:1]
	v_fmac_f32_e32 v4, 0x3fd744fd, v77
	global_store_dword v[0:1], v4, off
	v_mul_f32_e32 v4, v38, v10
	v_fmac_f32_e32 v4, 0x3fd744fd, v83
	global_store_dword v[0:1], v4, off offset:64
	v_mul_f32_e32 v4, v37, v6
	v_mul_f32_e32 v2, v36, v2
	v_fmac_f32_e32 v4, 0x3fd744fd, v81
	v_fmac_f32_e32 v2, 0x3fd744fd, v79
	global_store_dword v[0:1], v4, off offset:128
	global_store_dword v[0:1], v2, off offset:192
	v_or_b32_e32 v0, 51, v66
	v_ashrrev_i32_e32 v1, 31, v0
	v_lshlrev_b64 v[0:1], 12, v[0:1]
	v_mul_f32_e32 v2, v39, v15
	v_lshl_add_u64 v[0:1], v[32:33], 0, v[0:1]
	v_fmac_f32_e32 v2, 0x3fd744fd, v76
	global_store_dword v[0:1], v2, off
	v_mul_f32_e32 v2, v38, v11
	v_fmac_f32_e32 v2, 0x3fd744fd, v75
	global_store_dword v[0:1], v2, off offset:64
	v_mul_f32_e32 v2, v37, v7
	v_fmac_f32_e32 v2, 0x3fd744fd, v74
	global_store_dword v[0:1], v2, off offset:128
	v_mul_f32_e32 v2, v36, v3
	s_add_i32 s55, s55, s33
	s_add_i32 s54, s54, s66
	s_add_i32 s53, s53, s69
	v_fmac_f32_e32 v2, 0x3fd744fd, v67
	s_cmp_gt_u32 s55, 63
	global_store_dword v[0:1], v2, off offset:192
	s_cbranch_scc0 .LBB0_1216
	v_readlane_b32 s4, v235, 44
	v_readlane_b32 s5, v235, 45
	s_mul_hi_i32 s51, s4, 0x1b000
	s_mul_i32 s52, s4, 0x1b000
	v_readlane_b32 s4, v235, 34
	v_readlane_b32 s5, v235, 35
	s_add_u32 s44, s4, 0x14ae6000
	s_addc_u32 s45, s5, 0
	s_add_u32 s47, s47, s52
	s_addc_u32 s50, s50, s51
	s_lshl_b32 s46, s46, 2
	s_add_u32 s46, s47, s46
	s_addc_u32 s47, s50, 0
	s_add_u32 s46, s46, 0x12000
	s_addc_u32 s47, s47, 0
	s_mov_b32 s52, s67
	v_readlane_b32 s53, v235, 10
	s_mov_b32 s54, s67
	s_movk_i32 s96, 0x1000
	s_branch .LBB0_1221

.LBB0_1223:
	s_and_b32 s63, s62, 0x8000
	s_xor_b32 s66, s63, 0x8000
	v_add_u32_e32 v88, s66, v74
	v_lshl_add_u64 v[80:81], v[68:69], 0, s[50:51]
	v_add_u32_e32 v89, 0x4000, v88
	v_readfirstlane_b32 s66, v88
	v_lshl_add_u64 v[82:83], v[80:81], 0, s[94:95]
	v_lshl_add_u64 v[84:85], v[66:67], 0, s[50:51]
	s_mov_b32 m0, s66
	v_readfirstlane_b32 s66, v89
	v_lshl_add_u64 v[86:87], v[84:85], 0, s[94:95]
	global_load_lds_dwordx4 v[82:83], off
	s_mov_b32 m0, s66
	v_lshl_add_u64 v[82:83], v[80:81], 0, s[92:93]
	global_load_lds_dwordx4 v[86:87], off
	v_add_u32_e32 v86, 0x1000, v88
	v_add3_u32 v112, s63, v76, v77
	v_readfirstlane_b32 s66, v86
	v_add_u32_e32 v86, 0x5000, v88
	s_mov_b32 m0, s66
	v_readfirstlane_b32 s66, v86
	v_add_u32_e32 v86, 0x2000, v88
	global_load_lds_dwordx4 v[82:83], off
	v_lshl_add_u64 v[82:83], v[84:85], 0, s[92:93]
	s_mov_b32 m0, s66
	v_readfirstlane_b32 s66, v86
	v_add_u32_e32 v86, 0x6000, v88
	global_load_lds_dwordx4 v[82:83], off
	v_lshl_add_u64 v[82:83], v[80:81], 0, s[20:21]
	s_mov_b32 m0, s66
	v_readfirstlane_b32 s66, v86
	global_load_lds_dwordx4 v[82:83], off
	v_lshl_add_u64 v[82:83], v[84:85], 0, s[20:21]
	s_mov_b32 m0, s66
	v_lshl_add_u64 v[80:81], v[80:81], 0, s[80:81]
	global_load_lds_dwordx4 v[82:83], off
	v_add_u32_e32 v82, 0x3000, v88
	v_add_u32_e32 v100, v112, v79
	v_readfirstlane_b32 s66, v82
	v_add_u32_e32 v82, 0x7000, v88
	s_mov_b32 m0, s66
	v_readfirstlane_b32 s66, v82
	global_load_lds_dwordx4 v[80:81], off
	v_lshl_add_u64 v[80:81], v[84:85], 0, s[80:81]
	s_mov_b32 m0, s66
	s_nop 0
	global_load_lds_dwordx4 v[80:81], off
	v_or_b32_e32 v80, s63, v78
	v_add_u32_e32 v113, v80, v77
	v_add_u32_e32 v108, v113, v79
	ds_read_b128 v[80:83], v100
	ds_read_b128 v[84:87], v100 offset:2048
	ds_read_b128 v[88:91], v108 offset:16384
	ds_read_b128 v[92:95], v108 offset:18432
	ds_read_b128 v[96:99], v100 offset:4096
	ds_read_b128 v[100:103], v100 offset:6144
	ds_read_b128 v[104:107], v108 offset:20480
	ds_read_b128 v[108:111], v108 offset:22528
	s_setprio 1
	s_waitcnt lgkmcnt(0)
	v_mfma_f32_16x16x32_bf16 v[56:59], v[80:83], v[88:91], v[56:59]
	v_mfma_f32_16x16x32_bf16 v[44:47], v[80:83], v[92:95], v[44:47]
	v_mfma_f32_16x16x32_bf16 v[36:39], v[80:83], v[104:107], v[36:39]
	v_mfma_f32_16x16x32_bf16 v[32:35], v[80:83], v[108:111], v[32:35]
	v_mfma_f32_16x16x32_bf16 v[28:31], v[84:87], v[88:91], v[28:31]
	v_mfma_f32_16x16x32_bf16 v[24:27], v[84:87], v[92:95], v[24:27]
	v_mfma_f32_16x16x32_bf16 v[20:23], v[84:87], v[104:107], v[20:23]
	v_mfma_f32_16x16x32_bf16 v[16:19], v[84:87], v[108:111], v[16:19]
	v_mfma_f32_16x16x32_bf16 v[12:15], v[96:99], v[88:91], v[12:15]
	v_mfma_f32_16x16x32_bf16 v[8:11], v[96:99], v[92:95], v[8:11]
	v_mfma_f32_16x16x32_bf16 v[4:7], v[96:99], v[104:107], v[4:7]
	v_mfma_f32_16x16x32_bf16 v[0:3], v[96:99], v[108:111], v[0:3]
	v_mfma_f32_16x16x32_bf16 v[40:43], v[100:103], v[88:91], v[40:43]
	v_mfma_f32_16x16x32_bf16 v[48:51], v[100:103], v[92:95], v[48:51]
	v_mfma_f32_16x16x32_bf16 v[52:55], v[100:103], v[104:107], v[52:55]
	v_mfma_f32_16x16x32_bf16 v[60:63], v[100:103], v[108:111], v[60:63]
	s_setprio 0
	v_add_u32_e32 v100, v112, v75
	v_add_u32_e32 v108, v113, v75
	ds_read_b128 v[80:83], v100
	ds_read_b128 v[84:87], v100 offset:2048
	ds_read_b128 v[88:91], v108 offset:16384
	ds_read_b128 v[92:95], v108 offset:18432
	ds_read_b128 v[96:99], v100 offset:4096
	ds_read_b128 v[100:103], v100 offset:6144
	ds_read_b128 v[104:107], v108 offset:20480
	ds_read_b128 v[108:111], v108 offset:22528
	s_setprio 1
	s_waitcnt lgkmcnt(5)
	v_mfma_f32_16x16x32_bf16 v[56:59], v[80:83], v[88:91], v[56:59]
	s_waitcnt lgkmcnt(4)
	v_mfma_f32_16x16x32_bf16 v[44:47], v[80:83], v[92:95], v[44:47]
	s_waitcnt lgkmcnt(1)
	v_mfma_f32_16x16x32_bf16 v[36:39], v[80:83], v[104:107], v[36:39]
	s_waitcnt lgkmcnt(0)
	v_mfma_f32_16x16x32_bf16 v[32:35], v[80:83], v[108:111], v[32:35]
	v_mfma_f32_16x16x32_bf16 v[28:31], v[84:87], v[88:91], v[28:31]
	v_mfma_f32_16x16x32_bf16 v[24:27], v[84:87], v[92:95], v[24:27]
	v_mfma_f32_16x16x32_bf16 v[20:23], v[84:87], v[104:107], v[20:23]
	v_mfma_f32_16x16x32_bf16 v[16:19], v[84:87], v[108:111], v[16:19]
	v_mfma_f32_16x16x32_bf16 v[12:15], v[96:99], v[88:91], v[12:15]
	v_mfma_f32_16x16x32_bf16 v[8:11], v[96:99], v[92:95], v[8:11]
	v_mfma_f32_16x16x32_bf16 v[4:7], v[96:99], v[104:107], v[4:7]
	v_mfma_f32_16x16x32_bf16 v[0:3], v[96:99], v[108:111], v[0:3]
	v_mfma_f32_16x16x32_bf16 v[40:43], v[100:103], v[88:91], v[40:43]
	v_mfma_f32_16x16x32_bf16 v[48:51], v[100:103], v[92:95], v[48:51]
	v_mfma_f32_16x16x32_bf16 v[52:55], v[100:103], v[104:107], v[52:55]
	v_mfma_f32_16x16x32_bf16 v[60:63], v[100:103], v[108:111], v[60:63]
	s_setprio 0
	s_waitcnt vmcnt(0)
	s_add_u32 s50, s50, 0x80
	s_addc_u32 s51, s51, 0
	s_add_i32 s62, s62, 0x8000
	s_cmpk_eq_i32 s50, 0xa80
	s_barrier
	s_cbranch_scc0 .LBB0_1223
	v_add_u32_e32 v74, v76, v77
	v_add_u32_e32 v104, v78, v77
	v_add_u32_e32 v92, v74, v79
	v_add_u32_e32 v100, v104, v79
	ds_read_b128 v[66:69], v92 offset:32768
	ds_read_b128 v[76:79], v92 offset:34816
	ds_read_b128 v[80:83], v100 offset:49152
	ds_read_b128 v[84:87], v100 offset:51200
	ds_read_b128 v[88:91], v92 offset:36864
	ds_read_b128 v[92:95], v92 offset:38912
	ds_read_b128 v[96:99], v100 offset:53248
	ds_read_b128 v[100:103], v100 offset:55296
	s_setprio 1
	s_waitcnt lgkmcnt(5)
	v_mfma_f32_16x16x32_bf16 v[56:59], v[66:69], v[80:83], v[56:59]
	s_waitcnt lgkmcnt(4)
	v_mfma_f32_16x16x32_bf16 v[44:47], v[66:69], v[84:87], v[44:47]
	s_waitcnt lgkmcnt(1)
	v_mfma_f32_16x16x32_bf16 v[36:39], v[66:69], v[96:99], v[36:39]
	s_waitcnt lgkmcnt(0)
	v_mfma_f32_16x16x32_bf16 v[32:35], v[66:69], v[100:103], v[32:35]
	v_mfma_f32_16x16x32_bf16 v[28:31], v[76:79], v[80:83], v[28:31]
	v_mfma_f32_16x16x32_bf16 v[24:27], v[76:79], v[84:87], v[24:27]
	v_mfma_f32_16x16x32_bf16 v[20:23], v[76:79], v[96:99], v[20:23]
	v_mfma_f32_16x16x32_bf16 v[16:19], v[76:79], v[100:103], v[16:19]
	v_mfma_f32_16x16x32_bf16 v[12:15], v[88:91], v[80:83], v[12:15]
	v_mfma_f32_16x16x32_bf16 v[8:11], v[88:91], v[84:87], v[8:11]
	v_mfma_f32_16x16x32_bf16 v[4:7], v[88:91], v[96:99], v[4:7]
	v_mfma_f32_16x16x32_bf16 v[0:3], v[88:91], v[100:103], v[0:3]
	v_mfma_f32_16x16x32_bf16 v[66:69], v[92:95], v[80:83], v[40:43]
	v_mfma_f32_16x16x32_bf16 v[76:79], v[92:95], v[84:87], v[48:51]
	v_mfma_f32_16x16x32_bf16 v[80:83], v[92:95], v[96:99], v[52:55]
	v_mfma_f32_16x16x32_bf16 v[84:87], v[92:95], v[100:103], v[60:63]
	s_setprio 0
	v_add_u32_e32 v48, v74, v75
	v_add_u32_e32 v49, v104, v75
	ds_read_b128 v[40:43], v48 offset:32768
	ds_read_b128 v[88:91], v48 offset:34816
	ds_read_b128 v[92:95], v49 offset:49152
	ds_read_b128 v[96:99], v49 offset:51200
	ds_read_b128 v[100:103], v48 offset:36864
	ds_read_b128 v[104:107], v48 offset:38912
	ds_read_b128 v[108:111], v49 offset:53248
	ds_read_b128 v[112:115], v49 offset:55296
	s_setprio 1
	s_waitcnt lgkmcnt(5)
	v_mfma_f32_16x16x32_bf16 v[60:63], v[40:43], v[92:95], v[56:59]
	s_waitcnt lgkmcnt(4)
	v_mfma_f32_16x16x32_bf16 v[56:59], v[40:43], v[96:99], v[44:47]
	s_waitcnt lgkmcnt(1)
	v_mfma_f32_16x16x32_bf16 v[52:55], v[40:43], v[108:111], v[36:39]
	s_waitcnt lgkmcnt(0)
	v_mfma_f32_16x16x32_bf16 v[48:51], v[40:43], v[112:115], v[32:35]
	v_mfma_f32_16x16x32_bf16 v[44:47], v[88:91], v[92:95], v[28:31]
	v_mfma_f32_16x16x32_bf16 v[40:43], v[88:91], v[96:99], v[24:27]
	v_mfma_f32_16x16x32_bf16 v[36:39], v[88:91], v[108:111], v[20:23]
	v_mfma_f32_16x16x32_bf16 v[32:35], v[88:91], v[112:115], v[16:19]
	v_mfma_f32_16x16x32_bf16 v[28:31], v[100:103], v[92:95], v[12:15]
	v_mfma_f32_16x16x32_bf16 v[24:27], v[100:103], v[96:99], v[8:11]
	v_mfma_f32_16x16x32_bf16 v[20:23], v[100:103], v[108:111], v[4:7]
	v_mfma_f32_16x16x32_bf16 v[16:19], v[100:103], v[112:115], v[0:3]
	v_mfma_f32_16x16x32_bf16 v[12:15], v[104:107], v[92:95], v[66:69]
	v_mfma_f32_16x16x32_bf16 v[8:11], v[104:107], v[96:99], v[76:79]
	v_mfma_f32_16x16x32_bf16 v[4:7], v[104:107], v[108:111], v[80:83]
	v_mfma_f32_16x16x32_bf16 v[0:3], v[104:107], v[112:115], v[84:87]
	s_setprio 0
	v_lshlrev_b32_e32 v66, 6, v70
	v_or3_b32 v66, v66, s55, v71
	v_lshlrev_b32_e32 v128, 2, v66
	s_waitcnt vmcnt(0)
	s_barrier
	global_load_dword v66, v128, s[46:47]
	s_waitcnt vmcnt(0)
	v_mul_f32_e32 v74, 0.5, v66
	global_load_dword v66, v128, s[46:47] offset:64
	v_mul_f32_e32 v60, v60, v74
	s_waitcnt vmcnt(0)
	v_mul_f32_e32 v75, 0.5, v66
	global_load_dword v66, v128, s[46:47] offset:128
	v_mul_f32_e32 v56, v56, v75
	s_waitcnt vmcnt(0)
	v_mul_f32_e32 v76, 0.5, v66
	global_load_dword v66, v128, s[46:47] offset:192
	v_mul_f32_e32 v52, v52, v76
	s_waitcnt vmcnt(0)
	v_mul_f32_e32 v77, 0.5, v66
	v_lshl_add_u32 v66, v72, 6, s59
	v_lshl_or_b32 v68, v73, 2, v66
	v_ashrrev_i32_e32 v69, 31, v68
	v_lshl_add_u64 v[66:67], s[44:45], 0, v[128:129]
	v_lshlrev_b64 v[70:71], 12, v[68:69]
	v_lshl_add_u64 v[70:71], v[66:67], 0, v[70:71]
	v_mul_f32_e32 v48, v48, v77
	global_store_dword v[70:71], v60, off
	global_store_dword v[70:71], v56, off offset:64
	global_store_dword v[70:71], v52, off offset:128
	global_store_dword v[70:71], v48, off offset:192
	v_or_b32_e32 v70, 1, v68
	v_ashrrev_i32_e32 v71, 31, v70
	v_lshlrev_b64 v[70:71], 12, v[70:71]
	v_lshl_add_u64 v[70:71], v[66:67], 0, v[70:71]
	v_mul_f32_e32 v48, v61, v74
	global_store_dword v[70:71], v48, off
	v_mul_f32_e32 v48, v57, v75
	global_store_dword v[70:71], v48, off offset:64
	v_mul_f32_e32 v48, v53, v76
	global_store_dword v[70:71], v48, off offset:128
	v_mul_f32_e32 v48, v49, v77
	global_store_dword v[70:71], v48, off offset:192
	v_or_b32_e32 v48, 2, v68
	v_ashrrev_i32_e32 v49, 31, v48
	v_lshlrev_b64 v[48:49], 12, v[48:49]
	v_lshl_add_u64 v[48:49], v[66:67], 0, v[48:49]
	v_mul_f32_e32 v52, v62, v74
	global_store_dword v[48:49], v52, off
	v_mul_f32_e32 v52, v58, v75
	global_store_dword v[48:49], v52, off offset:64
	v_mul_f32_e32 v52, v54, v76
	v_mul_f32_e32 v50, v50, v77
	global_store_dword v[48:49], v52, off offset:128
	global_store_dword v[48:49], v50, off offset:192
	v_or_b32_e32 v48, 3, v68
	v_ashrrev_i32_e32 v49, 31, v48
	v_lshlrev_b64 v[48:49], 12, v[48:49]
	v_lshl_add_u64 v[48:49], v[66:67], 0, v[48:49]
	v_mul_f32_e32 v50, v63, v74
	global_store_dword v[48:49], v50, off
	v_mul_f32_e32 v50, v59, v75
	global_store_dword v[48:49], v50, off offset:64
	v_mul_f32_e32 v50, v55, v76
	global_store_dword v[48:49], v50, off offset:128
	v_mul_f32_e32 v50, v51, v77
	global_store_dword v[48:49], v50, off offset:192
	v_or_b32_e32 v48, 16, v68
	v_ashrrev_i32_e32 v49, 31, v48
	v_lshlrev_b64 v[48:49], 12, v[48:49]
	v_lshl_add_u64 v[48:49], v[66:67], 0, v[48:49]
	v_mul_f32_e32 v44, v44, v74
	v_mul_f32_e32 v40, v40, v75
	v_mul_f32_e32 v36, v36, v76
	v_mul_f32_e32 v32, v32, v77
	global_store_dword v[48:49], v44, off
	global_store_dword v[48:49], v40, off offset:64
	global_store_dword v[48:49], v36, off offset:128
	global_store_dword v[48:49], v32, off offset:192
	v_or_b32_e32 v48, 17, v68
	v_ashrrev_i32_e32 v49, 31, v48
	v_lshlrev_b64 v[48:49], 12, v[48:49]
	v_lshl_add_u64 v[48:49], v[66:67], 0, v[48:49]
	v_mul_f32_e32 v32, v45, v74
	global_store_dword v[48:49], v32, off
	v_mul_f32_e32 v32, v41, v75
	global_store_dword v[48:49], v32, off offset:64
	v_mul_f32_e32 v32, v37, v76
	global_store_dword v[48:49], v32, off offset:128
	v_mul_f32_e32 v32, v33, v77
	global_store_dword v[48:49], v32, off offset:192
	v_or_b32_e32 v32, 18, v68
	v_ashrrev_i32_e32 v33, 31, v32
	v_lshlrev_b64 v[32:33], 12, v[32:33]
	v_lshl_add_u64 v[32:33], v[66:67], 0, v[32:33]
	v_mul_f32_e32 v36, v46, v74
	global_store_dword v[32:33], v36, off
	v_mul_f32_e32 v36, v42, v75
	global_store_dword v[32:33], v36, off offset:64
	v_mul_f32_e32 v36, v38, v76
	v_mul_f32_e32 v34, v34, v77
	global_store_dword v[32:33], v36, off offset:128
	global_store_dword v[32:33], v34, off offset:192
	v_or_b32_e32 v32, 19, v68
	v_ashrrev_i32_e32 v33, 31, v32
	v_lshlrev_b64 v[32:33], 12, v[32:33]
	v_lshl_add_u64 v[32:33], v[66:67], 0, v[32:33]
	v_mul_f32_e32 v34, v47, v74
	global_store_dword v[32:33], v34, off
	v_mul_f32_e32 v34, v43, v75
	global_store_dword v[32:33], v34, off offset:64
	v_mul_f32_e32 v34, v39, v76
	global_store_dword v[32:33], v34, off offset:128
	v_mul_f32_e32 v34, v35, v77
	global_store_dword v[32:33], v34, off offset:192
	v_or_b32_e32 v32, 32, v68
	v_ashrrev_i32_e32 v33, 31, v32
	v_lshlrev_b64 v[32:33], 12, v[32:33]
	v_lshl_add_u64 v[32:33], v[66:67], 0, v[32:33]
	v_mul_f32_e32 v28, v28, v74
	v_mul_f32_e32 v24, v24, v75
	v_mul_f32_e32 v20, v20, v76
	v_mul_f32_e32 v16, v16, v77
	global_store_dword v[32:33], v28, off
	global_store_dword v[32:33], v24, off offset:64
	global_store_dword v[32:33], v20, off offset:128
	global_store_dword v[32:33], v16, off offset:192
	v_or_b32_e32 v32, 33, v68
	v_ashrrev_i32_e32 v33, 31, v32
	v_lshlrev_b64 v[32:33], 12, v[32:33]
	v_lshl_add_u64 v[32:33], v[66:67], 0, v[32:33]
	v_mul_f32_e32 v16, v29, v74
	global_store_dword v[32:33], v16, off
	v_mul_f32_e32 v16, v25, v75
	global_store_dword v[32:33], v16, off offset:64
	v_mul_f32_e32 v16, v21, v76
	global_store_dword v[32:33], v16, off offset:128
	v_mul_f32_e32 v16, v17, v77
	global_store_dword v[32:33], v16, off offset:192
	v_or_b32_e32 v16, 34, v68
	v_ashrrev_i32_e32 v17, 31, v16
	v_lshlrev_b64 v[16:17], 12, v[16:17]
	v_lshl_add_u64 v[16:17], v[66:67], 0, v[16:17]
	v_mul_f32_e32 v20, v30, v74
	global_store_dword v[16:17], v20, off
	v_mul_f32_e32 v20, v26, v75
	global_store_dword v[16:17], v20, off offset:64
	v_mul_f32_e32 v20, v22, v76
	v_mul_f32_e32 v18, v18, v77
	global_store_dword v[16:17], v20, off offset:128
	global_store_dword v[16:17], v18, off offset:192
	v_or_b32_e32 v16, 35, v68
	v_ashrrev_i32_e32 v17, 31, v16
	v_lshlrev_b64 v[16:17], 12, v[16:17]
	v_lshl_add_u64 v[16:17], v[66:67], 0, v[16:17]
	v_mul_f32_e32 v18, v31, v74
	global_store_dword v[16:17], v18, off
	v_mul_f32_e32 v18, v27, v75
	global_store_dword v[16:17], v18, off offset:64
	v_mul_f32_e32 v18, v23, v76
	global_store_dword v[16:17], v18, off offset:128
	v_mul_f32_e32 v18, v19, v77
	global_store_dword v[16:17], v18, off offset:192
	v_or_b32_e32 v16, 48, v68
	v_ashrrev_i32_e32 v17, 31, v16
	v_lshlrev_b64 v[16:17], 12, v[16:17]
	v_lshl_add_u64 v[16:17], v[66:67], 0, v[16:17]
	v_mul_f32_e32 v12, v12, v74
	v_mul_f32_e32 v8, v8, v75
	v_mul_f32_e32 v4, v4, v76
	v_mul_f32_e32 v0, v0, v77
	global_store_dword v[16:17], v12, off
	global_store_dword v[16:17], v8, off offset:64
	global_store_dword v[16:17], v4, off offset:128
	global_store_dword v[16:17], v0, off offset:192
	v_or_b32_e32 v16, 49, v68
	v_ashrrev_i32_e32 v17, 31, v16
	v_lshlrev_b64 v[16:17], 12, v[16:17]
	v_lshl_add_u64 v[16:17], v[66:67], 0, v[16:17]
	v_mul_f32_e32 v0, v13, v74
	global_store_dword v[16:17], v0, off
	v_mul_f32_e32 v0, v9, v75
	global_store_dword v[16:17], v0, off offset:64
	v_mul_f32_e32 v0, v5, v76
	global_store_dword v[16:17], v0, off offset:128
	v_mul_f32_e32 v0, v1, v77
	global_store_dword v[16:17], v0, off offset:192
	v_or_b32_e32 v0, 50, v68
	v_ashrrev_i32_e32 v1, 31, v0
	v_lshlrev_b64 v[0:1], 12, v[0:1]
	v_lshl_add_u64 v[0:1], v[66:67], 0, v[0:1]
	v_mul_f32_e32 v4, v14, v74
	global_store_dword v[0:1], v4, off
	v_mul_f32_e32 v4, v10, v75
	global_store_dword v[0:1], v4, off offset:64
	v_mul_f32_e32 v4, v6, v76
	v_mul_f32_e32 v2, v2, v77
	global_store_dword v[0:1], v4, off offset:128
	global_store_dword v[0:1], v2, off offset:192
	v_or_b32_e32 v0, 51, v68
	v_ashrrev_i32_e32 v1, 31, v0
	v_lshlrev_b64 v[0:1], 12, v[0:1]
	v_lshl_add_u64 v[0:1], v[66:67], 0, v[0:1]
	v_mul_f32_e32 v2, v15, v74
	global_store_dword v[0:1], v2, off
	v_mul_f32_e32 v2, v11, v75
	global_store_dword v[0:1], v2, off offset:64
	v_mul_f32_e32 v2, v7, v76
	global_store_dword v[0:1], v2, off offset:128
	v_mul_f32_e32 v2, v3, v77
	global_store_dword v[0:1], v2, off offset:192
	s_mov_b64 s[50:51], 0
	v_readlane_b32 s66, v235, 24

.LBB0_1227:
	s_and_b32 s56, s58, 0x8000
	s_xor_b32 s57, s56, 0x8000
	v_add_u32_e32 v160, s57, v147
	v_lshl_add_u64 v[152:153], v[72:73], 0, s[50:51]
	v_add_u32_e32 v161, 0x4000, v160
	v_readfirstlane_b32 s57, v160
	v_lshl_add_u64 v[154:155], v[152:153], 0, s[28:29]
	v_lshl_add_u64 v[156:157], v[70:71], 0, s[50:51]
	s_mov_b32 m0, s57
	v_readfirstlane_b32 s57, v161
	v_lshl_add_u64 v[158:159], v[156:157], 0, s[28:29]
	global_load_lds_dwordx4 v[154:155], off
	s_mov_b32 m0, s57
	v_lshl_add_u64 v[154:155], v[152:153], 0, s[42:43]
	global_load_lds_dwordx4 v[158:159], off
	v_add_u32_e32 v158, 0x1000, v160
	v_add_u32_e32 v168, s56, v148
	v_readfirstlane_b32 s57, v158
	v_add_u32_e32 v158, 0x5000, v160
	s_mov_b32 m0, s57
	v_readfirstlane_b32 s57, v158
	v_add_u32_e32 v158, 0x2000, v160
	global_load_lds_dwordx4 v[154:155], off
	v_lshl_add_u64 v[154:155], v[156:157], 0, s[42:43]
	s_mov_b32 m0, s57
	v_readfirstlane_b32 s57, v158
	v_add_u32_e32 v158, 0x6000, v160
	global_load_lds_dwordx4 v[154:155], off
	v_lshl_add_u64 v[154:155], v[152:153], 0, s[82:83]
	s_mov_b32 m0, s57
	v_readfirstlane_b32 s57, v158
	global_load_lds_dwordx4 v[154:155], off
	v_lshl_add_u64 v[154:155], v[156:157], 0, s[82:83]
	s_mov_b32 m0, s57
	v_lshl_add_u64 v[152:153], v[152:153], 0, s[86:87]
	global_load_lds_dwordx4 v[154:155], off
	v_add_u32_e32 v154, 0x3000, v160
	v_or_b32_e32 v169, s56, v149
	v_readfirstlane_b32 s57, v154
	v_add_u32_e32 v154, 0x7000, v160
	s_mov_b32 m0, s57
	v_readfirstlane_b32 s57, v154
	global_load_lds_dwordx4 v[152:153], off
	v_lshl_add_u64 v[152:153], v[156:157], 0, s[86:87]
	s_mov_b32 m0, s57
	v_add_u32_e32 v201, v168, v151
	global_load_lds_dwordx4 v[152:153], off
	v_add_u32_e32 v214, v169, v151
	ds_read_b128 v[152:155], v201
	ds_read_b128 v[156:159], v201 offset:2048
	ds_read_b128 v[160:163], v214 offset:16384
	ds_read_b128 v[164:167], v214 offset:18432
	ds_read_b128 v[202:205], v201 offset:4096
	ds_read_b128 v[206:209], v201 offset:6144
	ds_read_b128 v[210:213], v214 offset:20480
	ds_read_b128 v[214:217], v214 offset:22528
	s_setprio 1
	s_waitcnt lgkmcnt(0)
	v_mfma_f32_16x16x32_bf16 v[0:3], v[152:155], v[160:163], v[0:3]
	v_mfma_f32_16x16x32_bf16 v[4:7], v[152:155], v[164:167], v[4:7]
	v_mfma_f32_16x16x32_bf16 v[8:11], v[152:155], v[210:213], v[8:11]
	v_mfma_f32_16x16x32_bf16 v[12:15], v[152:155], v[214:217], v[12:15]
	v_mfma_f32_16x16x32_bf16 v[16:19], v[156:159], v[160:163], v[16:19]
	v_mfma_f32_16x16x32_bf16 v[20:23], v[156:159], v[164:167], v[20:23]
	v_mfma_f32_16x16x32_bf16 v[24:27], v[156:159], v[210:213], v[24:27]
	v_mfma_f32_16x16x32_bf16 v[28:31], v[156:159], v[214:217], v[28:31]
	v_mfma_f32_16x16x32_bf16 v[32:35], v[202:205], v[160:163], v[32:35]
	v_mfma_f32_16x16x32_bf16 v[36:39], v[202:205], v[164:167], v[36:39]
	v_mfma_f32_16x16x32_bf16 v[40:43], v[202:205], v[210:213], v[40:43]
	v_mfma_f32_16x16x32_bf16 v[44:47], v[202:205], v[214:217], v[44:47]
	v_mfma_f32_16x16x32_bf16 v[48:51], v[206:209], v[160:163], v[48:51]
	v_mfma_f32_16x16x32_bf16 v[52:55], v[206:209], v[164:167], v[52:55]
	v_mfma_f32_16x16x32_bf16 v[56:59], v[206:209], v[210:213], v[56:59]
	v_mfma_f32_16x16x32_bf16 v[60:63], v[206:209], v[214:217], v[60:63]
	s_setprio 0
	v_add_u32_e32 v168, v168, v150
	v_add_u32_e32 v169, v169, v150
	ds_read_b128 v[152:155], v168
	ds_read_b128 v[156:159], v168 offset:2048
	ds_read_b128 v[160:163], v169 offset:16384
	ds_read_b128 v[164:167], v169 offset:18432
	ds_read_b128 v[202:205], v168 offset:4096
	ds_read_b128 v[206:209], v168 offset:6144
	ds_read_b128 v[210:213], v169 offset:20480
	ds_read_b128 v[214:217], v169 offset:22528
	s_setprio 1
	s_waitcnt lgkmcnt(5)
	v_mfma_f32_16x16x32_bf16 v[0:3], v[152:155], v[160:163], v[0:3]
	s_waitcnt lgkmcnt(4)
	v_mfma_f32_16x16x32_bf16 v[4:7], v[152:155], v[164:167], v[4:7]
	s_waitcnt lgkmcnt(1)
	v_mfma_f32_16x16x32_bf16 v[8:11], v[152:155], v[210:213], v[8:11]
	s_waitcnt lgkmcnt(0)
	v_mfma_f32_16x16x32_bf16 v[12:15], v[152:155], v[214:217], v[12:15]
	v_mfma_f32_16x16x32_bf16 v[16:19], v[156:159], v[160:163], v[16:19]
	v_mfma_f32_16x16x32_bf16 v[20:23], v[156:159], v[164:167], v[20:23]
	v_mfma_f32_16x16x32_bf16 v[24:27], v[156:159], v[210:213], v[24:27]
	v_mfma_f32_16x16x32_bf16 v[28:31], v[156:159], v[214:217], v[28:31]
	v_mfma_f32_16x16x32_bf16 v[32:35], v[202:205], v[160:163], v[32:35]
	v_mfma_f32_16x16x32_bf16 v[36:39], v[202:205], v[164:167], v[36:39]
	v_mfma_f32_16x16x32_bf16 v[40:43], v[202:205], v[210:213], v[40:43]
	v_mfma_f32_16x16x32_bf16 v[44:47], v[202:205], v[214:217], v[44:47]
	v_mfma_f32_16x16x32_bf16 v[48:51], v[206:209], v[160:163], v[48:51]
	v_mfma_f32_16x16x32_bf16 v[52:55], v[206:209], v[164:167], v[52:55]
	v_mfma_f32_16x16x32_bf16 v[56:59], v[206:209], v[210:213], v[56:59]
	v_mfma_f32_16x16x32_bf16 v[60:63], v[206:209], v[214:217], v[60:63]
	s_setprio 0
	s_waitcnt vmcnt(0)
	s_add_u32 s50, s50, 0x80
	s_addc_u32 s51, s51, 0
	s_add_i32 s58, s58, 0x8000
	s_cmpk_eq_i32 s50, 0xa80
	s_barrier
	s_cbranch_scc0 .LBB0_1227
	v_add_u32_e32 v147, v148, v151
	v_add_u32_e32 v151, v149, v151
	ds_read_b128 v[70:73], v147 offset:32768
	ds_read_b128 v[152:155], v147 offset:34816
	ds_read_b128 v[156:159], v151 offset:49152
	ds_read_b128 v[160:163], v151 offset:51200
	ds_read_b128 v[164:167], v147 offset:36864
	ds_read_b128 v[202:205], v147 offset:38912
	ds_read_b128 v[206:209], v151 offset:53248
	ds_read_b128 v[210:213], v151 offset:55296
	s_setprio 1
	s_waitcnt lgkmcnt(5)
	v_mfma_f32_16x16x32_bf16 v[0:3], v[70:73], v[156:159], v[0:3]
	s_waitcnt lgkmcnt(4)
	v_mfma_f32_16x16x32_bf16 v[4:7], v[70:73], v[160:163], v[4:7]
	s_waitcnt lgkmcnt(1)
	v_mfma_f32_16x16x32_bf16 v[8:11], v[70:73], v[206:209], v[8:11]
	s_waitcnt lgkmcnt(0)
	v_mfma_f32_16x16x32_bf16 v[12:15], v[70:73], v[210:213], v[12:15]
	v_mfma_f32_16x16x32_bf16 v[16:19], v[152:155], v[156:159], v[16:19]
	v_mfma_f32_16x16x32_bf16 v[20:23], v[152:155], v[160:163], v[20:23]
	v_mfma_f32_16x16x32_bf16 v[24:27], v[152:155], v[206:209], v[24:27]
	v_mfma_f32_16x16x32_bf16 v[28:31], v[152:155], v[210:213], v[28:31]
	v_mfma_f32_16x16x32_bf16 v[32:35], v[164:167], v[156:159], v[32:35]
	v_mfma_f32_16x16x32_bf16 v[36:39], v[164:167], v[160:163], v[36:39]
	v_mfma_f32_16x16x32_bf16 v[40:43], v[164:167], v[206:209], v[40:43]
	v_mfma_f32_16x16x32_bf16 v[44:47], v[164:167], v[210:213], v[44:47]
	v_mfma_f32_16x16x32_bf16 v[48:51], v[202:205], v[156:159], v[48:51]
	v_mfma_f32_16x16x32_bf16 v[52:55], v[202:205], v[160:163], v[52:55]
	v_mfma_f32_16x16x32_bf16 v[56:59], v[202:205], v[206:209], v[56:59]
	v_mfma_f32_16x16x32_bf16 v[60:63], v[202:205], v[210:213], v[60:63]
	s_setprio 0
	v_add_u32_e32 v147, v148, v150
	v_add_u32_e32 v168, v149, v150
	ds_read_b128 v[70:73], v147 offset:32768
	ds_read_b128 v[148:151], v147 offset:34816
	ds_read_b128 v[152:155], v168 offset:49152
	ds_read_b128 v[156:159], v168 offset:51200
	ds_read_b128 v[160:163], v147 offset:36864
	ds_read_b128 v[164:167], v147 offset:38912
	ds_read_b128 v[202:205], v168 offset:53248
	ds_read_b128 v[206:209], v168 offset:55296
	s_setprio 1
	s_waitcnt lgkmcnt(5)
	v_mfma_f32_16x16x32_bf16 v[210:213], v[70:73], v[152:155], v[0:3]
	s_waitcnt lgkmcnt(4)
	v_mfma_f32_16x16x32_bf16 v[214:217], v[70:73], v[156:159], v[4:7]
	s_waitcnt lgkmcnt(1)
	v_mfma_f32_16x16x32_bf16 v[218:221], v[70:73], v[202:205], v[8:11]
	s_waitcnt lgkmcnt(0)
	v_mfma_f32_16x16x32_bf16 v[70:73], v[70:73], v[206:209], v[12:15]
	v_mfma_f32_16x16x32_bf16 v[222:225], v[148:151], v[152:155], v[16:19]
	v_mfma_f32_16x16x32_bf16 v[226:229], v[148:151], v[156:159], v[20:23]
	v_mfma_f32_16x16x32_bf16 v[230:233], v[148:151], v[202:205], v[24:27]
	v_mfma_f32_16x16x32_bf16 v[148:151], v[148:151], v[206:209], v[28:31]
	v_mfma_f32_16x16x32_bf16 v[28:31], v[160:163], v[152:155], v[32:35]
	v_mfma_f32_16x16x32_bf16 v[24:27], v[160:163], v[156:159], v[36:39]
	v_mfma_f32_16x16x32_bf16 v[20:23], v[160:163], v[202:205], v[40:43]
	v_mfma_f32_16x16x32_bf16 v[16:19], v[160:163], v[206:209], v[44:47]
	v_mfma_f32_16x16x32_bf16 v[12:15], v[164:167], v[152:155], v[48:51]
	v_mfma_f32_16x16x32_bf16 v[8:11], v[164:167], v[156:159], v[52:55]
	v_mfma_f32_16x16x32_bf16 v[4:7], v[164:167], v[202:205], v[56:59]
	v_mfma_f32_16x16x32_bf16 v[0:3], v[164:167], v[206:209], v[60:63]
	s_setprio 0
	v_or3_b32 v32, v124, s55, v117
	v_mul_f32_e32 v39, 0.5, v128
	v_lshlrev_b32_e32 v128, 2, v32
	v_lshl_add_u64 v[32:33], s[36:37], 0, v[128:129]
	v_mul_f32_e32 v40, v39, v210
	v_mul_f32_e32 v38, 0.5, v144
	v_lshl_add_u64 v[34:35], v[32:33], 0, v[68:69]
	v_fmac_f32_e32 v40, 0x3fd744fd, v136
	s_waitcnt vmcnt(0)
	s_barrier
	global_store_dword v[34:35], v40, off
	v_mul_f32_e32 v40, v38, v214
	v_mul_f32_e32 v37, 0.5, v145
	v_fmac_f32_e32 v40, 0x3fd744fd, v135
	global_store_dword v[34:35], v40, off offset:64
	v_mul_f32_e32 v40, v37, v218
	v_mul_f32_e32 v36, 0.5, v146
	v_fmac_f32_e32 v40, 0x3fd744fd, v133
	global_store_dword v[34:35], v40, off offset:128
	v_mul_f32_e32 v40, v36, v70
	v_fmac_f32_e32 v40, 0x3fd744fd, v131
	global_store_dword v[34:35], v40, off offset:192
	v_or_b32_e32 v34, 1, v66
	v_ashrrev_i32_e32 v35, 31, v34
	v_lshlrev_b64 v[34:35], 12, v[34:35]
	v_mul_f32_e32 v40, v39, v211
	v_lshl_add_u64 v[34:35], v[32:33], 0, v[34:35]
	v_fmac_f32_e32 v40, 0x3fd744fd, v143
	global_store_dword v[34:35], v40, off
	v_mul_f32_e32 v40, v38, v215
	v_fmac_f32_e32 v40, 0x3fd744fd, v127
	global_store_dword v[34:35], v40, off offset:64
	v_mul_f32_e32 v40, v37, v219
	v_fmac_f32_e32 v40, 0x3fd744fd, v126
	global_store_dword v[34:35], v40, off offset:128
	v_mul_f32_e32 v40, v36, v71
	v_fmac_f32_e32 v40, 0x3fd744fd, v125
	global_store_dword v[34:35], v40, off offset:192
	v_or_b32_e32 v34, 2, v66
	v_ashrrev_i32_e32 v35, 31, v34
	v_lshlrev_b64 v[34:35], 12, v[34:35]
	v_mul_f32_e32 v40, v39, v212
	v_lshl_add_u64 v[34:35], v[32:33], 0, v[34:35]
	v_fmac_f32_e32 v40, 0x3fd744fd, v142
	global_store_dword v[34:35], v40, off
	v_mul_f32_e32 v40, v38, v216
	v_fmac_f32_e32 v40, 0x3fd744fd, v141
	global_store_dword v[34:35], v40, off offset:64
	v_mul_f32_e32 v40, v37, v220
	v_fmac_f32_e32 v40, 0x3fd744fd, v140
	global_store_dword v[34:35], v40, off offset:128
	v_mul_f32_e32 v40, v36, v72
	v_fmac_f32_e32 v40, 0x3fd744fd, v139
	global_store_dword v[34:35], v40, off offset:192
	v_or_b32_e32 v34, 3, v66
	v_ashrrev_i32_e32 v35, 31, v34
	v_lshlrev_b64 v[34:35], 12, v[34:35]
	v_mul_f32_e32 v40, v39, v213
	v_lshl_add_u64 v[34:35], v[32:33], 0, v[34:35]
	v_fmac_f32_e32 v40, 0x3fd744fd, v115
	global_store_dword v[34:35], v40, off
	v_mul_f32_e32 v40, v38, v217
	v_fmac_f32_e32 v40, 0x3fd744fd, v123
	global_store_dword v[34:35], v40, off offset:64
	v_mul_f32_e32 v40, v37, v221
	v_fmac_f32_e32 v40, 0x3fd744fd, v122
	global_store_dword v[34:35], v40, off offset:128
	v_mul_f32_e32 v40, v36, v73
	v_fmac_f32_e32 v40, 0x3fd744fd, v120
	global_store_dword v[34:35], v40, off offset:192
	v_or_b32_e32 v34, 16, v66
	v_ashrrev_i32_e32 v35, 31, v34
	v_lshlrev_b64 v[34:35], 12, v[34:35]
	v_mul_f32_e32 v40, v39, v222
	v_lshl_add_u64 v[34:35], v[32:33], 0, v[34:35]
	v_fmac_f32_e32 v40, 0x3fd744fd, v138
	global_store_dword v[34:35], v40, off
	v_mul_f32_e32 v40, v38, v226
	v_fmac_f32_e32 v40, 0x3fd744fd, v119
	global_store_dword v[34:35], v40, off offset:64
	v_mul_f32_e32 v40, v37, v230
	v_fmac_f32_e32 v40, 0x3fd744fd, v118
	global_store_dword v[34:35], v40, off offset:128
	v_mul_f32_e32 v40, v36, v148
	v_fmac_f32_e32 v40, 0x3fd744fd, v116
	global_store_dword v[34:35], v40, off offset:192
	v_or_b32_e32 v34, 17, v66
	v_ashrrev_i32_e32 v35, 31, v34
	v_lshlrev_b64 v[34:35], 12, v[34:35]
	v_mul_f32_e32 v40, v39, v223
	v_lshl_add_u64 v[34:35], v[32:33], 0, v[34:35]
	v_fmac_f32_e32 v40, 0x3fd744fd, v137
	global_store_dword v[34:35], v40, off
	v_mul_f32_e32 v40, v38, v227
	v_fmac_f32_e32 v40, 0x3fd744fd, v114
	global_store_dword v[34:35], v40, off offset:64
	v_mul_f32_e32 v40, v37, v231
	v_fmac_f32_e32 v40, 0x3fd744fd, v113
	global_store_dword v[34:35], v40, off offset:128
	v_mul_f32_e32 v40, v36, v149
	v_fmac_f32_e32 v40, 0x3fd744fd, v112
	global_store_dword v[34:35], v40, off offset:192
	v_or_b32_e32 v34, 18, v66
	v_ashrrev_i32_e32 v35, 31, v34
	v_lshlrev_b64 v[34:35], 12, v[34:35]
	v_mul_f32_e32 v40, v39, v224
	v_lshl_add_u64 v[34:35], v[32:33], 0, v[34:35]
	v_fmac_f32_e32 v40, 0x3fd744fd, v108
	global_store_dword v[34:35], v40, off
	v_mul_f32_e32 v40, v38, v228
	v_fmac_f32_e32 v40, 0x3fd744fd, v107
	global_store_dword v[34:35], v40, off offset:64
	v_mul_f32_e32 v40, v37, v232
	v_fmac_f32_e32 v40, 0x3fd744fd, v105
	global_store_dword v[34:35], v40, off offset:128
	v_mul_f32_e32 v40, v36, v150
	v_fmac_f32_e32 v40, 0x3fd744fd, v121
	global_store_dword v[34:35], v40, off offset:192
	v_or_b32_e32 v34, 19, v66
	v_ashrrev_i32_e32 v35, 31, v34
	v_lshlrev_b64 v[34:35], 12, v[34:35]
	v_mul_f32_e32 v40, v39, v225
	v_lshl_add_u64 v[34:35], v[32:33], 0, v[34:35]
	v_fmac_f32_e32 v40, 0x3fd744fd, v104
	global_store_dword v[34:35], v40, off
	v_mul_f32_e32 v40, v38, v229
	v_fmac_f32_e32 v40, 0x3fd744fd, v103
	global_store_dword v[34:35], v40, off offset:64
	v_mul_f32_e32 v40, v37, v233
	v_fmac_f32_e32 v40, 0x3fd744fd, v102
	global_store_dword v[34:35], v40, off offset:128
	v_mul_f32_e32 v40, v36, v151
	v_fmac_f32_e32 v40, 0x3fd744fd, v101
	global_store_dword v[34:35], v40, off offset:192
	v_or_b32_e32 v34, 32, v66
	v_ashrrev_i32_e32 v35, 31, v34
	v_lshlrev_b64 v[34:35], 12, v[34:35]
	v_mul_f32_e32 v28, v39, v28
	v_mul_f32_e32 v24, v38, v24
	v_mul_f32_e32 v20, v37, v20
	v_mul_f32_e32 v16, v36, v16
	v_lshl_add_u64 v[34:35], v[32:33], 0, v[34:35]
	v_fmac_f32_e32 v28, 0x3fd744fd, v106
	v_fmac_f32_e32 v24, 0x3fd744fd, v111
	v_fmac_f32_e32 v20, 0x3fd744fd, v110
	v_fmac_f32_e32 v16, 0x3fd744fd, v109
	global_store_dword v[34:35], v28, off
	global_store_dword v[34:35], v24, off offset:64
	global_store_dword v[34:35], v20, off offset:128
	global_store_dword v[34:35], v16, off offset:192
	v_or_b32_e32 v34, 33, v66
	v_ashrrev_i32_e32 v35, 31, v34
	v_lshlrev_b64 v[34:35], 12, v[34:35]
	v_mul_f32_e32 v16, v39, v29
	v_lshl_add_u64 v[34:35], v[32:33], 0, v[34:35]
	v_fmac_f32_e32 v16, 0x3fd744fd, v99
	global_store_dword v[34:35], v16, off
	v_mul_f32_e32 v16, v38, v25
	v_fmac_f32_e32 v16, 0x3fd744fd, v96
	global_store_dword v[34:35], v16, off offset:64
	v_mul_f32_e32 v16, v37, v21
	v_fmac_f32_e32 v16, 0x3fd744fd, v92
	global_store_dword v[34:35], v16, off offset:128
	v_mul_f32_e32 v16, v36, v17
	v_fmac_f32_e32 v16, 0x3fd744fd, v90
	global_store_dword v[34:35], v16, off offset:192
	v_or_b32_e32 v16, 34, v66
	v_ashrrev_i32_e32 v17, 31, v16
	v_lshlrev_b64 v[16:17], 12, v[16:17]
	v_mul_f32_e32 v20, v39, v30
	v_lshl_add_u64 v[16:17], v[32:33], 0, v[16:17]
	v_fmac_f32_e32 v20, 0x3fd744fd, v89
	global_store_dword v[16:17], v20, off
	v_mul_f32_e32 v20, v38, v26
	v_fmac_f32_e32 v20, 0x3fd744fd, v100
	global_store_dword v[16:17], v20, off offset:64
	v_mul_f32_e32 v20, v37, v22
	v_mul_f32_e32 v18, v36, v18
	v_fmac_f32_e32 v20, 0x3fd744fd, v97
	v_fmac_f32_e32 v18, 0x3fd744fd, v93
	global_store_dword v[16:17], v20, off offset:128
	global_store_dword v[16:17], v18, off offset:192
	v_or_b32_e32 v16, 35, v66
	v_ashrrev_i32_e32 v17, 31, v16
	v_lshlrev_b64 v[16:17], 12, v[16:17]
	v_mul_f32_e32 v18, v39, v31
	v_lshl_add_u64 v[16:17], v[32:33], 0, v[16:17]
	v_fmac_f32_e32 v18, 0x3fd744fd, v87
	global_store_dword v[16:17], v18, off
	v_mul_f32_e32 v18, v38, v27
	v_fmac_f32_e32 v18, 0x3fd744fd, v86
	global_store_dword v[16:17], v18, off offset:64
	v_mul_f32_e32 v18, v37, v23
	v_fmac_f32_e32 v18, 0x3fd744fd, v94
	global_store_dword v[16:17], v18, off offset:128
	v_mul_f32_e32 v18, v36, v19
	v_fmac_f32_e32 v18, 0x3fd744fd, v91
	global_store_dword v[16:17], v18, off offset:192
	v_or_b32_e32 v16, 48, v66
	v_ashrrev_i32_e32 v17, 31, v16
	v_lshlrev_b64 v[16:17], 12, v[16:17]
	v_mul_f32_e32 v12, v39, v12
	v_mul_f32_e32 v8, v38, v8
	v_mul_f32_e32 v4, v37, v4
	v_mul_f32_e32 v0, v36, v0
	v_lshl_add_u64 v[16:17], v[32:33], 0, v[16:17]
	v_fmac_f32_e32 v12, 0x3fd744fd, v88
	v_fmac_f32_e32 v8, 0x3fd744fd, v84
	v_fmac_f32_e32 v4, 0x3fd744fd, v98
	v_fmac_f32_e32 v0, 0x3fd744fd, v95
	global_store_dword v[16:17], v12, off
	global_store_dword v[16:17], v8, off offset:64
	global_store_dword v[16:17], v4, off offset:128
	global_store_dword v[16:17], v0, off offset:192
	v_or_b32_e32 v16, 49, v66
	v_ashrrev_i32_e32 v17, 31, v16
	v_lshlrev_b64 v[16:17], 12, v[16:17]
	v_mul_f32_e32 v0, v39, v13
	v_lshl_add_u64 v[16:17], v[32:33], 0, v[16:17]
	v_fmac_f32_e32 v0, 0x3fd744fd, v85
	global_store_dword v[16:17], v0, off
	v_mul_f32_e32 v0, v38, v9
	v_fmac_f32_e32 v0, 0x3fd744fd, v82
	global_store_dword v[16:17], v0, off offset:64
	v_mul_f32_e32 v0, v37, v5
	v_fmac_f32_e32 v0, 0x3fd744fd, v80
	global_store_dword v[16:17], v0, off offset:128
	v_mul_f32_e32 v0, v36, v1
	v_fmac_f32_e32 v0, 0x3fd744fd, v78
	global_store_dword v[16:17], v0, off offset:192
	v_or_b32_e32 v0, 50, v66
	v_ashrrev_i32_e32 v1, 31, v0
	v_lshlrev_b64 v[0:1], 12, v[0:1]
	v_mul_f32_e32 v4, v39, v14
	v_lshl_add_u64 v[0:1], v[32:33], 0, v[0:1]
	v_fmac_f32_e32 v4, 0x3fd744fd, v77
	global_store_dword v[0:1], v4, off
	v_mul_f32_e32 v4, v38, v10
	v_fmac_f32_e32 v4, 0x3fd744fd, v83
	global_store_dword v[0:1], v4, off offset:64
	v_mul_f32_e32 v4, v37, v6
	v_mul_f32_e32 v2, v36, v2
	v_fmac_f32_e32 v4, 0x3fd744fd, v81
	v_fmac_f32_e32 v2, 0x3fd744fd, v79
	global_store_dword v[0:1], v4, off offset:128
	global_store_dword v[0:1], v2, off offset:192
	v_or_b32_e32 v0, 51, v66
	v_ashrrev_i32_e32 v1, 31, v0
	v_lshlrev_b64 v[0:1], 12, v[0:1]
	v_mul_f32_e32 v2, v39, v15
	v_lshl_add_u64 v[0:1], v[32:33], 0, v[0:1]
	v_fmac_f32_e32 v2, 0x3fd744fd, v76
	global_store_dword v[0:1], v2, off
	v_mul_f32_e32 v2, v38, v11
	v_fmac_f32_e32 v2, 0x3fd744fd, v75
	global_store_dword v[0:1], v2, off offset:64
	v_mul_f32_e32 v2, v37, v7
	v_fmac_f32_e32 v2, 0x3fd744fd, v74
	global_store_dword v[0:1], v2, off offset:128
	v_mul_f32_e32 v2, v36, v3
	v_fmac_f32_e32 v2, 0x3fd744fd, v67
	s_movk_i32 s96, 0x1000
	global_store_dword v[0:1], v2, off offset:192
	s_branch .LBB0_1220

.LBB0_1239:
	s_and_b32 s56, s55, 0x8000
	s_xor_b32 s57, s56, 0x8000
	v_add_u32_e32 v86, s57, v72
	v_lshl_add_u64 v[78:79], v[66:67], 0, s[40:41]
	v_add_u32_e32 v87, 0x4000, v86
	v_readfirstlane_b32 s57, v86
	v_lshl_add_u64 v[80:81], v[78:79], 0, s[28:29]
	v_lshl_add_u64 v[82:83], v[64:65], 0, s[40:41]
	s_mov_b32 m0, s57
	v_readfirstlane_b32 s57, v87
	v_lshl_add_u64 v[84:85], v[82:83], 0, s[28:29]
	global_load_lds_dwordx4 v[80:81], off
	s_mov_b32 m0, s57
	v_lshl_add_u64 v[80:81], v[78:79], 0, s[30:31]
	global_load_lds_dwordx4 v[84:85], off
	v_add_u32_e32 v84, 0x1000, v86
	v_add3_u32 v110, s56, v74, v75
	v_readfirstlane_b32 s57, v84
	v_add_u32_e32 v84, 0x5000, v86
	s_mov_b32 m0, s57
	v_readfirstlane_b32 s57, v84
	v_add_u32_e32 v84, 0x2000, v86
	global_load_lds_dwordx4 v[80:81], off
	v_lshl_add_u64 v[80:81], v[82:83], 0, s[30:31]
	s_mov_b32 m0, s57
	v_readfirstlane_b32 s57, v84
	v_add_u32_e32 v84, 0x6000, v86
	global_load_lds_dwordx4 v[80:81], off
	v_lshl_add_u64 v[80:81], v[78:79], 0, s[0:1]
	s_mov_b32 m0, s57
	v_readfirstlane_b32 s57, v84
	global_load_lds_dwordx4 v[80:81], off
	v_lshl_add_u64 v[80:81], v[82:83], 0, s[0:1]
	s_mov_b32 m0, s57
	v_lshl_add_u64 v[78:79], v[78:79], 0, s[22:23]
	global_load_lds_dwordx4 v[80:81], off
	v_add_u32_e32 v80, 0x3000, v86
	v_add_u32_e32 v98, v110, v76
	v_readfirstlane_b32 s57, v80
	v_add_u32_e32 v80, 0x7000, v86
	s_mov_b32 m0, s57
	v_readfirstlane_b32 s57, v80
	global_load_lds_dwordx4 v[78:79], off
	v_lshl_add_u64 v[78:79], v[82:83], 0, s[22:23]
	s_mov_b32 m0, s57
	s_nop 0
	global_load_lds_dwordx4 v[78:79], off
	v_or_b32_e32 v78, s56, v77
	v_add_u32_e32 v111, v78, v75
	v_add_u32_e32 v106, v111, v76
	ds_read_b128 v[78:81], v98
	ds_read_b128 v[82:85], v98 offset:2048
	ds_read_b128 v[86:89], v106 offset:16384
	ds_read_b128 v[90:93], v106 offset:18432
	ds_read_b128 v[94:97], v98 offset:4096
	ds_read_b128 v[98:101], v98 offset:6144
	ds_read_b128 v[102:105], v106 offset:20480
	ds_read_b128 v[106:109], v106 offset:22528
	s_setprio 1
	s_waitcnt lgkmcnt(0)
	v_mfma_f32_16x16x32_bf16 v[60:63], v[78:81], v[86:89], v[60:63]
	v_mfma_f32_16x16x32_bf16 v[56:59], v[78:81], v[90:93], v[56:59]
	v_mfma_f32_16x16x32_bf16 v[52:55], v[78:81], v[102:105], v[52:55]
	v_mfma_f32_16x16x32_bf16 v[48:51], v[78:81], v[106:109], v[48:51]
	v_mfma_f32_16x16x32_bf16 v[44:47], v[82:85], v[86:89], v[44:47]
	v_mfma_f32_16x16x32_bf16 v[40:43], v[82:85], v[90:93], v[40:43]
	v_mfma_f32_16x16x32_bf16 v[36:39], v[82:85], v[102:105], v[36:39]
	v_mfma_f32_16x16x32_bf16 v[32:35], v[82:85], v[106:109], v[32:35]
	v_mfma_f32_16x16x32_bf16 v[28:31], v[94:97], v[86:89], v[28:31]
	v_mfma_f32_16x16x32_bf16 v[24:27], v[94:97], v[90:93], v[24:27]
	v_mfma_f32_16x16x32_bf16 v[20:23], v[94:97], v[102:105], v[20:23]
	v_mfma_f32_16x16x32_bf16 v[16:19], v[94:97], v[106:109], v[16:19]
	v_mfma_f32_16x16x32_bf16 v[12:15], v[98:101], v[86:89], v[12:15]
	v_mfma_f32_16x16x32_bf16 v[8:11], v[98:101], v[90:93], v[8:11]
	v_mfma_f32_16x16x32_bf16 v[4:7], v[98:101], v[102:105], v[4:7]
	v_mfma_f32_16x16x32_bf16 v[0:3], v[98:101], v[106:109], v[0:3]
	s_setprio 0
	v_add_u32_e32 v98, v110, v73
	v_add_u32_e32 v106, v111, v73
	ds_read_b128 v[78:81], v98
	ds_read_b128 v[82:85], v98 offset:2048
	ds_read_b128 v[86:89], v106 offset:16384
	ds_read_b128 v[90:93], v106 offset:18432
	ds_read_b128 v[94:97], v98 offset:4096
	ds_read_b128 v[98:101], v98 offset:6144
	ds_read_b128 v[102:105], v106 offset:20480
	ds_read_b128 v[106:109], v106 offset:22528
	s_setprio 1
	s_waitcnt lgkmcnt(5)
	v_mfma_f32_16x16x32_bf16 v[60:63], v[78:81], v[86:89], v[60:63]
	s_waitcnt lgkmcnt(4)
	v_mfma_f32_16x16x32_bf16 v[56:59], v[78:81], v[90:93], v[56:59]
	s_waitcnt lgkmcnt(1)
	v_mfma_f32_16x16x32_bf16 v[52:55], v[78:81], v[102:105], v[52:55]
	s_waitcnt lgkmcnt(0)
	v_mfma_f32_16x16x32_bf16 v[48:51], v[78:81], v[106:109], v[48:51]
	v_mfma_f32_16x16x32_bf16 v[44:47], v[82:85], v[86:89], v[44:47]
	v_mfma_f32_16x16x32_bf16 v[40:43], v[82:85], v[90:93], v[40:43]
	v_mfma_f32_16x16x32_bf16 v[36:39], v[82:85], v[102:105], v[36:39]
	v_mfma_f32_16x16x32_bf16 v[32:35], v[82:85], v[106:109], v[32:35]
	v_mfma_f32_16x16x32_bf16 v[28:31], v[94:97], v[86:89], v[28:31]
	v_mfma_f32_16x16x32_bf16 v[24:27], v[94:97], v[90:93], v[24:27]
	v_mfma_f32_16x16x32_bf16 v[20:23], v[94:97], v[102:105], v[20:23]
	v_mfma_f32_16x16x32_bf16 v[16:19], v[94:97], v[106:109], v[16:19]
	v_mfma_f32_16x16x32_bf16 v[12:15], v[98:101], v[86:89], v[12:15]
	v_mfma_f32_16x16x32_bf16 v[8:11], v[98:101], v[90:93], v[8:11]
	v_mfma_f32_16x16x32_bf16 v[4:7], v[98:101], v[102:105], v[4:7]
	v_mfma_f32_16x16x32_bf16 v[0:3], v[98:101], v[106:109], v[0:3]
	s_setprio 0
	s_add_i32 s55, s55, 0x8000
	s_waitcnt vmcnt(0)
	s_add_u32 s40, s40, 0x80
	s_addc_u32 s41, s41, 0
	s_cmpk_lg_i32 s40, 0x780
	s_barrier
	s_cbranch_scc1 .LBB0_1239
	v_add_u32_e32 v72, v77, v75
	v_add_u32_e32 v102, v74, v75
	v_add_u32_e32 v90, v72, v76
	v_add_u32_e32 v98, v102, v76
	ds_read_b128 v[64:67], v90 offset:55296
	ds_read_b128 v[74:77], v90 offset:53248
	ds_read_b128 v[78:81], v98 offset:38912
	ds_read_b128 v[82:85], v98 offset:36864
	ds_read_b128 v[86:89], v90 offset:51200
	ds_read_b128 v[90:93], v90 offset:49152
	ds_read_b128 v[94:97], v98 offset:34816
	ds_read_b128 v[98:101], v98 offset:32768
	s_setprio 1
	s_waitcnt lgkmcnt(0)
	v_mfma_f32_16x16x32_bf16 v[60:63], v[98:101], v[90:93], v[60:63]
	v_mfma_f32_16x16x32_bf16 v[56:59], v[98:101], v[86:89], v[56:59]
	v_mfma_f32_16x16x32_bf16 v[52:55], v[98:101], v[74:77], v[52:55]
	v_mfma_f32_16x16x32_bf16 v[48:51], v[98:101], v[64:67], v[48:51]
	v_mfma_f32_16x16x32_bf16 v[44:47], v[94:97], v[90:93], v[44:47]
	v_mfma_f32_16x16x32_bf16 v[40:43], v[94:97], v[86:89], v[40:43]
	v_mfma_f32_16x16x32_bf16 v[36:39], v[94:97], v[74:77], v[36:39]
	v_mfma_f32_16x16x32_bf16 v[94:97], v[94:97], v[64:67], v[32:35]
	v_mfma_f32_16x16x32_bf16 v[28:31], v[82:85], v[90:93], v[28:31]
	v_mfma_f32_16x16x32_bf16 v[24:27], v[82:85], v[86:89], v[24:27]
	v_mfma_f32_16x16x32_bf16 v[20:23], v[82:85], v[74:77], v[20:23]
	v_mfma_f32_16x16x32_bf16 v[82:85], v[82:85], v[64:67], v[16:19]
	v_mfma_f32_16x16x32_bf16 v[12:15], v[78:81], v[90:93], v[12:15]
	v_mfma_f32_16x16x32_bf16 v[8:11], v[78:81], v[86:89], v[8:11]
	v_mfma_f32_16x16x32_bf16 v[4:7], v[78:81], v[74:77], v[4:7]
	v_mfma_f32_16x16x32_bf16 v[64:67], v[78:81], v[64:67], v[0:3]
	s_setprio 0
	v_add_u32_e32 v32, v102, v73
	v_add_u32_e32 v33, v72, v73
	ds_read_b128 v[0:3], v32 offset:32768
	ds_read_b128 v[16:19], v32 offset:34816
	ds_read_b128 v[72:75], v33 offset:49152
	ds_read_b128 v[76:79], v33 offset:51200
	ds_read_b128 v[86:89], v32 offset:36864
	ds_read_b128 v[90:93], v32 offset:38912
	ds_read_b128 v[98:101], v33 offset:53248
	ds_read_b128 v[102:105], v33 offset:55296
	s_setprio 1
	s_waitcnt lgkmcnt(5)
	v_mfma_f32_16x16x32_bf16 v[60:63], v[0:3], v[72:75], v[60:63]
	s_waitcnt lgkmcnt(4)
	v_mfma_f32_16x16x32_bf16 v[56:59], v[0:3], v[76:79], v[56:59]
	s_waitcnt lgkmcnt(1)
	v_mfma_f32_16x16x32_bf16 v[52:55], v[0:3], v[98:101], v[52:55]
	s_waitcnt lgkmcnt(0)
	v_mfma_f32_16x16x32_bf16 v[106:109], v[0:3], v[102:105], v[48:51]
	v_mfma_f32_16x16x32_bf16 v[44:47], v[16:19], v[72:75], v[44:47]
	v_mfma_f32_16x16x32_bf16 v[32:35], v[16:19], v[76:79], v[40:43]
	v_mfma_f32_16x16x32_bf16 v[40:43], v[16:19], v[98:101], v[36:39]
	v_mfma_f32_16x16x32_bf16 v[36:39], v[16:19], v[102:105], v[94:97]
	v_mfma_f32_16x16x32_bf16 v[28:31], v[86:89], v[72:75], v[28:31]
	v_mfma_f32_16x16x32_bf16 v[16:19], v[86:89], v[76:79], v[24:27]
	v_mfma_f32_16x16x32_bf16 v[24:27], v[86:89], v[98:101], v[20:23]
	v_mfma_f32_16x16x32_bf16 v[20:23], v[86:89], v[102:105], v[82:85]
	v_mfma_f32_16x16x32_bf16 v[12:15], v[90:93], v[72:75], v[12:15]
	v_mfma_f32_16x16x32_bf16 v[0:3], v[90:93], v[76:79], v[8:11]
	v_mfma_f32_16x16x32_bf16 v[8:11], v[90:93], v[98:101], v[4:7]
	v_mfma_f32_16x16x32_bf16 v[4:7], v[90:93], v[102:105], v[64:67]
	s_setprio 0
	v_lshl_add_u32 v48, v70, 6, s54
	v_lshl_or_b32 v50, v71, 2, v48
	v_mul_f32_e32 v48, 0xbfb8aa3b, v60
	v_exp_f32_e32 v51, v48
	s_lshl_b32 s40, s53, 7
	s_add_u32 s40, s60, s40
	s_addc_u32 s41, s61, 0
	v_lshlrev_b32_e32 v128, 6, v68
	v_add_f32_e32 v51, 1.0, v51
	v_lshl_add_u64 v[48:49], s[40:41], 0, v[128:129]
	v_div_scale_f32 v66, s[40:41], v51, v51, v60
	v_rcp_f32_e32 v67, v66
	v_lshlrev_b32_e32 v128, 1, v69
	v_lshl_add_u64 v[48:49], v[48:49], 0, v[128:129]
	v_mad_i64_i32 v[64:65], s[40:41], v50, s73, v[48:49]
	v_fma_f32 v68, -v66, v67, 1.0
	v_fmac_f32_e32 v67, v68, v67
	v_div_scale_f32 v68, vcc, v60, v51, v60
	v_mul_f32_e32 v69, v68, v67
	v_fma_f32 v70, -v66, v69, v68
	v_fmac_f32_e32 v69, v70, v67
	v_fma_f32 v66, -v66, v69, v68
	v_mul_f32_e32 v68, 0xbfb8aa3b, v56
	v_exp_f32_e32 v68, v68
	v_div_fmas_f32 v66, v66, v67, v69
	v_div_fixup_f32 v51, v66, v51, v60
	v_mul_f32_e32 v51, v52, v51
	v_add_f32_e32 v60, 1.0, v68
	v_div_scale_f32 v66, s[40:41], v60, v60, v56
	v_rcp_f32_e32 v67, v66
	v_cvt_pk_bf16_f32 v51, v51, v51
	s_waitcnt vmcnt(0)
	s_barrier
	global_store_short v[64:65], v51, off
	v_fma_f32 v51, -v66, v67, 1.0
	v_fmac_f32_e32 v67, v51, v67
	v_div_scale_f32 v51, vcc, v56, v60, v56
	v_mul_f32_e32 v52, v51, v67
	v_fma_f32 v68, -v66, v52, v51
	v_fmac_f32_e32 v52, v68, v67
	v_fma_f32 v51, -v66, v52, v51
	v_div_fmas_f32 v51, v51, v67, v52
	v_div_fixup_f32 v51, v51, v60, v56
	v_mul_f32_e32 v51, v106, v51
	v_cvt_pk_bf16_f32 v51, v51, v51
	global_store_short v[64:65], v51, off offset:32
	v_mul_f32_e32 v51, 0xbfb8aa3b, v61
	v_exp_f32_e32 v51, v51
	v_or_b32_e32 v52, 1, v50
	v_mad_i64_i32 v[64:65], s[40:41], v52, s73, v[48:49]
	v_add_f32_e32 v51, 1.0, v51
	v_div_scale_f32 v56, s[40:41], v51, v51, v61
	v_rcp_f32_e32 v60, v56
	v_div_scale_f32 v52, vcc, v61, v51, v61
	v_fma_f32 v66, -v56, v60, 1.0
	v_fmac_f32_e32 v60, v66, v60
	v_mul_f32_e32 v66, v52, v60
	v_fma_f32 v67, -v56, v66, v52
	v_fmac_f32_e32 v66, v67, v60
	v_fma_f32 v52, -v56, v66, v52
	v_mul_f32_e32 v56, 0xbfb8aa3b, v57
	v_exp_f32_e32 v56, v56
	v_div_fmas_f32 v52, v52, v60, v66
	v_div_fixup_f32 v51, v52, v51, v61
	v_mul_f32_e32 v51, v53, v51
	v_add_f32_e32 v52, 1.0, v56
	v_div_scale_f32 v56, s[40:41], v52, v52, v57
	v_rcp_f32_e32 v60, v56
	v_cvt_pk_bf16_f32 v51, v51, v51
	global_store_short v[64:65], v51, off
	v_fma_f32 v51, -v56, v60, 1.0
	v_fmac_f32_e32 v60, v51, v60
	v_div_scale_f32 v51, vcc, v57, v52, v57
	v_mul_f32_e32 v53, v51, v60
	v_fma_f32 v61, -v56, v53, v51
	v_fmac_f32_e32 v53, v61, v60
	v_fma_f32 v51, -v56, v53, v51
	v_div_fmas_f32 v51, v51, v60, v53
	v_div_fixup_f32 v51, v51, v52, v57
	v_mul_f32_e32 v51, v107, v51
	v_cvt_pk_bf16_f32 v51, v51, v51
	global_store_short v[64:65], v51, off offset:32
	v_mul_f32_e32 v51, 0xbfb8aa3b, v62
	v_exp_f32_e32 v51, v51
	v_or_b32_e32 v52, 2, v50
	v_mad_i64_i32 v[52:53], s[40:41], v52, s73, v[48:49]
	v_add_f32_e32 v51, 1.0, v51
	v_div_scale_f32 v56, s[40:41], v51, v51, v62
	v_rcp_f32_e32 v57, v56
	v_div_scale_f32 v60, vcc, v62, v51, v62
	v_fma_f32 v61, -v56, v57, 1.0
	v_fmac_f32_e32 v57, v61, v57
	v_mul_f32_e32 v61, v60, v57
	v_fma_f32 v64, -v56, v61, v60
	v_fmac_f32_e32 v61, v64, v57
	v_fma_f32 v56, -v56, v61, v60
	v_mul_f32_e32 v60, 0xbfb8aa3b, v58
	v_exp_f32_e32 v60, v60
	v_div_fmas_f32 v56, v56, v57, v61
	v_div_fixup_f32 v51, v56, v51, v62
	v_mul_f32_e32 v51, v54, v51
	v_add_f32_e32 v56, 1.0, v60
	v_div_scale_f32 v57, s[40:41], v56, v56, v58
	v_rcp_f32_e32 v60, v57
	v_cvt_pk_bf16_f32 v51, v51, v51
	global_store_short v[52:53], v51, off
	v_fma_f32 v51, -v57, v60, 1.0
	v_fmac_f32_e32 v60, v51, v60
	v_div_scale_f32 v51, vcc, v58, v56, v58
	v_mul_f32_e32 v54, v51, v60
	v_fma_f32 v61, -v57, v54, v51
	v_fmac_f32_e32 v54, v61, v60
	v_fma_f32 v51, -v57, v54, v51
	v_div_fmas_f32 v51, v51, v60, v54
	v_div_fixup_f32 v51, v51, v56, v58
	v_mul_f32_e32 v51, v108, v51
	v_cvt_pk_bf16_f32 v51, v51, v51
	global_store_short v[52:53], v51, off offset:32
	v_mul_f32_e32 v51, 0xbfb8aa3b, v63
	v_exp_f32_e32 v51, v51
	v_or_b32_e32 v52, 3, v50
	v_mad_i64_i32 v[52:53], s[40:41], v52, s73, v[48:49]
	v_add_f32_e32 v51, 1.0, v51
	v_div_scale_f32 v54, s[40:41], v51, v51, v63
	v_rcp_f32_e32 v56, v54
	v_div_scale_f32 v57, vcc, v63, v51, v63
	v_fma_f32 v58, -v54, v56, 1.0
	v_fmac_f32_e32 v56, v58, v56
	v_mul_f32_e32 v58, v57, v56
	v_fma_f32 v60, -v54, v58, v57
	v_fmac_f32_e32 v58, v60, v56
	v_fma_f32 v54, -v54, v58, v57
	v_mul_f32_e32 v57, 0xbfb8aa3b, v59
	v_exp_f32_e32 v57, v57
	v_div_fmas_f32 v54, v54, v56, v58
	v_div_fixup_f32 v51, v54, v51, v63
	v_mul_f32_e32 v51, v55, v51
	v_add_f32_e32 v54, 1.0, v57
	v_div_scale_f32 v56, s[40:41], v54, v54, v59
	v_rcp_f32_e32 v57, v56
	v_cvt_pk_bf16_f32 v51, v51, v51
	global_store_short v[52:53], v51, off
	v_fma_f32 v51, -v56, v57, 1.0
	v_fmac_f32_e32 v57, v51, v57
	v_div_scale_f32 v51, vcc, v59, v54, v59
	v_mul_f32_e32 v55, v51, v57
	v_fma_f32 v58, -v56, v55, v51
	v_fmac_f32_e32 v55, v58, v57
	v_fma_f32 v51, -v56, v55, v51
	v_div_fmas_f32 v51, v51, v57, v55
	v_div_fixup_f32 v51, v51, v54, v59
	v_mul_f32_e32 v51, v109, v51
	v_cvt_pk_bf16_f32 v51, v51, v51
	global_store_short v[52:53], v51, off offset:32
	v_mul_f32_e32 v51, 0xbfb8aa3b, v44
	v_exp_f32_e32 v51, v51
	v_or_b32_e32 v52, 16, v50
	v_mad_i64_i32 v[52:53], s[40:41], v52, s73, v[48:49]
	v_add_f32_e32 v51, 1.0, v51
	v_div_scale_f32 v54, s[40:41], v51, v51, v44
	v_rcp_f32_e32 v55, v54
	v_div_scale_f32 v56, vcc, v44, v51, v44
	v_fma_f32 v57, -v54, v55, 1.0
	v_fmac_f32_e32 v55, v57, v55
	v_mul_f32_e32 v57, v56, v55
	v_fma_f32 v58, -v54, v57, v56
	v_fmac_f32_e32 v57, v58, v55
	v_fma_f32 v54, -v54, v57, v56
	v_mul_f32_e32 v56, 0xbfb8aa3b, v32
	v_exp_f32_e32 v56, v56
	v_div_fmas_f32 v54, v54, v55, v57
	v_div_fixup_f32 v44, v54, v51, v44
	v_mul_f32_e32 v40, v40, v44
	v_add_f32_e32 v51, 1.0, v56
	v_div_scale_f32 v54, s[40:41], v51, v51, v32
	v_rcp_f32_e32 v55, v54
	v_cvt_pk_bf16_f32 v40, v40, v40
	global_store_short v[52:53], v40, off
	v_fma_f32 v40, -v54, v55, 1.0
	v_fmac_f32_e32 v55, v40, v55
	v_div_scale_f32 v40, vcc, v32, v51, v32
	v_mul_f32_e32 v44, v40, v55
	v_fma_f32 v56, -v54, v44, v40
	v_fmac_f32_e32 v44, v56, v55
	v_fma_f32 v40, -v54, v44, v40
	v_div_fmas_f32 v40, v40, v55, v44
	v_div_fixup_f32 v32, v40, v51, v32
	v_mul_f32_e32 v32, v36, v32
	v_cvt_pk_bf16_f32 v32, v32, v32
	global_store_short v[52:53], v32, off offset:32
	v_mul_f32_e32 v32, 0xbfb8aa3b, v45
	v_exp_f32_e32 v32, v32
	v_or_b32_e32 v36, 17, v50
	v_mad_i64_i32 v[52:53], s[40:41], v36, s73, v[48:49]
	v_add_f32_e32 v32, 1.0, v32
	v_div_scale_f32 v40, s[40:41], v32, v32, v45
	v_rcp_f32_e32 v44, v40
	v_div_scale_f32 v36, vcc, v45, v32, v45
	v_fma_f32 v51, -v40, v44, 1.0
	v_fmac_f32_e32 v44, v51, v44
	v_mul_f32_e32 v51, v36, v44
	v_fma_f32 v54, -v40, v51, v36
	v_fmac_f32_e32 v51, v54, v44
	v_fma_f32 v36, -v40, v51, v36
	v_mul_f32_e32 v40, 0xbfb8aa3b, v33
	v_exp_f32_e32 v40, v40
	v_div_fmas_f32 v36, v36, v44, v51
	v_div_fixup_f32 v32, v36, v32, v45
	v_mul_f32_e32 v32, v41, v32
	v_add_f32_e32 v36, 1.0, v40
	v_div_scale_f32 v40, s[40:41], v36, v36, v33
	v_rcp_f32_e32 v44, v40
	v_cvt_pk_bf16_f32 v32, v32, v32
	global_store_short v[52:53], v32, off
	v_fma_f32 v32, -v40, v44, 1.0
	v_fmac_f32_e32 v44, v32, v44
	v_div_scale_f32 v32, vcc, v33, v36, v33
	v_mul_f32_e32 v41, v32, v44
	v_fma_f32 v45, -v40, v41, v32
	v_fmac_f32_e32 v41, v45, v44
	v_fma_f32 v32, -v40, v41, v32
	v_div_fmas_f32 v32, v32, v44, v41
	v_div_fixup_f32 v32, v32, v36, v33
	v_mul_f32_e32 v32, v37, v32
	v_cvt_pk_bf16_f32 v32, v32, v32
	global_store_short v[52:53], v32, off offset:32
	v_mul_f32_e32 v32, 0xbfb8aa3b, v46
	v_exp_f32_e32 v32, v32
	v_or_b32_e32 v33, 18, v50
	v_add_f32_e32 v36, 1.0, v32
	v_div_scale_f32 v37, s[40:41], v36, v36, v46
	v_rcp_f32_e32 v40, v37
	v_div_scale_f32 v41, vcc, v46, v36, v46
	v_mad_i64_i32 v[32:33], s[40:41], v33, s73, v[48:49]
	v_fma_f32 v44, -v37, v40, 1.0
	v_fmac_f32_e32 v40, v44, v40
	v_mul_f32_e32 v44, v41, v40
	v_fma_f32 v45, -v37, v44, v41
	v_fmac_f32_e32 v44, v45, v40
	v_fma_f32 v37, -v37, v44, v41
	v_mul_f32_e32 v41, 0xbfb8aa3b, v34
	v_exp_f32_e32 v41, v41
	v_div_fmas_f32 v37, v37, v40, v44
	v_div_fixup_f32 v36, v37, v36, v46
	v_mul_f32_e32 v36, v42, v36
	v_add_f32_e32 v37, 1.0, v41
	v_div_scale_f32 v40, s[40:41], v37, v37, v34
	v_rcp_f32_e32 v41, v40
	v_cvt_pk_bf16_f32 v36, v36, v36
	global_store_short v[32:33], v36, off
	v_fma_f32 v36, -v40, v41, 1.0
	v_fmac_f32_e32 v41, v36, v41
	v_div_scale_f32 v36, vcc, v34, v37, v34
	v_mul_f32_e32 v42, v36, v41
	v_fma_f32 v44, -v40, v42, v36
	v_fmac_f32_e32 v42, v44, v41
	v_fma_f32 v36, -v40, v42, v36
	v_div_fmas_f32 v36, v36, v41, v42
	v_div_fixup_f32 v34, v36, v37, v34
	v_mul_f32_e32 v34, v38, v34
	v_cvt_pk_bf16_f32 v34, v34, v34
	global_store_short v[32:33], v34, off offset:32
	v_mul_f32_e32 v32, 0xbfb8aa3b, v47
	v_exp_f32_e32 v32, v32
	v_or_b32_e32 v33, 19, v50
	v_add_f32_e32 v34, 1.0, v32
	v_div_scale_f32 v36, s[40:41], v34, v34, v47
	v_rcp_f32_e32 v37, v36
	v_div_scale_f32 v38, vcc, v47, v34, v47
	v_mad_i64_i32 v[32:33], s[40:41], v33, s73, v[48:49]
	v_fma_f32 v40, -v36, v37, 1.0
	v_fmac_f32_e32 v37, v40, v37
	v_mul_f32_e32 v40, v38, v37
	v_fma_f32 v41, -v36, v40, v38
	v_fmac_f32_e32 v40, v41, v37
	v_fma_f32 v36, -v36, v40, v38
	v_mul_f32_e32 v38, 0xbfb8aa3b, v35
	v_exp_f32_e32 v38, v38
	v_div_fmas_f32 v36, v36, v37, v40
	v_div_fixup_f32 v34, v36, v34, v47
	v_mul_f32_e32 v34, v43, v34
	v_add_f32_e32 v36, 1.0, v38
	v_div_scale_f32 v37, s[40:41], v36, v36, v35
	v_rcp_f32_e32 v38, v37
	v_cvt_pk_bf16_f32 v34, v34, v34
	global_store_short v[32:33], v34, off
	v_fma_f32 v34, -v37, v38, 1.0
	v_fmac_f32_e32 v38, v34, v38
	v_div_scale_f32 v34, vcc, v35, v36, v35
	v_mul_f32_e32 v40, v34, v38
	v_fma_f32 v41, -v37, v40, v34
	v_fmac_f32_e32 v40, v41, v38
	v_fma_f32 v34, -v37, v40, v34
	v_div_fmas_f32 v34, v34, v38, v40
	v_div_fixup_f32 v34, v34, v36, v35
	v_mul_f32_e32 v34, v39, v34
	v_cvt_pk_bf16_f32 v34, v34, v34
	global_store_short v[32:33], v34, off offset:32
	v_mul_f32_e32 v32, 0xbfb8aa3b, v28
	v_exp_f32_e32 v32, v32
	v_or_b32_e32 v33, 32, v50
	v_add_f32_e32 v34, 1.0, v32
	v_div_scale_f32 v35, s[40:41], v34, v34, v28
	v_rcp_f32_e32 v36, v35
	v_div_scale_f32 v37, vcc, v28, v34, v28
	v_mad_i64_i32 v[32:33], s[40:41], v33, s73, v[48:49]
	v_fma_f32 v38, -v35, v36, 1.0
	v_fmac_f32_e32 v36, v38, v36
	v_mul_f32_e32 v38, v37, v36
	v_fma_f32 v39, -v35, v38, v37
	v_fmac_f32_e32 v38, v39, v36
	v_fma_f32 v35, -v35, v38, v37
	v_mul_f32_e32 v37, 0xbfb8aa3b, v16
	v_exp_f32_e32 v37, v37
	v_div_fmas_f32 v35, v35, v36, v38
	v_div_fixup_f32 v28, v35, v34, v28
	v_mul_f32_e32 v24, v24, v28
	v_add_f32_e32 v34, 1.0, v37
	v_div_scale_f32 v35, s[40:41], v34, v34, v16
	v_rcp_f32_e32 v36, v35
	v_cvt_pk_bf16_f32 v24, v24, v24
	global_store_short v[32:33], v24, off
	v_fma_f32 v24, -v35, v36, 1.0
	v_fmac_f32_e32 v36, v24, v36
	v_div_scale_f32 v24, vcc, v16, v34, v16
	v_mul_f32_e32 v28, v24, v36
	v_fma_f32 v37, -v35, v28, v24
	v_fmac_f32_e32 v28, v37, v36
	v_fma_f32 v24, -v35, v28, v24
	v_div_fmas_f32 v24, v24, v36, v28
	v_div_fixup_f32 v16, v24, v34, v16
	v_mul_f32_e32 v16, v20, v16
	v_cvt_pk_bf16_f32 v16, v16, v16
	global_store_short v[32:33], v16, off offset:32
	v_mul_f32_e32 v16, 0xbfb8aa3b, v29
	v_exp_f32_e32 v16, v16
	v_or_b32_e32 v20, 33, v50
	v_mad_i64_i32 v[32:33], s[40:41], v20, s73, v[48:49]
	v_add_f32_e32 v16, 1.0, v16
	v_div_scale_f32 v24, s[40:41], v16, v16, v29
	v_rcp_f32_e32 v28, v24
	v_div_scale_f32 v20, vcc, v29, v16, v29
	v_fma_f32 v34, -v24, v28, 1.0
	v_fmac_f32_e32 v28, v34, v28
	v_mul_f32_e32 v34, v20, v28
	v_fma_f32 v35, -v24, v34, v20
	v_fmac_f32_e32 v34, v35, v28
	v_fma_f32 v20, -v24, v34, v20
	v_mul_f32_e32 v24, 0xbfb8aa3b, v17
	v_exp_f32_e32 v24, v24
	v_div_fmas_f32 v20, v20, v28, v34
	v_div_fixup_f32 v16, v20, v16, v29
	v_mul_f32_e32 v16, v25, v16
	v_add_f32_e32 v20, 1.0, v24
	v_div_scale_f32 v24, s[40:41], v20, v20, v17
	v_rcp_f32_e32 v28, v24
	v_cvt_pk_bf16_f32 v16, v16, v16
	global_store_short v[32:33], v16, off
	v_fma_f32 v16, -v24, v28, 1.0
	v_fmac_f32_e32 v28, v16, v28
	v_div_scale_f32 v16, vcc, v17, v20, v17
	v_mul_f32_e32 v25, v16, v28
	v_fma_f32 v29, -v24, v25, v16
	v_fmac_f32_e32 v25, v29, v28
	v_fma_f32 v16, -v24, v25, v16
	v_div_fmas_f32 v16, v16, v28, v25
	v_div_fixup_f32 v16, v16, v20, v17
	v_mul_f32_e32 v16, v21, v16
	v_cvt_pk_bf16_f32 v16, v16, v16
	global_store_short v[32:33], v16, off offset:32
	v_mul_f32_e32 v16, 0xbfb8aa3b, v30
	v_exp_f32_e32 v16, v16
	v_or_b32_e32 v17, 34, v50
	v_add_f32_e32 v20, 1.0, v16
	v_div_scale_f32 v21, s[40:41], v20, v20, v30
	v_rcp_f32_e32 v24, v21
	v_div_scale_f32 v25, vcc, v30, v20, v30
	v_mad_i64_i32 v[16:17], s[40:41], v17, s73, v[48:49]
	v_fma_f32 v28, -v21, v24, 1.0
	v_fmac_f32_e32 v24, v28, v24
	v_mul_f32_e32 v28, v25, v24
	v_fma_f32 v29, -v21, v28, v25
	v_fmac_f32_e32 v28, v29, v24
	v_fma_f32 v21, -v21, v28, v25
	v_mul_f32_e32 v25, 0xbfb8aa3b, v18
	v_exp_f32_e32 v25, v25
	v_div_fmas_f32 v21, v21, v24, v28
	v_div_fixup_f32 v20, v21, v20, v30
	v_mul_f32_e32 v20, v26, v20
	v_add_f32_e32 v21, 1.0, v25
	v_div_scale_f32 v24, s[40:41], v21, v21, v18
	v_rcp_f32_e32 v25, v24
	v_cvt_pk_bf16_f32 v20, v20, v20
	global_store_short v[16:17], v20, off
	v_fma_f32 v20, -v24, v25, 1.0
	v_fmac_f32_e32 v25, v20, v25
	v_div_scale_f32 v20, vcc, v18, v21, v18
	v_mul_f32_e32 v26, v20, v25
	v_fma_f32 v28, -v24, v26, v20
	v_fmac_f32_e32 v26, v28, v25
	v_fma_f32 v20, -v24, v26, v20
	v_div_fmas_f32 v20, v20, v25, v26
	v_div_fixup_f32 v18, v20, v21, v18
	v_mul_f32_e32 v18, v22, v18
	v_cvt_pk_bf16_f32 v18, v18, v18
	global_store_short v[16:17], v18, off offset:32
	v_mul_f32_e32 v16, 0xbfb8aa3b, v31
	v_exp_f32_e32 v16, v16
	v_or_b32_e32 v17, 35, v50
	v_add_f32_e32 v18, 1.0, v16
	v_div_scale_f32 v20, s[40:41], v18, v18, v31
	v_rcp_f32_e32 v21, v20
	v_div_scale_f32 v22, vcc, v31, v18, v31
	v_mad_i64_i32 v[16:17], s[40:41], v17, s73, v[48:49]
	v_fma_f32 v24, -v20, v21, 1.0
	v_fmac_f32_e32 v21, v24, v21
	v_mul_f32_e32 v24, v22, v21
	v_fma_f32 v25, -v20, v24, v22
	v_fmac_f32_e32 v24, v25, v21
	v_fma_f32 v20, -v20, v24, v22
	v_mul_f32_e32 v22, 0xbfb8aa3b, v19
	v_exp_f32_e32 v22, v22
	v_div_fmas_f32 v20, v20, v21, v24
	v_div_fixup_f32 v18, v20, v18, v31
	v_mul_f32_e32 v18, v27, v18
	v_add_f32_e32 v20, 1.0, v22
	v_div_scale_f32 v21, s[40:41], v20, v20, v19
	v_rcp_f32_e32 v22, v21
	v_cvt_pk_bf16_f32 v18, v18, v18
	global_store_short v[16:17], v18, off
	v_fma_f32 v18, -v21, v22, 1.0
	v_fmac_f32_e32 v22, v18, v22
	v_div_scale_f32 v18, vcc, v19, v20, v19
	v_mul_f32_e32 v24, v18, v22
	v_fma_f32 v25, -v21, v24, v18
	v_fmac_f32_e32 v24, v25, v22
	v_fma_f32 v18, -v21, v24, v18
	v_div_fmas_f32 v18, v18, v22, v24
	v_div_fixup_f32 v18, v18, v20, v19
	v_mul_f32_e32 v18, v23, v18
	v_cvt_pk_bf16_f32 v18, v18, v18
	global_store_short v[16:17], v18, off offset:32
	v_mul_f32_e32 v16, 0xbfb8aa3b, v12
	v_exp_f32_e32 v16, v16
	v_or_b32_e32 v17, 48, v50
	v_add_f32_e32 v18, 1.0, v16
	v_div_scale_f32 v19, s[40:41], v18, v18, v12
	v_rcp_f32_e32 v20, v19
	v_div_scale_f32 v21, vcc, v12, v18, v12
	v_mad_i64_i32 v[16:17], s[40:41], v17, s73, v[48:49]
	v_fma_f32 v22, -v19, v20, 1.0
	v_fmac_f32_e32 v20, v22, v20
	v_mul_f32_e32 v22, v21, v20
	v_fma_f32 v23, -v19, v22, v21
	v_fmac_f32_e32 v22, v23, v20
	v_fma_f32 v19, -v19, v22, v21
	v_mul_f32_e32 v21, 0xbfb8aa3b, v0
	v_exp_f32_e32 v21, v21
	v_div_fmas_f32 v19, v19, v20, v22
	v_div_fixup_f32 v12, v19, v18, v12
	v_mul_f32_e32 v8, v8, v12
	v_add_f32_e32 v18, 1.0, v21
	v_div_scale_f32 v19, s[40:41], v18, v18, v0
	v_rcp_f32_e32 v20, v19
	v_cvt_pk_bf16_f32 v8, v8, v8
	global_store_short v[16:17], v8, off
	v_fma_f32 v8, -v19, v20, 1.0
	v_fmac_f32_e32 v20, v8, v20
	v_div_scale_f32 v8, vcc, v0, v18, v0
	v_mul_f32_e32 v12, v8, v20
	v_fma_f32 v21, -v19, v12, v8
	v_fmac_f32_e32 v12, v21, v20
	v_fma_f32 v8, -v19, v12, v8
	v_div_fmas_f32 v8, v8, v20, v12
	v_div_fixup_f32 v0, v8, v18, v0
	v_mul_f32_e32 v0, v4, v0
	v_cvt_pk_bf16_f32 v0, v0, v0
	global_store_short v[16:17], v0, off offset:32
	v_mul_f32_e32 v0, 0xbfb8aa3b, v13
	v_exp_f32_e32 v0, v0
	v_or_b32_e32 v4, 49, v50
	v_mad_i64_i32 v[16:17], s[40:41], v4, s73, v[48:49]
	v_add_f32_e32 v0, 1.0, v0
	v_div_scale_f32 v8, s[40:41], v0, v0, v13
	v_rcp_f32_e32 v12, v8
	v_div_scale_f32 v4, vcc, v13, v0, v13
	v_fma_f32 v18, -v8, v12, 1.0
	v_fmac_f32_e32 v12, v18, v12
	v_mul_f32_e32 v18, v4, v12
	v_fma_f32 v19, -v8, v18, v4
	v_fmac_f32_e32 v18, v19, v12
	v_fma_f32 v4, -v8, v18, v4
	v_mul_f32_e32 v8, 0xbfb8aa3b, v1
	v_exp_f32_e32 v8, v8
	v_div_fmas_f32 v4, v4, v12, v18
	v_div_fixup_f32 v0, v4, v0, v13
	v_mul_f32_e32 v0, v9, v0
	v_add_f32_e32 v4, 1.0, v8
	v_div_scale_f32 v8, s[40:41], v4, v4, v1
	v_rcp_f32_e32 v12, v8
	v_cvt_pk_bf16_f32 v0, v0, v0
	global_store_short v[16:17], v0, off
	v_fma_f32 v0, -v8, v12, 1.0
	v_fmac_f32_e32 v12, v0, v12
	v_div_scale_f32 v0, vcc, v1, v4, v1
	v_mul_f32_e32 v9, v0, v12
	v_fma_f32 v13, -v8, v9, v0
	v_fmac_f32_e32 v9, v13, v12
	v_fma_f32 v0, -v8, v9, v0
	v_div_fmas_f32 v0, v0, v12, v9
	v_div_fixup_f32 v0, v0, v4, v1
	v_mul_f32_e32 v0, v5, v0
	v_cvt_pk_bf16_f32 v0, v0, v0
	global_store_short v[16:17], v0, off offset:32
	v_mul_f32_e32 v0, 0xbfb8aa3b, v14
	v_exp_f32_e32 v0, v0
	v_or_b32_e32 v1, 50, v50
	v_add_f32_e32 v4, 1.0, v0
	v_div_scale_f32 v5, s[40:41], v4, v4, v14
	v_rcp_f32_e32 v8, v5
	v_div_scale_f32 v9, vcc, v14, v4, v14
	v_mad_i64_i32 v[0:1], s[40:41], v1, s73, v[48:49]
	v_fma_f32 v12, -v5, v8, 1.0
	v_fmac_f32_e32 v8, v12, v8
	v_mul_f32_e32 v12, v9, v8
	v_fma_f32 v13, -v5, v12, v9
	v_fmac_f32_e32 v12, v13, v8
	v_fma_f32 v5, -v5, v12, v9
	v_mul_f32_e32 v9, 0xbfb8aa3b, v2
	v_exp_f32_e32 v9, v9
	v_div_fmas_f32 v5, v5, v8, v12
	v_div_fixup_f32 v4, v5, v4, v14
	v_mul_f32_e32 v4, v10, v4
	v_add_f32_e32 v5, 1.0, v9
	v_div_scale_f32 v8, s[40:41], v5, v5, v2
	v_rcp_f32_e32 v9, v8
	v_cvt_pk_bf16_f32 v4, v4, v4
	global_store_short v[0:1], v4, off
	v_fma_f32 v4, -v8, v9, 1.0
	v_fmac_f32_e32 v9, v4, v9
	v_div_scale_f32 v4, vcc, v2, v5, v2
	v_mul_f32_e32 v10, v4, v9
	v_fma_f32 v12, -v8, v10, v4
	v_fmac_f32_e32 v10, v12, v9
	v_fma_f32 v4, -v8, v10, v4
	v_div_fmas_f32 v4, v4, v9, v10
	v_div_fixup_f32 v2, v4, v5, v2
	v_mul_f32_e32 v2, v6, v2
	v_cvt_pk_bf16_f32 v2, v2, v2
	global_store_short v[0:1], v2, off offset:32
	v_mul_f32_e32 v0, 0xbfb8aa3b, v15
	v_exp_f32_e32 v0, v0
	v_or_b32_e32 v1, 51, v50
	v_add_f32_e32 v2, 1.0, v0
	v_div_scale_f32 v4, s[40:41], v2, v2, v15
	v_rcp_f32_e32 v5, v4
	v_div_scale_f32 v6, vcc, v15, v2, v15
	v_mad_i64_i32 v[0:1], s[40:41], v1, s73, v[48:49]
	v_fma_f32 v8, -v4, v5, 1.0
	v_fmac_f32_e32 v5, v8, v5
	v_mul_f32_e32 v8, v6, v5
	v_fma_f32 v9, -v4, v8, v6
	v_fmac_f32_e32 v8, v9, v5
	v_fma_f32 v4, -v4, v8, v6
	v_mul_f32_e32 v6, 0xbfb8aa3b, v3
	v_exp_f32_e32 v6, v6
	v_div_fmas_f32 v4, v4, v5, v8
	v_div_fixup_f32 v2, v4, v2, v15
	v_mul_f32_e32 v2, v11, v2
	v_add_f32_e32 v4, 1.0, v6
	v_div_scale_f32 v5, s[40:41], v4, v4, v3
	v_rcp_f32_e32 v6, v5
	v_cvt_pk_bf16_f32 v2, v2, v2
	global_store_short v[0:1], v2, off
	v_fma_f32 v2, -v5, v6, 1.0
	v_fmac_f32_e32 v6, v2, v6
	v_div_scale_f32 v2, vcc, v3, v4, v3
	v_mul_f32_e32 v8, v2, v6
	v_fma_f32 v9, -v5, v8, v2
	v_fmac_f32_e32 v8, v9, v6
	v_fma_f32 v2, -v5, v8, v2
	v_div_fmas_f32 v2, v2, v6, v8
	v_div_fixup_f32 v2, v2, v4, v3
	v_mul_f32_e32 v2, v7, v2
	v_cvt_pk_bf16_f32 v2, v2, v2
	global_store_short v[0:1], v2, off offset:32
	s_branch .LBB0_1236
